# GEMM 256x128 tile epilogue + next-tile prologue run at s_setprio 3 (reset to 0 at phase end); loops unchanged
# speedup vs baseline: 1.0016x; 1.0010x over previous
; DEVI f32x4 mfma16(bf16x8 a, bf16x8 b, f32x4 c) { return __builtin_amdgcn_mfma_f32_16x16x32_bf16(a, b, c, 0, 0, 0); }
; DEVI void gemm_core3(f32x4 (&acc)[8][4], const bf* __restrict__ A, int lda, const bf* __restrict__ Bt, int ldb, int K, char* smem) {
;     ...
;   for (int kt = 0; kt < nk; ++kt) {
;     const int k1 = min((kt + 1) * 32, klast);
;     const int sn = ((kt + 1) & 1) * STG;
;     const int so = (kt & 1) * STG;
;     bf16x8 bfr[4], af[8];
; #pragma unroll
;     for (int n = 0; n < 4; ++n) bfr[n] = *reinterpret_cast<const bf16x8*>(bbase + so + n * 16 * 64);
; #pragma unroll
;     for (int m = 0; m < 8; ++m) af[m] = *reinterpret_cast<const bf16x8*>(abase + so + m * 16 * 64);
; #pragma unroll
;     for (int i = 0; i < 4; ++i) glds16(Ap + i * sa + k1, dbase + sn + i * 4096);
; #pragma unroll
;     for (int i = 0; i < 2; ++i) glds16(Bp + i * sb + k1, dbase + sn + ASZ + i * 4096);
;     __builtin_amdgcn_s_setprio(1);
; #pragma unroll
;     for (int m = 0; m < 8; ++m)
; #pragma unroll
;       for (int n = 0; n < 4; ++n) acc[m][n] = mfma16(af[m], bfr[n], acc[m][n]);
;     __builtin_amdgcn_s_setprio(0);
;     __syncthreads();
;   }
.Lg3_loop_173:
	v_add_u32_e32 v216, s10, v146
	v_add_u32_e32 v217, s10, v2
	ds_read_b128 v[148:151], v217 offset:16384
	ds_read_b128 v[166:169], v216
	ds_read_b128 v[154:157], v217 offset:17408
	ds_read_b128 v[158:161], v217 offset:18432
	ds_read_b128 v[162:165], v217 offset:19456
	ds_read_b128 v[170:173], v216 offset:1024
	ds_read_b128 v[174:177], v216 offset:2048
	ds_read_b128 v[192:195], v216 offset:3072
	ds_read_b128 v[196:199], v216 offset:4096
	ds_read_b128 v[204:207], v216 offset:5120
	ds_read_b128 v[208:211], v216 offset:6144
	ds_read_b128 v[212:215], v216 offset:7168
	s_setprio 1
	s_waitcnt lgkmcnt(10)
	v_mfma_f32_16x16x32_bf16 v[128:131], v[166:169], v[148:151], v[128:131]
	s_waitcnt lgkmcnt(9)
	v_mfma_f32_16x16x32_bf16 v[124:127], v[166:169], v[154:157], v[124:127]
	s_waitcnt lgkmcnt(8)
	v_mfma_f32_16x16x32_bf16 v[120:123], v[166:169], v[158:161], v[120:123]
	s_waitcnt lgkmcnt(7)
	v_mfma_f32_16x16x32_bf16 v[116:119], v[166:169], v[162:165], v[116:119]
	s_waitcnt lgkmcnt(6)
	v_mfma_f32_16x16x32_bf16 v[112:115], v[170:173], v[148:151], v[112:115]
	v_mfma_f32_16x16x32_bf16 v[108:111], v[170:173], v[154:157], v[108:111]
	v_mfma_f32_16x16x32_bf16 v[104:107], v[170:173], v[158:161], v[104:107]
	v_mfma_f32_16x16x32_bf16 v[100:103], v[170:173], v[162:165], v[100:103]
	s_waitcnt lgkmcnt(5)
	v_mfma_f32_16x16x32_bf16 v[96:99], v[174:177], v[148:151], v[96:99]
	v_mfma_f32_16x16x32_bf16 v[92:95], v[174:177], v[154:157], v[92:95]
	v_mfma_f32_16x16x32_bf16 v[88:91], v[174:177], v[158:161], v[88:91]
	v_mfma_f32_16x16x32_bf16 v[84:87], v[174:177], v[162:165], v[84:87]
	s_waitcnt lgkmcnt(4)
	v_mfma_f32_16x16x32_bf16 v[80:83], v[192:195], v[148:151], v[80:83]
	v_mfma_f32_16x16x32_bf16 v[76:79], v[192:195], v[154:157], v[76:79]
	v_mfma_f32_16x16x32_bf16 v[72:75], v[192:195], v[158:161], v[72:75]
	v_mfma_f32_16x16x32_bf16 v[68:71], v[192:195], v[162:165], v[68:71]
	s_waitcnt lgkmcnt(3)
	v_mfma_f32_16x16x32_bf16 v[64:67], v[196:199], v[148:151], v[64:67]
	v_mfma_f32_16x16x32_bf16 v[60:63], v[196:199], v[154:157], v[60:63]
	v_mfma_f32_16x16x32_bf16 v[56:59], v[196:199], v[158:161], v[56:59]
	v_mfma_f32_16x16x32_bf16 v[52:55], v[196:199], v[162:165], v[52:55]
	s_waitcnt lgkmcnt(2)
	v_mfma_f32_16x16x32_bf16 v[48:51], v[204:207], v[148:151], v[48:51]
	v_mfma_f32_16x16x32_bf16 v[44:47], v[204:207], v[154:157], v[44:47]
	v_mfma_f32_16x16x32_bf16 v[40:43], v[204:207], v[158:161], v[40:43]
	v_mfma_f32_16x16x32_bf16 v[36:39], v[204:207], v[162:165], v[36:39]
	s_waitcnt lgkmcnt(1)
	v_mfma_f32_16x16x32_bf16 v[32:35], v[208:211], v[148:151], v[32:35]
	v_mfma_f32_16x16x32_bf16 v[28:31], v[208:211], v[154:157], v[28:31]
	v_mfma_f32_16x16x32_bf16 v[24:27], v[208:211], v[158:161], v[24:27]
	v_mfma_f32_16x16x32_bf16 v[20:23], v[208:211], v[162:165], v[20:23]
	s_waitcnt lgkmcnt(0)
	v_mfma_f32_16x16x32_bf16 v[16:19], v[212:215], v[148:151], v[16:19]
	v_mfma_f32_16x16x32_bf16 v[12:15], v[212:215], v[154:157], v[12:15]
	v_mfma_f32_16x16x32_bf16 v[8:11], v[212:215], v[158:161], v[8:11]
	v_mfma_f32_16x16x32_bf16 v[4:7], v[212:215], v[162:165], v[4:7]
	s_setprio 0
	s_add_i32 s10, s10, 0x6000
	s_cmp_lg_u32 s10, 0x12000
	s_cselect_b32 s10, s10, 0
	s_waitcnt vmcnt(0)
	s_barrier
	v_add_u32_e32 v216, s10, v146
	v_add_u32_e32 v217, s10, v2
	ds_read_b128 v[148:151], v217 offset:16384
	ds_read_b128 v[166:169], v216
	ds_read_b128 v[154:157], v217 offset:17408
	ds_read_b128 v[158:161], v217 offset:18432
	ds_read_b128 v[162:165], v217 offset:19456
	ds_read_b128 v[170:173], v216 offset:1024
	ds_read_b128 v[174:177], v216 offset:2048
	ds_read_b128 v[192:195], v216 offset:3072
	ds_read_b128 v[196:199], v216 offset:4096
	ds_read_b128 v[204:207], v216 offset:5120
	ds_read_b128 v[208:211], v216 offset:6144
	ds_read_b128 v[212:215], v216 offset:7168
	v_readfirstlane_b32 s17, v140
	s_add_i32 s96, s11, 0x6000
	s_cmp_lg_u32 s96, 0x12000
	s_cselect_b32 s96, s96, 0
	s_add_i32 s96, s96, s17
	s_add_i32 s17, s17, s11
	s_setprio 2
	s_waitcnt lgkmcnt(10)
	s_mov_b32 m0, s17
	s_add_i32 s17, s17, 0x1000
	v_mfma_f32_16x16x32_bf16 v[128:131], v[166:169], v[148:151], v[128:131]
	s_waitcnt lgkmcnt(9)
	v_mfma_f32_16x16x32_bf16 v[124:127], v[166:169], v[154:157], v[124:127]
	global_load_lds_dwordx4 v[218:219], off
	v_lshl_add_u64 v[218:219], v[218:219], 0, 64
	s_waitcnt lgkmcnt(8)
	s_mov_b32 m0, s96
	s_add_i32 s96, s96, 0x1000
	v_mfma_f32_16x16x32_bf16 v[120:123], v[166:169], v[158:161], v[120:123]
	s_waitcnt lgkmcnt(7)
	v_mfma_f32_16x16x32_bf16 v[116:119], v[166:169], v[162:165], v[116:119]
	global_load_lds_dwordx4 v[218:219], off
	v_lshl_add_u64 v[218:219], v[218:219], 0, 64
	s_waitcnt lgkmcnt(6)
	v_mfma_f32_16x16x32_bf16 v[112:115], v[170:173], v[148:151], v[112:115]
	s_mov_b32 m0, s17
	s_add_i32 s17, s17, 0x1000
	v_mfma_f32_16x16x32_bf16 v[108:111], v[170:173], v[154:157], v[108:111]
	v_mfma_f32_16x16x32_bf16 v[104:107], v[170:173], v[158:161], v[104:107]
	global_load_lds_dwordx4 v[220:221], off
	v_lshl_add_u64 v[220:221], v[220:221], 0, 64
	s_mov_b32 m0, s96
	s_add_i32 s96, s96, 0x1000
	v_mfma_f32_16x16x32_bf16 v[100:103], v[170:173], v[162:165], v[100:103]
	s_waitcnt lgkmcnt(5)
	v_mfma_f32_16x16x32_bf16 v[96:99], v[174:177], v[148:151], v[96:99]
	global_load_lds_dwordx4 v[220:221], off
	v_lshl_add_u64 v[220:221], v[220:221], 0, 64
	v_mfma_f32_16x16x32_bf16 v[92:95], v[174:177], v[154:157], v[92:95]
	s_mov_b32 m0, s17
	s_add_i32 s17, s17, 0x1000
	v_mfma_f32_16x16x32_bf16 v[88:91], v[174:177], v[158:161], v[88:91]
	v_mfma_f32_16x16x32_bf16 v[84:87], v[174:177], v[162:165], v[84:87]
	global_load_lds_dwordx4 v[222:223], off
	v_lshl_add_u64 v[222:223], v[222:223], 0, 64
	s_waitcnt lgkmcnt(4)
; DEVI f32x4 mfma16(bf16x8 a, bf16x8 b, f32x4 c) { return __builtin_amdgcn_mfma_f32_16x16x32_bf16(a, b, c, 0, 0, 0); }
; DEVI void gemm_core3(f32x4 (&acc)[8][4], const bf* __restrict__ A, int lda, const bf* __restrict__ Bt, int ldb, int K, char* smem) {
;     ...
;   for (int kt = 0; kt < nk; ++kt) {
;     const int k1 = min((kt + 1) * 32, klast);
;     const int sn = ((kt + 1) & 1) * STG;
;     const int so = (kt & 1) * STG;
;     bf16x8 bfr[4], af[8];
; #pragma unroll
;     for (int n = 0; n < 4; ++n) bfr[n] = *reinterpret_cast<const bf16x8*>(bbase + so + n * 16 * 64);
; #pragma unroll
;     for (int m = 0; m < 8; ++m) af[m] = *reinterpret_cast<const bf16x8*>(abase + so + m * 16 * 64);
; #pragma unroll
;     for (int i = 0; i < 4; ++i) glds16(Ap + i * sa + k1, dbase + sn + i * 4096);
; #pragma unroll
;     for (int i = 0; i < 2; ++i) glds16(Bp + i * sb + k1, dbase + sn + ASZ + i * 4096);
;     __builtin_amdgcn_s_setprio(1);
; #pragma unroll
;     for (int m = 0; m < 8; ++m)
; #pragma unroll
;       for (int n = 0; n < 4; ++n) acc[m][n] = mfma16(af[m], bfr[n], acc[m][n]);
;     __builtin_amdgcn_s_setprio(0);
;     __syncthreads();
;   }
	s_mov_b32 m0, s96
	s_add_i32 s96, s96, 0x1000
	v_mfma_f32_16x16x32_bf16 v[80:83], v[192:195], v[148:151], v[80:83]
	v_mfma_f32_16x16x32_bf16 v[76:79], v[192:195], v[154:157], v[76:79]
	global_load_lds_dwordx4 v[222:223], off
	v_lshl_add_u64 v[222:223], v[222:223], 0, 64
	v_mfma_f32_16x16x32_bf16 v[72:75], v[192:195], v[158:161], v[72:75]
	s_mov_b32 m0, s17
	s_add_i32 s17, s17, 0x1000
	v_mfma_f32_16x16x32_bf16 v[68:71], v[192:195], v[162:165], v[68:71]
	s_waitcnt lgkmcnt(3)
	v_mfma_f32_16x16x32_bf16 v[64:67], v[196:199], v[148:151], v[64:67]
	global_load_lds_dwordx4 v[224:225], off
	v_lshl_add_u64 v[224:225], v[224:225], 0, 64
	s_mov_b32 m0, s96
	s_add_i32 s96, s96, 0x1000
	v_mfma_f32_16x16x32_bf16 v[60:63], v[196:199], v[154:157], v[60:63]
	v_mfma_f32_16x16x32_bf16 v[56:59], v[196:199], v[158:161], v[56:59]
	global_load_lds_dwordx4 v[224:225], off
	v_lshl_add_u64 v[224:225], v[224:225], 0, 64
	v_mfma_f32_16x16x32_bf16 v[52:55], v[196:199], v[162:165], v[52:55]
	s_waitcnt lgkmcnt(2)
	s_mov_b32 m0, s17
	s_add_i32 s17, s17, 0x1000
	v_mfma_f32_16x16x32_bf16 v[48:51], v[204:207], v[148:151], v[48:51]
	v_mfma_f32_16x16x32_bf16 v[44:47], v[204:207], v[154:157], v[44:47]
	global_load_lds_dwordx4 v[226:227], off
	v_lshl_add_u64 v[226:227], v[226:227], 0, 64
	s_mov_b32 m0, s96
	s_add_i32 s96, s96, 0x1000
	v_mfma_f32_16x16x32_bf16 v[40:43], v[204:207], v[158:161], v[40:43]
	v_mfma_f32_16x16x32_bf16 v[36:39], v[204:207], v[162:165], v[36:39]
	global_load_lds_dwordx4 v[226:227], off
	v_lshl_add_u64 v[226:227], v[226:227], 0, 64
	s_waitcnt lgkmcnt(1)
	v_mfma_f32_16x16x32_bf16 v[32:35], v[208:211], v[148:151], v[32:35]
	s_mov_b32 m0, s17
	s_add_i32 s17, s17, 0x1000
	v_mfma_f32_16x16x32_bf16 v[28:31], v[208:211], v[154:157], v[28:31]
	v_mfma_f32_16x16x32_bf16 v[24:27], v[208:211], v[158:161], v[24:27]
	global_load_lds_dwordx4 v[228:229], off
	v_lshl_add_u64 v[228:229], v[228:229], 0, 64
	s_mov_b32 m0, s96
	s_add_i32 s96, s96, 0x1000
	v_mfma_f32_16x16x32_bf16 v[20:23], v[208:211], v[162:165], v[20:23]
	s_waitcnt lgkmcnt(0)
	v_mfma_f32_16x16x32_bf16 v[16:19], v[212:215], v[148:151], v[16:19]
	global_load_lds_dwordx4 v[228:229], off
	v_lshl_add_u64 v[228:229], v[228:229], 0, 64
	v_mfma_f32_16x16x32_bf16 v[12:15], v[212:215], v[154:157], v[12:15]
	v_mfma_f32_16x16x32_bf16 v[8:11], v[212:215], v[158:161], v[8:11]
	v_mfma_f32_16x16x32_bf16 v[4:7], v[212:215], v[162:165], v[4:7]
	s_setprio 0
	s_add_i32 s10, s10, 0x6000
	s_cmp_lg_u32 s10, 0x12000
	s_cselect_b32 s10, s10, 0
	s_sub_i32 s11, s11, 0x6000
	s_cmp_lt_i32 s11, 0
	s_cselect_b32 s11, 0xc000, s11
	s_add_i32 s3, s3, 1
	s_cmp_lt_i32 s3, 43
	s_waitcnt vmcnt(1)
	s_barrier
	s_cbranch_scc1 .Lg3_loop_173
	v_add_u32_e32 v216, s10, v146
	v_add_u32_e32 v217, s10, v2
	ds_read_b128 v[148:151], v217 offset:16384
	ds_read_b128 v[166:169], v216
	ds_read_b128 v[154:157], v217 offset:17408
	ds_read_b128 v[158:161], v217 offset:18432
	ds_read_b128 v[162:165], v217 offset:19456
	ds_read_b128 v[170:173], v216 offset:1024
	ds_read_b128 v[174:177], v216 offset:2048
	ds_read_b128 v[192:195], v216 offset:3072
	ds_read_b128 v[196:199], v216 offset:4096
	ds_read_b128 v[204:207], v216 offset:5120
	ds_read_b128 v[208:211], v216 offset:6144
	ds_read_b128 v[212:215], v216 offset:7168
	s_setprio 1
	s_waitcnt lgkmcnt(10)
	v_mfma_f32_16x16x32_bf16 v[128:131], v[166:169], v[148:151], v[128:131]
	s_waitcnt lgkmcnt(9)
	v_mfma_f32_16x16x32_bf16 v[124:127], v[166:169], v[154:157], v[124:127]
	s_waitcnt lgkmcnt(8)
	v_mfma_f32_16x16x32_bf16 v[120:123], v[166:169], v[158:161], v[120:123]
	s_waitcnt lgkmcnt(7)
	v_mfma_f32_16x16x32_bf16 v[116:119], v[166:169], v[162:165], v[116:119]
	s_waitcnt lgkmcnt(6)
	v_mfma_f32_16x16x32_bf16 v[112:115], v[170:173], v[148:151], v[112:115]
	v_mfma_f32_16x16x32_bf16 v[108:111], v[170:173], v[154:157], v[108:111]
	v_mfma_f32_16x16x32_bf16 v[104:107], v[170:173], v[158:161], v[104:107]
	v_mfma_f32_16x16x32_bf16 v[100:103], v[170:173], v[162:165], v[100:103]
	s_waitcnt lgkmcnt(5)
	v_mfma_f32_16x16x32_bf16 v[96:99], v[174:177], v[148:151], v[96:99]
	v_mfma_f32_16x16x32_bf16 v[92:95], v[174:177], v[154:157], v[92:95]
	v_mfma_f32_16x16x32_bf16 v[88:91], v[174:177], v[158:161], v[88:91]
	v_mfma_f32_16x16x32_bf16 v[84:87], v[174:177], v[162:165], v[84:87]
	s_waitcnt lgkmcnt(4)
	v_mfma_f32_16x16x32_bf16 v[80:83], v[192:195], v[148:151], v[80:83]
	v_mfma_f32_16x16x32_bf16 v[76:79], v[192:195], v[154:157], v[76:79]
	v_mfma_f32_16x16x32_bf16 v[72:75], v[192:195], v[158:161], v[72:75]
	v_mfma_f32_16x16x32_bf16 v[68:71], v[192:195], v[162:165], v[68:71]
	s_waitcnt lgkmcnt(3)
	v_mfma_f32_16x16x32_bf16 v[64:67], v[196:199], v[148:151], v[64:67]
	v_mfma_f32_16x16x32_bf16 v[60:63], v[196:199], v[154:157], v[60:63]
	v_mfma_f32_16x16x32_bf16 v[56:59], v[196:199], v[158:161], v[56:59]
	v_mfma_f32_16x16x32_bf16 v[52:55], v[196:199], v[162:165], v[52:55]
	s_waitcnt lgkmcnt(2)
	v_mfma_f32_16x16x32_bf16 v[48:51], v[204:207], v[148:151], v[48:51]
	v_mfma_f32_16x16x32_bf16 v[44:47], v[204:207], v[154:157], v[44:47]
	v_mfma_f32_16x16x32_bf16 v[40:43], v[204:207], v[158:161], v[40:43]
	v_mfma_f32_16x16x32_bf16 v[36:39], v[204:207], v[162:165], v[36:39]
	s_waitcnt lgkmcnt(1)
	v_mfma_f32_16x16x32_bf16 v[32:35], v[208:211], v[148:151], v[32:35]
	v_mfma_f32_16x16x32_bf16 v[28:31], v[208:211], v[154:157], v[28:31]
	v_mfma_f32_16x16x32_bf16 v[24:27], v[208:211], v[158:161], v[24:27]
	v_mfma_f32_16x16x32_bf16 v[20:23], v[208:211], v[162:165], v[20:23]
	s_waitcnt lgkmcnt(0)
	v_mfma_f32_16x16x32_bf16 v[16:19], v[212:215], v[148:151], v[16:19]
	v_mfma_f32_16x16x32_bf16 v[12:15], v[212:215], v[154:157], v[12:15]
	v_mfma_f32_16x16x32_bf16 v[8:11], v[212:215], v[158:161], v[8:11]
	v_mfma_f32_16x16x32_bf16 v[4:7], v[212:215], v[162:165], v[4:7]
	s_setprio 0
	s_add_i32 s10, s10, 0x6000
	s_cmp_lg_u32 s10, 0x12000
	s_cselect_b32 s10, s10, 0
	s_waitcnt vmcnt(0)
	s_barrier
; DEVI f32x4 mfma16(bf16x8 a, bf16x8 b, f32x4 c) { return __builtin_amdgcn_mfma_f32_16x16x32_bf16(a, b, c, 0, 0, 0); }
; DEVI void gemm_core3(f32x4 (&acc)[8][4], const bf* __restrict__ A, int lda, const bf* __restrict__ Bt, int ldb, int K, char* smem) {
;     ...
;     __builtin_amdgcn_s_setprio(1);
; #pragma unroll
;     for (int m = 0; m < 8; ++m)
; #pragma unroll
;       for (int n = 0; n < 4; ++n) acc[m][n] = mfma16(af[m], bfr[n], acc[m][n]);
;     __builtin_amdgcn_s_setprio(0);
;     __syncthreads();
; DEVI void plain_tile256(const bf* A, int lda, const bf* Wt, int K, bf* C, int ldc, long row0, int n0, char* smem) {
;     ...
;   bf* tl = reinterpret_cast<bf*>(smem);
; #pragma unroll
;   for (int m = 0; m < 8; ++m)
; #pragma unroll
;     for (int n = 0; n < 4; ++n) {
;       const int cl = wc * 64 + n * 16 + l15;
; #pragma unroll
;       for (int j = 0; j < 4; ++j) tl[(wr * 128 + m * 16 + quad * 4 + j) * 136 + cl] = f2bf(acc[m][n][j]);
;     }
	v_add_u32_e32 v216, s10, v146
	v_add_u32_e32 v217, s10, v2
	ds_read_b128 v[148:151], v217 offset:16384
	ds_read_b128 v[166:169], v216
	ds_read_b128 v[154:157], v217 offset:17408
	ds_read_b128 v[158:161], v217 offset:18432
	ds_read_b128 v[162:165], v217 offset:19456
	ds_read_b128 v[170:173], v216 offset:1024
	ds_read_b128 v[174:177], v216 offset:2048
	ds_read_b128 v[192:195], v216 offset:3072
	ds_read_b128 v[196:199], v216 offset:4096
	ds_read_b128 v[204:207], v216 offset:5120
	ds_read_b128 v[208:211], v216 offset:6144
	ds_read_b128 v[212:215], v216 offset:7168
	s_setprio 1
	s_waitcnt lgkmcnt(10)
	v_mfma_f32_16x16x32_bf16 v[128:131], v[166:169], v[148:151], v[128:131]
	s_waitcnt lgkmcnt(9)
	v_mfma_f32_16x16x32_bf16 v[124:127], v[166:169], v[154:157], v[124:127]
	s_waitcnt lgkmcnt(8)
	v_mfma_f32_16x16x32_bf16 v[120:123], v[166:169], v[158:161], v[120:123]
	s_waitcnt lgkmcnt(7)
	v_mfma_f32_16x16x32_bf16 v[116:119], v[166:169], v[162:165], v[116:119]
	s_waitcnt lgkmcnt(6)
	v_mfma_f32_16x16x32_bf16 v[112:115], v[170:173], v[148:151], v[112:115]
	v_mfma_f32_16x16x32_bf16 v[108:111], v[170:173], v[154:157], v[108:111]
	v_mfma_f32_16x16x32_bf16 v[104:107], v[170:173], v[158:161], v[104:107]
	v_mfma_f32_16x16x32_bf16 v[100:103], v[170:173], v[162:165], v[100:103]
	s_waitcnt lgkmcnt(5)
	v_mfma_f32_16x16x32_bf16 v[96:99], v[174:177], v[148:151], v[96:99]
	v_mfma_f32_16x16x32_bf16 v[92:95], v[174:177], v[154:157], v[92:95]
	v_mfma_f32_16x16x32_bf16 v[88:91], v[174:177], v[158:161], v[88:91]
	v_mfma_f32_16x16x32_bf16 v[84:87], v[174:177], v[162:165], v[84:87]
	s_waitcnt lgkmcnt(4)
	v_mfma_f32_16x16x32_bf16 v[80:83], v[192:195], v[148:151], v[80:83]
	v_mfma_f32_16x16x32_bf16 v[76:79], v[192:195], v[154:157], v[76:79]
	v_mfma_f32_16x16x32_bf16 v[72:75], v[192:195], v[158:161], v[72:75]
	v_mfma_f32_16x16x32_bf16 v[68:71], v[192:195], v[162:165], v[68:71]
	s_waitcnt lgkmcnt(3)
	v_mfma_f32_16x16x32_bf16 v[64:67], v[196:199], v[148:151], v[64:67]
	v_mfma_f32_16x16x32_bf16 v[60:63], v[196:199], v[154:157], v[60:63]
	v_mfma_f32_16x16x32_bf16 v[56:59], v[196:199], v[158:161], v[56:59]
	v_mfma_f32_16x16x32_bf16 v[52:55], v[196:199], v[162:165], v[52:55]
	s_waitcnt lgkmcnt(2)
	v_mfma_f32_16x16x32_bf16 v[48:51], v[204:207], v[148:151], v[48:51]
	v_mfma_f32_16x16x32_bf16 v[44:47], v[204:207], v[154:157], v[44:47]
	v_mfma_f32_16x16x32_bf16 v[40:43], v[204:207], v[158:161], v[40:43]
	v_mfma_f32_16x16x32_bf16 v[36:39], v[204:207], v[162:165], v[36:39]
	s_waitcnt lgkmcnt(1)
	v_mfma_f32_16x16x32_bf16 v[32:35], v[208:211], v[148:151], v[32:35]
	v_mfma_f32_16x16x32_bf16 v[28:31], v[208:211], v[154:157], v[28:31]
	v_mfma_f32_16x16x32_bf16 v[24:27], v[208:211], v[158:161], v[24:27]
	v_mfma_f32_16x16x32_bf16 v[20:23], v[208:211], v[162:165], v[20:23]
	s_waitcnt lgkmcnt(0)
	v_mfma_f32_16x16x32_bf16 v[16:19], v[212:215], v[148:151], v[16:19]
	v_mfma_f32_16x16x32_bf16 v[12:15], v[212:215], v[154:157], v[12:15]
	v_mfma_f32_16x16x32_bf16 v[8:11], v[212:215], v[158:161], v[8:11]
	v_mfma_f32_16x16x32_bf16 v[4:7], v[212:215], v[162:165], v[4:7]
	s_setprio 0
	s_add_i32 s10, s10, 0x6000
	s_cmp_lg_u32 s10, 0x12000
	s_cselect_b32 s10, s10, 0
	s_waitcnt vmcnt(0)
	s_barrier
	s_setprio 3
	v_and_b32_e32 v2, 0x4f, v1
	v_and_b32_e32 v132, 0xfffff80, v1
	v_lshrrev_b32_e32 v1, 2, v1
	v_and_or_b32 v1, v1, 12, v132
	v_mul_lo_u32 v1, v1, s16
	v_lshl_add_u32 v1, v2, 1, v1
	v_cvt_pk_bf16_f32 v2, v129, s0
	ds_write_b16 v1, v2 offset:272
	v_cvt_pk_bf16_f32 v2, v130, s0
	ds_write_b16 v1, v2 offset:544
	v_cvt_pk_bf16_f32 v2, v131, s0
	ds_write_b16 v1, v2 offset:816
	v_cvt_pk_bf16_f32 v2, v124, s0
	ds_write_b16 v1, v2 offset:32
	v_cvt_pk_bf16_f32 v2, v125, s0
	ds_write_b16 v1, v2 offset:304
	v_cvt_pk_bf16_f32 v2, v126, s0
	ds_write_b16 v1, v2 offset:576
	v_cvt_pk_bf16_f32 v2, v127, s0
	ds_write_b16 v1, v2 offset:848
	v_cvt_pk_bf16_f32 v2, v120, s0
	ds_write_b16 v1, v2 offset:64
	v_cvt_pk_bf16_f32 v2, v121, s0
	ds_write_b16 v1, v2 offset:336
	v_cvt_pk_bf16_f32 v2, v122, s0
	ds_write_b16 v1, v2 offset:608
	v_cvt_pk_bf16_f32 v2, v123, s0
	ds_write_b16 v1, v2 offset:880
	v_cvt_pk_bf16_f32 v2, v116, s0
	ds_write_b16 v1, v2 offset:96
	v_cvt_pk_bf16_f32 v2, v117, s0
	ds_write_b16 v1, v2 offset:368
	v_cvt_pk_bf16_f32 v2, v118, s0
	ds_write_b16 v1, v2 offset:640
	v_cvt_pk_bf16_f32 v2, v119, s0
	ds_write_b16 v1, v2 offset:912
	v_cvt_pk_bf16_f32 v2, v112, s0
	ds_write_b16 v1, v2 offset:4352
	v_cvt_pk_bf16_f32 v2, v113, s0
	ds_write_b16 v1, v2 offset:4624
	v_cvt_pk_bf16_f32 v2, v114, s0
	ds_write_b16 v1, v2 offset:4896
	v_cvt_pk_bf16_f32 v2, v115, s0
	ds_write_b16 v1, v2 offset:5168
	v_cvt_pk_bf16_f32 v2, v108, s0
	ds_write_b16 v1, v2 offset:4384
	v_cvt_pk_bf16_f32 v2, v109, s0
	ds_write_b16 v1, v2 offset:4656
	v_cvt_pk_bf16_f32 v2, v110, s0
	ds_write_b16 v1, v2 offset:4928
	v_cvt_pk_bf16_f32 v2, v111, s0
	ds_write_b16 v1, v2 offset:5200
	v_cvt_pk_bf16_f32 v2, v104, s0
	ds_write_b16 v1, v2 offset:4416
	v_cvt_pk_bf16_f32 v2, v105, s0
	ds_write_b16 v1, v2 offset:4688
	v_cvt_pk_bf16_f32 v2, v106, s0
	ds_write_b16 v1, v2 offset:4960
	v_cvt_pk_bf16_f32 v2, v107, s0
	ds_write_b16 v1, v2 offset:5232
	v_cvt_pk_bf16_f32 v2, v100, s0
	ds_write_b16 v1, v2 offset:4448
	v_cvt_pk_bf16_f32 v2, v101, s0
	ds_write_b16 v1, v2 offset:4720
	v_cvt_pk_bf16_f32 v2, v102, s0
	ds_write_b16 v1, v2 offset:4992
	v_cvt_pk_bf16_f32 v2, v103, s0
	ds_write_b16 v1, v2 offset:5264
	v_cvt_pk_bf16_f32 v2, v96, s0
	ds_write_b16 v1, v2 offset:8704
	v_cvt_pk_bf16_f32 v2, v97, s0
	ds_write_b16 v1, v2 offset:8976
	v_cvt_pk_bf16_f32 v2, v98, s0
	ds_write_b16 v1, v2 offset:9248
	v_cvt_pk_bf16_f32 v2, v99, s0
	ds_write_b16 v1, v2 offset:9520
; DEVI void plain_tile256(const bf* A, int lda, const bf* Wt, int K, bf* C, int ldc, long row0, int n0, char* smem) {
;     ...
;   bf* tl = reinterpret_cast<bf*>(smem);
; #pragma unroll
;   for (int m = 0; m < 8; ++m)
; #pragma unroll
;     for (int n = 0; n < 4; ++n) {
;       const int cl = wc * 64 + n * 16 + l15;
; #pragma unroll
;       for (int j = 0; j < 4; ++j) tl[(wr * 128 + m * 16 + quad * 4 + j) * 136 + cl] = f2bf(acc[m][n][j]);
;     }
;   __syncthreads();
	v_cvt_pk_bf16_f32 v2, v92, s0
	ds_write_b16 v1, v2 offset:8736
	v_cvt_pk_bf16_f32 v2, v93, s0
	ds_write_b16 v1, v2 offset:9008
	v_cvt_pk_bf16_f32 v2, v94, s0
	ds_write_b16 v1, v2 offset:9280
	v_cvt_pk_bf16_f32 v2, v95, s0
	ds_write_b16 v1, v2 offset:9552
	v_cvt_pk_bf16_f32 v2, v88, s0
	ds_write_b16 v1, v2 offset:8768
	v_cvt_pk_bf16_f32 v2, v89, s0
	ds_write_b16 v1, v2 offset:9040
	v_cvt_pk_bf16_f32 v2, v90, s0
	ds_write_b16 v1, v2 offset:9312
	v_cvt_pk_bf16_f32 v2, v91, s0
	ds_write_b16 v1, v2 offset:9584
	v_cvt_pk_bf16_f32 v2, v84, s0
	ds_write_b16 v1, v2 offset:8800
	v_cvt_pk_bf16_f32 v2, v85, s0
	ds_write_b16 v1, v2 offset:9072
	v_cvt_pk_bf16_f32 v2, v86, s0
	ds_write_b16 v1, v2 offset:9344
	v_cvt_pk_bf16_f32 v2, v87, s0
	ds_write_b16 v1, v2 offset:9616
	v_cvt_pk_bf16_f32 v2, v80, s0
	ds_write_b16 v1, v2 offset:13056
	v_cvt_pk_bf16_f32 v2, v81, s0
	ds_write_b16 v1, v2 offset:13328
	v_cvt_pk_bf16_f32 v2, v82, s0
	ds_write_b16 v1, v2 offset:13600
	v_cvt_pk_bf16_f32 v2, v83, s0
	ds_write_b16 v1, v2 offset:13872
	v_cvt_pk_bf16_f32 v2, v76, s0
	ds_write_b16 v1, v2 offset:13088
	v_cvt_pk_bf16_f32 v2, v77, s0
	ds_write_b16 v1, v2 offset:13360
	v_cvt_pk_bf16_f32 v2, v78, s0
	ds_write_b16 v1, v2 offset:13632
	v_cvt_pk_bf16_f32 v2, v79, s0
	ds_write_b16 v1, v2 offset:13904
	v_cvt_pk_bf16_f32 v2, v72, s0
	ds_write_b16 v1, v2 offset:13120
	v_cvt_pk_bf16_f32 v2, v73, s0
	ds_write_b16 v1, v2 offset:13392
	v_cvt_pk_bf16_f32 v2, v74, s0
	ds_write_b16 v1, v2 offset:13664
	v_cvt_pk_bf16_f32 v2, v75, s0
	ds_write_b16 v1, v2 offset:13936
	v_cvt_pk_bf16_f32 v2, v68, s0
	ds_write_b16 v1, v2 offset:13152
	v_cvt_pk_bf16_f32 v2, v69, s0
	ds_write_b16 v1, v2 offset:13424
	v_cvt_pk_bf16_f32 v2, v70, s0
	ds_write_b16 v1, v2 offset:13696
	v_cvt_pk_bf16_f32 v2, v71, s0
	ds_write_b16 v1, v2 offset:13968
	v_cvt_pk_bf16_f32 v2, v64, s0
	ds_write_b16 v1, v2 offset:17408
	v_cvt_pk_bf16_f32 v2, v65, s0
	ds_write_b16 v1, v2 offset:17680
	v_cvt_pk_bf16_f32 v2, v66, s0
	ds_write_b16 v1, v2 offset:17952
	v_cvt_pk_bf16_f32 v2, v67, s0
	ds_write_b16 v1, v2 offset:18224
	v_cvt_pk_bf16_f32 v2, v60, s0
	ds_write_b16 v1, v2 offset:17440
	v_cvt_pk_bf16_f32 v2, v61, s0
	ds_write_b16 v1, v2 offset:17712
	v_cvt_pk_bf16_f32 v2, v62, s0
	ds_write_b16 v1, v2 offset:17984
	v_cvt_pk_bf16_f32 v2, v63, s0
	ds_write_b16 v1, v2 offset:18256
	v_cvt_pk_bf16_f32 v2, v56, s0
	ds_write_b16 v1, v2 offset:17472
	v_cvt_pk_bf16_f32 v2, v57, s0
	ds_write_b16 v1, v2 offset:17744
	v_cvt_pk_bf16_f32 v2, v58, s0
	ds_write_b16 v1, v2 offset:18016
	v_cvt_pk_bf16_f32 v2, v59, s0
	ds_write_b16 v1, v2 offset:18288
	v_cvt_pk_bf16_f32 v2, v52, s0
	ds_write_b16 v1, v2 offset:17504
	v_cvt_pk_bf16_f32 v2, v53, s0
	ds_write_b16 v1, v2 offset:17776
	v_cvt_pk_bf16_f32 v2, v54, s0
	ds_write_b16 v1, v2 offset:18048
	v_cvt_pk_bf16_f32 v2, v55, s0
	ds_write_b16 v1, v2 offset:18320
	v_cvt_pk_bf16_f32 v2, v48, s0
	ds_write_b16 v1, v2 offset:21760
	v_cvt_pk_bf16_f32 v2, v49, s0
	ds_write_b16 v1, v2 offset:22032
	v_cvt_pk_bf16_f32 v2, v50, s0
	ds_write_b16 v1, v2 offset:22304
	v_cvt_pk_bf16_f32 v2, v51, s0
	ds_write_b16 v1, v2 offset:22576
	v_cvt_pk_bf16_f32 v2, v44, s0
	ds_write_b16 v1, v2 offset:21792
	v_cvt_pk_bf16_f32 v2, v45, s0
	ds_write_b16 v1, v2 offset:22064
	v_cvt_pk_bf16_f32 v2, v46, s0
	ds_write_b16 v1, v2 offset:22336
	v_cvt_pk_bf16_f32 v2, v47, s0
	ds_write_b16 v1, v2 offset:22608
	v_cvt_pk_bf16_f32 v2, v40, s0
	ds_write_b16 v1, v2 offset:21824
	v_cvt_pk_bf16_f32 v2, v41, s0
	ds_write_b16 v1, v2 offset:22096
	v_cvt_pk_bf16_f32 v2, v42, s0
	ds_write_b16 v1, v2 offset:22368
	v_cvt_pk_bf16_f32 v2, v43, s0
	ds_write_b16 v1, v2 offset:22640
	v_cvt_pk_bf16_f32 v2, v36, s0
	ds_write_b16 v1, v2 offset:21856
	v_cvt_pk_bf16_f32 v2, v37, s0
	ds_write_b16 v1, v2 offset:22128
	v_cvt_pk_bf16_f32 v2, v38, s0
	ds_write_b16 v1, v2 offset:22400
	v_cvt_pk_bf16_f32 v2, v39, s0
	ds_write_b16 v1, v2 offset:22672
	v_cvt_pk_bf16_f32 v2, v32, s0
	ds_write_b16 v1, v2 offset:26112
	v_cvt_pk_bf16_f32 v2, v33, s0
	ds_write_b16 v1, v2 offset:26384
	v_cvt_pk_bf16_f32 v2, v34, s0
	ds_write_b16 v1, v2 offset:26656
	v_cvt_pk_bf16_f32 v2, v35, s0
	ds_write_b16 v1, v2 offset:26928
	v_cvt_pk_bf16_f32 v2, v28, s0
	ds_write_b16 v1, v2 offset:26144
	v_cvt_pk_bf16_f32 v2, v29, s0
	ds_write_b16 v1, v2 offset:26416
	v_cvt_pk_bf16_f32 v2, v30, s0
	ds_write_b16 v1, v2 offset:26688
	v_cvt_pk_bf16_f32 v2, v31, s0
	ds_write_b16 v1, v2 offset:26960
	v_cvt_pk_bf16_f32 v2, v24, s0
	ds_write_b16 v1, v2 offset:26176
	v_cvt_pk_bf16_f32 v2, v25, s0
	ds_write_b16 v1, v2 offset:26448
	v_cvt_pk_bf16_f32 v2, v26, s0
	ds_write_b16 v1, v2 offset:26720
	v_cvt_pk_bf16_f32 v2, v27, s0
	ds_write_b16 v1, v2 offset:26992
	v_cvt_pk_bf16_f32 v2, v20, s0
	ds_write_b16 v1, v2 offset:26208
	v_cvt_pk_bf16_f32 v2, v21, s0
	ds_write_b16 v1, v2 offset:26480
	v_cvt_pk_bf16_f32 v2, v22, s0
	ds_write_b16 v1, v2 offset:26752
	v_cvt_pk_bf16_f32 v2, v23, s0
	ds_write_b16 v1, v2 offset:27024
	v_cvt_pk_bf16_f32 v2, v16, s0
	ds_write_b16 v1, v2 offset:30464
	v_cvt_pk_bf16_f32 v2, v17, s0
	ds_write_b16 v1, v2 offset:30736
	v_cvt_pk_bf16_f32 v2, v18, s0
	ds_write_b16 v1, v2 offset:31008
	v_cvt_pk_bf16_f32 v2, v19, s0
	ds_write_b16 v1, v2 offset:31280
	v_cvt_pk_bf16_f32 v2, v12, s0
	ds_write_b16 v1, v2 offset:30496
	v_cvt_pk_bf16_f32 v2, v13, s0
	ds_write_b16 v1, v2 offset:30768
	v_cvt_pk_bf16_f32 v2, v14, s0
	ds_write_b16 v1, v2 offset:31040
	v_cvt_pk_bf16_f32 v2, v15, s0
	ds_write_b16 v1, v2 offset:31312
	v_cvt_pk_bf16_f32 v2, v8, s0
	ds_write_b16 v1, v2 offset:30528
	v_cvt_pk_bf16_f32 v2, v9, s0
	ds_write_b16 v1, v2 offset:30800
	v_cvt_pk_bf16_f32 v2, v10, s0
	ds_write_b16 v1, v2 offset:31072
	v_cvt_pk_bf16_f32 v2, v11, s0
	ds_write_b16 v1, v2 offset:31344
	v_cvt_pk_bf16_f32 v2, v4, s0
	ds_write_b16 v1, v2 offset:30560
	v_cvt_pk_bf16_f32 v2, v5, s0
	ds_write_b16 v1, v2 offset:30832
	v_cvt_pk_bf16_f32 v2, v6, s0
	v_cvt_pk_bf16_f32 v128, v128, s0
	ds_write_b16 v1, v2 offset:31104
	v_cvt_pk_bf16_f32 v2, v7, s0
	ds_write_b16 v1, v128
	ds_write_b16 v1, v2 offset:31376
	v_mov_b32_e32 v1, v178
	s_waitcnt lgkmcnt(0)
	s_barrier
; DEVI int get_tid() { int t = threadIdx.x; asm volatile("" : "+v"(t)); return t; }
; template <int BN>
; DEVI void tile_store256(const char* smem, bf* __restrict__ C, long ldc, long row0, int col0) {
;   constexpr int LDT = BN + 8;
;   constexpr int CPR = BN / 8;
;   const int tid = get_tid();
; #pragma unroll
;   for (int i = 0; i < CPR; ++i) {
;     const int q = tid + 256 * i;
;     const int r = q / CPR, c = q - r * CPR;
;     u32x4 v = *reinterpret_cast<const u32x4*>(smem + (r * LDT + c * 8) * 2);
;     *reinterpret_cast<u32x4*>(C + (row0 + r) * ldc + col0 + c * 8) = v;
;   }
; }
	v_readlane_b32 s56, v251, 58
	v_ashrrev_i32_e32 v2, 31, v1
	v_lshrrev_b32_e32 v2, 28, v2
	v_add_u32_e32 v2, v1, v2
	v_ashrrev_i32_e32 v8, 4, v2
	s_lshl_b64 s[10:11], s[34:35], 1
	v_readlane_b32 s60, v251, 62
	v_lshlrev_b32_e32 v4, 7, v8
	v_lshlrev_b32_e32 v5, 3, v1
	v_ashrrev_i32_e32 v9, 31, v8
	v_readlane_b32 s61, v251, 63
	s_add_u32 s10, s60, s10
	v_mul_lo_u32 v2, v8, s39
	v_sub_u32_e32 v10, v5, v4
	v_lshl_add_u64 v[8:9], s[12:13], 0, v[8:9]
	s_addc_u32 s11, s61, s11
	v_add_lshl_u32 v2, v10, v2, 1
	v_lshlrev_b64 v[8:9], 11, v[8:9]
	ds_read_b128 v[4:7], v2
	v_lshl_add_u64 v[8:9], s[10:11], 0, v[8:9]
	v_ashrrev_i32_e32 v11, 31, v10
	v_add_u32_e32 v2, 0x100, v1
	v_lshl_add_u64 v[12:13], v[10:11], 1, v[8:9]
	v_ashrrev_i32_e32 v8, 31, v2
	v_lshrrev_b32_e32 v8, 28, v8
	v_add_u32_e32 v8, v2, v8
	v_ashrrev_i32_e32 v14, 4, v8
	v_lshlrev_b32_e32 v9, 7, v14
	v_lshlrev_b32_e32 v2, 3, v2
	v_mul_lo_u32 v8, v14, s39
	v_sub_u32_e32 v16, v2, v9
	v_add_lshl_u32 v2, v16, v8, 1
	ds_read_b128 v[8:11], v2
	v_ashrrev_i32_e32 v15, 31, v14
	s_waitcnt lgkmcnt(1)
	global_store_dwordx4 v[12:13], v[4:7], off
	v_ashrrev_i32_e32 v17, 31, v16
	v_add_u32_e32 v2, 0x200, v1
	v_lshl_add_u64 v[4:5], s[12:13], 0, v[14:15]
	v_lshlrev_b64 v[4:5], 11, v[4:5]
	v_lshl_add_u64 v[4:5], s[10:11], 0, v[4:5]
	v_lshl_add_u64 v[4:5], v[16:17], 1, v[4:5]
	s_waitcnt lgkmcnt(0)
	global_store_dwordx4 v[4:5], v[8:11], off
	v_ashrrev_i32_e32 v4, 31, v2
	v_lshrrev_b32_e32 v4, 28, v4
	v_add_u32_e32 v4, v2, v4
	v_ashrrev_i32_e32 v8, 4, v4
	v_lshlrev_b32_e32 v5, 7, v8
	v_lshlrev_b32_e32 v2, 3, v2
	v_ashrrev_i32_e32 v9, 31, v8
	v_mul_lo_u32 v4, v8, s39
	v_sub_u32_e32 v10, v2, v5
	v_lshl_add_u64 v[8:9], s[12:13], 0, v[8:9]
	v_add_lshl_u32 v2, v10, v4, 1
	v_lshlrev_b64 v[8:9], 11, v[8:9]
	ds_read_b128 v[4:7], v2
	v_lshl_add_u64 v[8:9], s[10:11], 0, v[8:9]
	v_ashrrev_i32_e32 v11, 31, v10
	v_add_u32_e32 v2, 0x300, v1
	v_lshl_add_u64 v[12:13], v[10:11], 1, v[8:9]
	v_ashrrev_i32_e32 v8, 31, v2
	v_lshrrev_b32_e32 v8, 28, v8
	v_add_u32_e32 v8, v2, v8
	v_ashrrev_i32_e32 v14, 4, v8
	v_lshlrev_b32_e32 v9, 7, v14
	v_lshlrev_b32_e32 v2, 3, v2
	v_mul_lo_u32 v8, v14, s39
	v_sub_u32_e32 v16, v2, v9
	v_add_lshl_u32 v2, v16, v8, 1
	ds_read_b128 v[8:11], v2
	v_ashrrev_i32_e32 v15, 31, v14
	s_waitcnt lgkmcnt(1)
	global_store_dwordx4 v[12:13], v[4:7], off
	v_ashrrev_i32_e32 v17, 31, v16
	v_add_u32_e32 v2, 0x400, v1
	v_lshl_add_u64 v[4:5], s[12:13], 0, v[14:15]
	v_lshlrev_b64 v[4:5], 11, v[4:5]
	v_lshl_add_u64 v[4:5], s[10:11], 0, v[4:5]
	v_lshl_add_u64 v[4:5], v[16:17], 1, v[4:5]
	s_waitcnt lgkmcnt(0)
	global_store_dwordx4 v[4:5], v[8:11], off
	v_ashrrev_i32_e32 v4, 31, v2
	v_lshrrev_b32_e32 v4, 28, v4
	v_add_u32_e32 v4, v2, v4
	v_ashrrev_i32_e32 v8, 4, v4
	v_lshlrev_b32_e32 v5, 7, v8
	v_lshlrev_b32_e32 v2, 3, v2
	v_ashrrev_i32_e32 v9, 31, v8
	v_mul_lo_u32 v4, v8, s39
	v_sub_u32_e32 v10, v2, v5
	v_lshl_add_u64 v[8:9], s[12:13], 0, v[8:9]
	v_add_lshl_u32 v2, v10, v4, 1
	v_lshlrev_b64 v[8:9], 11, v[8:9]
	ds_read_b128 v[4:7], v2
	v_lshl_add_u64 v[8:9], s[10:11], 0, v[8:9]
	v_ashrrev_i32_e32 v11, 31, v10
	v_add_u32_e32 v2, 0x500, v1
	v_lshl_add_u64 v[12:13], v[10:11], 1, v[8:9]
	v_ashrrev_i32_e32 v8, 31, v2
	v_lshrrev_b32_e32 v8, 28, v8
	v_add_u32_e32 v8, v2, v8
	v_ashrrev_i32_e32 v14, 4, v8
	v_lshlrev_b32_e32 v9, 7, v14
	v_lshlrev_b32_e32 v2, 3, v2
	v_mul_lo_u32 v8, v14, s39
	v_sub_u32_e32 v16, v2, v9
	v_add_lshl_u32 v2, v16, v8, 1
	ds_read_b128 v[8:11], v2
	v_ashrrev_i32_e32 v15, 31, v14
	s_waitcnt lgkmcnt(1)
	global_store_dwordx4 v[12:13], v[4:7], off
	v_ashrrev_i32_e32 v17, 31, v16
	v_add_u32_e32 v2, 0x600, v1
	v_lshl_add_u64 v[4:5], s[12:13], 0, v[14:15]
	v_lshlrev_b64 v[4:5], 11, v[4:5]
	v_lshl_add_u64 v[4:5], s[10:11], 0, v[4:5]
	v_lshl_add_u64 v[4:5], v[16:17], 1, v[4:5]
	s_waitcnt lgkmcnt(0)
	global_store_dwordx4 v[4:5], v[8:11], off
	v_ashrrev_i32_e32 v4, 31, v2
	v_lshrrev_b32_e32 v4, 28, v4
	v_add_u32_e32 v4, v2, v4
	v_ashrrev_i32_e32 v8, 4, v4
	v_lshlrev_b32_e32 v5, 7, v8
	v_lshlrev_b32_e32 v2, 3, v2
	v_ashrrev_i32_e32 v9, 31, v8
	v_mul_lo_u32 v4, v8, s39
	v_sub_u32_e32 v10, v2, v5
	v_lshl_add_u64 v[8:9], s[12:13], 0, v[8:9]
	v_add_lshl_u32 v2, v10, v4, 1
	v_lshlrev_b64 v[8:9], 11, v[8:9]
	ds_read_b128 v[4:7], v2
	v_lshl_add_u64 v[8:9], s[10:11], 0, v[8:9]
	v_ashrrev_i32_e32 v11, 31, v10
	v_add_u32_e32 v2, 0x700, v1
	v_lshl_add_u64 v[12:13], v[10:11], 1, v[8:9]
	v_ashrrev_i32_e32 v8, 31, v2
	v_lshrrev_b32_e32 v8, 28, v8
	v_add_u32_e32 v8, v2, v8
	v_ashrrev_i32_e32 v14, 4, v8
	v_lshlrev_b32_e32 v9, 7, v14
	v_lshlrev_b32_e32 v2, 3, v2
	v_mul_lo_u32 v8, v14, s39
	v_sub_u32_e32 v16, v2, v9
	v_add_lshl_u32 v2, v16, v8, 1
	ds_read_b128 v[8:11], v2
	v_ashrrev_i32_e32 v15, 31, v14
	s_waitcnt lgkmcnt(1)
	global_store_dwordx4 v[12:13], v[4:7], off
	v_ashrrev_i32_e32 v17, 31, v16
	v_add_u32_e32 v2, 0x800, v1
	v_lshl_add_u64 v[4:5], s[12:13], 0, v[14:15]
	v_lshlrev_b64 v[4:5], 11, v[4:5]
	v_lshl_add_u64 v[4:5], s[10:11], 0, v[4:5]
	v_lshl_add_u64 v[4:5], v[16:17], 1, v[4:5]
	s_waitcnt lgkmcnt(0)
; DEVI int get_tid() { int t = threadIdx.x; asm volatile("" : "+v"(t)); return t; }
; template <int BN>
; DEVI void tile_store256(const char* smem, bf* __restrict__ C, long ldc, long row0, int col0) {
;   constexpr int LDT = BN + 8;
;   constexpr int CPR = BN / 8;
;   const int tid = get_tid();
; #pragma unroll
;   for (int i = 0; i < CPR; ++i) {
;     const int q = tid + 256 * i;
;     const int r = q / CPR, c = q - r * CPR;
;     u32x4 v = *reinterpret_cast<const u32x4*>(smem + (r * LDT + c * 8) * 2);
;     *reinterpret_cast<u32x4*>(C + (row0 + r) * ldc + col0 + c * 8) = v;
;   }
; }
; DEVI void phase_gemm_plain128(const bf* A, int lda, const bf* Wt, int K, int N, bf* C, int ldc, char* smem) {
;     ...
;   for (int v = blockIdx.x; v < 128 * ntn; v += gridDim.x) {
;     int m2, nt;
;     lat_tile_map256(v, ntn, m2, nt);
;     plain_tile256(A, lda, Wt, K, C, ldc, lat_row0_256(m2), nt * 128, smem);
;   }
	global_store_dwordx4 v[4:5], v[8:11], off
	v_ashrrev_i32_e32 v4, 31, v2
	v_lshrrev_b32_e32 v4, 28, v4
	v_add_u32_e32 v4, v2, v4
	v_ashrrev_i32_e32 v8, 4, v4
	v_lshlrev_b32_e32 v5, 7, v8
	v_lshlrev_b32_e32 v2, 3, v2
	v_ashrrev_i32_e32 v9, 31, v8
	v_mul_lo_u32 v4, v8, s39
	v_sub_u32_e32 v10, v2, v5
	v_lshl_add_u64 v[8:9], s[12:13], 0, v[8:9]
	v_add_lshl_u32 v2, v10, v4, 1
	v_lshlrev_b64 v[8:9], 11, v[8:9]
	ds_read_b128 v[4:7], v2
	v_lshl_add_u64 v[8:9], s[10:11], 0, v[8:9]
	v_ashrrev_i32_e32 v11, 31, v10
	v_add_u32_e32 v2, 0x900, v1
	v_lshl_add_u64 v[12:13], v[10:11], 1, v[8:9]
	v_ashrrev_i32_e32 v8, 31, v2
	v_lshrrev_b32_e32 v8, 28, v8
	v_add_u32_e32 v8, v2, v8
	v_ashrrev_i32_e32 v14, 4, v8
	v_lshlrev_b32_e32 v9, 7, v14
	v_lshlrev_b32_e32 v2, 3, v2
	v_mul_lo_u32 v8, v14, s39
	v_sub_u32_e32 v16, v2, v9
	v_add_lshl_u32 v2, v16, v8, 1
	ds_read_b128 v[8:11], v2
	v_ashrrev_i32_e32 v15, 31, v14
	s_waitcnt lgkmcnt(1)
	global_store_dwordx4 v[12:13], v[4:7], off
	v_ashrrev_i32_e32 v17, 31, v16
	v_add_u32_e32 v2, 0xa00, v1
	v_lshl_add_u64 v[4:5], s[12:13], 0, v[14:15]
	v_lshlrev_b64 v[4:5], 11, v[4:5]
	v_lshl_add_u64 v[4:5], s[10:11], 0, v[4:5]
	v_lshl_add_u64 v[4:5], v[16:17], 1, v[4:5]
	s_waitcnt lgkmcnt(0)
	global_store_dwordx4 v[4:5], v[8:11], off
	v_ashrrev_i32_e32 v4, 31, v2
	v_lshrrev_b32_e32 v4, 28, v4
	v_add_u32_e32 v4, v2, v4
	v_ashrrev_i32_e32 v8, 4, v4
	v_lshlrev_b32_e32 v5, 7, v8
	v_lshlrev_b32_e32 v2, 3, v2
	v_ashrrev_i32_e32 v9, 31, v8
	v_mul_lo_u32 v4, v8, s39
	v_sub_u32_e32 v10, v2, v5
	v_lshl_add_u64 v[8:9], s[12:13], 0, v[8:9]
	v_add_lshl_u32 v2, v10, v4, 1
	v_lshlrev_b64 v[8:9], 11, v[8:9]
	ds_read_b128 v[4:7], v2
	v_lshl_add_u64 v[8:9], s[10:11], 0, v[8:9]
	v_ashrrev_i32_e32 v11, 31, v10
	v_add_u32_e32 v2, 0xb00, v1
	v_lshl_add_u64 v[12:13], v[10:11], 1, v[8:9]
	v_ashrrev_i32_e32 v8, 31, v2
	v_lshrrev_b32_e32 v8, 28, v8
	v_add_u32_e32 v8, v2, v8
	v_ashrrev_i32_e32 v14, 4, v8
	v_lshlrev_b32_e32 v9, 7, v14
	v_lshlrev_b32_e32 v2, 3, v2
	v_mul_lo_u32 v8, v14, s39
	v_sub_u32_e32 v16, v2, v9
	v_add_lshl_u32 v2, v16, v8, 1
	ds_read_b128 v[8:11], v2
	v_ashrrev_i32_e32 v15, 31, v14
	s_waitcnt lgkmcnt(1)
	global_store_dwordx4 v[12:13], v[4:7], off
	v_ashrrev_i32_e32 v17, 31, v16
	v_add_u32_e32 v2, 0xc00, v1
	v_lshl_add_u64 v[4:5], s[12:13], 0, v[14:15]
	v_lshlrev_b64 v[4:5], 11, v[4:5]
	v_lshl_add_u64 v[4:5], s[10:11], 0, v[4:5]
	v_lshl_add_u64 v[4:5], v[16:17], 1, v[4:5]
	s_waitcnt lgkmcnt(0)
	global_store_dwordx4 v[4:5], v[8:11], off
	v_ashrrev_i32_e32 v4, 31, v2
	v_lshrrev_b32_e32 v4, 28, v4
	v_add_u32_e32 v4, v2, v4
	v_ashrrev_i32_e32 v8, 4, v4
	v_lshlrev_b32_e32 v5, 7, v8
	v_lshlrev_b32_e32 v2, 3, v2
	v_ashrrev_i32_e32 v9, 31, v8
	v_mul_lo_u32 v4, v8, s39
	v_sub_u32_e32 v10, v2, v5
	v_lshl_add_u64 v[8:9], s[12:13], 0, v[8:9]
	v_add_lshl_u32 v2, v10, v4, 1
	v_lshlrev_b64 v[8:9], 11, v[8:9]
	ds_read_b128 v[4:7], v2
	v_lshl_add_u64 v[8:9], s[10:11], 0, v[8:9]
	v_ashrrev_i32_e32 v11, 31, v10
	v_add_u32_e32 v2, 0xd00, v1
	v_lshl_add_u64 v[12:13], v[10:11], 1, v[8:9]
	v_ashrrev_i32_e32 v8, 31, v2
	v_lshrrev_b32_e32 v8, 28, v8
	v_add_u32_e32 v8, v2, v8
	v_ashrrev_i32_e32 v14, 4, v8
	v_lshlrev_b32_e32 v9, 7, v14
	v_lshlrev_b32_e32 v2, 3, v2
	v_mul_lo_u32 v8, v14, s39
	v_sub_u32_e32 v16, v2, v9
	v_add_lshl_u32 v2, v16, v8, 1
	ds_read_b128 v[8:11], v2
	v_ashrrev_i32_e32 v15, 31, v14
	s_waitcnt lgkmcnt(1)
	global_store_dwordx4 v[12:13], v[4:7], off
	v_ashrrev_i32_e32 v17, 31, v16
	v_add_u32_e32 v2, 0xe00, v1
	v_lshl_add_u64 v[4:5], s[12:13], 0, v[14:15]
	v_lshlrev_b64 v[4:5], 11, v[4:5]
	v_lshl_add_u64 v[4:5], s[10:11], 0, v[4:5]
	v_lshl_add_u64 v[4:5], v[16:17], 1, v[4:5]
	s_waitcnt lgkmcnt(0)
	global_store_dwordx4 v[4:5], v[8:11], off
	v_ashrrev_i32_e32 v4, 31, v2
	v_lshrrev_b32_e32 v4, 28, v4
	v_add_u32_e32 v4, v2, v4
	v_ashrrev_i32_e32 v8, 4, v4
	v_lshlrev_b32_e32 v5, 7, v8
	v_lshlrev_b32_e32 v2, 3, v2
	v_mul_lo_u32 v4, v8, s39
	v_sub_u32_e32 v10, v2, v5
	v_add_lshl_u32 v2, v10, v4, 1
	v_add_u32_e32 v1, 0xf00, v1
	ds_read_b128 v[4:7], v2
	v_ashrrev_i32_e32 v9, 31, v8
	v_ashrrev_i32_e32 v2, 31, v1
	v_lshl_add_u64 v[8:9], s[12:13], 0, v[8:9]
	v_lshrrev_b32_e32 v2, 28, v2
	v_lshlrev_b64 v[8:9], 11, v[8:9]
	v_add_u32_e32 v2, v1, v2
	v_lshl_add_u64 v[8:9], s[10:11], 0, v[8:9]
	v_ashrrev_i32_e32 v11, 31, v10
	v_ashrrev_i32_e32 v14, 4, v2
	v_lshl_add_u64 v[12:13], v[10:11], 1, v[8:9]
	v_lshlrev_b32_e32 v8, 7, v14
	v_lshlrev_b32_e32 v1, 3, v1
	v_mul_lo_u32 v2, v14, s39
	v_sub_u32_e32 v16, v1, v8
	v_add_lshl_u32 v1, v16, v2, 1
	v_ashrrev_i32_e32 v15, 31, v14
	ds_read_b128 v[8:11], v1
	s_waitcnt lgkmcnt(1)
	global_store_dwordx4 v[12:13], v[4:7], off
	v_ashrrev_i32_e32 v17, 31, v16
	v_readlane_b32 s58, v251, 60
	v_lshl_add_u64 v[4:5], s[12:13], 0, v[14:15]
	v_lshlrev_b64 v[4:5], 11, v[4:5]
	v_lshl_add_u64 v[4:5], s[10:11], 0, v[4:5]
	v_readlane_b32 s10, v252, 59
	s_add_i32 s2, s2, s10
	v_readlane_b32 s59, v251, 61
	v_lshl_add_u64 v[4:5], v[16:17], 1, v[4:5]
	s_cmpk_gt_i32 s2, 0x3ff
	v_readlane_b32 s57, v251, 59
	v_readlane_b32 s62, v252, 0
	v_readlane_b32 s63, v252, 1
	v_readlane_b32 s64, v252, 2
	v_readlane_b32 s65, v252, 3
	v_readlane_b32 s66, v252, 4
	v_readlane_b32 s67, v252, 5
	v_readlane_b32 s68, v252, 6
	v_readlane_b32 s69, v252, 7
	v_readlane_b32 s70, v252, 8
	v_readlane_b32 s71, v252, 9
	s_waitcnt lgkmcnt(0)
	global_store_dwordx4 v[4:5], v[8:11], off
	s_barrier
	v_readlane_b32 s11, v252, 60
	s_cbranch_scc0 .LBB0_172

; DEVI f32x4 mfma16(bf16x8 a, bf16x8 b, f32x4 c) { return __builtin_amdgcn_mfma_f32_16x16x32_bf16(a, b, c, 0, 0, 0); }
; DEVI void gemm_core3(f32x4 (&acc)[8][4], const bf* __restrict__ A, int lda, const bf* __restrict__ Bt, int ldb, int K, char* smem) {
;     ...
;   for (int kt = 0; kt < nk; ++kt) {
;     const int k1 = min((kt + 1) * 32, klast);
;     const int sn = ((kt + 1) & 1) * STG;
;     const int so = (kt & 1) * STG;
;     bf16x8 bfr[4], af[8];
; #pragma unroll
;     for (int n = 0; n < 4; ++n) bfr[n] = *reinterpret_cast<const bf16x8*>(bbase + so + n * 16 * 64);
; #pragma unroll
;     for (int m = 0; m < 8; ++m) af[m] = *reinterpret_cast<const bf16x8*>(abase + so + m * 16 * 64);
; #pragma unroll
;     for (int i = 0; i < 4; ++i) glds16(Ap + i * sa + k1, dbase + sn + i * 4096);
; #pragma unroll
;     for (int i = 0; i < 2; ++i) glds16(Bp + i * sb + k1, dbase + sn + ASZ + i * 4096);
;     __builtin_amdgcn_s_setprio(1);
; #pragma unroll
;     for (int m = 0; m < 8; ++m)
; #pragma unroll
;       for (int n = 0; n < 4; ++n) acc[m][n] = mfma16(af[m], bfr[n], acc[m][n]);
;     __builtin_amdgcn_s_setprio(0);
;     __syncthreads();
;   }
.Lg3_loop_184:
	v_add_u32_e32 v216, s10, v146
	v_add_u32_e32 v217, s10, v2
	ds_read_b128 v[148:151], v217 offset:16384
	ds_read_b128 v[166:169], v216
	ds_read_b128 v[154:157], v217 offset:17408
	ds_read_b128 v[158:161], v217 offset:18432
	ds_read_b128 v[162:165], v217 offset:19456
	ds_read_b128 v[170:173], v216 offset:1024
	ds_read_b128 v[174:177], v216 offset:2048
	ds_read_b128 v[192:195], v216 offset:3072
	ds_read_b128 v[196:199], v216 offset:4096
	ds_read_b128 v[204:207], v216 offset:5120
	ds_read_b128 v[208:211], v216 offset:6144
	ds_read_b128 v[212:215], v216 offset:7168
	s_setprio 1
	s_waitcnt lgkmcnt(10)
	v_mfma_f32_16x16x32_bf16 v[128:131], v[166:169], v[148:151], v[128:131]
	s_waitcnt lgkmcnt(9)
	v_mfma_f32_16x16x32_bf16 v[124:127], v[166:169], v[154:157], v[124:127]
	s_waitcnt lgkmcnt(8)
	v_mfma_f32_16x16x32_bf16 v[120:123], v[166:169], v[158:161], v[120:123]
	s_waitcnt lgkmcnt(7)
	v_mfma_f32_16x16x32_bf16 v[116:119], v[166:169], v[162:165], v[116:119]
	s_waitcnt lgkmcnt(6)
	v_mfma_f32_16x16x32_bf16 v[112:115], v[170:173], v[148:151], v[112:115]
	v_mfma_f32_16x16x32_bf16 v[108:111], v[170:173], v[154:157], v[108:111]
	v_mfma_f32_16x16x32_bf16 v[104:107], v[170:173], v[158:161], v[104:107]
	v_mfma_f32_16x16x32_bf16 v[100:103], v[170:173], v[162:165], v[100:103]
	s_waitcnt lgkmcnt(5)
	v_mfma_f32_16x16x32_bf16 v[96:99], v[174:177], v[148:151], v[96:99]
	v_mfma_f32_16x16x32_bf16 v[92:95], v[174:177], v[154:157], v[92:95]
	v_mfma_f32_16x16x32_bf16 v[88:91], v[174:177], v[158:161], v[88:91]
	v_mfma_f32_16x16x32_bf16 v[84:87], v[174:177], v[162:165], v[84:87]
	s_waitcnt lgkmcnt(4)
	v_mfma_f32_16x16x32_bf16 v[80:83], v[192:195], v[148:151], v[80:83]
	v_mfma_f32_16x16x32_bf16 v[76:79], v[192:195], v[154:157], v[76:79]
	v_mfma_f32_16x16x32_bf16 v[72:75], v[192:195], v[158:161], v[72:75]
	v_mfma_f32_16x16x32_bf16 v[68:71], v[192:195], v[162:165], v[68:71]
	s_waitcnt lgkmcnt(3)
	v_mfma_f32_16x16x32_bf16 v[64:67], v[196:199], v[148:151], v[64:67]
	v_mfma_f32_16x16x32_bf16 v[60:63], v[196:199], v[154:157], v[60:63]
	v_mfma_f32_16x16x32_bf16 v[56:59], v[196:199], v[158:161], v[56:59]
	v_mfma_f32_16x16x32_bf16 v[52:55], v[196:199], v[162:165], v[52:55]
	s_waitcnt lgkmcnt(2)
	v_mfma_f32_16x16x32_bf16 v[48:51], v[204:207], v[148:151], v[48:51]
	v_mfma_f32_16x16x32_bf16 v[44:47], v[204:207], v[154:157], v[44:47]
	v_mfma_f32_16x16x32_bf16 v[40:43], v[204:207], v[158:161], v[40:43]
	v_mfma_f32_16x16x32_bf16 v[36:39], v[204:207], v[162:165], v[36:39]
	s_waitcnt lgkmcnt(1)
	v_mfma_f32_16x16x32_bf16 v[32:35], v[208:211], v[148:151], v[32:35]
	v_mfma_f32_16x16x32_bf16 v[28:31], v[208:211], v[154:157], v[28:31]
	v_mfma_f32_16x16x32_bf16 v[24:27], v[208:211], v[158:161], v[24:27]
	v_mfma_f32_16x16x32_bf16 v[20:23], v[208:211], v[162:165], v[20:23]
	s_waitcnt lgkmcnt(0)
	v_mfma_f32_16x16x32_bf16 v[16:19], v[212:215], v[148:151], v[16:19]
	v_mfma_f32_16x16x32_bf16 v[12:15], v[212:215], v[154:157], v[12:15]
	v_mfma_f32_16x16x32_bf16 v[8:11], v[212:215], v[158:161], v[8:11]
	v_mfma_f32_16x16x32_bf16 v[4:7], v[212:215], v[162:165], v[4:7]
	s_setprio 0
	s_add_i32 s10, s10, 0x6000
	s_cmp_lg_u32 s10, 0x12000
	s_cselect_b32 s10, s10, 0
	s_waitcnt vmcnt(0)
	s_barrier
	v_add_u32_e32 v216, s10, v146
	v_add_u32_e32 v217, s10, v2
	ds_read_b128 v[148:151], v217 offset:16384
	ds_read_b128 v[166:169], v216
	ds_read_b128 v[154:157], v217 offset:17408
	ds_read_b128 v[158:161], v217 offset:18432
	ds_read_b128 v[162:165], v217 offset:19456
	ds_read_b128 v[170:173], v216 offset:1024
	ds_read_b128 v[174:177], v216 offset:2048
	ds_read_b128 v[192:195], v216 offset:3072
	ds_read_b128 v[196:199], v216 offset:4096
	ds_read_b128 v[204:207], v216 offset:5120
	ds_read_b128 v[208:211], v216 offset:6144
	ds_read_b128 v[212:215], v216 offset:7168
	v_readfirstlane_b32 s17, v140
	s_add_i32 s96, s11, 0x6000
	s_cmp_lg_u32 s96, 0x12000
	s_cselect_b32 s96, s96, 0
	s_add_i32 s96, s96, s17
	s_add_i32 s17, s17, s11
	s_setprio 2
	s_waitcnt lgkmcnt(10)
	s_mov_b32 m0, s17
	s_add_i32 s17, s17, 0x1000
	v_mfma_f32_16x16x32_bf16 v[128:131], v[166:169], v[148:151], v[128:131]
	s_waitcnt lgkmcnt(9)
	v_mfma_f32_16x16x32_bf16 v[124:127], v[166:169], v[154:157], v[124:127]
	global_load_lds_dwordx4 v[218:219], off
	v_lshl_add_u64 v[218:219], v[218:219], 0, 64
	s_waitcnt lgkmcnt(8)
	s_mov_b32 m0, s96
	s_add_i32 s96, s96, 0x1000
	v_mfma_f32_16x16x32_bf16 v[120:123], v[166:169], v[158:161], v[120:123]
	s_waitcnt lgkmcnt(7)
	v_mfma_f32_16x16x32_bf16 v[116:119], v[166:169], v[162:165], v[116:119]
	global_load_lds_dwordx4 v[218:219], off
	v_lshl_add_u64 v[218:219], v[218:219], 0, 64
	s_waitcnt lgkmcnt(6)
	v_mfma_f32_16x16x32_bf16 v[112:115], v[170:173], v[148:151], v[112:115]
	s_mov_b32 m0, s17
	s_add_i32 s17, s17, 0x1000
	v_mfma_f32_16x16x32_bf16 v[108:111], v[170:173], v[154:157], v[108:111]
	v_mfma_f32_16x16x32_bf16 v[104:107], v[170:173], v[158:161], v[104:107]
	global_load_lds_dwordx4 v[220:221], off
	v_lshl_add_u64 v[220:221], v[220:221], 0, 64
	s_mov_b32 m0, s96
	s_add_i32 s96, s96, 0x1000
	v_mfma_f32_16x16x32_bf16 v[100:103], v[170:173], v[162:165], v[100:103]
	s_waitcnt lgkmcnt(5)
	v_mfma_f32_16x16x32_bf16 v[96:99], v[174:177], v[148:151], v[96:99]
	global_load_lds_dwordx4 v[220:221], off
	v_lshl_add_u64 v[220:221], v[220:221], 0, 64
	v_mfma_f32_16x16x32_bf16 v[92:95], v[174:177], v[154:157], v[92:95]
	s_mov_b32 m0, s17
	s_add_i32 s17, s17, 0x1000
	v_mfma_f32_16x16x32_bf16 v[88:91], v[174:177], v[158:161], v[88:91]
	v_mfma_f32_16x16x32_bf16 v[84:87], v[174:177], v[162:165], v[84:87]
	global_load_lds_dwordx4 v[222:223], off
	v_lshl_add_u64 v[222:223], v[222:223], 0, 64
	s_waitcnt lgkmcnt(4)
; DEVI f32x4 mfma16(bf16x8 a, bf16x8 b, f32x4 c) { return __builtin_amdgcn_mfma_f32_16x16x32_bf16(a, b, c, 0, 0, 0); }
; DEVI void gemm_core3(f32x4 (&acc)[8][4], const bf* __restrict__ A, int lda, const bf* __restrict__ Bt, int ldb, int K, char* smem) {
;     ...
;   for (int kt = 0; kt < nk; ++kt) {
;     const int k1 = min((kt + 1) * 32, klast);
;     const int sn = ((kt + 1) & 1) * STG;
;     const int so = (kt & 1) * STG;
;     bf16x8 bfr[4], af[8];
; #pragma unroll
;     for (int n = 0; n < 4; ++n) bfr[n] = *reinterpret_cast<const bf16x8*>(bbase + so + n * 16 * 64);
; #pragma unroll
;     for (int m = 0; m < 8; ++m) af[m] = *reinterpret_cast<const bf16x8*>(abase + so + m * 16 * 64);
; #pragma unroll
;     for (int i = 0; i < 4; ++i) glds16(Ap + i * sa + k1, dbase + sn + i * 4096);
; #pragma unroll
;     for (int i = 0; i < 2; ++i) glds16(Bp + i * sb + k1, dbase + sn + ASZ + i * 4096);
;     __builtin_amdgcn_s_setprio(1);
; #pragma unroll
;     for (int m = 0; m < 8; ++m)
; #pragma unroll
;       for (int n = 0; n < 4; ++n) acc[m][n] = mfma16(af[m], bfr[n], acc[m][n]);
;     __builtin_amdgcn_s_setprio(0);
;     __syncthreads();
;   }
	s_mov_b32 m0, s96
	s_add_i32 s96, s96, 0x1000
	v_mfma_f32_16x16x32_bf16 v[80:83], v[192:195], v[148:151], v[80:83]
	v_mfma_f32_16x16x32_bf16 v[76:79], v[192:195], v[154:157], v[76:79]
	global_load_lds_dwordx4 v[222:223], off
	v_lshl_add_u64 v[222:223], v[222:223], 0, 64
	v_mfma_f32_16x16x32_bf16 v[72:75], v[192:195], v[158:161], v[72:75]
	s_mov_b32 m0, s17
	s_add_i32 s17, s17, 0x1000
	v_mfma_f32_16x16x32_bf16 v[68:71], v[192:195], v[162:165], v[68:71]
	s_waitcnt lgkmcnt(3)
	v_mfma_f32_16x16x32_bf16 v[64:67], v[196:199], v[148:151], v[64:67]
	global_load_lds_dwordx4 v[224:225], off
	v_lshl_add_u64 v[224:225], v[224:225], 0, 64
	s_mov_b32 m0, s96
	s_add_i32 s96, s96, 0x1000
	v_mfma_f32_16x16x32_bf16 v[60:63], v[196:199], v[154:157], v[60:63]
	v_mfma_f32_16x16x32_bf16 v[56:59], v[196:199], v[158:161], v[56:59]
	global_load_lds_dwordx4 v[224:225], off
	v_lshl_add_u64 v[224:225], v[224:225], 0, 64
	v_mfma_f32_16x16x32_bf16 v[52:55], v[196:199], v[162:165], v[52:55]
	s_waitcnt lgkmcnt(2)
	s_mov_b32 m0, s17
	s_add_i32 s17, s17, 0x1000
	v_mfma_f32_16x16x32_bf16 v[48:51], v[204:207], v[148:151], v[48:51]
	v_mfma_f32_16x16x32_bf16 v[44:47], v[204:207], v[154:157], v[44:47]
	global_load_lds_dwordx4 v[226:227], off
	v_lshl_add_u64 v[226:227], v[226:227], 0, 64
	s_mov_b32 m0, s96
	s_add_i32 s96, s96, 0x1000
	v_mfma_f32_16x16x32_bf16 v[40:43], v[204:207], v[158:161], v[40:43]
	v_mfma_f32_16x16x32_bf16 v[36:39], v[204:207], v[162:165], v[36:39]
	global_load_lds_dwordx4 v[226:227], off
	v_lshl_add_u64 v[226:227], v[226:227], 0, 64
	s_waitcnt lgkmcnt(1)
	v_mfma_f32_16x16x32_bf16 v[32:35], v[208:211], v[148:151], v[32:35]
	s_mov_b32 m0, s17
	s_add_i32 s17, s17, 0x1000
	v_mfma_f32_16x16x32_bf16 v[28:31], v[208:211], v[154:157], v[28:31]
	v_mfma_f32_16x16x32_bf16 v[24:27], v[208:211], v[158:161], v[24:27]
	global_load_lds_dwordx4 v[228:229], off
	v_lshl_add_u64 v[228:229], v[228:229], 0, 64
	s_mov_b32 m0, s96
	s_add_i32 s96, s96, 0x1000
	v_mfma_f32_16x16x32_bf16 v[20:23], v[208:211], v[162:165], v[20:23]
	s_waitcnt lgkmcnt(0)
	v_mfma_f32_16x16x32_bf16 v[16:19], v[212:215], v[148:151], v[16:19]
	global_load_lds_dwordx4 v[228:229], off
	v_lshl_add_u64 v[228:229], v[228:229], 0, 64
	v_mfma_f32_16x16x32_bf16 v[12:15], v[212:215], v[154:157], v[12:15]
	v_mfma_f32_16x16x32_bf16 v[8:11], v[212:215], v[158:161], v[8:11]
	v_mfma_f32_16x16x32_bf16 v[4:7], v[212:215], v[162:165], v[4:7]
	s_setprio 0
	s_add_i32 s10, s10, 0x6000
	s_cmp_lg_u32 s10, 0x12000
	s_cselect_b32 s10, s10, 0
	s_sub_i32 s11, s11, 0x6000
	s_cmp_lt_i32 s11, 0
	s_cselect_b32 s11, 0xc000, s11
	s_add_i32 s3, s3, 1
	s_cmp_lt_i32 s3, 15
	s_waitcnt vmcnt(1)
	s_barrier
	s_cbranch_scc1 .Lg3_loop_184
	v_add_u32_e32 v216, s10, v146
	v_add_u32_e32 v217, s10, v2
	ds_read_b128 v[148:151], v217 offset:16384
	ds_read_b128 v[166:169], v216
	ds_read_b128 v[154:157], v217 offset:17408
	ds_read_b128 v[158:161], v217 offset:18432
	ds_read_b128 v[162:165], v217 offset:19456
	ds_read_b128 v[170:173], v216 offset:1024
	ds_read_b128 v[174:177], v216 offset:2048
	ds_read_b128 v[192:195], v216 offset:3072
	ds_read_b128 v[196:199], v216 offset:4096
	ds_read_b128 v[204:207], v216 offset:5120
	ds_read_b128 v[208:211], v216 offset:6144
	ds_read_b128 v[212:215], v216 offset:7168
	s_setprio 1
	s_waitcnt lgkmcnt(10)
	v_mfma_f32_16x16x32_bf16 v[128:131], v[166:169], v[148:151], v[128:131]
	s_waitcnt lgkmcnt(9)
	v_mfma_f32_16x16x32_bf16 v[124:127], v[166:169], v[154:157], v[124:127]
	s_waitcnt lgkmcnt(8)
	v_mfma_f32_16x16x32_bf16 v[120:123], v[166:169], v[158:161], v[120:123]
	s_waitcnt lgkmcnt(7)
	v_mfma_f32_16x16x32_bf16 v[116:119], v[166:169], v[162:165], v[116:119]
	s_waitcnt lgkmcnt(6)
	v_mfma_f32_16x16x32_bf16 v[112:115], v[170:173], v[148:151], v[112:115]
	v_mfma_f32_16x16x32_bf16 v[108:111], v[170:173], v[154:157], v[108:111]
	v_mfma_f32_16x16x32_bf16 v[104:107], v[170:173], v[158:161], v[104:107]
	v_mfma_f32_16x16x32_bf16 v[100:103], v[170:173], v[162:165], v[100:103]
	s_waitcnt lgkmcnt(5)
	v_mfma_f32_16x16x32_bf16 v[96:99], v[174:177], v[148:151], v[96:99]
	v_mfma_f32_16x16x32_bf16 v[92:95], v[174:177], v[154:157], v[92:95]
	v_mfma_f32_16x16x32_bf16 v[88:91], v[174:177], v[158:161], v[88:91]
	v_mfma_f32_16x16x32_bf16 v[84:87], v[174:177], v[162:165], v[84:87]
	s_waitcnt lgkmcnt(4)
	v_mfma_f32_16x16x32_bf16 v[80:83], v[192:195], v[148:151], v[80:83]
	v_mfma_f32_16x16x32_bf16 v[76:79], v[192:195], v[154:157], v[76:79]
	v_mfma_f32_16x16x32_bf16 v[72:75], v[192:195], v[158:161], v[72:75]
	v_mfma_f32_16x16x32_bf16 v[68:71], v[192:195], v[162:165], v[68:71]
	s_waitcnt lgkmcnt(3)
	v_mfma_f32_16x16x32_bf16 v[64:67], v[196:199], v[148:151], v[64:67]
	v_mfma_f32_16x16x32_bf16 v[60:63], v[196:199], v[154:157], v[60:63]
	v_mfma_f32_16x16x32_bf16 v[56:59], v[196:199], v[158:161], v[56:59]
	v_mfma_f32_16x16x32_bf16 v[52:55], v[196:199], v[162:165], v[52:55]
	s_waitcnt lgkmcnt(2)
	v_mfma_f32_16x16x32_bf16 v[48:51], v[204:207], v[148:151], v[48:51]
	v_mfma_f32_16x16x32_bf16 v[44:47], v[204:207], v[154:157], v[44:47]
	v_mfma_f32_16x16x32_bf16 v[40:43], v[204:207], v[158:161], v[40:43]
	v_mfma_f32_16x16x32_bf16 v[36:39], v[204:207], v[162:165], v[36:39]
	s_waitcnt lgkmcnt(1)
	v_mfma_f32_16x16x32_bf16 v[32:35], v[208:211], v[148:151], v[32:35]
	v_mfma_f32_16x16x32_bf16 v[28:31], v[208:211], v[154:157], v[28:31]
	v_mfma_f32_16x16x32_bf16 v[24:27], v[208:211], v[158:161], v[24:27]
	v_mfma_f32_16x16x32_bf16 v[20:23], v[208:211], v[162:165], v[20:23]
	s_waitcnt lgkmcnt(0)
	v_mfma_f32_16x16x32_bf16 v[16:19], v[212:215], v[148:151], v[16:19]
	v_mfma_f32_16x16x32_bf16 v[12:15], v[212:215], v[154:157], v[12:15]
	v_mfma_f32_16x16x32_bf16 v[8:11], v[212:215], v[158:161], v[8:11]
	v_mfma_f32_16x16x32_bf16 v[4:7], v[212:215], v[162:165], v[4:7]
	s_setprio 0
	s_add_i32 s10, s10, 0x6000
	s_cmp_lg_u32 s10, 0x12000
	s_cselect_b32 s10, s10, 0
	s_waitcnt vmcnt(0)
	s_barrier
; DEVI float silu_(float x) { return x / (1.f + __expf(-x)); }
; DEVI void ffn1_tile256(const P& p, const bf* W, long row0, int n0  , char* smem) {
;     ...
; #pragma unroll
;   for (int m = 0; m < 8; ++m)
; #pragma unroll
;     for (int pr = 0; pr < 2; ++pr) {
;       const int cl = (wc * 2 + pr) * 16 + l15;
; #pragma unroll
;       for (int j = 0; j < 4; ++j) {
;         const int rl = wr * 128 + m * 16 + quad * 4 + j;
;         float a = acc[m][2 * pr][j], b = acc[m][2 * pr + 1][j];
;         tl[rl * 72 + cl] = f2bf(silu_(a) * b);
;       }
;     }
	v_add_u32_e32 v216, s10, v146
	v_add_u32_e32 v217, s10, v2
	ds_read_b128 v[148:151], v217 offset:16384
	ds_read_b128 v[166:169], v216
	ds_read_b128 v[154:157], v217 offset:17408
	ds_read_b128 v[158:161], v217 offset:18432
	ds_read_b128 v[162:165], v217 offset:19456
	ds_read_b128 v[170:173], v216 offset:1024
	ds_read_b128 v[174:177], v216 offset:2048
	ds_read_b128 v[192:195], v216 offset:3072
	ds_read_b128 v[196:199], v216 offset:4096
	ds_read_b128 v[204:207], v216 offset:5120
	ds_read_b128 v[208:211], v216 offset:6144
	ds_read_b128 v[212:215], v216 offset:7168
	s_setprio 1
	s_waitcnt lgkmcnt(10)
	v_mfma_f32_16x16x32_bf16 v[128:131], v[166:169], v[148:151], v[128:131]
	s_waitcnt lgkmcnt(9)
	v_mfma_f32_16x16x32_bf16 v[124:127], v[166:169], v[154:157], v[124:127]
	s_waitcnt lgkmcnt(8)
	v_mfma_f32_16x16x32_bf16 v[120:123], v[166:169], v[158:161], v[120:123]
	s_waitcnt lgkmcnt(7)
	v_mfma_f32_16x16x32_bf16 v[116:119], v[166:169], v[162:165], v[116:119]
	s_waitcnt lgkmcnt(6)
	v_mfma_f32_16x16x32_bf16 v[112:115], v[170:173], v[148:151], v[112:115]
	v_mfma_f32_16x16x32_bf16 v[108:111], v[170:173], v[154:157], v[108:111]
	v_mfma_f32_16x16x32_bf16 v[104:107], v[170:173], v[158:161], v[104:107]
	v_mfma_f32_16x16x32_bf16 v[100:103], v[170:173], v[162:165], v[100:103]
	s_waitcnt lgkmcnt(5)
	v_mfma_f32_16x16x32_bf16 v[96:99], v[174:177], v[148:151], v[96:99]
	v_mfma_f32_16x16x32_bf16 v[92:95], v[174:177], v[154:157], v[92:95]
	v_mfma_f32_16x16x32_bf16 v[88:91], v[174:177], v[158:161], v[88:91]
	v_mfma_f32_16x16x32_bf16 v[84:87], v[174:177], v[162:165], v[84:87]
	s_waitcnt lgkmcnt(4)
	v_mfma_f32_16x16x32_bf16 v[80:83], v[192:195], v[148:151], v[80:83]
	v_mfma_f32_16x16x32_bf16 v[76:79], v[192:195], v[154:157], v[76:79]
	v_mfma_f32_16x16x32_bf16 v[72:75], v[192:195], v[158:161], v[72:75]
	v_mfma_f32_16x16x32_bf16 v[68:71], v[192:195], v[162:165], v[68:71]
	s_waitcnt lgkmcnt(3)
	v_mfma_f32_16x16x32_bf16 v[64:67], v[196:199], v[148:151], v[64:67]
	v_mfma_f32_16x16x32_bf16 v[60:63], v[196:199], v[154:157], v[60:63]
	v_mfma_f32_16x16x32_bf16 v[56:59], v[196:199], v[158:161], v[56:59]
	v_mfma_f32_16x16x32_bf16 v[52:55], v[196:199], v[162:165], v[52:55]
	s_waitcnt lgkmcnt(2)
	v_mfma_f32_16x16x32_bf16 v[48:51], v[204:207], v[148:151], v[48:51]
	v_mfma_f32_16x16x32_bf16 v[44:47], v[204:207], v[154:157], v[44:47]
	v_mfma_f32_16x16x32_bf16 v[40:43], v[204:207], v[158:161], v[40:43]
	v_mfma_f32_16x16x32_bf16 v[36:39], v[204:207], v[162:165], v[36:39]
	s_waitcnt lgkmcnt(1)
	v_mfma_f32_16x16x32_bf16 v[32:35], v[208:211], v[148:151], v[32:35]
	v_mfma_f32_16x16x32_bf16 v[28:31], v[208:211], v[154:157], v[28:31]
	v_mfma_f32_16x16x32_bf16 v[24:27], v[208:211], v[158:161], v[24:27]
	v_mfma_f32_16x16x32_bf16 v[20:23], v[208:211], v[162:165], v[20:23]
	s_waitcnt lgkmcnt(0)
	v_mfma_f32_16x16x32_bf16 v[16:19], v[212:215], v[148:151], v[16:19]
	v_mfma_f32_16x16x32_bf16 v[12:15], v[212:215], v[154:157], v[12:15]
	v_mfma_f32_16x16x32_bf16 v[8:11], v[212:215], v[158:161], v[8:11]
	v_mfma_f32_16x16x32_bf16 v[4:7], v[212:215], v[162:165], v[4:7]
	s_setprio 0
	s_add_i32 s10, s10, 0x6000
	s_cmp_lg_u32 s10, 0x12000
	s_cselect_b32 s10, s10, 0
	s_waitcnt vmcnt(0)
	s_barrier
	s_setprio 3
	v_mul_f32_e32 v2, 0xbfb8aa3b, v128
	v_exp_f32_e32 v2, v2
	v_and_b32_e32 v132, 15, v1
	v_and_b32_e32 v133, 0xfffff80, v1
	v_lshrrev_b32_e32 v134, 2, v1
	v_add_f32_e32 v135, 1.0, v2
	v_div_scale_f32 v136, s[10:11], v135, v135, v128
	v_rcp_f32_e32 v137, v136
	v_lshlrev_b32_e32 v2, 1, v132
	v_and_or_b32 v2, v1, 64, v2
	v_and_or_b32 v133, v134, 12, v133
	v_fma_f32 v1, -v136, v137, 1.0
	v_fmac_f32_e32 v137, v1, v137
	v_div_scale_f32 v1, vcc, v128, v135, v128
	v_mul_f32_e32 v132, v1, v137
	v_fma_f32 v134, -v136, v132, v1
	v_fmac_f32_e32 v132, v134, v137
	v_fma_f32 v1, -v136, v132, v1
	v_div_fmas_f32 v1, v1, v137, v132
	v_mul_f32_e32 v132, 0xbfb8aa3b, v129
	v_exp_f32_e32 v132, v132
	v_div_fixup_f32 v1, v1, v135, v128
	v_mul_f32_e32 v1, v124, v1
	s_movk_i32 s3, 0x90
	v_add_f32_e32 v124, 1.0, v132
	v_div_scale_f32 v128, s[10:11], v124, v124, v129
	v_rcp_f32_e32 v134, v128
	v_cvt_pk_bf16_f32 v1, v1, s0
	v_mad_u64_u32 v[132:133], s[10:11], v133, s3, v[2:3]
	ds_write_b16 v132, v1
	v_fma_f32 v1, -v128, v134, 1.0
	v_fmac_f32_e32 v134, v1, v134
	v_div_scale_f32 v1, vcc, v129, v124, v129
	v_mul_f32_e32 v2, v1, v134
	v_fma_f32 v133, -v128, v2, v1
	v_fmac_f32_e32 v2, v133, v134
	v_fma_f32 v1, -v128, v2, v1
	v_mul_f32_e32 v128, 0xbfb8aa3b, v130
	v_exp_f32_e32 v128, v128
	v_div_fmas_f32 v1, v1, v134, v2
	v_div_fixup_f32 v1, v1, v124, v129
	v_mul_f32_e32 v1, v125, v1
	v_add_f32_e32 v2, 1.0, v128
	v_div_scale_f32 v124, s[10:11], v2, v2, v130
	v_rcp_f32_e32 v128, v124
	v_cvt_pk_bf16_f32 v1, v1, s0
	ds_write_b16 v132, v1 offset:144
	v_readlane_b32 s56, v251, 58
	v_fma_f32 v1, -v124, v128, 1.0
	v_fmac_f32_e32 v128, v1, v128
	v_div_scale_f32 v1, vcc, v130, v2, v130
	v_mul_f32_e32 v125, v1, v128
	v_fma_f32 v129, -v124, v125, v1
	v_fmac_f32_e32 v125, v129, v128
	v_fma_f32 v1, -v124, v125, v1
	v_mul_f32_e32 v124, 0xbfb8aa3b, v131
	v_exp_f32_e32 v124, v124
	v_div_fmas_f32 v1, v1, v128, v125
	v_div_fixup_f32 v1, v1, v2, v130
	v_mul_f32_e32 v1, v126, v1
	v_add_f32_e32 v2, 1.0, v124
	v_div_scale_f32 v124, s[10:11], v2, v2, v131
	v_rcp_f32_e32 v125, v124
	v_cvt_pk_bf16_f32 v1, v1, s0
	ds_write_b16 v132, v1 offset:288
	v_readlane_b32 s58, v251, 60
	v_fma_f32 v1, -v124, v125, 1.0
	v_fmac_f32_e32 v125, v1, v125
	v_div_scale_f32 v1, vcc, v131, v2, v131
	v_mul_f32_e32 v126, v1, v125
	v_fma_f32 v128, -v124, v126, v1
	v_fmac_f32_e32 v126, v128, v125
	v_fma_f32 v1, -v124, v126, v1
	v_mul_f32_e32 v124, 0xbfb8aa3b, v120
	v_exp_f32_e32 v124, v124
; DEVI float silu_(float x) { return x / (1.f + __expf(-x)); }
; DEVI void ffn1_tile256(const P& p, const bf* W, long row0, int n0  , char* smem) {
;     ...
; #pragma unroll
;   for (int m = 0; m < 8; ++m)
; #pragma unroll
;     for (int pr = 0; pr < 2; ++pr) {
;       const int cl = (wc * 2 + pr) * 16 + l15;
; #pragma unroll
;       for (int j = 0; j < 4; ++j) {
;         const int rl = wr * 128 + m * 16 + quad * 4 + j;
;         float a = acc[m][2 * pr][j], b = acc[m][2 * pr + 1][j];
;         tl[rl * 72 + cl] = f2bf(silu_(a) * b);
;       }
;     }
	v_div_fmas_f32 v1, v1, v125, v126
	v_div_fixup_f32 v1, v1, v2, v131
	v_mul_f32_e32 v1, v127, v1
	v_add_f32_e32 v2, 1.0, v124
	v_div_scale_f32 v124, s[10:11], v2, v2, v120
	v_rcp_f32_e32 v125, v124
	v_cvt_pk_bf16_f32 v1, v1, s0
	ds_write_b16 v132, v1 offset:432
	v_readlane_b32 s59, v251, 61
	v_fma_f32 v1, -v124, v125, 1.0
	v_fmac_f32_e32 v125, v1, v125
	v_div_scale_f32 v1, vcc, v120, v2, v120
	v_mul_f32_e32 v126, v1, v125
	v_fma_f32 v127, -v124, v126, v1
	v_fmac_f32_e32 v126, v127, v125
	v_fma_f32 v1, -v124, v126, v1
	v_mul_f32_e32 v124, 0xbfb8aa3b, v121
	v_exp_f32_e32 v124, v124
	v_div_fmas_f32 v1, v1, v125, v126
	v_div_fixup_f32 v1, v1, v2, v120
	v_mul_f32_e32 v1, v116, v1
	v_add_f32_e32 v2, 1.0, v124
	v_div_scale_f32 v120, s[10:11], v2, v2, v121
	v_rcp_f32_e32 v124, v120
	v_cvt_pk_bf16_f32 v1, v1, s0
	ds_write_b16 v132, v1 offset:32
	v_readlane_b32 s57, v251, 59
	v_fma_f32 v1, -v120, v124, 1.0
	v_fmac_f32_e32 v124, v1, v124
	v_div_scale_f32 v1, vcc, v121, v2, v121
	v_mul_f32_e32 v116, v1, v124
	v_fma_f32 v125, -v120, v116, v1
	v_fmac_f32_e32 v116, v125, v124
	v_fma_f32 v1, -v120, v116, v1
	v_mul_f32_e32 v120, 0xbfb8aa3b, v122
	v_exp_f32_e32 v120, v120
	v_div_fmas_f32 v1, v1, v124, v116
	v_div_fixup_f32 v1, v1, v2, v121
	v_mul_f32_e32 v1, v117, v1
	v_add_f32_e32 v2, 1.0, v120
	v_div_scale_f32 v116, s[10:11], v2, v2, v122
	v_rcp_f32_e32 v120, v116
	v_cvt_pk_bf16_f32 v1, v1, s0
	ds_write_b16 v132, v1 offset:176
	v_readlane_b32 s60, v251, 62
	v_fma_f32 v1, -v116, v120, 1.0
	v_fmac_f32_e32 v120, v1, v120
	v_div_scale_f32 v1, vcc, v122, v2, v122
	v_mul_f32_e32 v117, v1, v120
	v_fma_f32 v121, -v116, v117, v1
	v_fmac_f32_e32 v117, v121, v120
	v_fma_f32 v1, -v116, v117, v1
	v_mul_f32_e32 v116, 0xbfb8aa3b, v123
	v_exp_f32_e32 v116, v116
	v_div_fmas_f32 v1, v1, v120, v117
	v_div_fixup_f32 v1, v1, v2, v122
	v_mul_f32_e32 v1, v118, v1
	v_add_f32_e32 v2, 1.0, v116
	v_div_scale_f32 v116, s[10:11], v2, v2, v123
	v_rcp_f32_e32 v117, v116
	v_cvt_pk_bf16_f32 v1, v1, s0
	ds_write_b16 v132, v1 offset:320
	v_readlane_b32 s61, v251, 63
	v_fma_f32 v1, -v116, v117, 1.0
	v_fmac_f32_e32 v117, v1, v117
	v_div_scale_f32 v1, vcc, v123, v2, v123
	v_mul_f32_e32 v118, v1, v117
	v_fma_f32 v120, -v116, v118, v1
	v_fmac_f32_e32 v118, v120, v117
	v_fma_f32 v1, -v116, v118, v1
	v_mul_f32_e32 v116, 0xbfb8aa3b, v112
	v_exp_f32_e32 v116, v116
	v_div_fmas_f32 v1, v1, v117, v118
	v_div_fixup_f32 v1, v1, v2, v123
	v_mul_f32_e32 v1, v119, v1
	v_add_f32_e32 v2, 1.0, v116
	v_div_scale_f32 v116, s[10:11], v2, v2, v112
	v_rcp_f32_e32 v117, v116
	v_cvt_pk_bf16_f32 v1, v1, s0
	ds_write_b16 v132, v1 offset:464
	v_readlane_b32 s62, v252, 0
	v_fma_f32 v1, -v116, v117, 1.0
	v_fmac_f32_e32 v117, v1, v117
	v_div_scale_f32 v1, vcc, v112, v2, v112
	v_mul_f32_e32 v118, v1, v117
	v_fma_f32 v119, -v116, v118, v1
	v_fmac_f32_e32 v118, v119, v117
	v_fma_f32 v1, -v116, v118, v1
	v_mul_f32_e32 v116, 0xbfb8aa3b, v113
	v_exp_f32_e32 v116, v116
	v_div_fmas_f32 v1, v1, v117, v118
	v_div_fixup_f32 v1, v1, v2, v112
	v_mul_f32_e32 v1, v108, v1
	v_add_f32_e32 v2, 1.0, v116
	v_div_scale_f32 v112, s[10:11], v2, v2, v113
	v_rcp_f32_e32 v116, v112
	v_cvt_pk_bf16_f32 v1, v1, s0
	ds_write_b16 v132, v1 offset:2304
	v_readlane_b32 s63, v252, 1
	v_fma_f32 v1, -v112, v116, 1.0
	v_fmac_f32_e32 v116, v1, v116
	v_div_scale_f32 v1, vcc, v113, v2, v113
	v_mul_f32_e32 v108, v1, v116
	v_fma_f32 v117, -v112, v108, v1
	v_fmac_f32_e32 v108, v117, v116
	v_fma_f32 v1, -v112, v108, v1
	v_mul_f32_e32 v112, 0xbfb8aa3b, v114
	v_exp_f32_e32 v112, v112
	v_div_fmas_f32 v1, v1, v116, v108
	v_div_fixup_f32 v1, v1, v2, v113
	v_mul_f32_e32 v1, v109, v1
	v_add_f32_e32 v2, 1.0, v112
	v_div_scale_f32 v108, s[10:11], v2, v2, v114
	v_rcp_f32_e32 v112, v108
	v_cvt_pk_bf16_f32 v1, v1, s0
	ds_write_b16 v132, v1 offset:2448
	v_readlane_b32 s64, v252, 2
	v_fma_f32 v1, -v108, v112, 1.0
	v_fmac_f32_e32 v112, v1, v112
	v_div_scale_f32 v1, vcc, v114, v2, v114
	v_mul_f32_e32 v109, v1, v112
	v_fma_f32 v113, -v108, v109, v1
	v_fmac_f32_e32 v109, v113, v112
	v_fma_f32 v1, -v108, v109, v1
	v_mul_f32_e32 v108, 0xbfb8aa3b, v115
	v_exp_f32_e32 v108, v108
	v_div_fmas_f32 v1, v1, v112, v109
	v_div_fixup_f32 v1, v1, v2, v114
	v_mul_f32_e32 v1, v110, v1
	v_add_f32_e32 v2, 1.0, v108
	v_div_scale_f32 v108, s[10:11], v2, v2, v115
	v_rcp_f32_e32 v109, v108
	v_cvt_pk_bf16_f32 v1, v1, s0
	ds_write_b16 v132, v1 offset:2592
	v_readlane_b32 s65, v252, 3
	v_fma_f32 v1, -v108, v109, 1.0
	v_fmac_f32_e32 v109, v1, v109
	v_div_scale_f32 v1, vcc, v115, v2, v115
	v_mul_f32_e32 v110, v1, v109
	v_fma_f32 v112, -v108, v110, v1
	v_fmac_f32_e32 v110, v112, v109
	v_fma_f32 v1, -v108, v110, v1
	v_mul_f32_e32 v108, 0xbfb8aa3b, v104
	v_exp_f32_e32 v108, v108
	v_div_fmas_f32 v1, v1, v109, v110
	v_div_fixup_f32 v1, v1, v2, v115
	v_mul_f32_e32 v1, v111, v1
	v_add_f32_e32 v2, 1.0, v108
	v_div_scale_f32 v108, s[10:11], v2, v2, v104
	v_rcp_f32_e32 v109, v108
	v_cvt_pk_bf16_f32 v1, v1, s0
	ds_write_b16 v132, v1 offset:2736
	v_readlane_b32 s66, v252, 4
	v_fma_f32 v1, -v108, v109, 1.0
	v_fmac_f32_e32 v109, v1, v109
	v_div_scale_f32 v1, vcc, v104, v2, v104
	v_mul_f32_e32 v110, v1, v109
	v_fma_f32 v111, -v108, v110, v1
	v_fmac_f32_e32 v110, v111, v109
	v_fma_f32 v1, -v108, v110, v1
	v_mul_f32_e32 v108, 0xbfb8aa3b, v105
	v_exp_f32_e32 v108, v108
	v_div_fmas_f32 v1, v1, v109, v110
	v_div_fixup_f32 v1, v1, v2, v104
	v_mul_f32_e32 v1, v100, v1
	v_add_f32_e32 v2, 1.0, v108
	v_div_scale_f32 v104, s[10:11], v2, v2, v105
	v_rcp_f32_e32 v108, v104
	v_cvt_pk_bf16_f32 v1, v1, s0
	ds_write_b16 v132, v1 offset:2336
	v_readlane_b32 s67, v252, 5
	v_fma_f32 v1, -v104, v108, 1.0
	v_fmac_f32_e32 v108, v1, v108
; DEVI float silu_(float x) { return x / (1.f + __expf(-x)); }
; DEVI void ffn1_tile256(const P& p, const bf* W, long row0, int n0  , char* smem) {
;     ...
; #pragma unroll
;   for (int m = 0; m < 8; ++m)
; #pragma unroll
;     for (int pr = 0; pr < 2; ++pr) {
;       const int cl = (wc * 2 + pr) * 16 + l15;
; #pragma unroll
;       for (int j = 0; j < 4; ++j) {
;         const int rl = wr * 128 + m * 16 + quad * 4 + j;
;         float a = acc[m][2 * pr][j], b = acc[m][2 * pr + 1][j];
;         tl[rl * 72 + cl] = f2bf(silu_(a) * b);
;       }
;     }
	v_div_scale_f32 v1, vcc, v105, v2, v105
	v_mul_f32_e32 v100, v1, v108
	v_fma_f32 v109, -v104, v100, v1
	v_fmac_f32_e32 v100, v109, v108
	v_fma_f32 v1, -v104, v100, v1
	v_mul_f32_e32 v104, 0xbfb8aa3b, v106
	v_exp_f32_e32 v104, v104
	v_div_fmas_f32 v1, v1, v108, v100
	v_div_fixup_f32 v1, v1, v2, v105
	v_mul_f32_e32 v1, v101, v1
	v_add_f32_e32 v2, 1.0, v104
	v_div_scale_f32 v100, s[10:11], v2, v2, v106
	v_rcp_f32_e32 v104, v100
	v_cvt_pk_bf16_f32 v1, v1, s0
	ds_write_b16 v132, v1 offset:2480
	v_readlane_b32 s68, v252, 6
	v_fma_f32 v1, -v100, v104, 1.0
	v_fmac_f32_e32 v104, v1, v104
	v_div_scale_f32 v1, vcc, v106, v2, v106
	v_mul_f32_e32 v101, v1, v104
	v_fma_f32 v105, -v100, v101, v1
	v_fmac_f32_e32 v101, v105, v104
	v_fma_f32 v1, -v100, v101, v1
	v_mul_f32_e32 v100, 0xbfb8aa3b, v107
	v_exp_f32_e32 v100, v100
	v_div_fmas_f32 v1, v1, v104, v101
	v_div_fixup_f32 v1, v1, v2, v106
	v_mul_f32_e32 v1, v102, v1
	v_add_f32_e32 v2, 1.0, v100
	v_div_scale_f32 v100, s[10:11], v2, v2, v107
	v_rcp_f32_e32 v101, v100
	v_cvt_pk_bf16_f32 v1, v1, s0
	ds_write_b16 v132, v1 offset:2624
	v_readlane_b32 s69, v252, 7
	v_fma_f32 v1, -v100, v101, 1.0
	v_fmac_f32_e32 v101, v1, v101
	v_div_scale_f32 v1, vcc, v107, v2, v107
	v_mul_f32_e32 v102, v1, v101
	v_fma_f32 v104, -v100, v102, v1
	v_fmac_f32_e32 v102, v104, v101
	v_fma_f32 v1, -v100, v102, v1
	v_mul_f32_e32 v100, 0xbfb8aa3b, v96
	v_exp_f32_e32 v100, v100
	v_div_fmas_f32 v1, v1, v101, v102
	v_div_fixup_f32 v1, v1, v2, v107
	v_mul_f32_e32 v1, v103, v1
	v_add_f32_e32 v2, 1.0, v100
	v_div_scale_f32 v100, s[10:11], v2, v2, v96
	v_rcp_f32_e32 v101, v100
	v_cvt_pk_bf16_f32 v1, v1, s0
	ds_write_b16 v132, v1 offset:2768
	v_readlane_b32 s70, v252, 8
	v_fma_f32 v1, -v100, v101, 1.0
	v_fmac_f32_e32 v101, v1, v101
	v_div_scale_f32 v1, vcc, v96, v2, v96
	v_mul_f32_e32 v102, v1, v101
	v_fma_f32 v103, -v100, v102, v1
	v_fmac_f32_e32 v102, v103, v101
	v_fma_f32 v1, -v100, v102, v1
	v_mul_f32_e32 v100, 0xbfb8aa3b, v97
	v_exp_f32_e32 v100, v100
	v_div_fmas_f32 v1, v1, v101, v102
	v_div_fixup_f32 v1, v1, v2, v96
	v_mul_f32_e32 v1, v92, v1
	v_add_f32_e32 v2, 1.0, v100
	v_div_scale_f32 v96, s[10:11], v2, v2, v97
	v_rcp_f32_e32 v100, v96
	v_cvt_pk_bf16_f32 v1, v1, s0
	ds_write_b16 v132, v1 offset:4608
	v_readlane_b32 s71, v252, 9
	v_fma_f32 v1, -v96, v100, 1.0
	v_fmac_f32_e32 v100, v1, v100
	v_div_scale_f32 v1, vcc, v97, v2, v97
	v_mul_f32_e32 v92, v1, v100
	v_fma_f32 v101, -v96, v92, v1
	v_fmac_f32_e32 v92, v101, v100
	v_fma_f32 v1, -v96, v92, v1
	v_mul_f32_e32 v96, 0xbfb8aa3b, v98
	v_exp_f32_e32 v96, v96
	v_div_fmas_f32 v1, v1, v100, v92
	v_div_fixup_f32 v1, v1, v2, v97
	v_mul_f32_e32 v1, v93, v1
	v_add_f32_e32 v2, 1.0, v96
	v_div_scale_f32 v92, s[10:11], v2, v2, v98
	v_rcp_f32_e32 v96, v92
	v_cvt_pk_bf16_f32 v1, v1, s0
	ds_write_b16 v132, v1 offset:4752
	v_fma_f32 v1, -v92, v96, 1.0
	v_fmac_f32_e32 v96, v1, v96
	v_div_scale_f32 v1, vcc, v98, v2, v98
	v_mul_f32_e32 v93, v1, v96
	v_fma_f32 v97, -v92, v93, v1
	v_fmac_f32_e32 v93, v97, v96
	v_fma_f32 v1, -v92, v93, v1
	v_mul_f32_e32 v92, 0xbfb8aa3b, v99
	v_exp_f32_e32 v92, v92
	v_div_fmas_f32 v1, v1, v96, v93
	v_div_fixup_f32 v1, v1, v2, v98
	v_mul_f32_e32 v1, v94, v1
	v_add_f32_e32 v2, 1.0, v92
	v_div_scale_f32 v92, s[10:11], v2, v2, v99
	v_rcp_f32_e32 v93, v92
	v_cvt_pk_bf16_f32 v1, v1, s0
	ds_write_b16 v132, v1 offset:4896
	v_fma_f32 v1, -v92, v93, 1.0
	v_fmac_f32_e32 v93, v1, v93
	v_div_scale_f32 v1, vcc, v99, v2, v99
	v_mul_f32_e32 v94, v1, v93
	v_fma_f32 v96, -v92, v94, v1
	v_fmac_f32_e32 v94, v96, v93
	v_fma_f32 v1, -v92, v94, v1
	v_mul_f32_e32 v92, 0xbfb8aa3b, v88
	v_exp_f32_e32 v92, v92
	v_div_fmas_f32 v1, v1, v93, v94
	v_div_fixup_f32 v1, v1, v2, v99
	v_mul_f32_e32 v1, v95, v1
	v_add_f32_e32 v2, 1.0, v92
	v_div_scale_f32 v92, s[10:11], v2, v2, v88
	v_rcp_f32_e32 v93, v92
	v_cvt_pk_bf16_f32 v1, v1, s0
	ds_write_b16 v132, v1 offset:5040
	v_fma_f32 v1, -v92, v93, 1.0
	v_fmac_f32_e32 v93, v1, v93
	v_div_scale_f32 v1, vcc, v88, v2, v88
	v_mul_f32_e32 v94, v1, v93
	v_fma_f32 v95, -v92, v94, v1
	v_fmac_f32_e32 v94, v95, v93
	v_fma_f32 v1, -v92, v94, v1
	v_mul_f32_e32 v92, 0xbfb8aa3b, v89
	v_exp_f32_e32 v92, v92
	v_div_fmas_f32 v1, v1, v93, v94
	v_div_fixup_f32 v1, v1, v2, v88
	v_mul_f32_e32 v1, v84, v1
	v_add_f32_e32 v2, 1.0, v92
	v_div_scale_f32 v88, s[10:11], v2, v2, v89
	v_rcp_f32_e32 v92, v88
	v_cvt_pk_bf16_f32 v1, v1, s0
	ds_write_b16 v132, v1 offset:4640
	v_fma_f32 v1, -v88, v92, 1.0
	v_fmac_f32_e32 v92, v1, v92
	v_div_scale_f32 v1, vcc, v89, v2, v89
	v_mul_f32_e32 v84, v1, v92
	v_fma_f32 v93, -v88, v84, v1
	v_fmac_f32_e32 v84, v93, v92
	v_fma_f32 v1, -v88, v84, v1
	v_mul_f32_e32 v88, 0xbfb8aa3b, v90
	v_exp_f32_e32 v88, v88
	v_div_fmas_f32 v1, v1, v92, v84
	v_div_fixup_f32 v1, v1, v2, v89
	v_mul_f32_e32 v1, v85, v1
	v_add_f32_e32 v2, 1.0, v88
	v_div_scale_f32 v84, s[10:11], v2, v2, v90
	v_rcp_f32_e32 v88, v84
	v_cvt_pk_bf16_f32 v1, v1, s0
	ds_write_b16 v132, v1 offset:4784
	v_fma_f32 v1, -v84, v88, 1.0
	v_fmac_f32_e32 v88, v1, v88
	v_div_scale_f32 v1, vcc, v90, v2, v90
	v_mul_f32_e32 v85, v1, v88
	v_fma_f32 v89, -v84, v85, v1
	v_fmac_f32_e32 v85, v89, v88
	v_fma_f32 v1, -v84, v85, v1
	v_mul_f32_e32 v84, 0xbfb8aa3b, v91
	v_exp_f32_e32 v84, v84
	v_div_fmas_f32 v1, v1, v88, v85
	v_div_fixup_f32 v1, v1, v2, v90
	v_mul_f32_e32 v1, v86, v1
	v_add_f32_e32 v2, 1.0, v84
	v_div_scale_f32 v84, s[10:11], v2, v2, v91
	v_rcp_f32_e32 v85, v84
	v_cvt_pk_bf16_f32 v1, v1, s0
	ds_write_b16 v132, v1 offset:4928
	v_fma_f32 v1, -v84, v85, 1.0
	v_fmac_f32_e32 v85, v1, v85
	v_div_scale_f32 v1, vcc, v91, v2, v91
	v_mul_f32_e32 v86, v1, v85
	v_fma_f32 v88, -v84, v86, v1
	v_fmac_f32_e32 v86, v88, v85
; DEVI float silu_(float x) { return x / (1.f + __expf(-x)); }
; DEVI void ffn1_tile256(const P& p, const bf* W, long row0, int n0  , char* smem) {
;     ...
; #pragma unroll
;   for (int m = 0; m < 8; ++m)
; #pragma unroll
;     for (int pr = 0; pr < 2; ++pr) {
;       const int cl = (wc * 2 + pr) * 16 + l15;
; #pragma unroll
;       for (int j = 0; j < 4; ++j) {
;         const int rl = wr * 128 + m * 16 + quad * 4 + j;
;         float a = acc[m][2 * pr][j], b = acc[m][2 * pr + 1][j];
;         tl[rl * 72 + cl] = f2bf(silu_(a) * b);
;       }
;     }
	v_fma_f32 v1, -v84, v86, v1
	v_mul_f32_e32 v84, 0xbfb8aa3b, v80
	v_exp_f32_e32 v84, v84
	v_div_fmas_f32 v1, v1, v85, v86
	v_div_fixup_f32 v1, v1, v2, v91
	v_mul_f32_e32 v1, v87, v1
	v_add_f32_e32 v2, 1.0, v84
	v_div_scale_f32 v84, s[10:11], v2, v2, v80
	v_rcp_f32_e32 v85, v84
	v_cvt_pk_bf16_f32 v1, v1, s0
	ds_write_b16 v132, v1 offset:5072
	v_fma_f32 v1, -v84, v85, 1.0
	v_fmac_f32_e32 v85, v1, v85
	v_div_scale_f32 v1, vcc, v80, v2, v80
	v_mul_f32_e32 v86, v1, v85
	v_fma_f32 v87, -v84, v86, v1
	v_fmac_f32_e32 v86, v87, v85
	v_fma_f32 v1, -v84, v86, v1
	v_mul_f32_e32 v84, 0xbfb8aa3b, v81
	v_exp_f32_e32 v84, v84
	v_div_fmas_f32 v1, v1, v85, v86
	v_div_fixup_f32 v1, v1, v2, v80
	v_mul_f32_e32 v1, v76, v1
	v_add_f32_e32 v2, 1.0, v84
	v_div_scale_f32 v80, s[10:11], v2, v2, v81
	v_rcp_f32_e32 v84, v80
	v_cvt_pk_bf16_f32 v1, v1, s0
	ds_write_b16 v132, v1 offset:6912
	v_fma_f32 v1, -v80, v84, 1.0
	v_fmac_f32_e32 v84, v1, v84
	v_div_scale_f32 v1, vcc, v81, v2, v81
	v_mul_f32_e32 v76, v1, v84
	v_fma_f32 v85, -v80, v76, v1
	v_fmac_f32_e32 v76, v85, v84
	v_fma_f32 v1, -v80, v76, v1
	v_mul_f32_e32 v80, 0xbfb8aa3b, v82
	v_exp_f32_e32 v80, v80
	v_div_fmas_f32 v1, v1, v84, v76
	v_div_fixup_f32 v1, v1, v2, v81
	v_mul_f32_e32 v1, v77, v1
	v_add_f32_e32 v2, 1.0, v80
	v_div_scale_f32 v76, s[10:11], v2, v2, v82
	v_rcp_f32_e32 v80, v76
	v_cvt_pk_bf16_f32 v1, v1, s0
	ds_write_b16 v132, v1 offset:7056
	v_fma_f32 v1, -v76, v80, 1.0
	v_fmac_f32_e32 v80, v1, v80
	v_div_scale_f32 v1, vcc, v82, v2, v82
	v_mul_f32_e32 v77, v1, v80
	v_fma_f32 v81, -v76, v77, v1
	v_fmac_f32_e32 v77, v81, v80
	v_fma_f32 v1, -v76, v77, v1
	v_mul_f32_e32 v76, 0xbfb8aa3b, v83
	v_exp_f32_e32 v76, v76
	v_div_fmas_f32 v1, v1, v80, v77
	v_div_fixup_f32 v1, v1, v2, v82
	v_mul_f32_e32 v1, v78, v1
	v_add_f32_e32 v2, 1.0, v76
	v_div_scale_f32 v76, s[10:11], v2, v2, v83
	v_rcp_f32_e32 v77, v76
	v_cvt_pk_bf16_f32 v1, v1, s0
	ds_write_b16 v132, v1 offset:7200
	v_fma_f32 v1, -v76, v77, 1.0
	v_fmac_f32_e32 v77, v1, v77
	v_div_scale_f32 v1, vcc, v83, v2, v83
	v_mul_f32_e32 v78, v1, v77
	v_fma_f32 v80, -v76, v78, v1
	v_fmac_f32_e32 v78, v80, v77
	v_fma_f32 v1, -v76, v78, v1
	v_mul_f32_e32 v76, 0xbfb8aa3b, v72
	v_exp_f32_e32 v76, v76
	v_div_fmas_f32 v1, v1, v77, v78
	v_div_fixup_f32 v1, v1, v2, v83
	v_mul_f32_e32 v1, v79, v1
	v_add_f32_e32 v2, 1.0, v76
	v_div_scale_f32 v76, s[10:11], v2, v2, v72
	v_rcp_f32_e32 v77, v76
	v_cvt_pk_bf16_f32 v1, v1, s0
	ds_write_b16 v132, v1 offset:7344
	v_fma_f32 v1, -v76, v77, 1.0
	v_fmac_f32_e32 v77, v1, v77
	v_div_scale_f32 v1, vcc, v72, v2, v72
	v_mul_f32_e32 v78, v1, v77
	v_fma_f32 v79, -v76, v78, v1
	v_fmac_f32_e32 v78, v79, v77
	v_fma_f32 v1, -v76, v78, v1
	v_mul_f32_e32 v76, 0xbfb8aa3b, v73
	v_exp_f32_e32 v76, v76
	v_div_fmas_f32 v1, v1, v77, v78
	v_div_fixup_f32 v1, v1, v2, v72
	v_mul_f32_e32 v1, v68, v1
	v_add_f32_e32 v2, 1.0, v76
	v_div_scale_f32 v72, s[10:11], v2, v2, v73
	v_rcp_f32_e32 v76, v72
	v_cvt_pk_bf16_f32 v1, v1, s0
	ds_write_b16 v132, v1 offset:6944
	v_fma_f32 v1, -v72, v76, 1.0
	v_fmac_f32_e32 v76, v1, v76
	v_div_scale_f32 v1, vcc, v73, v2, v73
	v_mul_f32_e32 v68, v1, v76
	v_fma_f32 v77, -v72, v68, v1
	v_fmac_f32_e32 v68, v77, v76
	v_fma_f32 v1, -v72, v68, v1
	v_mul_f32_e32 v72, 0xbfb8aa3b, v74
	v_exp_f32_e32 v72, v72
	v_div_fmas_f32 v1, v1, v76, v68
	v_div_fixup_f32 v1, v1, v2, v73
	v_mul_f32_e32 v1, v69, v1
	v_add_f32_e32 v2, 1.0, v72
	v_div_scale_f32 v68, s[10:11], v2, v2, v74
	v_rcp_f32_e32 v72, v68
	v_cvt_pk_bf16_f32 v1, v1, s0
	ds_write_b16 v132, v1 offset:7088
	v_fma_f32 v1, -v68, v72, 1.0
	v_fmac_f32_e32 v72, v1, v72
	v_div_scale_f32 v1, vcc, v74, v2, v74
	v_mul_f32_e32 v69, v1, v72
	v_fma_f32 v73, -v68, v69, v1
	v_fmac_f32_e32 v69, v73, v72
	v_fma_f32 v1, -v68, v69, v1
	v_mul_f32_e32 v68, 0xbfb8aa3b, v75
	v_exp_f32_e32 v68, v68
	v_div_fmas_f32 v1, v1, v72, v69
	v_div_fixup_f32 v1, v1, v2, v74
	v_mul_f32_e32 v1, v70, v1
	v_add_f32_e32 v2, 1.0, v68
	v_div_scale_f32 v68, s[10:11], v2, v2, v75
	v_rcp_f32_e32 v69, v68
	v_cvt_pk_bf16_f32 v1, v1, s0
	ds_write_b16 v132, v1 offset:7232
	v_fma_f32 v1, -v68, v69, 1.0
	v_fmac_f32_e32 v69, v1, v69
	v_div_scale_f32 v1, vcc, v75, v2, v75
	v_mul_f32_e32 v70, v1, v69
	v_fma_f32 v72, -v68, v70, v1
	v_fmac_f32_e32 v70, v72, v69
	v_fma_f32 v1, -v68, v70, v1
	v_mul_f32_e32 v68, 0xbfb8aa3b, v64
	v_exp_f32_e32 v68, v68
	v_div_fmas_f32 v1, v1, v69, v70
	v_div_fixup_f32 v1, v1, v2, v75
	v_mul_f32_e32 v1, v71, v1
	v_add_f32_e32 v2, 1.0, v68
	v_div_scale_f32 v68, s[10:11], v2, v2, v64
	v_rcp_f32_e32 v69, v68
	v_cvt_pk_bf16_f32 v1, v1, s0
	ds_write_b16 v132, v1 offset:7376
	v_fma_f32 v1, -v68, v69, 1.0
	v_fmac_f32_e32 v69, v1, v69
	v_div_scale_f32 v1, vcc, v64, v2, v64
	v_mul_f32_e32 v70, v1, v69
	v_fma_f32 v71, -v68, v70, v1
	v_fmac_f32_e32 v70, v71, v69
	v_fma_f32 v1, -v68, v70, v1
	v_mul_f32_e32 v68, 0xbfb8aa3b, v65
	v_exp_f32_e32 v68, v68
	v_div_fmas_f32 v1, v1, v69, v70
	v_div_fixup_f32 v1, v1, v2, v64
	v_mul_f32_e32 v1, v60, v1
	v_add_f32_e32 v2, 1.0, v68
	v_div_scale_f32 v64, s[10:11], v2, v2, v65
	v_rcp_f32_e32 v68, v64
	v_cvt_pk_bf16_f32 v1, v1, s0
	ds_write_b16 v132, v1 offset:9216
	v_fma_f32 v1, -v64, v68, 1.0
	v_fmac_f32_e32 v68, v1, v68
	v_div_scale_f32 v1, vcc, v65, v2, v65
	v_mul_f32_e32 v60, v1, v68
	v_fma_f32 v69, -v64, v60, v1
	v_fmac_f32_e32 v60, v69, v68
	v_fma_f32 v1, -v64, v60, v1
	v_mul_f32_e32 v64, 0xbfb8aa3b, v66
	v_exp_f32_e32 v64, v64
	v_div_fmas_f32 v1, v1, v68, v60
	v_div_fixup_f32 v1, v1, v2, v65
	v_mul_f32_e32 v1, v61, v1
	v_add_f32_e32 v2, 1.0, v64
	v_div_scale_f32 v60, s[10:11], v2, v2, v66
	v_rcp_f32_e32 v64, v60
	v_cvt_pk_bf16_f32 v1, v1, s0
	ds_write_b16 v132, v1 offset:9360
; DEVI float silu_(float x) { return x / (1.f + __expf(-x)); }
; DEVI void ffn1_tile256(const P& p, const bf* W, long row0, int n0  , char* smem) {
;     ...
; #pragma unroll
;   for (int m = 0; m < 8; ++m)
; #pragma unroll
;     for (int pr = 0; pr < 2; ++pr) {
;       const int cl = (wc * 2 + pr) * 16 + l15;
; #pragma unroll
;       for (int j = 0; j < 4; ++j) {
;         const int rl = wr * 128 + m * 16 + quad * 4 + j;
;         float a = acc[m][2 * pr][j], b = acc[m][2 * pr + 1][j];
;         tl[rl * 72 + cl] = f2bf(silu_(a) * b);
;       }
;     }
	v_fma_f32 v1, -v60, v64, 1.0
	v_fmac_f32_e32 v64, v1, v64
	v_div_scale_f32 v1, vcc, v66, v2, v66
	v_mul_f32_e32 v61, v1, v64
	v_fma_f32 v65, -v60, v61, v1
	v_fmac_f32_e32 v61, v65, v64
	v_fma_f32 v1, -v60, v61, v1
	v_mul_f32_e32 v60, 0xbfb8aa3b, v67
	v_exp_f32_e32 v60, v60
	v_div_fmas_f32 v1, v1, v64, v61
	v_div_fixup_f32 v1, v1, v2, v66
	v_mul_f32_e32 v1, v62, v1
	v_add_f32_e32 v2, 1.0, v60
	v_div_scale_f32 v60, s[10:11], v2, v2, v67
	v_rcp_f32_e32 v61, v60
	v_cvt_pk_bf16_f32 v1, v1, s0
	ds_write_b16 v132, v1 offset:9504
	v_fma_f32 v1, -v60, v61, 1.0
	v_fmac_f32_e32 v61, v1, v61
	v_div_scale_f32 v1, vcc, v67, v2, v67
	v_mul_f32_e32 v62, v1, v61
	v_fma_f32 v64, -v60, v62, v1
	v_fmac_f32_e32 v62, v64, v61
	v_fma_f32 v1, -v60, v62, v1
	v_mul_f32_e32 v60, 0xbfb8aa3b, v56
	v_exp_f32_e32 v60, v60
	v_div_fmas_f32 v1, v1, v61, v62
	v_div_fixup_f32 v1, v1, v2, v67
	v_mul_f32_e32 v1, v63, v1
	v_add_f32_e32 v2, 1.0, v60
	v_div_scale_f32 v60, s[10:11], v2, v2, v56
	v_rcp_f32_e32 v61, v60
	v_cvt_pk_bf16_f32 v1, v1, s0
	ds_write_b16 v132, v1 offset:9648
	v_fma_f32 v1, -v60, v61, 1.0
	v_fmac_f32_e32 v61, v1, v61
	v_div_scale_f32 v1, vcc, v56, v2, v56
	v_mul_f32_e32 v62, v1, v61
	v_fma_f32 v63, -v60, v62, v1
	v_fmac_f32_e32 v62, v63, v61
	v_fma_f32 v1, -v60, v62, v1
	v_mul_f32_e32 v60, 0xbfb8aa3b, v57
	v_exp_f32_e32 v60, v60
	v_div_fmas_f32 v1, v1, v61, v62
	v_div_fixup_f32 v1, v1, v2, v56
	v_mul_f32_e32 v1, v52, v1
	v_add_f32_e32 v2, 1.0, v60
	v_div_scale_f32 v56, s[10:11], v2, v2, v57
	v_rcp_f32_e32 v60, v56
	v_cvt_pk_bf16_f32 v1, v1, s0
	ds_write_b16 v132, v1 offset:9248
	v_fma_f32 v1, -v56, v60, 1.0
	v_fmac_f32_e32 v60, v1, v60
	v_div_scale_f32 v1, vcc, v57, v2, v57
	v_mul_f32_e32 v52, v1, v60
	v_fma_f32 v61, -v56, v52, v1
	v_fmac_f32_e32 v52, v61, v60
	v_fma_f32 v1, -v56, v52, v1
	v_mul_f32_e32 v56, 0xbfb8aa3b, v58
	v_exp_f32_e32 v56, v56
	v_div_fmas_f32 v1, v1, v60, v52
	v_div_fixup_f32 v1, v1, v2, v57
	v_mul_f32_e32 v1, v53, v1
	v_add_f32_e32 v2, 1.0, v56
	v_div_scale_f32 v52, s[10:11], v2, v2, v58
	v_rcp_f32_e32 v56, v52
	v_cvt_pk_bf16_f32 v1, v1, s0
	ds_write_b16 v132, v1 offset:9392
	v_fma_f32 v1, -v52, v56, 1.0
	v_fmac_f32_e32 v56, v1, v56
	v_div_scale_f32 v1, vcc, v58, v2, v58
	v_mul_f32_e32 v53, v1, v56
	v_fma_f32 v57, -v52, v53, v1
	v_fmac_f32_e32 v53, v57, v56
	v_fma_f32 v1, -v52, v53, v1
	v_mul_f32_e32 v52, 0xbfb8aa3b, v59
	v_exp_f32_e32 v52, v52
	v_div_fmas_f32 v1, v1, v56, v53
	v_div_fixup_f32 v1, v1, v2, v58
	v_mul_f32_e32 v1, v54, v1
	v_add_f32_e32 v2, 1.0, v52
	v_div_scale_f32 v52, s[10:11], v2, v2, v59
	v_rcp_f32_e32 v53, v52
	v_cvt_pk_bf16_f32 v1, v1, s0
	ds_write_b16 v132, v1 offset:9536
	v_fma_f32 v1, -v52, v53, 1.0
	v_fmac_f32_e32 v53, v1, v53
	v_div_scale_f32 v1, vcc, v59, v2, v59
	v_mul_f32_e32 v54, v1, v53
	v_fma_f32 v56, -v52, v54, v1
	v_fmac_f32_e32 v54, v56, v53
	v_fma_f32 v1, -v52, v54, v1
	v_mul_f32_e32 v52, 0xbfb8aa3b, v48
	v_exp_f32_e32 v52, v52
	v_div_fmas_f32 v1, v1, v53, v54
	v_div_fixup_f32 v1, v1, v2, v59
	v_mul_f32_e32 v1, v55, v1
	v_add_f32_e32 v2, 1.0, v52
	v_div_scale_f32 v52, s[10:11], v2, v2, v48
	v_rcp_f32_e32 v53, v52
	v_cvt_pk_bf16_f32 v1, v1, s0
	ds_write_b16 v132, v1 offset:9680
	v_fma_f32 v1, -v52, v53, 1.0
	v_fmac_f32_e32 v53, v1, v53
	v_div_scale_f32 v1, vcc, v48, v2, v48
	v_mul_f32_e32 v54, v1, v53
	v_fma_f32 v55, -v52, v54, v1
	v_fmac_f32_e32 v54, v55, v53
	v_fma_f32 v1, -v52, v54, v1
	v_mul_f32_e32 v52, 0xbfb8aa3b, v49
	v_exp_f32_e32 v52, v52
	v_div_fmas_f32 v1, v1, v53, v54
	v_div_fixup_f32 v1, v1, v2, v48
	v_mul_f32_e32 v1, v44, v1
	v_add_f32_e32 v2, 1.0, v52
	v_div_scale_f32 v48, s[10:11], v2, v2, v49
	v_rcp_f32_e32 v52, v48
	v_cvt_pk_bf16_f32 v1, v1, s0
	ds_write_b16 v132, v1 offset:11520
	v_fma_f32 v1, -v48, v52, 1.0
	v_fmac_f32_e32 v52, v1, v52
	v_div_scale_f32 v1, vcc, v49, v2, v49
	v_mul_f32_e32 v44, v1, v52
	v_fma_f32 v53, -v48, v44, v1
	v_fmac_f32_e32 v44, v53, v52
	v_fma_f32 v1, -v48, v44, v1
	v_mul_f32_e32 v48, 0xbfb8aa3b, v50
	v_exp_f32_e32 v48, v48
	v_div_fmas_f32 v1, v1, v52, v44
	v_div_fixup_f32 v1, v1, v2, v49
	v_mul_f32_e32 v1, v45, v1
	v_add_f32_e32 v2, 1.0, v48
	v_div_scale_f32 v44, s[10:11], v2, v2, v50
	v_rcp_f32_e32 v48, v44
	v_cvt_pk_bf16_f32 v1, v1, s0
	ds_write_b16 v132, v1 offset:11664
	v_fma_f32 v1, -v44, v48, 1.0
	v_fmac_f32_e32 v48, v1, v48
	v_div_scale_f32 v1, vcc, v50, v2, v50
	v_mul_f32_e32 v45, v1, v48
	v_fma_f32 v49, -v44, v45, v1
	v_fmac_f32_e32 v45, v49, v48
	v_fma_f32 v1, -v44, v45, v1
	v_mul_f32_e32 v44, 0xbfb8aa3b, v51
	v_exp_f32_e32 v44, v44
	v_div_fmas_f32 v1, v1, v48, v45
	v_div_fixup_f32 v1, v1, v2, v50
	v_mul_f32_e32 v1, v46, v1
	v_add_f32_e32 v2, 1.0, v44
	v_div_scale_f32 v44, s[10:11], v2, v2, v51
	v_rcp_f32_e32 v45, v44
	v_cvt_pk_bf16_f32 v1, v1, s0
	ds_write_b16 v132, v1 offset:11808
	v_fma_f32 v1, -v44, v45, 1.0
	v_fmac_f32_e32 v45, v1, v45
	v_div_scale_f32 v1, vcc, v51, v2, v51
	v_mul_f32_e32 v46, v1, v45
	v_fma_f32 v48, -v44, v46, v1
	v_fmac_f32_e32 v46, v48, v45
	v_fma_f32 v1, -v44, v46, v1
	v_mul_f32_e32 v44, 0xbfb8aa3b, v40
	v_exp_f32_e32 v44, v44
	v_div_fmas_f32 v1, v1, v45, v46
	v_div_fixup_f32 v1, v1, v2, v51
	v_mul_f32_e32 v1, v47, v1
	v_add_f32_e32 v2, 1.0, v44
	v_div_scale_f32 v44, s[10:11], v2, v2, v40
	v_rcp_f32_e32 v45, v44
	v_cvt_pk_bf16_f32 v1, v1, s0
	ds_write_b16 v132, v1 offset:11952
	v_fma_f32 v1, -v44, v45, 1.0
	v_fmac_f32_e32 v45, v1, v45
	v_div_scale_f32 v1, vcc, v40, v2, v40
	v_mul_f32_e32 v46, v1, v45
	v_fma_f32 v47, -v44, v46, v1
	v_fmac_f32_e32 v46, v47, v45
	v_fma_f32 v1, -v44, v46, v1
	v_mul_f32_e32 v44, 0xbfb8aa3b, v41
	v_exp_f32_e32 v44, v44
	v_div_fmas_f32 v1, v1, v45, v46
	v_div_fixup_f32 v1, v1, v2, v40
; DEVI float silu_(float x) { return x / (1.f + __expf(-x)); }
; DEVI void ffn1_tile256(const P& p, const bf* W, long row0, int n0  , char* smem) {
;     ...
; #pragma unroll
;   for (int m = 0; m < 8; ++m)
; #pragma unroll
;     for (int pr = 0; pr < 2; ++pr) {
;       const int cl = (wc * 2 + pr) * 16 + l15;
; #pragma unroll
;       for (int j = 0; j < 4; ++j) {
;         const int rl = wr * 128 + m * 16 + quad * 4 + j;
;         float a = acc[m][2 * pr][j], b = acc[m][2 * pr + 1][j];
;         tl[rl * 72 + cl] = f2bf(silu_(a) * b);
;       }
;     }
	v_mul_f32_e32 v1, v36, v1
	v_add_f32_e32 v2, 1.0, v44
	v_div_scale_f32 v40, s[10:11], v2, v2, v41
	v_rcp_f32_e32 v44, v40
	v_cvt_pk_bf16_f32 v1, v1, s0
	ds_write_b16 v132, v1 offset:11552
	v_fma_f32 v1, -v40, v44, 1.0
	v_fmac_f32_e32 v44, v1, v44
	v_div_scale_f32 v1, vcc, v41, v2, v41
	v_mul_f32_e32 v36, v1, v44
	v_fma_f32 v45, -v40, v36, v1
	v_fmac_f32_e32 v36, v45, v44
	v_fma_f32 v1, -v40, v36, v1
	v_mul_f32_e32 v40, 0xbfb8aa3b, v42
	v_exp_f32_e32 v40, v40
	v_div_fmas_f32 v1, v1, v44, v36
	v_div_fixup_f32 v1, v1, v2, v41
	v_mul_f32_e32 v1, v37, v1
	v_add_f32_e32 v2, 1.0, v40
	v_div_scale_f32 v36, s[10:11], v2, v2, v42
	v_rcp_f32_e32 v40, v36
	v_cvt_pk_bf16_f32 v1, v1, s0
	ds_write_b16 v132, v1 offset:11696
	v_fma_f32 v1, -v36, v40, 1.0
	v_fmac_f32_e32 v40, v1, v40
	v_div_scale_f32 v1, vcc, v42, v2, v42
	v_mul_f32_e32 v37, v1, v40
	v_fma_f32 v41, -v36, v37, v1
	v_fmac_f32_e32 v37, v41, v40
	v_fma_f32 v1, -v36, v37, v1
	v_mul_f32_e32 v36, 0xbfb8aa3b, v43
	v_exp_f32_e32 v36, v36
	v_div_fmas_f32 v1, v1, v40, v37
	v_div_fixup_f32 v1, v1, v2, v42
	v_mul_f32_e32 v1, v38, v1
	v_add_f32_e32 v2, 1.0, v36
	v_div_scale_f32 v36, s[10:11], v2, v2, v43
	v_rcp_f32_e32 v37, v36
	v_cvt_pk_bf16_f32 v1, v1, s0
	ds_write_b16 v132, v1 offset:11840
	v_fma_f32 v1, -v36, v37, 1.0
	v_fmac_f32_e32 v37, v1, v37
	v_div_scale_f32 v1, vcc, v43, v2, v43
	v_mul_f32_e32 v38, v1, v37
	v_fma_f32 v40, -v36, v38, v1
	v_fmac_f32_e32 v38, v40, v37
	v_fma_f32 v1, -v36, v38, v1
	v_mul_f32_e32 v36, 0xbfb8aa3b, v32
	v_exp_f32_e32 v36, v36
	v_div_fmas_f32 v1, v1, v37, v38
	v_div_fixup_f32 v1, v1, v2, v43
	v_mul_f32_e32 v1, v39, v1
	v_add_f32_e32 v2, 1.0, v36
	v_div_scale_f32 v36, s[10:11], v2, v2, v32
	v_rcp_f32_e32 v37, v36
	v_cvt_pk_bf16_f32 v1, v1, s0
	ds_write_b16 v132, v1 offset:11984
	v_fma_f32 v1, -v36, v37, 1.0
	v_fmac_f32_e32 v37, v1, v37
	v_div_scale_f32 v1, vcc, v32, v2, v32
	v_mul_f32_e32 v38, v1, v37
	v_fma_f32 v39, -v36, v38, v1
	v_fmac_f32_e32 v38, v39, v37
	v_fma_f32 v1, -v36, v38, v1
	v_mul_f32_e32 v36, 0xbfb8aa3b, v33
	v_exp_f32_e32 v36, v36
	v_div_fmas_f32 v1, v1, v37, v38
	v_div_fixup_f32 v1, v1, v2, v32
	v_mul_f32_e32 v1, v28, v1
	v_add_f32_e32 v2, 1.0, v36
	v_div_scale_f32 v32, s[10:11], v2, v2, v33
	v_rcp_f32_e32 v36, v32
	v_cvt_pk_bf16_f32 v1, v1, s0
	ds_write_b16 v132, v1 offset:13824
	v_fma_f32 v1, -v32, v36, 1.0
	v_fmac_f32_e32 v36, v1, v36
	v_div_scale_f32 v1, vcc, v33, v2, v33
	v_mul_f32_e32 v28, v1, v36
	v_fma_f32 v37, -v32, v28, v1
	v_fmac_f32_e32 v28, v37, v36
	v_fma_f32 v1, -v32, v28, v1
	v_mul_f32_e32 v32, 0xbfb8aa3b, v34
	v_exp_f32_e32 v32, v32
	v_div_fmas_f32 v1, v1, v36, v28
	v_div_fixup_f32 v1, v1, v2, v33
	v_mul_f32_e32 v1, v29, v1
	v_add_f32_e32 v2, 1.0, v32
	v_div_scale_f32 v28, s[10:11], v2, v2, v34
	v_rcp_f32_e32 v32, v28
	v_cvt_pk_bf16_f32 v1, v1, s0
	ds_write_b16 v132, v1 offset:13968
	v_fma_f32 v1, -v28, v32, 1.0
	v_fmac_f32_e32 v32, v1, v32
	v_div_scale_f32 v1, vcc, v34, v2, v34
	v_mul_f32_e32 v29, v1, v32
	v_fma_f32 v33, -v28, v29, v1
	v_fmac_f32_e32 v29, v33, v32
	v_fma_f32 v1, -v28, v29, v1
	v_mul_f32_e32 v28, 0xbfb8aa3b, v35
	v_exp_f32_e32 v28, v28
	v_div_fmas_f32 v1, v1, v32, v29
	v_div_fixup_f32 v1, v1, v2, v34
	v_mul_f32_e32 v1, v30, v1
	v_add_f32_e32 v2, 1.0, v28
	v_div_scale_f32 v28, s[10:11], v2, v2, v35
	v_rcp_f32_e32 v29, v28
	v_cvt_pk_bf16_f32 v1, v1, s0
	ds_write_b16 v132, v1 offset:14112
	v_fma_f32 v1, -v28, v29, 1.0
	v_fmac_f32_e32 v29, v1, v29
	v_div_scale_f32 v1, vcc, v35, v2, v35
	v_mul_f32_e32 v30, v1, v29
	v_fma_f32 v32, -v28, v30, v1
	v_fmac_f32_e32 v30, v32, v29
	v_fma_f32 v1, -v28, v30, v1
	v_mul_f32_e32 v28, 0xbfb8aa3b, v24
	v_exp_f32_e32 v28, v28
	v_div_fmas_f32 v1, v1, v29, v30
	v_div_fixup_f32 v1, v1, v2, v35
	v_mul_f32_e32 v1, v31, v1
	v_add_f32_e32 v2, 1.0, v28
	v_div_scale_f32 v28, s[10:11], v2, v2, v24
	v_rcp_f32_e32 v29, v28
	v_cvt_pk_bf16_f32 v1, v1, s0
	ds_write_b16 v132, v1 offset:14256
	v_fma_f32 v1, -v28, v29, 1.0
	v_fmac_f32_e32 v29, v1, v29
	v_div_scale_f32 v1, vcc, v24, v2, v24
	v_mul_f32_e32 v30, v1, v29
	v_fma_f32 v31, -v28, v30, v1
	v_fmac_f32_e32 v30, v31, v29
	v_fma_f32 v1, -v28, v30, v1
	v_mul_f32_e32 v28, 0xbfb8aa3b, v25
	v_exp_f32_e32 v28, v28
	v_div_fmas_f32 v1, v1, v29, v30
	v_div_fixup_f32 v1, v1, v2, v24
	v_mul_f32_e32 v1, v20, v1
	v_add_f32_e32 v2, 1.0, v28
	v_div_scale_f32 v24, s[10:11], v2, v2, v25
	v_rcp_f32_e32 v28, v24
	v_cvt_pk_bf16_f32 v1, v1, s0
	ds_write_b16 v132, v1 offset:13856
	v_fma_f32 v1, -v24, v28, 1.0
	v_fmac_f32_e32 v28, v1, v28
	v_div_scale_f32 v1, vcc, v25, v2, v25
	v_mul_f32_e32 v20, v1, v28
	v_fma_f32 v29, -v24, v20, v1
	v_fmac_f32_e32 v20, v29, v28
	v_fma_f32 v1, -v24, v20, v1
	v_mul_f32_e32 v24, 0xbfb8aa3b, v26
	v_exp_f32_e32 v24, v24
	v_div_fmas_f32 v1, v1, v28, v20
	v_div_fixup_f32 v1, v1, v2, v25
	v_mul_f32_e32 v1, v21, v1
	v_add_f32_e32 v2, 1.0, v24
	v_div_scale_f32 v20, s[10:11], v2, v2, v26
	v_rcp_f32_e32 v24, v20
	v_cvt_pk_bf16_f32 v1, v1, s0
	ds_write_b16 v132, v1 offset:14000
	v_fma_f32 v1, -v20, v24, 1.0
	v_fmac_f32_e32 v24, v1, v24
	v_div_scale_f32 v1, vcc, v26, v2, v26
	v_mul_f32_e32 v21, v1, v24
	v_fma_f32 v25, -v20, v21, v1
	v_fmac_f32_e32 v21, v25, v24
	v_fma_f32 v1, -v20, v21, v1
	v_mul_f32_e32 v20, 0xbfb8aa3b, v27
	v_exp_f32_e32 v20, v20
	v_div_fmas_f32 v1, v1, v24, v21
	v_div_fixup_f32 v1, v1, v2, v26
	v_mul_f32_e32 v1, v22, v1
	v_add_f32_e32 v2, 1.0, v20
	v_div_scale_f32 v20, s[10:11], v2, v2, v27
	v_rcp_f32_e32 v21, v20
	v_cvt_pk_bf16_f32 v1, v1, s0
	ds_write_b16 v132, v1 offset:14144
	v_fma_f32 v1, -v20, v21, 1.0
	v_fmac_f32_e32 v21, v1, v21
	v_div_scale_f32 v1, vcc, v27, v2, v27
	v_mul_f32_e32 v22, v1, v21
	v_fma_f32 v24, -v20, v22, v1
; DEVI float silu_(float x) { return x / (1.f + __expf(-x)); }
; DEVI void ffn1_tile256(const P& p, const bf* W, long row0, int n0  , char* smem) {
;     ...
; #pragma unroll
;   for (int m = 0; m < 8; ++m)
; #pragma unroll
;     for (int pr = 0; pr < 2; ++pr) {
;       const int cl = (wc * 2 + pr) * 16 + l15;
; #pragma unroll
;       for (int j = 0; j < 4; ++j) {
;         const int rl = wr * 128 + m * 16 + quad * 4 + j;
;         float a = acc[m][2 * pr][j], b = acc[m][2 * pr + 1][j];
;         tl[rl * 72 + cl] = f2bf(silu_(a) * b);
;       }
;     }
;   __syncthreads();
	v_fmac_f32_e32 v22, v24, v21
	v_fma_f32 v1, -v20, v22, v1
	v_mul_f32_e32 v20, 0xbfb8aa3b, v16
	v_exp_f32_e32 v20, v20
	v_div_fmas_f32 v1, v1, v21, v22
	v_div_fixup_f32 v1, v1, v2, v27
	v_mul_f32_e32 v1, v23, v1
	v_add_f32_e32 v2, 1.0, v20
	v_div_scale_f32 v20, s[10:11], v2, v2, v16
	v_rcp_f32_e32 v21, v20
	v_cvt_pk_bf16_f32 v1, v1, s0
	ds_write_b16 v132, v1 offset:14288
	v_fma_f32 v1, -v20, v21, 1.0
	v_fmac_f32_e32 v21, v1, v21
	v_div_scale_f32 v1, vcc, v16, v2, v16
	v_mul_f32_e32 v22, v1, v21
	v_fma_f32 v23, -v20, v22, v1
	v_fmac_f32_e32 v22, v23, v21
	v_fma_f32 v1, -v20, v22, v1
	v_mul_f32_e32 v20, 0xbfb8aa3b, v17
	v_exp_f32_e32 v20, v20
	v_div_fmas_f32 v1, v1, v21, v22
	v_div_fixup_f32 v1, v1, v2, v16
	v_mul_f32_e32 v1, v12, v1
	v_add_f32_e32 v2, 1.0, v20
	v_div_scale_f32 v16, s[10:11], v2, v2, v17
	v_rcp_f32_e32 v20, v16
	v_cvt_pk_bf16_f32 v1, v1, s0
	ds_write_b16 v132, v1 offset:16128
	v_fma_f32 v1, -v16, v20, 1.0
	v_fmac_f32_e32 v20, v1, v20
	v_div_scale_f32 v1, vcc, v17, v2, v17
	v_mul_f32_e32 v12, v1, v20
	v_fma_f32 v21, -v16, v12, v1
	v_fmac_f32_e32 v12, v21, v20
	v_fma_f32 v1, -v16, v12, v1
	v_mul_f32_e32 v16, 0xbfb8aa3b, v18
	v_exp_f32_e32 v16, v16
	v_div_fmas_f32 v1, v1, v20, v12
	v_div_fixup_f32 v1, v1, v2, v17
	v_mul_f32_e32 v1, v13, v1
	v_add_f32_e32 v2, 1.0, v16
	v_div_scale_f32 v12, s[10:11], v2, v2, v18
	v_rcp_f32_e32 v16, v12
	v_cvt_pk_bf16_f32 v1, v1, s0
	ds_write_b16 v132, v1 offset:16272
	v_fma_f32 v1, -v12, v16, 1.0
	v_fmac_f32_e32 v16, v1, v16
	v_div_scale_f32 v1, vcc, v18, v2, v18
	v_mul_f32_e32 v13, v1, v16
	v_fma_f32 v17, -v12, v13, v1
	v_fmac_f32_e32 v13, v17, v16
	v_fma_f32 v1, -v12, v13, v1
	v_mul_f32_e32 v12, 0xbfb8aa3b, v19
	v_exp_f32_e32 v12, v12
	v_div_fmas_f32 v1, v1, v16, v13
	v_div_fixup_f32 v1, v1, v2, v18
	v_mul_f32_e32 v1, v14, v1
	v_add_f32_e32 v2, 1.0, v12
	v_div_scale_f32 v12, s[10:11], v2, v2, v19
	v_rcp_f32_e32 v13, v12
	v_cvt_pk_bf16_f32 v1, v1, s0
	ds_write_b16 v132, v1 offset:16416
	v_fma_f32 v1, -v12, v13, 1.0
	v_fmac_f32_e32 v13, v1, v13
	v_div_scale_f32 v1, vcc, v19, v2, v19
	v_mul_f32_e32 v14, v1, v13
	v_fma_f32 v16, -v12, v14, v1
	v_fmac_f32_e32 v14, v16, v13
	v_fma_f32 v1, -v12, v14, v1
	v_mul_f32_e32 v12, 0xbfb8aa3b, v8
	v_exp_f32_e32 v12, v12
	v_div_fmas_f32 v1, v1, v13, v14
	v_div_fixup_f32 v1, v1, v2, v19
	v_mul_f32_e32 v1, v15, v1
	v_add_f32_e32 v2, 1.0, v12
	v_div_scale_f32 v12, s[10:11], v2, v2, v8
	v_rcp_f32_e32 v13, v12
	v_cvt_pk_bf16_f32 v1, v1, s0
	ds_write_b16 v132, v1 offset:16560
	v_fma_f32 v1, -v12, v13, 1.0
	v_fmac_f32_e32 v13, v1, v13
	v_div_scale_f32 v1, vcc, v8, v2, v8
	v_mul_f32_e32 v14, v1, v13
	v_fma_f32 v15, -v12, v14, v1
	v_fmac_f32_e32 v14, v15, v13
	v_fma_f32 v1, -v12, v14, v1
	v_mul_f32_e32 v12, 0xbfb8aa3b, v9
	v_exp_f32_e32 v12, v12
	v_div_fmas_f32 v1, v1, v13, v14
	v_div_fixup_f32 v1, v1, v2, v8
	v_mul_f32_e32 v1, v4, v1
	v_add_f32_e32 v2, 1.0, v12
	v_div_scale_f32 v8, s[10:11], v2, v2, v9
	v_rcp_f32_e32 v12, v8
	v_cvt_pk_bf16_f32 v1, v1, s0
	ds_write_b16 v132, v1 offset:16160
	v_fma_f32 v1, -v8, v12, 1.0
	v_fmac_f32_e32 v12, v1, v12
	v_div_scale_f32 v1, vcc, v9, v2, v9
	v_mul_f32_e32 v4, v1, v12
	v_fma_f32 v13, -v8, v4, v1
	v_fmac_f32_e32 v4, v13, v12
	v_fma_f32 v1, -v8, v4, v1
	v_mul_f32_e32 v8, 0xbfb8aa3b, v10
	v_exp_f32_e32 v8, v8
	v_div_fmas_f32 v1, v1, v12, v4
	v_div_fixup_f32 v1, v1, v2, v9
	v_mul_f32_e32 v1, v5, v1
	v_add_f32_e32 v2, 1.0, v8
	v_div_scale_f32 v4, s[10:11], v2, v2, v10
	v_rcp_f32_e32 v8, v4
	v_cvt_pk_bf16_f32 v1, v1, s0
	ds_write_b16 v132, v1 offset:16304
	v_fma_f32 v1, -v4, v8, 1.0
	v_fmac_f32_e32 v8, v1, v8
	v_div_scale_f32 v1, vcc, v10, v2, v10
	v_mul_f32_e32 v5, v1, v8
	v_fma_f32 v9, -v4, v5, v1
	v_fmac_f32_e32 v5, v9, v8
	v_fma_f32 v1, -v4, v5, v1
	v_mul_f32_e32 v4, 0xbfb8aa3b, v11
	v_exp_f32_e32 v4, v4
	v_div_fmas_f32 v1, v1, v8, v5
	v_div_fixup_f32 v1, v1, v2, v10
	v_mul_f32_e32 v1, v6, v1
	v_add_f32_e32 v2, 1.0, v4
	v_div_scale_f32 v4, s[10:11], v2, v2, v11
	v_rcp_f32_e32 v5, v4
	v_cvt_pk_bf16_f32 v1, v1, s0
	ds_write_b16 v132, v1 offset:16448
	s_ashr_i32 s10, s38, 1
	v_fma_f32 v1, -v4, v5, 1.0
	v_fmac_f32_e32 v5, v1, v5
	v_div_scale_f32 v1, vcc, v11, v2, v11
	v_mul_f32_e32 v6, v1, v5
	v_fma_f32 v8, -v4, v6, v1
	v_fmac_f32_e32 v6, v8, v5
	v_fma_f32 v1, -v4, v6, v1
	v_div_fmas_f32 v1, v1, v5, v6
	v_div_fixup_f32 v1, v1, v2, v11
	v_mul_f32_e32 v1, v7, v1
	v_cvt_pk_bf16_f32 v1, v1, s0
	ds_write_b16 v132, v1 offset:16592
	v_mov_b32_e32 v1, v178
	s_waitcnt lgkmcnt(0)
	s_barrier
; DEVI int get_tid() { int t = threadIdx.x; asm volatile("" : "+v"(t)); return t; }
; template <int BN>
; DEVI void tile_store256(const char* smem, bf* __restrict__ C, long ldc, long row0, int col0) {
;   constexpr int LDT = BN + 8;
;   constexpr int CPR = BN / 8;
;   const int tid = get_tid();
; #pragma unroll
;   for (int i = 0; i < CPR; ++i) {
;     const int q = tid + 256 * i;
;     const int r = q / CPR, c = q - r * CPR;
;     u32x4 v = *reinterpret_cast<const u32x4*>(smem + (r * LDT + c * 8) * 2);
;     *reinterpret_cast<u32x4*>(C + (row0 + r) * ldc + col0 + c * 8) = v;
;   }
; }
; DEVI void phase_ffn1(const P& p, int f, char* smem) {
;     ...
;   for (int v = blockIdx.x; v < 128 * 44; v += gridDim.x) {
;     int m2, nt;
;     lat_tile_map256(v, 44, m2, nt);
;     ffn1_tile256(p, W, lat_row0_256(m2), nt * 128, smem);
	s_ashr_i32 s11, s10, 31
	v_ashrrev_i32_e32 v2, 31, v1
	v_lshrrev_b32_e32 v2, 29, v2
	s_lshl_b64 s[10:11], s[10:11], 1
	v_add_u32_e32 v2, v1, v2
	s_add_u32 s10, s58, s10
	v_ashrrev_i32_e32 v8, 3, v2
	s_addc_u32 s11, s59, s11
	v_lshlrev_b32_e32 v4, 6, v8
	v_lshlrev_b32_e32 v5, 3, v1
	v_ashrrev_i32_e32 v9, 31, v8
	v_mul_lo_u32 v2, v8, s25
	v_sub_u32_e32 v10, v5, v4
	v_lshl_add_u64 v[8:9], s[34:35], 0, v[8:9]
	v_mov_b64_e32 v[12:13], s[10:11]
	v_add_lshl_u32 v2, v10, v2, 1
	v_mad_u64_u32 v[14:15], s[10:11], v8, s73, v[12:13]
	ds_read_b128 v[4:7], v2
	v_mov_b32_e32 v2, v15
	v_mad_u64_u32 v[8:9], s[10:11], v9, s73, v[2:3]
	v_add_u32_e32 v2, 0x100, v1
	v_mov_b32_e32 v15, v8
	v_ashrrev_i32_e32 v8, 31, v2
	v_lshrrev_b32_e32 v8, 29, v8
	v_add_u32_e32 v8, v2, v8
	v_ashrrev_i32_e32 v16, 3, v8
	v_ashrrev_i32_e32 v11, 31, v10
	v_lshlrev_b32_e32 v9, 6, v16
	v_lshlrev_b32_e32 v2, 3, v2
	v_lshl_add_u64 v[14:15], v[10:11], 1, v[14:15]
	v_mul_lo_u32 v8, v16, s25
	v_sub_u32_e32 v18, v2, v9
	v_ashrrev_i32_e32 v17, 31, v16
	v_add_lshl_u32 v2, v18, v8, 1
	s_waitcnt lgkmcnt(0)
	global_store_dwordx4 v[14:15], v[4:7], off
	ds_read_b128 v[8:11], v2
	v_ashrrev_i32_e32 v19, 31, v18
	v_lshl_add_u64 v[4:5], s[34:35], 0, v[16:17]
	v_mad_u64_u32 v[6:7], s[10:11], v4, s73, v[12:13]
	v_mov_b32_e32 v2, v7
	v_mad_u64_u32 v[4:5], s[10:11], v5, s73, v[2:3]
	v_mov_b32_e32 v7, v4
	v_lshl_add_u64 v[4:5], v[18:19], 1, v[6:7]
	v_add_u32_e32 v2, 0x200, v1
	s_waitcnt lgkmcnt(0)
	global_store_dwordx4 v[4:5], v[8:11], off
	v_ashrrev_i32_e32 v4, 31, v2
	v_lshrrev_b32_e32 v4, 29, v4
	v_add_u32_e32 v4, v2, v4
	v_ashrrev_i32_e32 v8, 3, v4
	v_lshlrev_b32_e32 v5, 6, v8
	v_lshlrev_b32_e32 v2, 3, v2
	v_ashrrev_i32_e32 v9, 31, v8
	v_mul_lo_u32 v4, v8, s25
	v_sub_u32_e32 v10, v2, v5
	v_lshl_add_u64 v[8:9], s[34:35], 0, v[8:9]
	v_add_lshl_u32 v2, v10, v4, 1
	v_mad_u64_u32 v[14:15], s[10:11], v8, s73, v[12:13]
	ds_read_b128 v[4:7], v2
	v_mov_b32_e32 v2, v15
	v_mad_u64_u32 v[8:9], s[10:11], v9, s73, v[2:3]
	v_add_u32_e32 v2, 0x300, v1
	v_mov_b32_e32 v15, v8
	v_ashrrev_i32_e32 v8, 31, v2
	v_lshrrev_b32_e32 v8, 29, v8
	v_add_u32_e32 v8, v2, v8
	v_ashrrev_i32_e32 v16, 3, v8
	v_ashrrev_i32_e32 v11, 31, v10
	v_lshlrev_b32_e32 v9, 6, v16
	v_lshlrev_b32_e32 v2, 3, v2
	v_lshl_add_u64 v[14:15], v[10:11], 1, v[14:15]
	v_mul_lo_u32 v8, v16, s25
	v_sub_u32_e32 v18, v2, v9
	v_ashrrev_i32_e32 v17, 31, v16
	v_add_lshl_u32 v2, v18, v8, 1
	s_waitcnt lgkmcnt(0)
	global_store_dwordx4 v[14:15], v[4:7], off
	ds_read_b128 v[8:11], v2
	v_ashrrev_i32_e32 v19, 31, v18
	v_lshl_add_u64 v[4:5], s[34:35], 0, v[16:17]
	v_mad_u64_u32 v[6:7], s[10:11], v4, s73, v[12:13]
	v_mov_b32_e32 v2, v7
	v_mad_u64_u32 v[4:5], s[10:11], v5, s73, v[2:3]
	v_mov_b32_e32 v7, v4
	v_lshl_add_u64 v[4:5], v[18:19], 1, v[6:7]
	v_add_u32_e32 v2, 0x400, v1
	s_waitcnt lgkmcnt(0)
	global_store_dwordx4 v[4:5], v[8:11], off
	v_ashrrev_i32_e32 v4, 31, v2
	v_lshrrev_b32_e32 v4, 29, v4
	v_add_u32_e32 v4, v2, v4
	v_ashrrev_i32_e32 v8, 3, v4
	v_lshlrev_b32_e32 v5, 6, v8
	v_lshlrev_b32_e32 v2, 3, v2
	v_ashrrev_i32_e32 v9, 31, v8
	v_mul_lo_u32 v4, v8, s25
	v_sub_u32_e32 v10, v2, v5
	v_lshl_add_u64 v[8:9], s[34:35], 0, v[8:9]
	v_add_lshl_u32 v2, v10, v4, 1
	v_mad_u64_u32 v[14:15], s[10:11], v8, s73, v[12:13]
	ds_read_b128 v[4:7], v2
	v_mov_b32_e32 v2, v15
	v_mad_u64_u32 v[8:9], s[10:11], v9, s73, v[2:3]
	v_add_u32_e32 v2, 0x500, v1
	v_mov_b32_e32 v15, v8
	v_ashrrev_i32_e32 v8, 31, v2
	v_lshrrev_b32_e32 v8, 29, v8
	v_add_u32_e32 v8, v2, v8
	v_ashrrev_i32_e32 v16, 3, v8
	v_ashrrev_i32_e32 v11, 31, v10
	v_lshlrev_b32_e32 v9, 6, v16
	v_lshlrev_b32_e32 v2, 3, v2
	v_lshl_add_u64 v[14:15], v[10:11], 1, v[14:15]
	v_mul_lo_u32 v8, v16, s25
	v_sub_u32_e32 v18, v2, v9
	v_ashrrev_i32_e32 v17, 31, v16
	v_add_lshl_u32 v2, v18, v8, 1
	s_waitcnt lgkmcnt(0)
	global_store_dwordx4 v[14:15], v[4:7], off
	ds_read_b128 v[8:11], v2
	v_ashrrev_i32_e32 v19, 31, v18
	v_lshl_add_u64 v[4:5], s[34:35], 0, v[16:17]
	v_mad_u64_u32 v[6:7], s[10:11], v4, s73, v[12:13]
	v_mov_b32_e32 v2, v7
	v_mad_u64_u32 v[4:5], s[10:11], v5, s73, v[2:3]
	v_mov_b32_e32 v7, v4
	v_lshl_add_u64 v[4:5], v[18:19], 1, v[6:7]
	v_add_u32_e32 v2, 0x600, v1
	s_waitcnt lgkmcnt(0)
	global_store_dwordx4 v[4:5], v[8:11], off
	v_ashrrev_i32_e32 v4, 31, v2
	v_lshrrev_b32_e32 v4, 29, v4
	v_add_u32_e32 v4, v2, v4
	v_ashrrev_i32_e32 v8, 3, v4
	v_lshlrev_b32_e32 v5, 6, v8
	v_lshlrev_b32_e32 v2, 3, v2
	v_ashrrev_i32_e32 v9, 31, v8
	v_mul_lo_u32 v4, v8, s25
	v_sub_u32_e32 v10, v2, v5
	v_lshl_add_u64 v[8:9], s[34:35], 0, v[8:9]
	v_add_lshl_u32 v2, v10, v4, 1
	v_mad_u64_u32 v[14:15], s[10:11], v8, s73, v[12:13]
	ds_read_b128 v[4:7], v2
	v_mov_b32_e32 v2, v15
	v_add_u32_e32 v1, 0x700, v1
	v_mad_u64_u32 v[8:9], s[10:11], v9, s73, v[2:3]
	v_ashrrev_i32_e32 v2, 31, v1
	v_lshrrev_b32_e32 v2, 29, v2
	v_add_u32_e32 v2, v1, v2
	v_mov_b32_e32 v15, v8
	v_ashrrev_i32_e32 v11, 31, v10
	v_ashrrev_i32_e32 v16, 3, v2
	v_lshl_add_u64 v[14:15], v[10:11], 1, v[14:15]
	v_lshlrev_b32_e32 v8, 6, v16
	v_lshlrev_b32_e32 v1, 3, v1
	v_ashrrev_i32_e32 v17, 31, v16
	v_mul_lo_u32 v2, v16, s25
	v_sub_u32_e32 v18, v1, v8
	s_waitcnt lgkmcnt(0)
	global_store_dwordx4 v[14:15], v[4:7], off
	v_add_lshl_u32 v1, v18, v2, 1
	ds_read_b128 v[8:11], v1
	v_lshl_add_u64 v[4:5], s[34:35], 0, v[16:17]
	v_mad_u64_u32 v[6:7], s[10:11], v4, s73, v[12:13]
	v_mov_b32_e32 v2, v7
	v_mad_u64_u32 v[4:5], s[10:11], v5, s73, v[2:3]
	v_readlane_b32 s10, v252, 59
	v_mov_b32_e32 v7, v4
	v_ashrrev_i32_e32 v19, 31, v18
	s_add_i32 s2, s2, s10
	v_lshl_add_u64 v[4:5], v[18:19], 1, v[6:7]
	s_cmpk_gt_i32 s2, 0x15ff
	s_waitcnt lgkmcnt(0)
	global_store_dwordx4 v[4:5], v[8:11], off
	s_barrier
	v_readlane_b32 s11, v252, 60
	s_cbranch_scc0 .LBB0_183

; DEVI f32x4 mfma16(bf16x8 a, bf16x8 b, f32x4 c) { return __builtin_amdgcn_mfma_f32_16x16x32_bf16(a, b, c, 0, 0, 0); }
; DEVI void gemm_core3(f32x4 (&acc)[8][4], const bf* __restrict__ A, int lda, const bf* __restrict__ Bt, int ldb, int K, char* smem) {
;     ...
;   for (int kt = 0; kt < nk; ++kt) {
;     const int k1 = min((kt + 1) * 32, klast);
;     const int sn = ((kt + 1) & 1) * STG;
;     const int so = (kt & 1) * STG;
;     bf16x8 bfr[4], af[8];
; #pragma unroll
;     for (int n = 0; n < 4; ++n) bfr[n] = *reinterpret_cast<const bf16x8*>(bbase + so + n * 16 * 64);
; #pragma unroll
;     for (int m = 0; m < 8; ++m) af[m] = *reinterpret_cast<const bf16x8*>(abase + so + m * 16 * 64);
; #pragma unroll
;     for (int i = 0; i < 4; ++i) glds16(Ap + i * sa + k1, dbase + sn + i * 4096);
; #pragma unroll
;     for (int i = 0; i < 2; ++i) glds16(Bp + i * sb + k1, dbase + sn + ASZ + i * 4096);
;     __builtin_amdgcn_s_setprio(1);
; #pragma unroll
;     for (int m = 0; m < 8; ++m)
; #pragma unroll
;       for (int n = 0; n < 4; ++n) acc[m][n] = mfma16(af[m], bfr[n], acc[m][n]);
;     __builtin_amdgcn_s_setprio(0);
;     __syncthreads();
;   }
.Lg3_loop_206:
	v_add_u32_e32 v216, s10, v146
	v_add_u32_e32 v217, s10, v2
	ds_read_b128 v[148:151], v217 offset:16384
	ds_read_b128 v[166:169], v216
	ds_read_b128 v[154:157], v217 offset:17408
	ds_read_b128 v[158:161], v217 offset:18432
	ds_read_b128 v[162:165], v217 offset:19456
	ds_read_b128 v[170:173], v216 offset:1024
	ds_read_b128 v[174:177], v216 offset:2048
	ds_read_b128 v[192:195], v216 offset:3072
	ds_read_b128 v[196:199], v216 offset:4096
	ds_read_b128 v[204:207], v216 offset:5120
	ds_read_b128 v[208:211], v216 offset:6144
	ds_read_b128 v[212:215], v216 offset:7168
	s_setprio 1
	s_waitcnt lgkmcnt(10)
	v_mfma_f32_16x16x32_bf16 v[128:131], v[166:169], v[148:151], v[128:131]
	s_waitcnt lgkmcnt(9)
	v_mfma_f32_16x16x32_bf16 v[124:127], v[166:169], v[154:157], v[124:127]
	s_waitcnt lgkmcnt(8)
	v_mfma_f32_16x16x32_bf16 v[120:123], v[166:169], v[158:161], v[120:123]
	s_waitcnt lgkmcnt(7)
	v_mfma_f32_16x16x32_bf16 v[116:119], v[166:169], v[162:165], v[116:119]
	s_waitcnt lgkmcnt(6)
	v_mfma_f32_16x16x32_bf16 v[112:115], v[170:173], v[148:151], v[112:115]
	v_mfma_f32_16x16x32_bf16 v[108:111], v[170:173], v[154:157], v[108:111]
	v_mfma_f32_16x16x32_bf16 v[104:107], v[170:173], v[158:161], v[104:107]
	v_mfma_f32_16x16x32_bf16 v[100:103], v[170:173], v[162:165], v[100:103]
	s_waitcnt lgkmcnt(5)
	v_mfma_f32_16x16x32_bf16 v[96:99], v[174:177], v[148:151], v[96:99]
	v_mfma_f32_16x16x32_bf16 v[92:95], v[174:177], v[154:157], v[92:95]
	v_mfma_f32_16x16x32_bf16 v[88:91], v[174:177], v[158:161], v[88:91]
	v_mfma_f32_16x16x32_bf16 v[84:87], v[174:177], v[162:165], v[84:87]
	s_waitcnt lgkmcnt(4)
	v_mfma_f32_16x16x32_bf16 v[80:83], v[192:195], v[148:151], v[80:83]
	v_mfma_f32_16x16x32_bf16 v[76:79], v[192:195], v[154:157], v[76:79]
	v_mfma_f32_16x16x32_bf16 v[72:75], v[192:195], v[158:161], v[72:75]
	v_mfma_f32_16x16x32_bf16 v[68:71], v[192:195], v[162:165], v[68:71]
	s_waitcnt lgkmcnt(3)
	v_mfma_f32_16x16x32_bf16 v[64:67], v[196:199], v[148:151], v[64:67]
	v_mfma_f32_16x16x32_bf16 v[60:63], v[196:199], v[154:157], v[60:63]
	v_mfma_f32_16x16x32_bf16 v[56:59], v[196:199], v[158:161], v[56:59]
	v_mfma_f32_16x16x32_bf16 v[52:55], v[196:199], v[162:165], v[52:55]
	s_waitcnt lgkmcnt(2)
	v_mfma_f32_16x16x32_bf16 v[48:51], v[204:207], v[148:151], v[48:51]
	v_mfma_f32_16x16x32_bf16 v[44:47], v[204:207], v[154:157], v[44:47]
	v_mfma_f32_16x16x32_bf16 v[40:43], v[204:207], v[158:161], v[40:43]
	v_mfma_f32_16x16x32_bf16 v[36:39], v[204:207], v[162:165], v[36:39]
	s_waitcnt lgkmcnt(1)
	v_mfma_f32_16x16x32_bf16 v[32:35], v[208:211], v[148:151], v[32:35]
	v_mfma_f32_16x16x32_bf16 v[28:31], v[208:211], v[154:157], v[28:31]
	v_mfma_f32_16x16x32_bf16 v[24:27], v[208:211], v[158:161], v[24:27]
	v_mfma_f32_16x16x32_bf16 v[20:23], v[208:211], v[162:165], v[20:23]
	s_waitcnt lgkmcnt(0)
	v_mfma_f32_16x16x32_bf16 v[16:19], v[212:215], v[148:151], v[16:19]
	v_mfma_f32_16x16x32_bf16 v[12:15], v[212:215], v[154:157], v[12:15]
	v_mfma_f32_16x16x32_bf16 v[8:11], v[212:215], v[158:161], v[8:11]
	v_mfma_f32_16x16x32_bf16 v[4:7], v[212:215], v[162:165], v[4:7]
	s_setprio 0
	s_add_i32 s10, s10, 0x6000
	s_cmp_lg_u32 s10, 0x12000
	s_cselect_b32 s10, s10, 0
	s_waitcnt vmcnt(0)
	s_barrier
	v_add_u32_e32 v216, s10, v146
	v_add_u32_e32 v217, s10, v2
	ds_read_b128 v[148:151], v217 offset:16384
	ds_read_b128 v[166:169], v216
	ds_read_b128 v[154:157], v217 offset:17408
	ds_read_b128 v[158:161], v217 offset:18432
	ds_read_b128 v[162:165], v217 offset:19456
	ds_read_b128 v[170:173], v216 offset:1024
	ds_read_b128 v[174:177], v216 offset:2048
	ds_read_b128 v[192:195], v216 offset:3072
	ds_read_b128 v[196:199], v216 offset:4096
	ds_read_b128 v[204:207], v216 offset:5120
	ds_read_b128 v[208:211], v216 offset:6144
	ds_read_b128 v[212:215], v216 offset:7168
	v_readfirstlane_b32 s17, v140
	s_add_i32 s96, s11, 0x6000
	s_cmp_lg_u32 s96, 0x12000
	s_cselect_b32 s96, s96, 0
	s_add_i32 s96, s96, s17
	s_add_i32 s17, s17, s11
	s_setprio 2
	s_waitcnt lgkmcnt(10)
	s_mov_b32 m0, s17
	s_add_i32 s17, s17, 0x1000
	v_mfma_f32_16x16x32_bf16 v[128:131], v[166:169], v[148:151], v[128:131]
	s_waitcnt lgkmcnt(9)
	v_mfma_f32_16x16x32_bf16 v[124:127], v[166:169], v[154:157], v[124:127]
	global_load_lds_dwordx4 v[218:219], off
	v_lshl_add_u64 v[218:219], v[218:219], 0, 64
	s_waitcnt lgkmcnt(8)
	s_mov_b32 m0, s96
	s_add_i32 s96, s96, 0x1000
	v_mfma_f32_16x16x32_bf16 v[120:123], v[166:169], v[158:161], v[120:123]
	s_waitcnt lgkmcnt(7)
	v_mfma_f32_16x16x32_bf16 v[116:119], v[166:169], v[162:165], v[116:119]
	global_load_lds_dwordx4 v[218:219], off
	v_lshl_add_u64 v[218:219], v[218:219], 0, 64
	s_waitcnt lgkmcnt(6)
	v_mfma_f32_16x16x32_bf16 v[112:115], v[170:173], v[148:151], v[112:115]
	s_mov_b32 m0, s17
	s_add_i32 s17, s17, 0x1000
	v_mfma_f32_16x16x32_bf16 v[108:111], v[170:173], v[154:157], v[108:111]
	v_mfma_f32_16x16x32_bf16 v[104:107], v[170:173], v[158:161], v[104:107]
	global_load_lds_dwordx4 v[220:221], off
	v_lshl_add_u64 v[220:221], v[220:221], 0, 64
	s_mov_b32 m0, s96
	s_add_i32 s96, s96, 0x1000
	v_mfma_f32_16x16x32_bf16 v[100:103], v[170:173], v[162:165], v[100:103]
	s_waitcnt lgkmcnt(5)
	v_mfma_f32_16x16x32_bf16 v[96:99], v[174:177], v[148:151], v[96:99]
	global_load_lds_dwordx4 v[220:221], off
	v_lshl_add_u64 v[220:221], v[220:221], 0, 64
	v_mfma_f32_16x16x32_bf16 v[92:95], v[174:177], v[154:157], v[92:95]
	s_mov_b32 m0, s17
	s_add_i32 s17, s17, 0x1000
	v_mfma_f32_16x16x32_bf16 v[88:91], v[174:177], v[158:161], v[88:91]
	v_mfma_f32_16x16x32_bf16 v[84:87], v[174:177], v[162:165], v[84:87]
	global_load_lds_dwordx4 v[222:223], off
	v_lshl_add_u64 v[222:223], v[222:223], 0, 64
	s_waitcnt lgkmcnt(4)
; DEVI f32x4 mfma16(bf16x8 a, bf16x8 b, f32x4 c) { return __builtin_amdgcn_mfma_f32_16x16x32_bf16(a, b, c, 0, 0, 0); }
; DEVI void gemm_core3(f32x4 (&acc)[8][4], const bf* __restrict__ A, int lda, const bf* __restrict__ Bt, int ldb, int K, char* smem) {
;     ...
;   for (int kt = 0; kt < nk; ++kt) {
;     const int k1 = min((kt + 1) * 32, klast);
;     const int sn = ((kt + 1) & 1) * STG;
;     const int so = (kt & 1) * STG;
;     bf16x8 bfr[4], af[8];
; #pragma unroll
;     for (int n = 0; n < 4; ++n) bfr[n] = *reinterpret_cast<const bf16x8*>(bbase + so + n * 16 * 64);
; #pragma unroll
;     for (int m = 0; m < 8; ++m) af[m] = *reinterpret_cast<const bf16x8*>(abase + so + m * 16 * 64);
; #pragma unroll
;     for (int i = 0; i < 4; ++i) glds16(Ap + i * sa + k1, dbase + sn + i * 4096);
; #pragma unroll
;     for (int i = 0; i < 2; ++i) glds16(Bp + i * sb + k1, dbase + sn + ASZ + i * 4096);
;     __builtin_amdgcn_s_setprio(1);
; #pragma unroll
;     for (int m = 0; m < 8; ++m)
; #pragma unroll
;       for (int n = 0; n < 4; ++n) acc[m][n] = mfma16(af[m], bfr[n], acc[m][n]);
;     __builtin_amdgcn_s_setprio(0);
;     __syncthreads();
;   }
	s_mov_b32 m0, s96
	s_add_i32 s96, s96, 0x1000
	v_mfma_f32_16x16x32_bf16 v[80:83], v[192:195], v[148:151], v[80:83]
	v_mfma_f32_16x16x32_bf16 v[76:79], v[192:195], v[154:157], v[76:79]
	global_load_lds_dwordx4 v[222:223], off
	v_lshl_add_u64 v[222:223], v[222:223], 0, 64
	v_mfma_f32_16x16x32_bf16 v[72:75], v[192:195], v[158:161], v[72:75]
	s_mov_b32 m0, s17
	s_add_i32 s17, s17, 0x1000
	v_mfma_f32_16x16x32_bf16 v[68:71], v[192:195], v[162:165], v[68:71]
	s_waitcnt lgkmcnt(3)
	v_mfma_f32_16x16x32_bf16 v[64:67], v[196:199], v[148:151], v[64:67]
	global_load_lds_dwordx4 v[224:225], off
	v_lshl_add_u64 v[224:225], v[224:225], 0, 64
	s_mov_b32 m0, s96
	s_add_i32 s96, s96, 0x1000
	v_mfma_f32_16x16x32_bf16 v[60:63], v[196:199], v[154:157], v[60:63]
	v_mfma_f32_16x16x32_bf16 v[56:59], v[196:199], v[158:161], v[56:59]
	global_load_lds_dwordx4 v[224:225], off
	v_lshl_add_u64 v[224:225], v[224:225], 0, 64
	v_mfma_f32_16x16x32_bf16 v[52:55], v[196:199], v[162:165], v[52:55]
	s_waitcnt lgkmcnt(2)
	s_mov_b32 m0, s17
	s_add_i32 s17, s17, 0x1000
	v_mfma_f32_16x16x32_bf16 v[48:51], v[204:207], v[148:151], v[48:51]
	v_mfma_f32_16x16x32_bf16 v[44:47], v[204:207], v[154:157], v[44:47]
	global_load_lds_dwordx4 v[226:227], off
	v_lshl_add_u64 v[226:227], v[226:227], 0, 64
	s_mov_b32 m0, s96
	s_add_i32 s96, s96, 0x1000
	v_mfma_f32_16x16x32_bf16 v[40:43], v[204:207], v[158:161], v[40:43]
	v_mfma_f32_16x16x32_bf16 v[36:39], v[204:207], v[162:165], v[36:39]
	global_load_lds_dwordx4 v[226:227], off
	v_lshl_add_u64 v[226:227], v[226:227], 0, 64
	s_waitcnt lgkmcnt(1)
	v_mfma_f32_16x16x32_bf16 v[32:35], v[208:211], v[148:151], v[32:35]
	s_mov_b32 m0, s17
	s_add_i32 s17, s17, 0x1000
	v_mfma_f32_16x16x32_bf16 v[28:31], v[208:211], v[154:157], v[28:31]
	v_mfma_f32_16x16x32_bf16 v[24:27], v[208:211], v[158:161], v[24:27]
	global_load_lds_dwordx4 v[228:229], off
	v_lshl_add_u64 v[228:229], v[228:229], 0, 64
	s_mov_b32 m0, s96
	s_add_i32 s96, s96, 0x1000
	v_mfma_f32_16x16x32_bf16 v[20:23], v[208:211], v[162:165], v[20:23]
	s_waitcnt lgkmcnt(0)
	v_mfma_f32_16x16x32_bf16 v[16:19], v[212:215], v[148:151], v[16:19]
	global_load_lds_dwordx4 v[228:229], off
	v_lshl_add_u64 v[228:229], v[228:229], 0, 64
	v_mfma_f32_16x16x32_bf16 v[12:15], v[212:215], v[154:157], v[12:15]
	v_mfma_f32_16x16x32_bf16 v[8:11], v[212:215], v[158:161], v[8:11]
	v_mfma_f32_16x16x32_bf16 v[4:7], v[212:215], v[162:165], v[4:7]
	s_setprio 0
	s_add_i32 s10, s10, 0x6000
	s_cmp_lg_u32 s10, 0x12000
	s_cselect_b32 s10, s10, 0
	s_sub_i32 s11, s11, 0x6000
	s_cmp_lt_i32 s11, 0
	s_cselect_b32 s11, 0xc000, s11
	s_add_i32 s3, s3, 1
	s_cmp_lt_i32 s3, 15
	s_waitcnt vmcnt(1)
	s_barrier
	s_cbranch_scc1 .Lg3_loop_206
	v_add_u32_e32 v216, s10, v146
	v_add_u32_e32 v217, s10, v2
	ds_read_b128 v[148:151], v217 offset:16384
	ds_read_b128 v[166:169], v216
	ds_read_b128 v[154:157], v217 offset:17408
	ds_read_b128 v[158:161], v217 offset:18432
	ds_read_b128 v[162:165], v217 offset:19456
	ds_read_b128 v[170:173], v216 offset:1024
	ds_read_b128 v[174:177], v216 offset:2048
	ds_read_b128 v[192:195], v216 offset:3072
	ds_read_b128 v[196:199], v216 offset:4096
	ds_read_b128 v[204:207], v216 offset:5120
	ds_read_b128 v[208:211], v216 offset:6144
	ds_read_b128 v[212:215], v216 offset:7168
	s_setprio 1
	s_waitcnt lgkmcnt(10)
	v_mfma_f32_16x16x32_bf16 v[128:131], v[166:169], v[148:151], v[128:131]
	s_waitcnt lgkmcnt(9)
	v_mfma_f32_16x16x32_bf16 v[124:127], v[166:169], v[154:157], v[124:127]
	s_waitcnt lgkmcnt(8)
	v_mfma_f32_16x16x32_bf16 v[120:123], v[166:169], v[158:161], v[120:123]
	s_waitcnt lgkmcnt(7)
	v_mfma_f32_16x16x32_bf16 v[116:119], v[166:169], v[162:165], v[116:119]
	s_waitcnt lgkmcnt(6)
	v_mfma_f32_16x16x32_bf16 v[112:115], v[170:173], v[148:151], v[112:115]
	v_mfma_f32_16x16x32_bf16 v[108:111], v[170:173], v[154:157], v[108:111]
	v_mfma_f32_16x16x32_bf16 v[104:107], v[170:173], v[158:161], v[104:107]
	v_mfma_f32_16x16x32_bf16 v[100:103], v[170:173], v[162:165], v[100:103]
	s_waitcnt lgkmcnt(5)
	v_mfma_f32_16x16x32_bf16 v[96:99], v[174:177], v[148:151], v[96:99]
	v_mfma_f32_16x16x32_bf16 v[92:95], v[174:177], v[154:157], v[92:95]
	v_mfma_f32_16x16x32_bf16 v[88:91], v[174:177], v[158:161], v[88:91]
	v_mfma_f32_16x16x32_bf16 v[84:87], v[174:177], v[162:165], v[84:87]
	s_waitcnt lgkmcnt(4)
	v_mfma_f32_16x16x32_bf16 v[80:83], v[192:195], v[148:151], v[80:83]
	v_mfma_f32_16x16x32_bf16 v[76:79], v[192:195], v[154:157], v[76:79]
	v_mfma_f32_16x16x32_bf16 v[72:75], v[192:195], v[158:161], v[72:75]
	v_mfma_f32_16x16x32_bf16 v[68:71], v[192:195], v[162:165], v[68:71]
	s_waitcnt lgkmcnt(3)
	v_mfma_f32_16x16x32_bf16 v[64:67], v[196:199], v[148:151], v[64:67]
	v_mfma_f32_16x16x32_bf16 v[60:63], v[196:199], v[154:157], v[60:63]
	v_mfma_f32_16x16x32_bf16 v[56:59], v[196:199], v[158:161], v[56:59]
	v_mfma_f32_16x16x32_bf16 v[52:55], v[196:199], v[162:165], v[52:55]
	s_waitcnt lgkmcnt(2)
	v_mfma_f32_16x16x32_bf16 v[48:51], v[204:207], v[148:151], v[48:51]
	v_mfma_f32_16x16x32_bf16 v[44:47], v[204:207], v[154:157], v[44:47]
	v_mfma_f32_16x16x32_bf16 v[40:43], v[204:207], v[158:161], v[40:43]
	v_mfma_f32_16x16x32_bf16 v[36:39], v[204:207], v[162:165], v[36:39]
	s_waitcnt lgkmcnt(1)
	v_mfma_f32_16x16x32_bf16 v[32:35], v[208:211], v[148:151], v[32:35]
	v_mfma_f32_16x16x32_bf16 v[28:31], v[208:211], v[154:157], v[28:31]
	v_mfma_f32_16x16x32_bf16 v[24:27], v[208:211], v[158:161], v[24:27]
	v_mfma_f32_16x16x32_bf16 v[20:23], v[208:211], v[162:165], v[20:23]
	s_waitcnt lgkmcnt(0)
	v_mfma_f32_16x16x32_bf16 v[16:19], v[212:215], v[148:151], v[16:19]
	v_mfma_f32_16x16x32_bf16 v[12:15], v[212:215], v[154:157], v[12:15]
	v_mfma_f32_16x16x32_bf16 v[8:11], v[212:215], v[158:161], v[8:11]
	v_mfma_f32_16x16x32_bf16 v[4:7], v[212:215], v[162:165], v[4:7]
	s_setprio 0
	s_add_i32 s10, s10, 0x6000
	s_cmp_lg_u32 s10, 0x12000
	s_cselect_b32 s10, s10, 0
	s_waitcnt vmcnt(0)
	s_barrier
; DEVI f32x4 mfma16(bf16x8 a, bf16x8 b, f32x4 c) { return __builtin_amdgcn_mfma_f32_16x16x32_bf16(a, b, c, 0, 0, 0); }
; DEVI void gemm_core3(f32x4 (&acc)[8][4], const bf* __restrict__ A, int lda, const bf* __restrict__ Bt, int ldb, int K, char* smem) {
;     ...
; #pragma unroll
;     for (int n = 0; n < 4; ++n) bfr[n] = *reinterpret_cast<const bf16x8*>(bbase + so + n * 16 * 64);
; #pragma unroll
;     for (int m = 0; m < 8; ++m) af[m] = *reinterpret_cast<const bf16x8*>(abase + so + m * 16 * 64);
; #pragma unroll
;     for (int i = 0; i < 4; ++i) glds16(Ap + i * sa + k1, dbase + sn + i * 4096);
; #pragma unroll
;     for (int i = 0; i < 2; ++i) glds16(Bp + i * sb + k1, dbase + sn + ASZ + i * 4096);
;     __builtin_amdgcn_s_setprio(1);
; #pragma unroll
;     for (int m = 0; m < 8; ++m)
; #pragma unroll
;       for (int n = 0; n < 4; ++n) acc[m][n] = mfma16(af[m], bfr[n], acc[m][n]);
;     __builtin_amdgcn_s_setprio(0);
;     __syncthreads();
;   }
; DEVI void plain_tile256(const bf* A, int lda, const bf* Wt, int K, bf* C, int ldc, long row0, int n0, char* smem) {
;     ...
;   bf* tl = reinterpret_cast<bf*>(smem);
; #pragma unroll
;   for (int m = 0; m < 8; ++m)
; #pragma unroll
;     for (int n = 0; n < 4; ++n) {
;       const int cl = wc * 64 + n * 16 + l15;
; #pragma unroll
;       for (int j = 0; j < 4; ++j) tl[(wr * 128 + m * 16 + quad * 4 + j) * 136 + cl] = f2bf(acc[m][n][j]);
;     }
;   __syncthreads();
	v_add_u32_e32 v216, s10, v146
	v_add_u32_e32 v217, s10, v2
	ds_read_b128 v[148:151], v217 offset:16384
	ds_read_b128 v[166:169], v216
	ds_read_b128 v[154:157], v217 offset:17408
	ds_read_b128 v[158:161], v217 offset:18432
	ds_read_b128 v[162:165], v217 offset:19456
	ds_read_b128 v[170:173], v216 offset:1024
	ds_read_b128 v[174:177], v216 offset:2048
	ds_read_b128 v[192:195], v216 offset:3072
	ds_read_b128 v[196:199], v216 offset:4096
	ds_read_b128 v[204:207], v216 offset:5120
	ds_read_b128 v[208:211], v216 offset:6144
	ds_read_b128 v[212:215], v216 offset:7168
	s_setprio 1
	s_waitcnt lgkmcnt(10)
	v_mfma_f32_16x16x32_bf16 v[128:131], v[166:169], v[148:151], v[128:131]
	s_waitcnt lgkmcnt(9)
	v_mfma_f32_16x16x32_bf16 v[124:127], v[166:169], v[154:157], v[124:127]
	s_waitcnt lgkmcnt(8)
	v_mfma_f32_16x16x32_bf16 v[120:123], v[166:169], v[158:161], v[120:123]
	s_waitcnt lgkmcnt(7)
	v_mfma_f32_16x16x32_bf16 v[116:119], v[166:169], v[162:165], v[116:119]
	s_waitcnt lgkmcnt(6)
	v_mfma_f32_16x16x32_bf16 v[112:115], v[170:173], v[148:151], v[112:115]
	v_mfma_f32_16x16x32_bf16 v[108:111], v[170:173], v[154:157], v[108:111]
	v_mfma_f32_16x16x32_bf16 v[104:107], v[170:173], v[158:161], v[104:107]
	v_mfma_f32_16x16x32_bf16 v[100:103], v[170:173], v[162:165], v[100:103]
	s_waitcnt lgkmcnt(5)
	v_mfma_f32_16x16x32_bf16 v[96:99], v[174:177], v[148:151], v[96:99]
	v_mfma_f32_16x16x32_bf16 v[92:95], v[174:177], v[154:157], v[92:95]
	v_mfma_f32_16x16x32_bf16 v[88:91], v[174:177], v[158:161], v[88:91]
	v_mfma_f32_16x16x32_bf16 v[84:87], v[174:177], v[162:165], v[84:87]
	s_waitcnt lgkmcnt(4)
	v_mfma_f32_16x16x32_bf16 v[80:83], v[192:195], v[148:151], v[80:83]
	v_mfma_f32_16x16x32_bf16 v[76:79], v[192:195], v[154:157], v[76:79]
	v_mfma_f32_16x16x32_bf16 v[72:75], v[192:195], v[158:161], v[72:75]
	v_mfma_f32_16x16x32_bf16 v[68:71], v[192:195], v[162:165], v[68:71]
	s_waitcnt lgkmcnt(3)
	v_mfma_f32_16x16x32_bf16 v[64:67], v[196:199], v[148:151], v[64:67]
	v_mfma_f32_16x16x32_bf16 v[60:63], v[196:199], v[154:157], v[60:63]
	v_mfma_f32_16x16x32_bf16 v[56:59], v[196:199], v[158:161], v[56:59]
	v_mfma_f32_16x16x32_bf16 v[52:55], v[196:199], v[162:165], v[52:55]
	s_waitcnt lgkmcnt(2)
	v_mfma_f32_16x16x32_bf16 v[48:51], v[204:207], v[148:151], v[48:51]
	v_mfma_f32_16x16x32_bf16 v[44:47], v[204:207], v[154:157], v[44:47]
	v_mfma_f32_16x16x32_bf16 v[40:43], v[204:207], v[158:161], v[40:43]
	v_mfma_f32_16x16x32_bf16 v[36:39], v[204:207], v[162:165], v[36:39]
	s_waitcnt lgkmcnt(1)
	v_mfma_f32_16x16x32_bf16 v[32:35], v[208:211], v[148:151], v[32:35]
	v_mfma_f32_16x16x32_bf16 v[28:31], v[208:211], v[154:157], v[28:31]
	v_mfma_f32_16x16x32_bf16 v[24:27], v[208:211], v[158:161], v[24:27]
	v_mfma_f32_16x16x32_bf16 v[20:23], v[208:211], v[162:165], v[20:23]
	s_waitcnt lgkmcnt(0)
	v_mfma_f32_16x16x32_bf16 v[16:19], v[212:215], v[148:151], v[16:19]
	v_mfma_f32_16x16x32_bf16 v[12:15], v[212:215], v[154:157], v[12:15]
	v_mfma_f32_16x16x32_bf16 v[8:11], v[212:215], v[158:161], v[8:11]
	v_mfma_f32_16x16x32_bf16 v[4:7], v[212:215], v[162:165], v[4:7]
	s_setprio 0
	s_add_i32 s10, s10, 0x6000
	s_cmp_lg_u32 s10, 0x12000
	s_cselect_b32 s10, s10, 0
	s_waitcnt vmcnt(0)
	s_barrier
	s_setprio 3
	v_and_b32_e32 v2, 0x4f, v1
	v_and_b32_e32 v132, 0xfffff80, v1
	v_lshrrev_b32_e32 v1, 2, v1
	v_and_or_b32 v1, v1, 12, v132
	v_mul_lo_u32 v1, v1, s16
	v_lshl_add_u32 v1, v2, 1, v1
	v_cvt_pk_bf16_f32 v2, v129, s0
	ds_write_b16 v1, v2 offset:272
	v_cvt_pk_bf16_f32 v2, v130, s0
	ds_write_b16 v1, v2 offset:544
	v_cvt_pk_bf16_f32 v2, v131, s0
	ds_write_b16 v1, v2 offset:816
	v_cvt_pk_bf16_f32 v2, v124, s0
	ds_write_b16 v1, v2 offset:32
	v_cvt_pk_bf16_f32 v2, v125, s0
	ds_write_b16 v1, v2 offset:304
	v_cvt_pk_bf16_f32 v2, v126, s0
	ds_write_b16 v1, v2 offset:576
	v_cvt_pk_bf16_f32 v2, v127, s0
	ds_write_b16 v1, v2 offset:848
	v_cvt_pk_bf16_f32 v2, v120, s0
	ds_write_b16 v1, v2 offset:64
	v_cvt_pk_bf16_f32 v2, v121, s0
	ds_write_b16 v1, v2 offset:336
	v_cvt_pk_bf16_f32 v2, v122, s0
	ds_write_b16 v1, v2 offset:608
	v_cvt_pk_bf16_f32 v2, v123, s0
	ds_write_b16 v1, v2 offset:880
	v_cvt_pk_bf16_f32 v2, v116, s0
	ds_write_b16 v1, v2 offset:96
	v_cvt_pk_bf16_f32 v2, v117, s0
	ds_write_b16 v1, v2 offset:368
	v_cvt_pk_bf16_f32 v2, v118, s0
	ds_write_b16 v1, v2 offset:640
	v_cvt_pk_bf16_f32 v2, v119, s0
	ds_write_b16 v1, v2 offset:912
	v_cvt_pk_bf16_f32 v2, v112, s0
	ds_write_b16 v1, v2 offset:4352
	v_cvt_pk_bf16_f32 v2, v113, s0
	ds_write_b16 v1, v2 offset:4624
	v_cvt_pk_bf16_f32 v2, v114, s0
	ds_write_b16 v1, v2 offset:4896
	v_cvt_pk_bf16_f32 v2, v115, s0
	ds_write_b16 v1, v2 offset:5168
	v_cvt_pk_bf16_f32 v2, v108, s0
	ds_write_b16 v1, v2 offset:4384
	v_cvt_pk_bf16_f32 v2, v109, s0
	ds_write_b16 v1, v2 offset:4656
	v_cvt_pk_bf16_f32 v2, v110, s0
	ds_write_b16 v1, v2 offset:4928
	v_cvt_pk_bf16_f32 v2, v111, s0
	ds_write_b16 v1, v2 offset:5200
	v_cvt_pk_bf16_f32 v2, v104, s0
	ds_write_b16 v1, v2 offset:4416
	v_cvt_pk_bf16_f32 v2, v105, s0
	ds_write_b16 v1, v2 offset:4688
	v_cvt_pk_bf16_f32 v2, v106, s0
	ds_write_b16 v1, v2 offset:4960
	v_cvt_pk_bf16_f32 v2, v107, s0
	ds_write_b16 v1, v2 offset:5232
	v_cvt_pk_bf16_f32 v2, v100, s0
	ds_write_b16 v1, v2 offset:4448
	v_cvt_pk_bf16_f32 v2, v101, s0
	ds_write_b16 v1, v2 offset:4720
	v_cvt_pk_bf16_f32 v2, v102, s0
	ds_write_b16 v1, v2 offset:4992
	v_cvt_pk_bf16_f32 v2, v103, s0
	ds_write_b16 v1, v2 offset:5264
	v_cvt_pk_bf16_f32 v2, v96, s0
	ds_write_b16 v1, v2 offset:8704
	v_cvt_pk_bf16_f32 v2, v97, s0
	ds_write_b16 v1, v2 offset:8976
	v_cvt_pk_bf16_f32 v2, v98, s0
	ds_write_b16 v1, v2 offset:9248
	v_cvt_pk_bf16_f32 v2, v99, s0
	ds_write_b16 v1, v2 offset:9520
; DEVI void plain_tile256(const bf* A, int lda, const bf* Wt, int K, bf* C, int ldc, long row0, int n0, char* smem) {
;     ...
;   bf* tl = reinterpret_cast<bf*>(smem);
; #pragma unroll
;   for (int m = 0; m < 8; ++m)
; #pragma unroll
;     for (int n = 0; n < 4; ++n) {
;       const int cl = wc * 64 + n * 16 + l15;
; #pragma unroll
;       for (int j = 0; j < 4; ++j) tl[(wr * 128 + m * 16 + quad * 4 + j) * 136 + cl] = f2bf(acc[m][n][j]);
;     }
;   __syncthreads();
	v_cvt_pk_bf16_f32 v2, v92, s0
	ds_write_b16 v1, v2 offset:8736
	v_cvt_pk_bf16_f32 v2, v93, s0
	ds_write_b16 v1, v2 offset:9008
	v_cvt_pk_bf16_f32 v2, v94, s0
	ds_write_b16 v1, v2 offset:9280
	v_cvt_pk_bf16_f32 v2, v95, s0
	ds_write_b16 v1, v2 offset:9552
	v_cvt_pk_bf16_f32 v2, v88, s0
	ds_write_b16 v1, v2 offset:8768
	v_cvt_pk_bf16_f32 v2, v89, s0
	ds_write_b16 v1, v2 offset:9040
	v_cvt_pk_bf16_f32 v2, v90, s0
	ds_write_b16 v1, v2 offset:9312
	v_cvt_pk_bf16_f32 v2, v91, s0
	ds_write_b16 v1, v2 offset:9584
	v_cvt_pk_bf16_f32 v2, v84, s0
	ds_write_b16 v1, v2 offset:8800
	v_cvt_pk_bf16_f32 v2, v85, s0
	ds_write_b16 v1, v2 offset:9072
	v_cvt_pk_bf16_f32 v2, v86, s0
	ds_write_b16 v1, v2 offset:9344
	v_cvt_pk_bf16_f32 v2, v87, s0
	ds_write_b16 v1, v2 offset:9616
	v_cvt_pk_bf16_f32 v2, v80, s0
	ds_write_b16 v1, v2 offset:13056
	v_cvt_pk_bf16_f32 v2, v81, s0
	ds_write_b16 v1, v2 offset:13328
	v_cvt_pk_bf16_f32 v2, v82, s0
	ds_write_b16 v1, v2 offset:13600
	v_cvt_pk_bf16_f32 v2, v83, s0
	ds_write_b16 v1, v2 offset:13872
	v_cvt_pk_bf16_f32 v2, v76, s0
	ds_write_b16 v1, v2 offset:13088
	v_cvt_pk_bf16_f32 v2, v77, s0
	ds_write_b16 v1, v2 offset:13360
	v_cvt_pk_bf16_f32 v2, v78, s0
	ds_write_b16 v1, v2 offset:13632
	v_cvt_pk_bf16_f32 v2, v79, s0
	ds_write_b16 v1, v2 offset:13904
	v_cvt_pk_bf16_f32 v2, v72, s0
	ds_write_b16 v1, v2 offset:13120
	v_cvt_pk_bf16_f32 v2, v73, s0
	ds_write_b16 v1, v2 offset:13392
	v_cvt_pk_bf16_f32 v2, v74, s0
	ds_write_b16 v1, v2 offset:13664
	v_cvt_pk_bf16_f32 v2, v75, s0
	ds_write_b16 v1, v2 offset:13936
	v_cvt_pk_bf16_f32 v2, v68, s0
	ds_write_b16 v1, v2 offset:13152
	v_cvt_pk_bf16_f32 v2, v69, s0
	ds_write_b16 v1, v2 offset:13424
	v_cvt_pk_bf16_f32 v2, v70, s0
	ds_write_b16 v1, v2 offset:13696
	v_cvt_pk_bf16_f32 v2, v71, s0
	ds_write_b16 v1, v2 offset:13968
	v_cvt_pk_bf16_f32 v2, v64, s0
	ds_write_b16 v1, v2 offset:17408
	v_cvt_pk_bf16_f32 v2, v65, s0
	ds_write_b16 v1, v2 offset:17680
	v_cvt_pk_bf16_f32 v2, v66, s0
	ds_write_b16 v1, v2 offset:17952
	v_cvt_pk_bf16_f32 v2, v67, s0
	ds_write_b16 v1, v2 offset:18224
	v_cvt_pk_bf16_f32 v2, v60, s0
	ds_write_b16 v1, v2 offset:17440
	v_cvt_pk_bf16_f32 v2, v61, s0
	ds_write_b16 v1, v2 offset:17712
	v_cvt_pk_bf16_f32 v2, v62, s0
	ds_write_b16 v1, v2 offset:17984
	v_cvt_pk_bf16_f32 v2, v63, s0
	ds_write_b16 v1, v2 offset:18256
	v_cvt_pk_bf16_f32 v2, v56, s0
	ds_write_b16 v1, v2 offset:17472
	v_cvt_pk_bf16_f32 v2, v57, s0
	ds_write_b16 v1, v2 offset:17744
	v_cvt_pk_bf16_f32 v2, v58, s0
	ds_write_b16 v1, v2 offset:18016
	v_cvt_pk_bf16_f32 v2, v59, s0
	ds_write_b16 v1, v2 offset:18288
	v_cvt_pk_bf16_f32 v2, v52, s0
	ds_write_b16 v1, v2 offset:17504
	v_cvt_pk_bf16_f32 v2, v53, s0
	ds_write_b16 v1, v2 offset:17776
	v_cvt_pk_bf16_f32 v2, v54, s0
	ds_write_b16 v1, v2 offset:18048
	v_cvt_pk_bf16_f32 v2, v55, s0
	ds_write_b16 v1, v2 offset:18320
	v_cvt_pk_bf16_f32 v2, v48, s0
	ds_write_b16 v1, v2 offset:21760
	v_cvt_pk_bf16_f32 v2, v49, s0
	ds_write_b16 v1, v2 offset:22032
	v_cvt_pk_bf16_f32 v2, v50, s0
	ds_write_b16 v1, v2 offset:22304
	v_cvt_pk_bf16_f32 v2, v51, s0
	ds_write_b16 v1, v2 offset:22576
	v_cvt_pk_bf16_f32 v2, v44, s0
	ds_write_b16 v1, v2 offset:21792
	v_cvt_pk_bf16_f32 v2, v45, s0
	ds_write_b16 v1, v2 offset:22064
	v_cvt_pk_bf16_f32 v2, v46, s0
	ds_write_b16 v1, v2 offset:22336
	v_cvt_pk_bf16_f32 v2, v47, s0
	ds_write_b16 v1, v2 offset:22608
	v_cvt_pk_bf16_f32 v2, v40, s0
	ds_write_b16 v1, v2 offset:21824
	v_cvt_pk_bf16_f32 v2, v41, s0
	ds_write_b16 v1, v2 offset:22096
	v_cvt_pk_bf16_f32 v2, v42, s0
	ds_write_b16 v1, v2 offset:22368
	v_cvt_pk_bf16_f32 v2, v43, s0
	ds_write_b16 v1, v2 offset:22640
	v_cvt_pk_bf16_f32 v2, v36, s0
	ds_write_b16 v1, v2 offset:21856
	v_cvt_pk_bf16_f32 v2, v37, s0
	ds_write_b16 v1, v2 offset:22128
	v_cvt_pk_bf16_f32 v2, v38, s0
	ds_write_b16 v1, v2 offset:22400
	v_cvt_pk_bf16_f32 v2, v39, s0
	ds_write_b16 v1, v2 offset:22672
	v_cvt_pk_bf16_f32 v2, v32, s0
	ds_write_b16 v1, v2 offset:26112
	v_cvt_pk_bf16_f32 v2, v33, s0
	ds_write_b16 v1, v2 offset:26384
	v_cvt_pk_bf16_f32 v2, v34, s0
	ds_write_b16 v1, v2 offset:26656
	v_cvt_pk_bf16_f32 v2, v35, s0
	ds_write_b16 v1, v2 offset:26928
	v_cvt_pk_bf16_f32 v2, v28, s0
	ds_write_b16 v1, v2 offset:26144
	v_cvt_pk_bf16_f32 v2, v29, s0
	ds_write_b16 v1, v2 offset:26416
	v_cvt_pk_bf16_f32 v2, v30, s0
	ds_write_b16 v1, v2 offset:26688
	v_cvt_pk_bf16_f32 v2, v31, s0
	ds_write_b16 v1, v2 offset:26960
	v_cvt_pk_bf16_f32 v2, v24, s0
	ds_write_b16 v1, v2 offset:26176
	v_cvt_pk_bf16_f32 v2, v25, s0
	ds_write_b16 v1, v2 offset:26448
	v_cvt_pk_bf16_f32 v2, v26, s0
	ds_write_b16 v1, v2 offset:26720
	v_cvt_pk_bf16_f32 v2, v27, s0
	ds_write_b16 v1, v2 offset:26992
	v_cvt_pk_bf16_f32 v2, v20, s0
	ds_write_b16 v1, v2 offset:26208
	v_cvt_pk_bf16_f32 v2, v21, s0
	ds_write_b16 v1, v2 offset:26480
	v_cvt_pk_bf16_f32 v2, v22, s0
	ds_write_b16 v1, v2 offset:26752
	v_cvt_pk_bf16_f32 v2, v23, s0
	ds_write_b16 v1, v2 offset:27024
	v_cvt_pk_bf16_f32 v2, v16, s0
	ds_write_b16 v1, v2 offset:30464
	v_cvt_pk_bf16_f32 v2, v17, s0
	ds_write_b16 v1, v2 offset:30736
	v_cvt_pk_bf16_f32 v2, v18, s0
	ds_write_b16 v1, v2 offset:31008
	v_cvt_pk_bf16_f32 v2, v19, s0
	ds_write_b16 v1, v2 offset:31280
	v_cvt_pk_bf16_f32 v2, v12, s0
	ds_write_b16 v1, v2 offset:30496
	v_cvt_pk_bf16_f32 v2, v13, s0
	ds_write_b16 v1, v2 offset:30768
	v_cvt_pk_bf16_f32 v2, v14, s0
	ds_write_b16 v1, v2 offset:31040
	v_cvt_pk_bf16_f32 v2, v15, s0
	ds_write_b16 v1, v2 offset:31312
	v_cvt_pk_bf16_f32 v2, v8, s0
	ds_write_b16 v1, v2 offset:30528
	v_cvt_pk_bf16_f32 v2, v9, s0
	ds_write_b16 v1, v2 offset:30800
	v_cvt_pk_bf16_f32 v2, v10, s0
	ds_write_b16 v1, v2 offset:31072
	v_cvt_pk_bf16_f32 v2, v11, s0
	ds_write_b16 v1, v2 offset:31344
	v_cvt_pk_bf16_f32 v2, v4, s0
	ds_write_b16 v1, v2 offset:30560
	v_cvt_pk_bf16_f32 v2, v5, s0
	ds_write_b16 v1, v2 offset:30832
	v_cvt_pk_bf16_f32 v2, v6, s0
	v_cvt_pk_bf16_f32 v128, v128, s0
	ds_write_b16 v1, v2 offset:31104
	v_cvt_pk_bf16_f32 v2, v7, s0
	ds_write_b16 v1, v128
	ds_write_b16 v1, v2 offset:31376
	v_mov_b32_e32 v1, v178
	s_waitcnt lgkmcnt(0)
	s_barrier
; DEVI int get_tid() { int t = threadIdx.x; asm volatile("" : "+v"(t)); return t; }
; template <int BN>
; DEVI void tile_store256(const char* smem, bf* __restrict__ C, long ldc, long row0, int col0) {
;   constexpr int LDT = BN + 8;
;   constexpr int CPR = BN / 8;
;   const int tid = get_tid();
; #pragma unroll
;   for (int i = 0; i < CPR; ++i) {
;     const int q = tid + 256 * i;
;     const int r = q / CPR, c = q - r * CPR;
;     u32x4 v = *reinterpret_cast<const u32x4*>(smem + (r * LDT + c * 8) * 2);
;     *reinterpret_cast<u32x4*>(C + (row0 + r) * ldc + col0 + c * 8) = v;
;   }
; }
; DEVI void plain_tile256(const bf* A, int lda, const bf* Wt, int K, bf* C, int ldc, long row0, int n0, char* smem) {
;     ...
;   tile_store256<128>(smem, C, ldc, row0, n0);
;   __syncthreads();
	v_readlane_b32 s56, v251, 58
	v_ashrrev_i32_e32 v2, 31, v1
	v_lshrrev_b32_e32 v2, 28, v2
	v_add_u32_e32 v2, v1, v2
	v_ashrrev_i32_e32 v8, 4, v2
	s_lshl_b64 s[10:11], s[34:35], 1
	v_readlane_b32 s60, v251, 62
	v_lshlrev_b32_e32 v4, 7, v8
	v_lshlrev_b32_e32 v5, 3, v1
	v_ashrrev_i32_e32 v9, 31, v8
	v_readlane_b32 s61, v251, 63
	s_add_u32 s10, s60, s10
	v_mul_lo_u32 v2, v8, s83
	v_sub_u32_e32 v10, v5, v4
	v_lshl_add_u64 v[8:9], s[12:13], 0, v[8:9]
	s_addc_u32 s11, s61, s11
	v_add_lshl_u32 v2, v10, v2, 1
	v_lshlrev_b64 v[8:9], 11, v[8:9]
	ds_read_b128 v[4:7], v2
	v_lshl_add_u64 v[8:9], s[10:11], 0, v[8:9]
	v_ashrrev_i32_e32 v11, 31, v10
	v_add_u32_e32 v2, 0x100, v1
	v_lshl_add_u64 v[12:13], v[10:11], 1, v[8:9]
	v_ashrrev_i32_e32 v8, 31, v2
	v_lshrrev_b32_e32 v8, 28, v8
	v_add_u32_e32 v8, v2, v8
	v_ashrrev_i32_e32 v14, 4, v8
	v_lshlrev_b32_e32 v9, 7, v14
	v_lshlrev_b32_e32 v2, 3, v2
	v_mul_lo_u32 v8, v14, s83
	v_sub_u32_e32 v16, v2, v9
	v_add_lshl_u32 v2, v16, v8, 1
	ds_read_b128 v[8:11], v2
	v_ashrrev_i32_e32 v15, 31, v14
	s_waitcnt lgkmcnt(1)
	global_store_dwordx4 v[12:13], v[4:7], off
	v_ashrrev_i32_e32 v17, 31, v16
	v_add_u32_e32 v2, 0x200, v1
	v_lshl_add_u64 v[4:5], s[12:13], 0, v[14:15]
	v_lshlrev_b64 v[4:5], 11, v[4:5]
	v_lshl_add_u64 v[4:5], s[10:11], 0, v[4:5]
	v_lshl_add_u64 v[4:5], v[16:17], 1, v[4:5]
	s_waitcnt lgkmcnt(0)
	global_store_dwordx4 v[4:5], v[8:11], off
	v_ashrrev_i32_e32 v4, 31, v2
	v_lshrrev_b32_e32 v4, 28, v4
	v_add_u32_e32 v4, v2, v4
	v_ashrrev_i32_e32 v8, 4, v4
	v_lshlrev_b32_e32 v5, 7, v8
	v_lshlrev_b32_e32 v2, 3, v2
	v_ashrrev_i32_e32 v9, 31, v8
	v_mul_lo_u32 v4, v8, s83
	v_sub_u32_e32 v10, v2, v5
	v_lshl_add_u64 v[8:9], s[12:13], 0, v[8:9]
	v_add_lshl_u32 v2, v10, v4, 1
	v_lshlrev_b64 v[8:9], 11, v[8:9]
	ds_read_b128 v[4:7], v2
	v_lshl_add_u64 v[8:9], s[10:11], 0, v[8:9]
	v_ashrrev_i32_e32 v11, 31, v10
	v_add_u32_e32 v2, 0x300, v1
	v_lshl_add_u64 v[12:13], v[10:11], 1, v[8:9]
	v_ashrrev_i32_e32 v8, 31, v2
	v_lshrrev_b32_e32 v8, 28, v8
	v_add_u32_e32 v8, v2, v8
	v_ashrrev_i32_e32 v14, 4, v8
	v_lshlrev_b32_e32 v9, 7, v14
	v_lshlrev_b32_e32 v2, 3, v2
	v_mul_lo_u32 v8, v14, s83
	v_sub_u32_e32 v16, v2, v9
	v_add_lshl_u32 v2, v16, v8, 1
	ds_read_b128 v[8:11], v2
	v_ashrrev_i32_e32 v15, 31, v14
	s_waitcnt lgkmcnt(1)
	global_store_dwordx4 v[12:13], v[4:7], off
	v_ashrrev_i32_e32 v17, 31, v16
	v_add_u32_e32 v2, 0x400, v1
	v_lshl_add_u64 v[4:5], s[12:13], 0, v[14:15]
	v_lshlrev_b64 v[4:5], 11, v[4:5]
	v_lshl_add_u64 v[4:5], s[10:11], 0, v[4:5]
	v_lshl_add_u64 v[4:5], v[16:17], 1, v[4:5]
	s_waitcnt lgkmcnt(0)
	global_store_dwordx4 v[4:5], v[8:11], off
	v_ashrrev_i32_e32 v4, 31, v2
	v_lshrrev_b32_e32 v4, 28, v4
	v_add_u32_e32 v4, v2, v4
	v_ashrrev_i32_e32 v8, 4, v4
	v_lshlrev_b32_e32 v5, 7, v8
	v_lshlrev_b32_e32 v2, 3, v2
	v_ashrrev_i32_e32 v9, 31, v8
	v_mul_lo_u32 v4, v8, s83
	v_sub_u32_e32 v10, v2, v5
	v_lshl_add_u64 v[8:9], s[12:13], 0, v[8:9]
	v_add_lshl_u32 v2, v10, v4, 1
	v_lshlrev_b64 v[8:9], 11, v[8:9]
	ds_read_b128 v[4:7], v2
	v_lshl_add_u64 v[8:9], s[10:11], 0, v[8:9]
	v_ashrrev_i32_e32 v11, 31, v10
	v_add_u32_e32 v2, 0x500, v1
	v_lshl_add_u64 v[12:13], v[10:11], 1, v[8:9]
	v_ashrrev_i32_e32 v8, 31, v2
	v_lshrrev_b32_e32 v8, 28, v8
	v_add_u32_e32 v8, v2, v8
	v_ashrrev_i32_e32 v14, 4, v8
	v_lshlrev_b32_e32 v9, 7, v14
	v_lshlrev_b32_e32 v2, 3, v2
	v_mul_lo_u32 v8, v14, s83
	v_sub_u32_e32 v16, v2, v9
	v_add_lshl_u32 v2, v16, v8, 1
	ds_read_b128 v[8:11], v2
	v_ashrrev_i32_e32 v15, 31, v14
	s_waitcnt lgkmcnt(1)
	global_store_dwordx4 v[12:13], v[4:7], off
	v_ashrrev_i32_e32 v17, 31, v16
	v_add_u32_e32 v2, 0x600, v1
	v_lshl_add_u64 v[4:5], s[12:13], 0, v[14:15]
	v_lshlrev_b64 v[4:5], 11, v[4:5]
	v_lshl_add_u64 v[4:5], s[10:11], 0, v[4:5]
	v_lshl_add_u64 v[4:5], v[16:17], 1, v[4:5]
	s_waitcnt lgkmcnt(0)
	global_store_dwordx4 v[4:5], v[8:11], off
	v_ashrrev_i32_e32 v4, 31, v2
	v_lshrrev_b32_e32 v4, 28, v4
	v_add_u32_e32 v4, v2, v4
	v_ashrrev_i32_e32 v8, 4, v4
	v_lshlrev_b32_e32 v5, 7, v8
	v_lshlrev_b32_e32 v2, 3, v2
	v_ashrrev_i32_e32 v9, 31, v8
	v_mul_lo_u32 v4, v8, s83
	v_sub_u32_e32 v10, v2, v5
	v_lshl_add_u64 v[8:9], s[12:13], 0, v[8:9]
	v_add_lshl_u32 v2, v10, v4, 1
	v_lshlrev_b64 v[8:9], 11, v[8:9]
	ds_read_b128 v[4:7], v2
	v_lshl_add_u64 v[8:9], s[10:11], 0, v[8:9]
	v_ashrrev_i32_e32 v11, 31, v10
	v_add_u32_e32 v2, 0x700, v1
	v_lshl_add_u64 v[12:13], v[10:11], 1, v[8:9]
	v_ashrrev_i32_e32 v8, 31, v2
	v_lshrrev_b32_e32 v8, 28, v8
	v_add_u32_e32 v8, v2, v8
	v_ashrrev_i32_e32 v14, 4, v8
	v_lshlrev_b32_e32 v9, 7, v14
	v_lshlrev_b32_e32 v2, 3, v2
	v_mul_lo_u32 v8, v14, s83
	v_sub_u32_e32 v16, v2, v9
	v_add_lshl_u32 v2, v16, v8, 1
	ds_read_b128 v[8:11], v2
	v_ashrrev_i32_e32 v15, 31, v14
	s_waitcnt lgkmcnt(1)
	global_store_dwordx4 v[12:13], v[4:7], off
	v_ashrrev_i32_e32 v17, 31, v16
	v_add_u32_e32 v2, 0x800, v1
	v_lshl_add_u64 v[4:5], s[12:13], 0, v[14:15]
	v_lshlrev_b64 v[4:5], 11, v[4:5]
	v_lshl_add_u64 v[4:5], s[10:11], 0, v[4:5]
	v_lshl_add_u64 v[4:5], v[16:17], 1, v[4:5]
	s_waitcnt lgkmcnt(0)
; DEVI int get_tid() { int t = threadIdx.x; asm volatile("" : "+v"(t)); return t; }
; template <int BN>
; DEVI void tile_store256(const char* smem, bf* __restrict__ C, long ldc, long row0, int col0) {
;   constexpr int LDT = BN + 8;
;   constexpr int CPR = BN / 8;
;   const int tid = get_tid();
; #pragma unroll
;   for (int i = 0; i < CPR; ++i) {
;     const int q = tid + 256 * i;
;     const int r = q / CPR, c = q - r * CPR;
;     u32x4 v = *reinterpret_cast<const u32x4*>(smem + (r * LDT + c * 8) * 2);
;     *reinterpret_cast<u32x4*>(C + (row0 + r) * ldc + col0 + c * 8) = v;
;   }
; }
; DEVI void phase_gemm_plain128(const bf* A, int lda, const bf* Wt, int K, int N, bf* C, int ldc, char* smem) {
;     ...
;   for (int v = blockIdx.x; v < 128 * ntn; v += gridDim.x) {
;     int m2, nt;
;     lat_tile_map256(v, ntn, m2, nt);
;     plain_tile256(A, lda, Wt, K, C, ldc, lat_row0_256(m2), nt * 128, smem);
	global_store_dwordx4 v[4:5], v[8:11], off
	v_ashrrev_i32_e32 v4, 31, v2
	v_lshrrev_b32_e32 v4, 28, v4
	v_add_u32_e32 v4, v2, v4
	v_ashrrev_i32_e32 v8, 4, v4
	v_lshlrev_b32_e32 v5, 7, v8
	v_lshlrev_b32_e32 v2, 3, v2
	v_ashrrev_i32_e32 v9, 31, v8
	v_mul_lo_u32 v4, v8, s83
	v_sub_u32_e32 v10, v2, v5
	v_lshl_add_u64 v[8:9], s[12:13], 0, v[8:9]
	v_add_lshl_u32 v2, v10, v4, 1
	v_lshlrev_b64 v[8:9], 11, v[8:9]
	ds_read_b128 v[4:7], v2
	v_lshl_add_u64 v[8:9], s[10:11], 0, v[8:9]
	v_ashrrev_i32_e32 v11, 31, v10
	v_add_u32_e32 v2, 0x900, v1
	v_lshl_add_u64 v[12:13], v[10:11], 1, v[8:9]
	v_ashrrev_i32_e32 v8, 31, v2
	v_lshrrev_b32_e32 v8, 28, v8
	v_add_u32_e32 v8, v2, v8
	v_ashrrev_i32_e32 v14, 4, v8
	v_lshlrev_b32_e32 v9, 7, v14
	v_lshlrev_b32_e32 v2, 3, v2
	v_mul_lo_u32 v8, v14, s83
	v_sub_u32_e32 v16, v2, v9
	v_add_lshl_u32 v2, v16, v8, 1
	ds_read_b128 v[8:11], v2
	v_ashrrev_i32_e32 v15, 31, v14
	s_waitcnt lgkmcnt(1)
	global_store_dwordx4 v[12:13], v[4:7], off
	v_ashrrev_i32_e32 v17, 31, v16
	v_add_u32_e32 v2, 0xa00, v1
	v_lshl_add_u64 v[4:5], s[12:13], 0, v[14:15]
	v_lshlrev_b64 v[4:5], 11, v[4:5]
	v_lshl_add_u64 v[4:5], s[10:11], 0, v[4:5]
	v_lshl_add_u64 v[4:5], v[16:17], 1, v[4:5]
	s_waitcnt lgkmcnt(0)
	global_store_dwordx4 v[4:5], v[8:11], off
	v_ashrrev_i32_e32 v4, 31, v2
	v_lshrrev_b32_e32 v4, 28, v4
	v_add_u32_e32 v4, v2, v4
	v_ashrrev_i32_e32 v8, 4, v4
	v_lshlrev_b32_e32 v5, 7, v8
	v_lshlrev_b32_e32 v2, 3, v2
	v_ashrrev_i32_e32 v9, 31, v8
	v_mul_lo_u32 v4, v8, s83
	v_sub_u32_e32 v10, v2, v5
	v_lshl_add_u64 v[8:9], s[12:13], 0, v[8:9]
	v_add_lshl_u32 v2, v10, v4, 1
	v_lshlrev_b64 v[8:9], 11, v[8:9]
	ds_read_b128 v[4:7], v2
	v_lshl_add_u64 v[8:9], s[10:11], 0, v[8:9]
	v_ashrrev_i32_e32 v11, 31, v10
	v_add_u32_e32 v2, 0xb00, v1
	v_lshl_add_u64 v[12:13], v[10:11], 1, v[8:9]
	v_ashrrev_i32_e32 v8, 31, v2
	v_lshrrev_b32_e32 v8, 28, v8
	v_add_u32_e32 v8, v2, v8
	v_ashrrev_i32_e32 v14, 4, v8
	v_lshlrev_b32_e32 v9, 7, v14
	v_lshlrev_b32_e32 v2, 3, v2
	v_mul_lo_u32 v8, v14, s83
	v_sub_u32_e32 v16, v2, v9
	v_add_lshl_u32 v2, v16, v8, 1
	ds_read_b128 v[8:11], v2
	v_ashrrev_i32_e32 v15, 31, v14
	s_waitcnt lgkmcnt(1)
	global_store_dwordx4 v[12:13], v[4:7], off
	v_ashrrev_i32_e32 v17, 31, v16
	v_add_u32_e32 v2, 0xc00, v1
	v_lshl_add_u64 v[4:5], s[12:13], 0, v[14:15]
	v_lshlrev_b64 v[4:5], 11, v[4:5]
	v_lshl_add_u64 v[4:5], s[10:11], 0, v[4:5]
	v_lshl_add_u64 v[4:5], v[16:17], 1, v[4:5]
	s_waitcnt lgkmcnt(0)
	global_store_dwordx4 v[4:5], v[8:11], off
	v_ashrrev_i32_e32 v4, 31, v2
	v_lshrrev_b32_e32 v4, 28, v4
	v_add_u32_e32 v4, v2, v4
	v_ashrrev_i32_e32 v8, 4, v4
	v_lshlrev_b32_e32 v5, 7, v8
	v_lshlrev_b32_e32 v2, 3, v2
	v_ashrrev_i32_e32 v9, 31, v8
	v_mul_lo_u32 v4, v8, s83
	v_sub_u32_e32 v10, v2, v5
	v_lshl_add_u64 v[8:9], s[12:13], 0, v[8:9]
	v_add_lshl_u32 v2, v10, v4, 1
	v_lshlrev_b64 v[8:9], 11, v[8:9]
	ds_read_b128 v[4:7], v2
	v_lshl_add_u64 v[8:9], s[10:11], 0, v[8:9]
	v_ashrrev_i32_e32 v11, 31, v10
	v_add_u32_e32 v2, 0xd00, v1
	v_lshl_add_u64 v[12:13], v[10:11], 1, v[8:9]
	v_ashrrev_i32_e32 v8, 31, v2
	v_lshrrev_b32_e32 v8, 28, v8
	v_add_u32_e32 v8, v2, v8
	v_ashrrev_i32_e32 v14, 4, v8
	v_lshlrev_b32_e32 v9, 7, v14
	v_lshlrev_b32_e32 v2, 3, v2
	v_mul_lo_u32 v8, v14, s83
	v_sub_u32_e32 v16, v2, v9
	v_add_lshl_u32 v2, v16, v8, 1
	ds_read_b128 v[8:11], v2
	v_ashrrev_i32_e32 v15, 31, v14
	s_waitcnt lgkmcnt(1)
	global_store_dwordx4 v[12:13], v[4:7], off
	v_ashrrev_i32_e32 v17, 31, v16
	v_add_u32_e32 v2, 0xe00, v1
	v_lshl_add_u64 v[4:5], s[12:13], 0, v[14:15]
	v_lshlrev_b64 v[4:5], 11, v[4:5]
	v_lshl_add_u64 v[4:5], s[10:11], 0, v[4:5]
	v_lshl_add_u64 v[4:5], v[16:17], 1, v[4:5]
	s_waitcnt lgkmcnt(0)
	global_store_dwordx4 v[4:5], v[8:11], off
	v_ashrrev_i32_e32 v4, 31, v2
	v_lshrrev_b32_e32 v4, 28, v4
	v_add_u32_e32 v4, v2, v4
	v_ashrrev_i32_e32 v8, 4, v4
	v_lshlrev_b32_e32 v5, 7, v8
	v_lshlrev_b32_e32 v2, 3, v2
	v_mul_lo_u32 v4, v8, s83
	v_sub_u32_e32 v10, v2, v5
	v_add_lshl_u32 v2, v10, v4, 1
	v_add_u32_e32 v1, 0xf00, v1
	ds_read_b128 v[4:7], v2
	v_ashrrev_i32_e32 v9, 31, v8
	v_ashrrev_i32_e32 v2, 31, v1
	v_lshl_add_u64 v[8:9], s[12:13], 0, v[8:9]
	v_lshrrev_b32_e32 v2, 28, v2
	v_lshlrev_b64 v[8:9], 11, v[8:9]
	v_add_u32_e32 v2, v1, v2
	v_lshl_add_u64 v[8:9], s[10:11], 0, v[8:9]
	v_ashrrev_i32_e32 v11, 31, v10
	v_ashrrev_i32_e32 v14, 4, v2
	v_lshl_add_u64 v[12:13], v[10:11], 1, v[8:9]
	v_lshlrev_b32_e32 v8, 7, v14
	v_lshlrev_b32_e32 v1, 3, v1
	v_mul_lo_u32 v2, v14, s83
	v_sub_u32_e32 v16, v1, v8
	v_add_lshl_u32 v1, v16, v2, 1
	v_ashrrev_i32_e32 v15, 31, v14
	ds_read_b128 v[8:11], v1
	s_waitcnt lgkmcnt(1)
	global_store_dwordx4 v[12:13], v[4:7], off
	v_ashrrev_i32_e32 v17, 31, v16
	v_readlane_b32 s58, v251, 60
	v_lshl_add_u64 v[4:5], s[12:13], 0, v[14:15]
	v_lshlrev_b64 v[4:5], 11, v[4:5]
	v_lshl_add_u64 v[4:5], s[10:11], 0, v[4:5]
	v_readlane_b32 s10, v252, 59
	s_add_i32 s2, s2, s10
	v_readlane_b32 s59, v251, 61
	v_lshl_add_u64 v[4:5], v[16:17], 1, v[4:5]
	s_cmpk_gt_i32 s2, 0x3ff
	s_movk_i32 s27, 0x100
	v_readlane_b32 s57, v251, 59
	v_readlane_b32 s62, v252, 0
	v_readlane_b32 s63, v252, 1
	v_readlane_b32 s64, v252, 2
	v_readlane_b32 s65, v252, 3
	v_readlane_b32 s66, v252, 4
	v_readlane_b32 s67, v252, 5
	v_readlane_b32 s68, v252, 6
	v_readlane_b32 s69, v252, 7
	v_readlane_b32 s70, v252, 8
	v_readlane_b32 s71, v252, 9
	s_waitcnt lgkmcnt(0)
	global_store_dwordx4 v[4:5], v[8:11], off
	s_barrier
	v_readlane_b32 s11, v252, 60
	s_cbranch_scc0 .LBB0_205

; DEVI f32x4 mfma16(bf16x8 a, bf16x8 b, f32x4 c) { return __builtin_amdgcn_mfma_f32_16x16x32_bf16(a, b, c, 0, 0, 0); }
; DEVI void gemm_core3(f32x4 (&acc)[8][4], const bf* __restrict__ A, int lda, const bf* __restrict__ Bt, int ldb, int K, char* smem) {
;     ...
;   for (int kt = 0; kt < nk; ++kt) {
;     const int k1 = min((kt + 1) * 32, klast);
;     const int sn = ((kt + 1) & 1) * STG;
;     const int so = (kt & 1) * STG;
;     bf16x8 bfr[4], af[8];
; #pragma unroll
;     for (int n = 0; n < 4; ++n) bfr[n] = *reinterpret_cast<const bf16x8*>(bbase + so + n * 16 * 64);
; #pragma unroll
;     for (int m = 0; m < 8; ++m) af[m] = *reinterpret_cast<const bf16x8*>(abase + so + m * 16 * 64);
; #pragma unroll
;     for (int i = 0; i < 4; ++i) glds16(Ap + i * sa + k1, dbase + sn + i * 4096);
; #pragma unroll
;     for (int i = 0; i < 2; ++i) glds16(Bp + i * sb + k1, dbase + sn + ASZ + i * 4096);
;     __builtin_amdgcn_s_setprio(1);
; #pragma unroll
;     for (int m = 0; m < 8; ++m)
; #pragma unroll
;       for (int n = 0; n < 4; ++n) acc[m][n] = mfma16(af[m], bfr[n], acc[m][n]);
;     __builtin_amdgcn_s_setprio(0);
;     __syncthreads();
;   }
.Lg3_loop_904:
	v_add_u32_e32 v216, s10, v146
	v_add_u32_e32 v217, s10, v2
	ds_read_b128 v[148:151], v217 offset:16384
	ds_read_b128 v[166:169], v216
	ds_read_b128 v[154:157], v217 offset:17408
	ds_read_b128 v[158:161], v217 offset:18432
	ds_read_b128 v[162:165], v217 offset:19456
	ds_read_b128 v[170:173], v216 offset:1024
	ds_read_b128 v[174:177], v216 offset:2048
	ds_read_b128 v[192:195], v216 offset:3072
	ds_read_b128 v[196:199], v216 offset:4096
	ds_read_b128 v[204:207], v216 offset:5120
	ds_read_b128 v[208:211], v216 offset:6144
	ds_read_b128 v[212:215], v216 offset:7168
	s_setprio 1
	s_waitcnt lgkmcnt(10)
	v_mfma_f32_16x16x32_bf16 v[128:131], v[166:169], v[148:151], v[128:131]
	s_waitcnt lgkmcnt(9)
	v_mfma_f32_16x16x32_bf16 v[124:127], v[166:169], v[154:157], v[124:127]
	s_waitcnt lgkmcnt(8)
	v_mfma_f32_16x16x32_bf16 v[120:123], v[166:169], v[158:161], v[120:123]
	s_waitcnt lgkmcnt(7)
	v_mfma_f32_16x16x32_bf16 v[116:119], v[166:169], v[162:165], v[116:119]
	s_waitcnt lgkmcnt(6)
	v_mfma_f32_16x16x32_bf16 v[112:115], v[170:173], v[148:151], v[112:115]
	v_mfma_f32_16x16x32_bf16 v[108:111], v[170:173], v[154:157], v[108:111]
	v_mfma_f32_16x16x32_bf16 v[104:107], v[170:173], v[158:161], v[104:107]
	v_mfma_f32_16x16x32_bf16 v[100:103], v[170:173], v[162:165], v[100:103]
	s_waitcnt lgkmcnt(5)
	v_mfma_f32_16x16x32_bf16 v[96:99], v[174:177], v[148:151], v[96:99]
	v_mfma_f32_16x16x32_bf16 v[92:95], v[174:177], v[154:157], v[92:95]
	v_mfma_f32_16x16x32_bf16 v[88:91], v[174:177], v[158:161], v[88:91]
	v_mfma_f32_16x16x32_bf16 v[84:87], v[174:177], v[162:165], v[84:87]
	s_waitcnt lgkmcnt(4)
	v_mfma_f32_16x16x32_bf16 v[80:83], v[192:195], v[148:151], v[80:83]
	v_mfma_f32_16x16x32_bf16 v[76:79], v[192:195], v[154:157], v[76:79]
	v_mfma_f32_16x16x32_bf16 v[72:75], v[192:195], v[158:161], v[72:75]
	v_mfma_f32_16x16x32_bf16 v[68:71], v[192:195], v[162:165], v[68:71]
	s_waitcnt lgkmcnt(3)
	v_mfma_f32_16x16x32_bf16 v[64:67], v[196:199], v[148:151], v[64:67]
	v_mfma_f32_16x16x32_bf16 v[60:63], v[196:199], v[154:157], v[60:63]
	v_mfma_f32_16x16x32_bf16 v[56:59], v[196:199], v[158:161], v[56:59]
	v_mfma_f32_16x16x32_bf16 v[52:55], v[196:199], v[162:165], v[52:55]
	s_waitcnt lgkmcnt(2)
	v_mfma_f32_16x16x32_bf16 v[48:51], v[204:207], v[148:151], v[48:51]
	v_mfma_f32_16x16x32_bf16 v[44:47], v[204:207], v[154:157], v[44:47]
	v_mfma_f32_16x16x32_bf16 v[40:43], v[204:207], v[158:161], v[40:43]
	v_mfma_f32_16x16x32_bf16 v[36:39], v[204:207], v[162:165], v[36:39]
	s_waitcnt lgkmcnt(1)
	v_mfma_f32_16x16x32_bf16 v[32:35], v[208:211], v[148:151], v[32:35]
	v_mfma_f32_16x16x32_bf16 v[28:31], v[208:211], v[154:157], v[28:31]
	v_mfma_f32_16x16x32_bf16 v[24:27], v[208:211], v[158:161], v[24:27]
	v_mfma_f32_16x16x32_bf16 v[20:23], v[208:211], v[162:165], v[20:23]
	s_waitcnt lgkmcnt(0)
	v_mfma_f32_16x16x32_bf16 v[16:19], v[212:215], v[148:151], v[16:19]
	v_mfma_f32_16x16x32_bf16 v[12:15], v[212:215], v[154:157], v[12:15]
	v_mfma_f32_16x16x32_bf16 v[8:11], v[212:215], v[158:161], v[8:11]
	v_mfma_f32_16x16x32_bf16 v[4:7], v[212:215], v[162:165], v[4:7]
	s_setprio 0
	s_add_i32 s10, s10, 0x6000
	s_cmp_lg_u32 s10, 0x12000
	s_cselect_b32 s10, s10, 0
	s_waitcnt vmcnt(0)
	s_barrier
	v_add_u32_e32 v216, s10, v146
	v_add_u32_e32 v217, s10, v2
	ds_read_b128 v[148:151], v217 offset:16384
	ds_read_b128 v[166:169], v216
	ds_read_b128 v[154:157], v217 offset:17408
	ds_read_b128 v[158:161], v217 offset:18432
	ds_read_b128 v[162:165], v217 offset:19456
	ds_read_b128 v[170:173], v216 offset:1024
	ds_read_b128 v[174:177], v216 offset:2048
	ds_read_b128 v[192:195], v216 offset:3072
	ds_read_b128 v[196:199], v216 offset:4096
	ds_read_b128 v[204:207], v216 offset:5120
	ds_read_b128 v[208:211], v216 offset:6144
	ds_read_b128 v[212:215], v216 offset:7168
	v_readfirstlane_b32 s17, v140
	s_add_i32 s96, s11, 0x6000
	s_cmp_lg_u32 s96, 0x12000
	s_cselect_b32 s96, s96, 0
	s_add_i32 s96, s96, s17
	s_add_i32 s17, s17, s11
	s_setprio 2
	s_waitcnt lgkmcnt(10)
	s_mov_b32 m0, s17
	s_add_i32 s17, s17, 0x1000
	v_mfma_f32_16x16x32_bf16 v[128:131], v[166:169], v[148:151], v[128:131]
	s_waitcnt lgkmcnt(9)
	v_mfma_f32_16x16x32_bf16 v[124:127], v[166:169], v[154:157], v[124:127]
	global_load_lds_dwordx4 v[218:219], off
	v_lshl_add_u64 v[218:219], v[218:219], 0, 64
	s_waitcnt lgkmcnt(8)
	s_mov_b32 m0, s96
	s_add_i32 s96, s96, 0x1000
	v_mfma_f32_16x16x32_bf16 v[120:123], v[166:169], v[158:161], v[120:123]
	s_waitcnt lgkmcnt(7)
	v_mfma_f32_16x16x32_bf16 v[116:119], v[166:169], v[162:165], v[116:119]
	global_load_lds_dwordx4 v[218:219], off
	v_lshl_add_u64 v[218:219], v[218:219], 0, 64
	s_waitcnt lgkmcnt(6)
	v_mfma_f32_16x16x32_bf16 v[112:115], v[170:173], v[148:151], v[112:115]
	s_mov_b32 m0, s17
	s_add_i32 s17, s17, 0x1000
	v_mfma_f32_16x16x32_bf16 v[108:111], v[170:173], v[154:157], v[108:111]
	v_mfma_f32_16x16x32_bf16 v[104:107], v[170:173], v[158:161], v[104:107]
	global_load_lds_dwordx4 v[220:221], off
	v_lshl_add_u64 v[220:221], v[220:221], 0, 64
	s_mov_b32 m0, s96
	s_add_i32 s96, s96, 0x1000
	v_mfma_f32_16x16x32_bf16 v[100:103], v[170:173], v[162:165], v[100:103]
	s_waitcnt lgkmcnt(5)
	v_mfma_f32_16x16x32_bf16 v[96:99], v[174:177], v[148:151], v[96:99]
	global_load_lds_dwordx4 v[220:221], off
	v_lshl_add_u64 v[220:221], v[220:221], 0, 64
	v_mfma_f32_16x16x32_bf16 v[92:95], v[174:177], v[154:157], v[92:95]
	s_mov_b32 m0, s17
	s_add_i32 s17, s17, 0x1000
	v_mfma_f32_16x16x32_bf16 v[88:91], v[174:177], v[158:161], v[88:91]
	v_mfma_f32_16x16x32_bf16 v[84:87], v[174:177], v[162:165], v[84:87]
	global_load_lds_dwordx4 v[222:223], off
	v_lshl_add_u64 v[222:223], v[222:223], 0, 64
	s_waitcnt lgkmcnt(4)
; DEVI f32x4 mfma16(bf16x8 a, bf16x8 b, f32x4 c) { return __builtin_amdgcn_mfma_f32_16x16x32_bf16(a, b, c, 0, 0, 0); }
; DEVI void gemm_core3(f32x4 (&acc)[8][4], const bf* __restrict__ A, int lda, const bf* __restrict__ Bt, int ldb, int K, char* smem) {
;     ...
;   for (int kt = 0; kt < nk; ++kt) {
;     const int k1 = min((kt + 1) * 32, klast);
;     const int sn = ((kt + 1) & 1) * STG;
;     const int so = (kt & 1) * STG;
;     bf16x8 bfr[4], af[8];
; #pragma unroll
;     for (int n = 0; n < 4; ++n) bfr[n] = *reinterpret_cast<const bf16x8*>(bbase + so + n * 16 * 64);
; #pragma unroll
;     for (int m = 0; m < 8; ++m) af[m] = *reinterpret_cast<const bf16x8*>(abase + so + m * 16 * 64);
; #pragma unroll
;     for (int i = 0; i < 4; ++i) glds16(Ap + i * sa + k1, dbase + sn + i * 4096);
; #pragma unroll
;     for (int i = 0; i < 2; ++i) glds16(Bp + i * sb + k1, dbase + sn + ASZ + i * 4096);
;     __builtin_amdgcn_s_setprio(1);
; #pragma unroll
;     for (int m = 0; m < 8; ++m)
; #pragma unroll
;       for (int n = 0; n < 4; ++n) acc[m][n] = mfma16(af[m], bfr[n], acc[m][n]);
;     __builtin_amdgcn_s_setprio(0);
;     __syncthreads();
;   }
	s_mov_b32 m0, s96
	s_add_i32 s96, s96, 0x1000
	v_mfma_f32_16x16x32_bf16 v[80:83], v[192:195], v[148:151], v[80:83]
	v_mfma_f32_16x16x32_bf16 v[76:79], v[192:195], v[154:157], v[76:79]
	global_load_lds_dwordx4 v[222:223], off
	v_lshl_add_u64 v[222:223], v[222:223], 0, 64
	v_mfma_f32_16x16x32_bf16 v[72:75], v[192:195], v[158:161], v[72:75]
	s_mov_b32 m0, s17
	s_add_i32 s17, s17, 0x1000
	v_mfma_f32_16x16x32_bf16 v[68:71], v[192:195], v[162:165], v[68:71]
	s_waitcnt lgkmcnt(3)
	v_mfma_f32_16x16x32_bf16 v[64:67], v[196:199], v[148:151], v[64:67]
	global_load_lds_dwordx4 v[224:225], off
	v_lshl_add_u64 v[224:225], v[224:225], 0, 64
	s_mov_b32 m0, s96
	s_add_i32 s96, s96, 0x1000
	v_mfma_f32_16x16x32_bf16 v[60:63], v[196:199], v[154:157], v[60:63]
	v_mfma_f32_16x16x32_bf16 v[56:59], v[196:199], v[158:161], v[56:59]
	global_load_lds_dwordx4 v[224:225], off
	v_lshl_add_u64 v[224:225], v[224:225], 0, 64
	v_mfma_f32_16x16x32_bf16 v[52:55], v[196:199], v[162:165], v[52:55]
	s_waitcnt lgkmcnt(2)
	s_mov_b32 m0, s17
	s_add_i32 s17, s17, 0x1000
	v_mfma_f32_16x16x32_bf16 v[48:51], v[204:207], v[148:151], v[48:51]
	v_mfma_f32_16x16x32_bf16 v[44:47], v[204:207], v[154:157], v[44:47]
	global_load_lds_dwordx4 v[226:227], off
	v_lshl_add_u64 v[226:227], v[226:227], 0, 64
	s_mov_b32 m0, s96
	s_add_i32 s96, s96, 0x1000
	v_mfma_f32_16x16x32_bf16 v[40:43], v[204:207], v[158:161], v[40:43]
	v_mfma_f32_16x16x32_bf16 v[36:39], v[204:207], v[162:165], v[36:39]
	global_load_lds_dwordx4 v[226:227], off
	v_lshl_add_u64 v[226:227], v[226:227], 0, 64
	s_waitcnt lgkmcnt(1)
	v_mfma_f32_16x16x32_bf16 v[32:35], v[208:211], v[148:151], v[32:35]
	s_mov_b32 m0, s17
	s_add_i32 s17, s17, 0x1000
	v_mfma_f32_16x16x32_bf16 v[28:31], v[208:211], v[154:157], v[28:31]
	v_mfma_f32_16x16x32_bf16 v[24:27], v[208:211], v[158:161], v[24:27]
	global_load_lds_dwordx4 v[228:229], off
	v_lshl_add_u64 v[228:229], v[228:229], 0, 64
	s_mov_b32 m0, s96
	s_add_i32 s96, s96, 0x1000
	v_mfma_f32_16x16x32_bf16 v[20:23], v[208:211], v[162:165], v[20:23]
	s_waitcnt lgkmcnt(0)
	v_mfma_f32_16x16x32_bf16 v[16:19], v[212:215], v[148:151], v[16:19]
	global_load_lds_dwordx4 v[228:229], off
	v_lshl_add_u64 v[228:229], v[228:229], 0, 64
	v_mfma_f32_16x16x32_bf16 v[12:15], v[212:215], v[154:157], v[12:15]
	v_mfma_f32_16x16x32_bf16 v[8:11], v[212:215], v[158:161], v[8:11]
	v_mfma_f32_16x16x32_bf16 v[4:7], v[212:215], v[162:165], v[4:7]
	s_setprio 0
	s_add_i32 s10, s10, 0x6000
	s_cmp_lg_u32 s10, 0x12000
	s_cselect_b32 s10, s10, 0
	s_sub_i32 s11, s11, 0x6000
	s_cmp_lt_i32 s11, 0
	s_cselect_b32 s11, 0xc000, s11
	s_add_i32 s3, s3, 1
	s_cmp_lt_i32 s3, 15
	s_waitcnt vmcnt(1)
	s_barrier
	s_cbranch_scc1 .Lg3_loop_904
	v_add_u32_e32 v216, s10, v146
	v_add_u32_e32 v217, s10, v2
	ds_read_b128 v[148:151], v217 offset:16384
	ds_read_b128 v[166:169], v216
	ds_read_b128 v[154:157], v217 offset:17408
	ds_read_b128 v[158:161], v217 offset:18432
	ds_read_b128 v[162:165], v217 offset:19456
	ds_read_b128 v[170:173], v216 offset:1024
	ds_read_b128 v[174:177], v216 offset:2048
	ds_read_b128 v[192:195], v216 offset:3072
	ds_read_b128 v[196:199], v216 offset:4096
	ds_read_b128 v[204:207], v216 offset:5120
	ds_read_b128 v[208:211], v216 offset:6144
	ds_read_b128 v[212:215], v216 offset:7168
	s_setprio 1
	s_waitcnt lgkmcnt(10)
	v_mfma_f32_16x16x32_bf16 v[128:131], v[166:169], v[148:151], v[128:131]
	s_waitcnt lgkmcnt(9)
	v_mfma_f32_16x16x32_bf16 v[124:127], v[166:169], v[154:157], v[124:127]
	s_waitcnt lgkmcnt(8)
	v_mfma_f32_16x16x32_bf16 v[120:123], v[166:169], v[158:161], v[120:123]
	s_waitcnt lgkmcnt(7)
	v_mfma_f32_16x16x32_bf16 v[116:119], v[166:169], v[162:165], v[116:119]
	s_waitcnt lgkmcnt(6)
	v_mfma_f32_16x16x32_bf16 v[112:115], v[170:173], v[148:151], v[112:115]
	v_mfma_f32_16x16x32_bf16 v[108:111], v[170:173], v[154:157], v[108:111]
	v_mfma_f32_16x16x32_bf16 v[104:107], v[170:173], v[158:161], v[104:107]
	v_mfma_f32_16x16x32_bf16 v[100:103], v[170:173], v[162:165], v[100:103]
	s_waitcnt lgkmcnt(5)
	v_mfma_f32_16x16x32_bf16 v[96:99], v[174:177], v[148:151], v[96:99]
	v_mfma_f32_16x16x32_bf16 v[92:95], v[174:177], v[154:157], v[92:95]
	v_mfma_f32_16x16x32_bf16 v[88:91], v[174:177], v[158:161], v[88:91]
	v_mfma_f32_16x16x32_bf16 v[84:87], v[174:177], v[162:165], v[84:87]
	s_waitcnt lgkmcnt(4)
	v_mfma_f32_16x16x32_bf16 v[80:83], v[192:195], v[148:151], v[80:83]
	v_mfma_f32_16x16x32_bf16 v[76:79], v[192:195], v[154:157], v[76:79]
	v_mfma_f32_16x16x32_bf16 v[72:75], v[192:195], v[158:161], v[72:75]
	v_mfma_f32_16x16x32_bf16 v[68:71], v[192:195], v[162:165], v[68:71]
	s_waitcnt lgkmcnt(3)
	v_mfma_f32_16x16x32_bf16 v[64:67], v[196:199], v[148:151], v[64:67]
	v_mfma_f32_16x16x32_bf16 v[60:63], v[196:199], v[154:157], v[60:63]
	v_mfma_f32_16x16x32_bf16 v[56:59], v[196:199], v[158:161], v[56:59]
	v_mfma_f32_16x16x32_bf16 v[52:55], v[196:199], v[162:165], v[52:55]
	s_waitcnt lgkmcnt(2)
	v_mfma_f32_16x16x32_bf16 v[48:51], v[204:207], v[148:151], v[48:51]
	v_mfma_f32_16x16x32_bf16 v[44:47], v[204:207], v[154:157], v[44:47]
	v_mfma_f32_16x16x32_bf16 v[40:43], v[204:207], v[158:161], v[40:43]
	v_mfma_f32_16x16x32_bf16 v[36:39], v[204:207], v[162:165], v[36:39]
	s_waitcnt lgkmcnt(1)
	v_mfma_f32_16x16x32_bf16 v[32:35], v[208:211], v[148:151], v[32:35]
	v_mfma_f32_16x16x32_bf16 v[28:31], v[208:211], v[154:157], v[28:31]
	v_mfma_f32_16x16x32_bf16 v[24:27], v[208:211], v[158:161], v[24:27]
	v_mfma_f32_16x16x32_bf16 v[20:23], v[208:211], v[162:165], v[20:23]
	s_waitcnt lgkmcnt(0)
	v_mfma_f32_16x16x32_bf16 v[16:19], v[212:215], v[148:151], v[16:19]
	v_mfma_f32_16x16x32_bf16 v[12:15], v[212:215], v[154:157], v[12:15]
	v_mfma_f32_16x16x32_bf16 v[8:11], v[212:215], v[158:161], v[8:11]
	v_mfma_f32_16x16x32_bf16 v[4:7], v[212:215], v[162:165], v[4:7]
	s_setprio 0
	s_add_i32 s10, s10, 0x6000
	s_cmp_lg_u32 s10, 0x12000
	s_cselect_b32 s10, s10, 0
	s_waitcnt vmcnt(0)
	s_barrier
; DEVI f32x4 mfma16(bf16x8 a, bf16x8 b, f32x4 c) { return __builtin_amdgcn_mfma_f32_16x16x32_bf16(a, b, c, 0, 0, 0); }
; DEVI void gemm_core3(f32x4 (&acc)[8][4], const bf* __restrict__ A, int lda, const bf* __restrict__ Bt, int ldb, int K, char* smem) {
;     ...
; #pragma unroll
;     for (int n = 0; n < 4; ++n) bfr[n] = *reinterpret_cast<const bf16x8*>(bbase + so + n * 16 * 64);
; #pragma unroll
;     for (int m = 0; m < 8; ++m) af[m] = *reinterpret_cast<const bf16x8*>(abase + so + m * 16 * 64);
; #pragma unroll
;     for (int i = 0; i < 4; ++i) glds16(Ap + i * sa + k1, dbase + sn + i * 4096);
; #pragma unroll
;     for (int i = 0; i < 2; ++i) glds16(Bp + i * sb + k1, dbase + sn + ASZ + i * 4096);
;     __builtin_amdgcn_s_setprio(1);
; #pragma unroll
;     for (int m = 0; m < 8; ++m)
; #pragma unroll
;       for (int n = 0; n < 4; ++n) acc[m][n] = mfma16(af[m], bfr[n], acc[m][n]);
;     __builtin_amdgcn_s_setprio(0);
;     __syncthreads();
;   }
; DEVI void plain_tile256(const bf* A, int lda, const bf* Wt, int K, bf* C, int ldc, long row0, int n0, char* smem) {
;     ...
;   bf* tl = reinterpret_cast<bf*>(smem);
; #pragma unroll
;   for (int m = 0; m < 8; ++m)
; #pragma unroll
;     for (int n = 0; n < 4; ++n) {
;       const int cl = wc * 64 + n * 16 + l15;
; #pragma unroll
;       for (int j = 0; j < 4; ++j) tl[(wr * 128 + m * 16 + quad * 4 + j) * 136 + cl] = f2bf(acc[m][n][j]);
;     }
;   __syncthreads();
	v_add_u32_e32 v216, s10, v146
	v_add_u32_e32 v217, s10, v2
	ds_read_b128 v[148:151], v217 offset:16384
	ds_read_b128 v[166:169], v216
	ds_read_b128 v[154:157], v217 offset:17408
	ds_read_b128 v[158:161], v217 offset:18432
	ds_read_b128 v[162:165], v217 offset:19456
	ds_read_b128 v[170:173], v216 offset:1024
	ds_read_b128 v[174:177], v216 offset:2048
	ds_read_b128 v[192:195], v216 offset:3072
	ds_read_b128 v[196:199], v216 offset:4096
	ds_read_b128 v[204:207], v216 offset:5120
	ds_read_b128 v[208:211], v216 offset:6144
	ds_read_b128 v[212:215], v216 offset:7168
	s_setprio 1
	s_waitcnt lgkmcnt(10)
	v_mfma_f32_16x16x32_bf16 v[128:131], v[166:169], v[148:151], v[128:131]
	s_waitcnt lgkmcnt(9)
	v_mfma_f32_16x16x32_bf16 v[124:127], v[166:169], v[154:157], v[124:127]
	s_waitcnt lgkmcnt(8)
	v_mfma_f32_16x16x32_bf16 v[120:123], v[166:169], v[158:161], v[120:123]
	s_waitcnt lgkmcnt(7)
	v_mfma_f32_16x16x32_bf16 v[116:119], v[166:169], v[162:165], v[116:119]
	s_waitcnt lgkmcnt(6)
	v_mfma_f32_16x16x32_bf16 v[112:115], v[170:173], v[148:151], v[112:115]
	v_mfma_f32_16x16x32_bf16 v[108:111], v[170:173], v[154:157], v[108:111]
	v_mfma_f32_16x16x32_bf16 v[104:107], v[170:173], v[158:161], v[104:107]
	v_mfma_f32_16x16x32_bf16 v[100:103], v[170:173], v[162:165], v[100:103]
	s_waitcnt lgkmcnt(5)
	v_mfma_f32_16x16x32_bf16 v[96:99], v[174:177], v[148:151], v[96:99]
	v_mfma_f32_16x16x32_bf16 v[92:95], v[174:177], v[154:157], v[92:95]
	v_mfma_f32_16x16x32_bf16 v[88:91], v[174:177], v[158:161], v[88:91]
	v_mfma_f32_16x16x32_bf16 v[84:87], v[174:177], v[162:165], v[84:87]
	s_waitcnt lgkmcnt(4)
	v_mfma_f32_16x16x32_bf16 v[80:83], v[192:195], v[148:151], v[80:83]
	v_mfma_f32_16x16x32_bf16 v[76:79], v[192:195], v[154:157], v[76:79]
	v_mfma_f32_16x16x32_bf16 v[72:75], v[192:195], v[158:161], v[72:75]
	v_mfma_f32_16x16x32_bf16 v[68:71], v[192:195], v[162:165], v[68:71]
	s_waitcnt lgkmcnt(3)
	v_mfma_f32_16x16x32_bf16 v[64:67], v[196:199], v[148:151], v[64:67]
	v_mfma_f32_16x16x32_bf16 v[60:63], v[196:199], v[154:157], v[60:63]
	v_mfma_f32_16x16x32_bf16 v[56:59], v[196:199], v[158:161], v[56:59]
	v_mfma_f32_16x16x32_bf16 v[52:55], v[196:199], v[162:165], v[52:55]
	s_waitcnt lgkmcnt(2)
	v_mfma_f32_16x16x32_bf16 v[48:51], v[204:207], v[148:151], v[48:51]
	v_mfma_f32_16x16x32_bf16 v[44:47], v[204:207], v[154:157], v[44:47]
	v_mfma_f32_16x16x32_bf16 v[40:43], v[204:207], v[158:161], v[40:43]
	v_mfma_f32_16x16x32_bf16 v[36:39], v[204:207], v[162:165], v[36:39]
	s_waitcnt lgkmcnt(1)
	v_mfma_f32_16x16x32_bf16 v[32:35], v[208:211], v[148:151], v[32:35]
	v_mfma_f32_16x16x32_bf16 v[28:31], v[208:211], v[154:157], v[28:31]
	v_mfma_f32_16x16x32_bf16 v[24:27], v[208:211], v[158:161], v[24:27]
	v_mfma_f32_16x16x32_bf16 v[20:23], v[208:211], v[162:165], v[20:23]
	s_waitcnt lgkmcnt(0)
	v_mfma_f32_16x16x32_bf16 v[16:19], v[212:215], v[148:151], v[16:19]
	v_mfma_f32_16x16x32_bf16 v[12:15], v[212:215], v[154:157], v[12:15]
	v_mfma_f32_16x16x32_bf16 v[8:11], v[212:215], v[158:161], v[8:11]
	v_mfma_f32_16x16x32_bf16 v[4:7], v[212:215], v[162:165], v[4:7]
	s_setprio 0
	s_add_i32 s10, s10, 0x6000
	s_cmp_lg_u32 s10, 0x12000
	s_cselect_b32 s10, s10, 0
	s_waitcnt vmcnt(0)
	s_barrier
	s_setprio 3
	v_and_b32_e32 v2, 0x4f, v1
	v_and_b32_e32 v132, 0xfffff80, v1
	v_lshrrev_b32_e32 v1, 2, v1
	v_and_or_b32 v1, v1, 12, v132
	v_mul_lo_u32 v1, v1, s16
	v_lshl_add_u32 v1, v2, 1, v1
	v_cvt_pk_bf16_f32 v2, v129, s0
	ds_write_b16 v1, v2 offset:272
	v_cvt_pk_bf16_f32 v2, v130, s0
	ds_write_b16 v1, v2 offset:544
	v_cvt_pk_bf16_f32 v2, v131, s0
	ds_write_b16 v1, v2 offset:816
	v_cvt_pk_bf16_f32 v2, v124, s0
	ds_write_b16 v1, v2 offset:32
	v_cvt_pk_bf16_f32 v2, v125, s0
	ds_write_b16 v1, v2 offset:304
	v_cvt_pk_bf16_f32 v2, v126, s0
	ds_write_b16 v1, v2 offset:576
	v_cvt_pk_bf16_f32 v2, v127, s0
	ds_write_b16 v1, v2 offset:848
	v_cvt_pk_bf16_f32 v2, v120, s0
	ds_write_b16 v1, v2 offset:64
	v_cvt_pk_bf16_f32 v2, v121, s0
	ds_write_b16 v1, v2 offset:336
	v_cvt_pk_bf16_f32 v2, v122, s0
	ds_write_b16 v1, v2 offset:608
	v_cvt_pk_bf16_f32 v2, v123, s0
	ds_write_b16 v1, v2 offset:880
	v_cvt_pk_bf16_f32 v2, v116, s0
	ds_write_b16 v1, v2 offset:96
	v_cvt_pk_bf16_f32 v2, v117, s0
	ds_write_b16 v1, v2 offset:368
	v_cvt_pk_bf16_f32 v2, v118, s0
	ds_write_b16 v1, v2 offset:640
	v_cvt_pk_bf16_f32 v2, v119, s0
	ds_write_b16 v1, v2 offset:912
	v_cvt_pk_bf16_f32 v2, v112, s0
	ds_write_b16 v1, v2 offset:4352
	v_cvt_pk_bf16_f32 v2, v113, s0
	ds_write_b16 v1, v2 offset:4624
	v_cvt_pk_bf16_f32 v2, v114, s0
	ds_write_b16 v1, v2 offset:4896
	v_cvt_pk_bf16_f32 v2, v115, s0
	ds_write_b16 v1, v2 offset:5168
	v_cvt_pk_bf16_f32 v2, v108, s0
	ds_write_b16 v1, v2 offset:4384
	v_cvt_pk_bf16_f32 v2, v109, s0
	ds_write_b16 v1, v2 offset:4656
	v_cvt_pk_bf16_f32 v2, v110, s0
	ds_write_b16 v1, v2 offset:4928
	v_cvt_pk_bf16_f32 v2, v111, s0
	ds_write_b16 v1, v2 offset:5200
	v_cvt_pk_bf16_f32 v2, v104, s0
	ds_write_b16 v1, v2 offset:4416
	v_cvt_pk_bf16_f32 v2, v105, s0
	ds_write_b16 v1, v2 offset:4688
	v_cvt_pk_bf16_f32 v2, v106, s0
	ds_write_b16 v1, v2 offset:4960
	v_cvt_pk_bf16_f32 v2, v107, s0
	ds_write_b16 v1, v2 offset:5232
	v_cvt_pk_bf16_f32 v2, v100, s0
	ds_write_b16 v1, v2 offset:4448
	v_cvt_pk_bf16_f32 v2, v101, s0
	ds_write_b16 v1, v2 offset:4720
	v_cvt_pk_bf16_f32 v2, v102, s0
	ds_write_b16 v1, v2 offset:4992
	v_cvt_pk_bf16_f32 v2, v103, s0
	ds_write_b16 v1, v2 offset:5264
	v_cvt_pk_bf16_f32 v2, v96, s0
	ds_write_b16 v1, v2 offset:8704
	v_cvt_pk_bf16_f32 v2, v97, s0
	ds_write_b16 v1, v2 offset:8976
	v_cvt_pk_bf16_f32 v2, v98, s0
	ds_write_b16 v1, v2 offset:9248
	v_cvt_pk_bf16_f32 v2, v99, s0
	ds_write_b16 v1, v2 offset:9520
; DEVI void plain_tile256(const bf* A, int lda, const bf* Wt, int K, bf* C, int ldc, long row0, int n0, char* smem) {
;     ...
;   bf* tl = reinterpret_cast<bf*>(smem);
; #pragma unroll
;   for (int m = 0; m < 8; ++m)
; #pragma unroll
;     for (int n = 0; n < 4; ++n) {
;       const int cl = wc * 64 + n * 16 + l15;
; #pragma unroll
;       for (int j = 0; j < 4; ++j) tl[(wr * 128 + m * 16 + quad * 4 + j) * 136 + cl] = f2bf(acc[m][n][j]);
;     }
;   __syncthreads();
	v_cvt_pk_bf16_f32 v2, v92, s0
	ds_write_b16 v1, v2 offset:8736
	v_cvt_pk_bf16_f32 v2, v93, s0
	ds_write_b16 v1, v2 offset:9008
	v_cvt_pk_bf16_f32 v2, v94, s0
	ds_write_b16 v1, v2 offset:9280
	v_cvt_pk_bf16_f32 v2, v95, s0
	ds_write_b16 v1, v2 offset:9552
	v_cvt_pk_bf16_f32 v2, v88, s0
	ds_write_b16 v1, v2 offset:8768
	v_cvt_pk_bf16_f32 v2, v89, s0
	ds_write_b16 v1, v2 offset:9040
	v_cvt_pk_bf16_f32 v2, v90, s0
	ds_write_b16 v1, v2 offset:9312
	v_cvt_pk_bf16_f32 v2, v91, s0
	ds_write_b16 v1, v2 offset:9584
	v_cvt_pk_bf16_f32 v2, v84, s0
	ds_write_b16 v1, v2 offset:8800
	v_cvt_pk_bf16_f32 v2, v85, s0
	ds_write_b16 v1, v2 offset:9072
	v_cvt_pk_bf16_f32 v2, v86, s0
	ds_write_b16 v1, v2 offset:9344
	v_cvt_pk_bf16_f32 v2, v87, s0
	ds_write_b16 v1, v2 offset:9616
	v_cvt_pk_bf16_f32 v2, v80, s0
	ds_write_b16 v1, v2 offset:13056
	v_cvt_pk_bf16_f32 v2, v81, s0
	ds_write_b16 v1, v2 offset:13328
	v_cvt_pk_bf16_f32 v2, v82, s0
	ds_write_b16 v1, v2 offset:13600
	v_cvt_pk_bf16_f32 v2, v83, s0
	ds_write_b16 v1, v2 offset:13872
	v_cvt_pk_bf16_f32 v2, v76, s0
	ds_write_b16 v1, v2 offset:13088
	v_cvt_pk_bf16_f32 v2, v77, s0
	ds_write_b16 v1, v2 offset:13360
	v_cvt_pk_bf16_f32 v2, v78, s0
	ds_write_b16 v1, v2 offset:13632
	v_cvt_pk_bf16_f32 v2, v79, s0
	ds_write_b16 v1, v2 offset:13904
	v_cvt_pk_bf16_f32 v2, v72, s0
	ds_write_b16 v1, v2 offset:13120
	v_cvt_pk_bf16_f32 v2, v73, s0
	ds_write_b16 v1, v2 offset:13392
	v_cvt_pk_bf16_f32 v2, v74, s0
	ds_write_b16 v1, v2 offset:13664
	v_cvt_pk_bf16_f32 v2, v75, s0
	ds_write_b16 v1, v2 offset:13936
	v_cvt_pk_bf16_f32 v2, v68, s0
	ds_write_b16 v1, v2 offset:13152
	v_cvt_pk_bf16_f32 v2, v69, s0
	ds_write_b16 v1, v2 offset:13424
	v_cvt_pk_bf16_f32 v2, v70, s0
	ds_write_b16 v1, v2 offset:13696
	v_cvt_pk_bf16_f32 v2, v71, s0
	ds_write_b16 v1, v2 offset:13968
	v_cvt_pk_bf16_f32 v2, v64, s0
	ds_write_b16 v1, v2 offset:17408
	v_cvt_pk_bf16_f32 v2, v65, s0
	ds_write_b16 v1, v2 offset:17680
	v_cvt_pk_bf16_f32 v2, v66, s0
	ds_write_b16 v1, v2 offset:17952
	v_cvt_pk_bf16_f32 v2, v67, s0
	ds_write_b16 v1, v2 offset:18224
	v_cvt_pk_bf16_f32 v2, v60, s0
	ds_write_b16 v1, v2 offset:17440
	v_cvt_pk_bf16_f32 v2, v61, s0
	ds_write_b16 v1, v2 offset:17712
	v_cvt_pk_bf16_f32 v2, v62, s0
	ds_write_b16 v1, v2 offset:17984
	v_cvt_pk_bf16_f32 v2, v63, s0
	ds_write_b16 v1, v2 offset:18256
	v_cvt_pk_bf16_f32 v2, v56, s0
	ds_write_b16 v1, v2 offset:17472
	v_cvt_pk_bf16_f32 v2, v57, s0
	ds_write_b16 v1, v2 offset:17744
	v_cvt_pk_bf16_f32 v2, v58, s0
	ds_write_b16 v1, v2 offset:18016
	v_cvt_pk_bf16_f32 v2, v59, s0
	ds_write_b16 v1, v2 offset:18288
	v_cvt_pk_bf16_f32 v2, v52, s0
	ds_write_b16 v1, v2 offset:17504
	v_cvt_pk_bf16_f32 v2, v53, s0
	ds_write_b16 v1, v2 offset:17776
	v_cvt_pk_bf16_f32 v2, v54, s0
	ds_write_b16 v1, v2 offset:18048
	v_cvt_pk_bf16_f32 v2, v55, s0
	ds_write_b16 v1, v2 offset:18320
	v_cvt_pk_bf16_f32 v2, v48, s0
	ds_write_b16 v1, v2 offset:21760
	v_cvt_pk_bf16_f32 v2, v49, s0
	ds_write_b16 v1, v2 offset:22032
	v_cvt_pk_bf16_f32 v2, v50, s0
	ds_write_b16 v1, v2 offset:22304
	v_cvt_pk_bf16_f32 v2, v51, s0
	ds_write_b16 v1, v2 offset:22576
	v_cvt_pk_bf16_f32 v2, v44, s0
	ds_write_b16 v1, v2 offset:21792
	v_cvt_pk_bf16_f32 v2, v45, s0
	ds_write_b16 v1, v2 offset:22064
	v_cvt_pk_bf16_f32 v2, v46, s0
	ds_write_b16 v1, v2 offset:22336
	v_cvt_pk_bf16_f32 v2, v47, s0
	ds_write_b16 v1, v2 offset:22608
	v_cvt_pk_bf16_f32 v2, v40, s0
	ds_write_b16 v1, v2 offset:21824
	v_cvt_pk_bf16_f32 v2, v41, s0
	ds_write_b16 v1, v2 offset:22096
	v_cvt_pk_bf16_f32 v2, v42, s0
	ds_write_b16 v1, v2 offset:22368
	v_cvt_pk_bf16_f32 v2, v43, s0
	ds_write_b16 v1, v2 offset:22640
	v_cvt_pk_bf16_f32 v2, v36, s0
	ds_write_b16 v1, v2 offset:21856
	v_cvt_pk_bf16_f32 v2, v37, s0
	ds_write_b16 v1, v2 offset:22128
	v_cvt_pk_bf16_f32 v2, v38, s0
	ds_write_b16 v1, v2 offset:22400
	v_cvt_pk_bf16_f32 v2, v39, s0
	ds_write_b16 v1, v2 offset:22672
	v_cvt_pk_bf16_f32 v2, v32, s0
	ds_write_b16 v1, v2 offset:26112
	v_cvt_pk_bf16_f32 v2, v33, s0
	ds_write_b16 v1, v2 offset:26384
	v_cvt_pk_bf16_f32 v2, v34, s0
	ds_write_b16 v1, v2 offset:26656
	v_cvt_pk_bf16_f32 v2, v35, s0
	ds_write_b16 v1, v2 offset:26928
	v_cvt_pk_bf16_f32 v2, v28, s0
	ds_write_b16 v1, v2 offset:26144
	v_cvt_pk_bf16_f32 v2, v29, s0
	ds_write_b16 v1, v2 offset:26416
	v_cvt_pk_bf16_f32 v2, v30, s0
	ds_write_b16 v1, v2 offset:26688
	v_cvt_pk_bf16_f32 v2, v31, s0
	ds_write_b16 v1, v2 offset:26960
	v_cvt_pk_bf16_f32 v2, v24, s0
	ds_write_b16 v1, v2 offset:26176
	v_cvt_pk_bf16_f32 v2, v25, s0
	ds_write_b16 v1, v2 offset:26448
	v_cvt_pk_bf16_f32 v2, v26, s0
	ds_write_b16 v1, v2 offset:26720
	v_cvt_pk_bf16_f32 v2, v27, s0
	ds_write_b16 v1, v2 offset:26992
	v_cvt_pk_bf16_f32 v2, v20, s0
	ds_write_b16 v1, v2 offset:26208
	v_cvt_pk_bf16_f32 v2, v21, s0
	ds_write_b16 v1, v2 offset:26480
	v_cvt_pk_bf16_f32 v2, v22, s0
	ds_write_b16 v1, v2 offset:26752
	v_cvt_pk_bf16_f32 v2, v23, s0
	ds_write_b16 v1, v2 offset:27024
	v_cvt_pk_bf16_f32 v2, v16, s0
	ds_write_b16 v1, v2 offset:30464
	v_cvt_pk_bf16_f32 v2, v17, s0
	ds_write_b16 v1, v2 offset:30736
	v_cvt_pk_bf16_f32 v2, v18, s0
	ds_write_b16 v1, v2 offset:31008
	v_cvt_pk_bf16_f32 v2, v19, s0
	ds_write_b16 v1, v2 offset:31280
	v_cvt_pk_bf16_f32 v2, v12, s0
	ds_write_b16 v1, v2 offset:30496
	v_cvt_pk_bf16_f32 v2, v13, s0
	ds_write_b16 v1, v2 offset:30768
	v_cvt_pk_bf16_f32 v2, v14, s0
	ds_write_b16 v1, v2 offset:31040
	v_cvt_pk_bf16_f32 v2, v15, s0
	ds_write_b16 v1, v2 offset:31312
	v_cvt_pk_bf16_f32 v2, v8, s0
	ds_write_b16 v1, v2 offset:30528
	v_cvt_pk_bf16_f32 v2, v9, s0
	ds_write_b16 v1, v2 offset:30800
	v_cvt_pk_bf16_f32 v2, v10, s0
	ds_write_b16 v1, v2 offset:31072
	v_cvt_pk_bf16_f32 v2, v11, s0
	ds_write_b16 v1, v2 offset:31344
	v_cvt_pk_bf16_f32 v2, v4, s0
	ds_write_b16 v1, v2 offset:30560
	v_cvt_pk_bf16_f32 v2, v5, s0
	ds_write_b16 v1, v2 offset:30832
	v_cvt_pk_bf16_f32 v2, v6, s0
	v_cvt_pk_bf16_f32 v128, v128, s0
	ds_write_b16 v1, v2 offset:31104
	v_cvt_pk_bf16_f32 v2, v7, s0
	ds_write_b16 v1, v128
	ds_write_b16 v1, v2 offset:31376
	v_mov_b32_e32 v1, v178
	s_waitcnt lgkmcnt(0)
	s_barrier
; DEVI int get_tid() { int t = threadIdx.x; asm volatile("" : "+v"(t)); return t; }
; template <int BN>
; DEVI void tile_store256(const char* smem, bf* __restrict__ C, long ldc, long row0, int col0) {
;   constexpr int LDT = BN + 8;
;   constexpr int CPR = BN / 8;
;   const int tid = get_tid();
; #pragma unroll
;   for (int i = 0; i < CPR; ++i) {
;     const int q = tid + 256 * i;
;     const int r = q / CPR, c = q - r * CPR;
;     u32x4 v = *reinterpret_cast<const u32x4*>(smem + (r * LDT + c * 8) * 2);
;     *reinterpret_cast<u32x4*>(C + (row0 + r) * ldc + col0 + c * 8) = v;
;   }
; }
	v_readlane_b32 s56, v251, 58
	v_ashrrev_i32_e32 v2, 31, v1
	v_lshrrev_b32_e32 v2, 28, v2
	v_add_u32_e32 v2, v1, v2
	s_lshl_b64 s[10:11], s[34:35], 1
	v_readlane_b32 s58, v251, 60
	v_ashrrev_i32_e32 v4, 4, v2
	v_readlane_b32 s59, v251, 61
	s_add_u32 s10, s58, s10
	v_lshlrev_b32_e32 v5, 7, v4
	v_lshlrev_b32_e32 v6, 3, v1
	s_addc_u32 s11, s59, s11
	v_sub_u32_e32 v10, v6, v5
	v_ashrrev_i32_e32 v5, 31, v4
	v_mul_lo_u32 v2, v4, s29
	v_lshl_add_u64 v[12:13], s[12:13], 0, v[4:5]
	v_mov_b64_e32 v[4:5], s[10:11]
	v_add_lshl_u32 v2, v10, v2, 1
	v_mad_u64_u32 v[14:15], s[10:11], v12, s39, v[4:5]
	ds_read_b128 v[6:9], v2
	v_mov_b32_e32 v2, v15
	v_mad_u64_u32 v[12:13], s[10:11], v13, s39, v[2:3]
	v_mov_b32_e32 v15, v12
	v_ashrrev_i32_e32 v11, 31, v10
	v_add_u32_e32 v2, 0x100, v1
	v_lshl_add_u64 v[14:15], v[10:11], 1, v[14:15]
	v_ashrrev_i32_e32 v10, 31, v2
	v_lshrrev_b32_e32 v10, 28, v10
	v_add_u32_e32 v10, v2, v10
	v_ashrrev_i32_e32 v16, 4, v10
	v_lshlrev_b32_e32 v11, 7, v16
	v_lshlrev_b32_e32 v2, 3, v2
	v_mul_lo_u32 v10, v16, s29
	v_sub_u32_e32 v18, v2, v11
	v_ashrrev_i32_e32 v17, 31, v16
	v_add_lshl_u32 v2, v18, v10, 1
	s_waitcnt lgkmcnt(0)
	global_store_dwordx4 v[14:15], v[6:9], off
	ds_read_b128 v[10:13], v2
	v_ashrrev_i32_e32 v19, 31, v18
	v_lshl_add_u64 v[6:7], s[12:13], 0, v[16:17]
	v_mad_u64_u32 v[8:9], s[10:11], v6, s39, v[4:5]
	v_mov_b32_e32 v2, v9
	v_mad_u64_u32 v[6:7], s[10:11], v7, s39, v[2:3]
	v_mov_b32_e32 v9, v6
	v_lshl_add_u64 v[6:7], v[18:19], 1, v[8:9]
	v_add_u32_e32 v2, 0x200, v1
	s_waitcnt lgkmcnt(0)
	global_store_dwordx4 v[6:7], v[10:13], off
	v_ashrrev_i32_e32 v6, 31, v2
	v_lshrrev_b32_e32 v6, 28, v6
	v_add_u32_e32 v6, v2, v6
	v_ashrrev_i32_e32 v10, 4, v6
	v_lshlrev_b32_e32 v7, 7, v10
	v_lshlrev_b32_e32 v2, 3, v2
	v_ashrrev_i32_e32 v11, 31, v10
	v_mul_lo_u32 v6, v10, s29
	v_sub_u32_e32 v12, v2, v7
	v_lshl_add_u64 v[10:11], s[12:13], 0, v[10:11]
	v_add_lshl_u32 v2, v12, v6, 1
	v_mad_u64_u32 v[14:15], s[10:11], v10, s39, v[4:5]
	ds_read_b128 v[6:9], v2
	v_mov_b32_e32 v2, v15
	v_mad_u64_u32 v[10:11], s[10:11], v11, s39, v[2:3]
	v_add_u32_e32 v2, 0x300, v1
	v_mov_b32_e32 v15, v10
	v_ashrrev_i32_e32 v10, 31, v2
	v_lshrrev_b32_e32 v10, 28, v10
	v_add_u32_e32 v10, v2, v10
	v_ashrrev_i32_e32 v16, 4, v10
	v_ashrrev_i32_e32 v13, 31, v12
	v_lshlrev_b32_e32 v11, 7, v16
	v_lshlrev_b32_e32 v2, 3, v2
	v_lshl_add_u64 v[14:15], v[12:13], 1, v[14:15]
	v_mul_lo_u32 v10, v16, s29
	v_sub_u32_e32 v18, v2, v11
	v_ashrrev_i32_e32 v17, 31, v16
	v_add_lshl_u32 v2, v18, v10, 1
	s_waitcnt lgkmcnt(0)
	global_store_dwordx4 v[14:15], v[6:9], off
	ds_read_b128 v[10:13], v2
	v_ashrrev_i32_e32 v19, 31, v18
	v_lshl_add_u64 v[6:7], s[12:13], 0, v[16:17]
	v_mad_u64_u32 v[8:9], s[10:11], v6, s39, v[4:5]
	v_mov_b32_e32 v2, v9
	v_mad_u64_u32 v[6:7], s[10:11], v7, s39, v[2:3]
	v_mov_b32_e32 v9, v6
	v_lshl_add_u64 v[6:7], v[18:19], 1, v[8:9]
	v_add_u32_e32 v2, 0x400, v1
	s_waitcnt lgkmcnt(0)
	global_store_dwordx4 v[6:7], v[10:13], off
	v_ashrrev_i32_e32 v6, 31, v2
	v_lshrrev_b32_e32 v6, 28, v6
	v_add_u32_e32 v6, v2, v6
	v_ashrrev_i32_e32 v10, 4, v6
	v_lshlrev_b32_e32 v7, 7, v10
	v_lshlrev_b32_e32 v2, 3, v2
	v_ashrrev_i32_e32 v11, 31, v10
	v_mul_lo_u32 v6, v10, s29
	v_sub_u32_e32 v12, v2, v7
	v_lshl_add_u64 v[10:11], s[12:13], 0, v[10:11]
	v_add_lshl_u32 v2, v12, v6, 1
	v_mad_u64_u32 v[14:15], s[10:11], v10, s39, v[4:5]
	ds_read_b128 v[6:9], v2
	v_mov_b32_e32 v2, v15
	v_mad_u64_u32 v[10:11], s[10:11], v11, s39, v[2:3]
	v_add_u32_e32 v2, 0x500, v1
	v_mov_b32_e32 v15, v10
	v_ashrrev_i32_e32 v10, 31, v2
	v_lshrrev_b32_e32 v10, 28, v10
	v_add_u32_e32 v10, v2, v10
	v_ashrrev_i32_e32 v16, 4, v10
	v_ashrrev_i32_e32 v13, 31, v12
	v_lshlrev_b32_e32 v11, 7, v16
	v_lshlrev_b32_e32 v2, 3, v2
	v_lshl_add_u64 v[14:15], v[12:13], 1, v[14:15]
	v_mul_lo_u32 v10, v16, s29
	v_sub_u32_e32 v18, v2, v11
	v_ashrrev_i32_e32 v17, 31, v16
	v_add_lshl_u32 v2, v18, v10, 1
	s_waitcnt lgkmcnt(0)
	global_store_dwordx4 v[14:15], v[6:9], off
	ds_read_b128 v[10:13], v2
	v_ashrrev_i32_e32 v19, 31, v18
	v_lshl_add_u64 v[6:7], s[12:13], 0, v[16:17]
	v_mad_u64_u32 v[8:9], s[10:11], v6, s39, v[4:5]
	v_mov_b32_e32 v2, v9
	v_mad_u64_u32 v[6:7], s[10:11], v7, s39, v[2:3]
	v_mov_b32_e32 v9, v6
	v_lshl_add_u64 v[6:7], v[18:19], 1, v[8:9]
	v_add_u32_e32 v2, 0x600, v1
	s_waitcnt lgkmcnt(0)
	global_store_dwordx4 v[6:7], v[10:13], off
	v_ashrrev_i32_e32 v6, 31, v2
	v_lshrrev_b32_e32 v6, 28, v6
	v_add_u32_e32 v6, v2, v6
	v_ashrrev_i32_e32 v10, 4, v6
	v_lshlrev_b32_e32 v7, 7, v10
	v_lshlrev_b32_e32 v2, 3, v2
	v_ashrrev_i32_e32 v11, 31, v10
	v_mul_lo_u32 v6, v10, s29
	v_sub_u32_e32 v12, v2, v7
	v_lshl_add_u64 v[10:11], s[12:13], 0, v[10:11]
	v_add_lshl_u32 v2, v12, v6, 1
	v_mad_u64_u32 v[14:15], s[10:11], v10, s39, v[4:5]
	ds_read_b128 v[6:9], v2
	v_mov_b32_e32 v2, v15
	v_mad_u64_u32 v[10:11], s[10:11], v11, s39, v[2:3]
	v_add_u32_e32 v2, 0x700, v1
	v_mov_b32_e32 v15, v10
	v_ashrrev_i32_e32 v10, 31, v2
	v_lshrrev_b32_e32 v10, 28, v10
	v_add_u32_e32 v10, v2, v10
	v_ashrrev_i32_e32 v16, 4, v10
	v_ashrrev_i32_e32 v13, 31, v12
	v_lshlrev_b32_e32 v11, 7, v16
	v_lshlrev_b32_e32 v2, 3, v2
	v_lshl_add_u64 v[14:15], v[12:13], 1, v[14:15]
	v_mul_lo_u32 v10, v16, s29
	v_sub_u32_e32 v18, v2, v11
	v_ashrrev_i32_e32 v17, 31, v16
	v_add_lshl_u32 v2, v18, v10, 1
	s_waitcnt lgkmcnt(0)
	global_store_dwordx4 v[14:15], v[6:9], off
	ds_read_b128 v[10:13], v2
	v_ashrrev_i32_e32 v19, 31, v18
	v_lshl_add_u64 v[6:7], s[12:13], 0, v[16:17]
	v_mad_u64_u32 v[8:9], s[10:11], v6, s39, v[4:5]
	v_mov_b32_e32 v2, v9
	v_mad_u64_u32 v[6:7], s[10:11], v7, s39, v[2:3]
	v_mov_b32_e32 v9, v6
	v_lshl_add_u64 v[6:7], v[18:19], 1, v[8:9]
	v_add_u32_e32 v2, 0x800, v1
	s_waitcnt lgkmcnt(0)
; DEVI int get_tid() { int t = threadIdx.x; asm volatile("" : "+v"(t)); return t; }
; template <int BN>
; DEVI void tile_store256(const char* smem, bf* __restrict__ C, long ldc, long row0, int col0) {
;   constexpr int LDT = BN + 8;
;   constexpr int CPR = BN / 8;
;   const int tid = get_tid();
; #pragma unroll
;   for (int i = 0; i < CPR; ++i) {
;     const int q = tid + 256 * i;
;     const int r = q / CPR, c = q - r * CPR;
;     u32x4 v = *reinterpret_cast<const u32x4*>(smem + (r * LDT + c * 8) * 2);
;     *reinterpret_cast<u32x4*>(C + (row0 + r) * ldc + col0 + c * 8) = v;
;   }
; }
; DEVI void phase_gemm_plain128(const bf* A, int lda, const bf* Wt, int K, int N, bf* C, int ldc, char* smem) {
;     ...
;   for (int v = blockIdx.x; v < 128 * ntn; v += gridDim.x) {
;     int m2, nt;
;     lat_tile_map256(v, ntn, m2, nt);
;     plain_tile256(A, lda, Wt, K, C, ldc, lat_row0_256(m2), nt * 128, smem);
	global_store_dwordx4 v[6:7], v[10:13], off
	v_ashrrev_i32_e32 v6, 31, v2
	v_lshrrev_b32_e32 v6, 28, v6
	v_add_u32_e32 v6, v2, v6
	v_ashrrev_i32_e32 v10, 4, v6
	v_lshlrev_b32_e32 v7, 7, v10
	v_lshlrev_b32_e32 v2, 3, v2
	v_ashrrev_i32_e32 v11, 31, v10
	v_mul_lo_u32 v6, v10, s29
	v_sub_u32_e32 v12, v2, v7
	v_lshl_add_u64 v[10:11], s[12:13], 0, v[10:11]
	v_add_lshl_u32 v2, v12, v6, 1
	v_mad_u64_u32 v[14:15], s[10:11], v10, s39, v[4:5]
	ds_read_b128 v[6:9], v2
	v_mov_b32_e32 v2, v15
	v_mad_u64_u32 v[10:11], s[10:11], v11, s39, v[2:3]
	v_add_u32_e32 v2, 0x900, v1
	v_mov_b32_e32 v15, v10
	v_ashrrev_i32_e32 v10, 31, v2
	v_lshrrev_b32_e32 v10, 28, v10
	v_add_u32_e32 v10, v2, v10
	v_ashrrev_i32_e32 v16, 4, v10
	v_ashrrev_i32_e32 v13, 31, v12
	v_lshlrev_b32_e32 v11, 7, v16
	v_lshlrev_b32_e32 v2, 3, v2
	v_lshl_add_u64 v[14:15], v[12:13], 1, v[14:15]
	v_mul_lo_u32 v10, v16, s29
	v_sub_u32_e32 v18, v2, v11
	v_ashrrev_i32_e32 v17, 31, v16
	v_add_lshl_u32 v2, v18, v10, 1
	s_waitcnt lgkmcnt(0)
	global_store_dwordx4 v[14:15], v[6:9], off
	ds_read_b128 v[10:13], v2
	v_ashrrev_i32_e32 v19, 31, v18
	v_lshl_add_u64 v[6:7], s[12:13], 0, v[16:17]
	v_mad_u64_u32 v[8:9], s[10:11], v6, s39, v[4:5]
	v_mov_b32_e32 v2, v9
	v_mad_u64_u32 v[6:7], s[10:11], v7, s39, v[2:3]
	v_mov_b32_e32 v9, v6
	v_lshl_add_u64 v[6:7], v[18:19], 1, v[8:9]
	v_add_u32_e32 v2, 0xa00, v1
	s_waitcnt lgkmcnt(0)
	global_store_dwordx4 v[6:7], v[10:13], off
	v_ashrrev_i32_e32 v6, 31, v2
	v_lshrrev_b32_e32 v6, 28, v6
	v_add_u32_e32 v6, v2, v6
	v_ashrrev_i32_e32 v10, 4, v6
	v_lshlrev_b32_e32 v7, 7, v10
	v_lshlrev_b32_e32 v2, 3, v2
	v_ashrrev_i32_e32 v11, 31, v10
	v_mul_lo_u32 v6, v10, s29
	v_sub_u32_e32 v12, v2, v7
	v_lshl_add_u64 v[10:11], s[12:13], 0, v[10:11]
	v_add_lshl_u32 v2, v12, v6, 1
	v_mad_u64_u32 v[14:15], s[10:11], v10, s39, v[4:5]
	ds_read_b128 v[6:9], v2
	v_mov_b32_e32 v2, v15
	v_mad_u64_u32 v[10:11], s[10:11], v11, s39, v[2:3]
	v_add_u32_e32 v2, 0xb00, v1
	v_mov_b32_e32 v15, v10
	v_ashrrev_i32_e32 v10, 31, v2
	v_lshrrev_b32_e32 v10, 28, v10
	v_add_u32_e32 v10, v2, v10
	v_ashrrev_i32_e32 v16, 4, v10
	v_ashrrev_i32_e32 v13, 31, v12
	v_lshlrev_b32_e32 v11, 7, v16
	v_lshlrev_b32_e32 v2, 3, v2
	v_lshl_add_u64 v[14:15], v[12:13], 1, v[14:15]
	v_mul_lo_u32 v10, v16, s29
	v_sub_u32_e32 v18, v2, v11
	v_ashrrev_i32_e32 v17, 31, v16
	v_add_lshl_u32 v2, v18, v10, 1
	s_waitcnt lgkmcnt(0)
	global_store_dwordx4 v[14:15], v[6:9], off
	ds_read_b128 v[10:13], v2
	v_ashrrev_i32_e32 v19, 31, v18
	v_lshl_add_u64 v[6:7], s[12:13], 0, v[16:17]
	v_mad_u64_u32 v[8:9], s[10:11], v6, s39, v[4:5]
	v_mov_b32_e32 v2, v9
	v_mad_u64_u32 v[6:7], s[10:11], v7, s39, v[2:3]
	v_mov_b32_e32 v9, v6
	v_lshl_add_u64 v[6:7], v[18:19], 1, v[8:9]
	v_add_u32_e32 v2, 0xc00, v1
	s_waitcnt lgkmcnt(0)
	global_store_dwordx4 v[6:7], v[10:13], off
	v_ashrrev_i32_e32 v6, 31, v2
	v_lshrrev_b32_e32 v6, 28, v6
	v_add_u32_e32 v6, v2, v6
	v_ashrrev_i32_e32 v10, 4, v6
	v_lshlrev_b32_e32 v7, 7, v10
	v_lshlrev_b32_e32 v2, 3, v2
	v_ashrrev_i32_e32 v11, 31, v10
	v_mul_lo_u32 v6, v10, s29
	v_sub_u32_e32 v12, v2, v7
	v_lshl_add_u64 v[10:11], s[12:13], 0, v[10:11]
	v_add_lshl_u32 v2, v12, v6, 1
	v_mad_u64_u32 v[14:15], s[10:11], v10, s39, v[4:5]
	ds_read_b128 v[6:9], v2
	v_mov_b32_e32 v2, v15
	v_mad_u64_u32 v[10:11], s[10:11], v11, s39, v[2:3]
	v_add_u32_e32 v2, 0xd00, v1
	v_mov_b32_e32 v15, v10
	v_ashrrev_i32_e32 v10, 31, v2
	v_lshrrev_b32_e32 v10, 28, v10
	v_add_u32_e32 v10, v2, v10
	v_ashrrev_i32_e32 v16, 4, v10
	v_ashrrev_i32_e32 v13, 31, v12
	v_lshlrev_b32_e32 v11, 7, v16
	v_lshlrev_b32_e32 v2, 3, v2
	v_lshl_add_u64 v[14:15], v[12:13], 1, v[14:15]
	v_mul_lo_u32 v10, v16, s29
	v_sub_u32_e32 v18, v2, v11
	v_ashrrev_i32_e32 v17, 31, v16
	v_add_lshl_u32 v2, v18, v10, 1
	s_waitcnt lgkmcnt(0)
	global_store_dwordx4 v[14:15], v[6:9], off
	ds_read_b128 v[10:13], v2
	v_ashrrev_i32_e32 v19, 31, v18
	v_lshl_add_u64 v[6:7], s[12:13], 0, v[16:17]
	v_mad_u64_u32 v[8:9], s[10:11], v6, s39, v[4:5]
	v_mov_b32_e32 v2, v9
	v_mad_u64_u32 v[6:7], s[10:11], v7, s39, v[2:3]
	v_mov_b32_e32 v9, v6
	v_lshl_add_u64 v[6:7], v[18:19], 1, v[8:9]
	v_add_u32_e32 v2, 0xe00, v1
	s_waitcnt lgkmcnt(0)
	global_store_dwordx4 v[6:7], v[10:13], off
	v_ashrrev_i32_e32 v6, 31, v2
	v_lshrrev_b32_e32 v6, 28, v6
	v_add_u32_e32 v6, v2, v6
	v_ashrrev_i32_e32 v10, 4, v6
	v_lshlrev_b32_e32 v7, 7, v10
	v_lshlrev_b32_e32 v2, 3, v2
	v_ashrrev_i32_e32 v11, 31, v10
	v_mul_lo_u32 v6, v10, s29
	v_sub_u32_e32 v12, v2, v7
	v_lshl_add_u64 v[10:11], s[12:13], 0, v[10:11]
	v_add_lshl_u32 v2, v12, v6, 1
	v_mad_u64_u32 v[14:15], s[10:11], v10, s39, v[4:5]
	ds_read_b128 v[6:9], v2
	v_mov_b32_e32 v2, v15
	v_add_u32_e32 v1, 0xf00, v1
	v_mad_u64_u32 v[10:11], s[10:11], v11, s39, v[2:3]
	v_ashrrev_i32_e32 v2, 31, v1
	v_lshrrev_b32_e32 v2, 28, v2
	v_add_u32_e32 v2, v1, v2
	v_mov_b32_e32 v15, v10
	v_ashrrev_i32_e32 v13, 31, v12
	v_ashrrev_i32_e32 v16, 4, v2
	v_lshl_add_u64 v[14:15], v[12:13], 1, v[14:15]
	v_lshlrev_b32_e32 v10, 7, v16
	v_lshlrev_b32_e32 v1, 3, v1
	v_ashrrev_i32_e32 v17, 31, v16
	v_mul_lo_u32 v2, v16, s29
	v_sub_u32_e32 v18, v1, v10
	s_waitcnt lgkmcnt(0)
	global_store_dwordx4 v[14:15], v[6:9], off
	v_add_lshl_u32 v1, v18, v2, 1
	ds_read_b128 v[10:13], v1
	v_lshl_add_u64 v[6:7], s[12:13], 0, v[16:17]
	v_mad_u64_u32 v[4:5], s[10:11], v6, s39, v[4:5]
	v_mov_b32_e32 v2, v5
	v_mad_u64_u32 v[6:7], s[10:11], v7, s39, v[2:3]
	v_readlane_b32 s10, v252, 59
	v_mov_b32_e32 v5, v6
	v_ashrrev_i32_e32 v19, 31, v18
	s_add_i32 s2, s2, s10
	v_readlane_b32 s57, v251, 59
	v_lshl_add_u64 v[4:5], v[18:19], 1, v[4:5]
	s_cmpk_gt_i32 s2, 0x97f
	v_readlane_b32 s60, v251, 62
	v_readlane_b32 s61, v251, 63
	v_readlane_b32 s62, v252, 0
	v_readlane_b32 s63, v252, 1
	v_readlane_b32 s64, v252, 2
	v_readlane_b32 s65, v252, 3
	v_readlane_b32 s66, v252, 4
	v_readlane_b32 s67, v252, 5
	v_readlane_b32 s68, v252, 6
	v_readlane_b32 s69, v252, 7
	v_readlane_b32 s70, v252, 8
	v_readlane_b32 s71, v252, 9
	s_waitcnt lgkmcnt(0)
	global_store_dwordx4 v[4:5], v[10:13], off
	s_barrier
	v_readlane_b32 s11, v252, 60
	s_cbranch_scc0 .LBB0_903

; DEVI f32x4 mfma16(bf16x8 a, bf16x8 b, f32x4 c) { return __builtin_amdgcn_mfma_f32_16x16x32_bf16(a, b, c, 0, 0, 0); }
; DEVI void gemm_core3(f32x4 (&acc)[8][4], const bf* __restrict__ A, int lda, const bf* __restrict__ Bt, int ldb, int K, char* smem) {
;     ...
;   for (int kt = 0; kt < nk; ++kt) {
;     const int k1 = min((kt + 1) * 32, klast);
;     const int sn = ((kt + 1) & 1) * STG;
;     const int so = (kt & 1) * STG;
;     bf16x8 bfr[4], af[8];
; #pragma unroll
;     for (int n = 0; n < 4; ++n) bfr[n] = *reinterpret_cast<const bf16x8*>(bbase + so + n * 16 * 64);
; #pragma unroll
;     for (int m = 0; m < 8; ++m) af[m] = *reinterpret_cast<const bf16x8*>(abase + so + m * 16 * 64);
; #pragma unroll
;     for (int i = 0; i < 4; ++i) glds16(Ap + i * sa + k1, dbase + sn + i * 4096);
; #pragma unroll
;     for (int i = 0; i < 2; ++i) glds16(Bp + i * sb + k1, dbase + sn + ASZ + i * 4096);
;     __builtin_amdgcn_s_setprio(1);
; #pragma unroll
;     for (int m = 0; m < 8; ++m)
; #pragma unroll
;       for (int n = 0; n < 4; ++n) acc[m][n] = mfma16(af[m], bfr[n], acc[m][n]);
;     __builtin_amdgcn_s_setprio(0);
;     __syncthreads();
;   }
.Lg3_loop_926:
	v_add_u32_e32 v216, s10, v146
	v_add_u32_e32 v217, s10, v2
	ds_read_b128 v[148:151], v217 offset:16384
	ds_read_b128 v[166:169], v216
	ds_read_b128 v[154:157], v217 offset:17408
	ds_read_b128 v[158:161], v217 offset:18432
	ds_read_b128 v[162:165], v217 offset:19456
	ds_read_b128 v[170:173], v216 offset:1024
	ds_read_b128 v[174:177], v216 offset:2048
	ds_read_b128 v[192:195], v216 offset:3072
	ds_read_b128 v[196:199], v216 offset:4096
	ds_read_b128 v[204:207], v216 offset:5120
	ds_read_b128 v[208:211], v216 offset:6144
	ds_read_b128 v[212:215], v216 offset:7168
	s_setprio 1
	s_waitcnt lgkmcnt(10)
	v_mfma_f32_16x16x32_bf16 v[128:131], v[166:169], v[148:151], v[128:131]
	s_waitcnt lgkmcnt(9)
	v_mfma_f32_16x16x32_bf16 v[124:127], v[166:169], v[154:157], v[124:127]
	s_waitcnt lgkmcnt(8)
	v_mfma_f32_16x16x32_bf16 v[120:123], v[166:169], v[158:161], v[120:123]
	s_waitcnt lgkmcnt(7)
	v_mfma_f32_16x16x32_bf16 v[116:119], v[166:169], v[162:165], v[116:119]
	s_waitcnt lgkmcnt(6)
	v_mfma_f32_16x16x32_bf16 v[112:115], v[170:173], v[148:151], v[112:115]
	v_mfma_f32_16x16x32_bf16 v[108:111], v[170:173], v[154:157], v[108:111]
	v_mfma_f32_16x16x32_bf16 v[104:107], v[170:173], v[158:161], v[104:107]
	v_mfma_f32_16x16x32_bf16 v[100:103], v[170:173], v[162:165], v[100:103]
	s_waitcnt lgkmcnt(5)
	v_mfma_f32_16x16x32_bf16 v[96:99], v[174:177], v[148:151], v[96:99]
	v_mfma_f32_16x16x32_bf16 v[92:95], v[174:177], v[154:157], v[92:95]
	v_mfma_f32_16x16x32_bf16 v[88:91], v[174:177], v[158:161], v[88:91]
	v_mfma_f32_16x16x32_bf16 v[84:87], v[174:177], v[162:165], v[84:87]
	s_waitcnt lgkmcnt(4)
	v_mfma_f32_16x16x32_bf16 v[80:83], v[192:195], v[148:151], v[80:83]
	v_mfma_f32_16x16x32_bf16 v[76:79], v[192:195], v[154:157], v[76:79]
	v_mfma_f32_16x16x32_bf16 v[72:75], v[192:195], v[158:161], v[72:75]
	v_mfma_f32_16x16x32_bf16 v[68:71], v[192:195], v[162:165], v[68:71]
	s_waitcnt lgkmcnt(3)
	v_mfma_f32_16x16x32_bf16 v[64:67], v[196:199], v[148:151], v[64:67]
	v_mfma_f32_16x16x32_bf16 v[60:63], v[196:199], v[154:157], v[60:63]
	v_mfma_f32_16x16x32_bf16 v[56:59], v[196:199], v[158:161], v[56:59]
	v_mfma_f32_16x16x32_bf16 v[52:55], v[196:199], v[162:165], v[52:55]
	s_waitcnt lgkmcnt(2)
	v_mfma_f32_16x16x32_bf16 v[48:51], v[204:207], v[148:151], v[48:51]
	v_mfma_f32_16x16x32_bf16 v[44:47], v[204:207], v[154:157], v[44:47]
	v_mfma_f32_16x16x32_bf16 v[40:43], v[204:207], v[158:161], v[40:43]
	v_mfma_f32_16x16x32_bf16 v[36:39], v[204:207], v[162:165], v[36:39]
	s_waitcnt lgkmcnt(1)
	v_mfma_f32_16x16x32_bf16 v[32:35], v[208:211], v[148:151], v[32:35]
	v_mfma_f32_16x16x32_bf16 v[28:31], v[208:211], v[154:157], v[28:31]
	v_mfma_f32_16x16x32_bf16 v[24:27], v[208:211], v[158:161], v[24:27]
	v_mfma_f32_16x16x32_bf16 v[20:23], v[208:211], v[162:165], v[20:23]
	s_waitcnt lgkmcnt(0)
	v_mfma_f32_16x16x32_bf16 v[16:19], v[212:215], v[148:151], v[16:19]
	v_mfma_f32_16x16x32_bf16 v[12:15], v[212:215], v[154:157], v[12:15]
	v_mfma_f32_16x16x32_bf16 v[8:11], v[212:215], v[158:161], v[8:11]
	v_mfma_f32_16x16x32_bf16 v[4:7], v[212:215], v[162:165], v[4:7]
	s_setprio 0
	s_add_i32 s10, s10, 0x6000
	s_cmp_lg_u32 s10, 0x12000
	s_cselect_b32 s10, s10, 0
	s_waitcnt vmcnt(0)
	s_barrier
	v_add_u32_e32 v216, s10, v146
	v_add_u32_e32 v217, s10, v2
	ds_read_b128 v[148:151], v217 offset:16384
	ds_read_b128 v[166:169], v216
	ds_read_b128 v[154:157], v217 offset:17408
	ds_read_b128 v[158:161], v217 offset:18432
	ds_read_b128 v[162:165], v217 offset:19456
	ds_read_b128 v[170:173], v216 offset:1024
	ds_read_b128 v[174:177], v216 offset:2048
	ds_read_b128 v[192:195], v216 offset:3072
	ds_read_b128 v[196:199], v216 offset:4096
	ds_read_b128 v[204:207], v216 offset:5120
	ds_read_b128 v[208:211], v216 offset:6144
	ds_read_b128 v[212:215], v216 offset:7168
	v_readfirstlane_b32 s17, v140
	s_add_i32 s96, s11, 0x6000
	s_cmp_lg_u32 s96, 0x12000
	s_cselect_b32 s96, s96, 0
	s_add_i32 s96, s96, s17
	s_add_i32 s17, s17, s11
	s_setprio 2
	s_waitcnt lgkmcnt(10)
	s_mov_b32 m0, s17
	s_add_i32 s17, s17, 0x1000
	v_mfma_f32_16x16x32_bf16 v[128:131], v[166:169], v[148:151], v[128:131]
	s_waitcnt lgkmcnt(9)
	v_mfma_f32_16x16x32_bf16 v[124:127], v[166:169], v[154:157], v[124:127]
	global_load_lds_dwordx4 v[218:219], off
	v_lshl_add_u64 v[218:219], v[218:219], 0, 64
	s_waitcnt lgkmcnt(8)
	s_mov_b32 m0, s96
	s_add_i32 s96, s96, 0x1000
	v_mfma_f32_16x16x32_bf16 v[120:123], v[166:169], v[158:161], v[120:123]
	s_waitcnt lgkmcnt(7)
	v_mfma_f32_16x16x32_bf16 v[116:119], v[166:169], v[162:165], v[116:119]
	global_load_lds_dwordx4 v[218:219], off
	v_lshl_add_u64 v[218:219], v[218:219], 0, 64
	s_waitcnt lgkmcnt(6)
	v_mfma_f32_16x16x32_bf16 v[112:115], v[170:173], v[148:151], v[112:115]
	s_mov_b32 m0, s17
	s_add_i32 s17, s17, 0x1000
	v_mfma_f32_16x16x32_bf16 v[108:111], v[170:173], v[154:157], v[108:111]
	v_mfma_f32_16x16x32_bf16 v[104:107], v[170:173], v[158:161], v[104:107]
	global_load_lds_dwordx4 v[220:221], off
	v_lshl_add_u64 v[220:221], v[220:221], 0, 64
	s_mov_b32 m0, s96
	s_add_i32 s96, s96, 0x1000
	v_mfma_f32_16x16x32_bf16 v[100:103], v[170:173], v[162:165], v[100:103]
	s_waitcnt lgkmcnt(5)
	v_mfma_f32_16x16x32_bf16 v[96:99], v[174:177], v[148:151], v[96:99]
	global_load_lds_dwordx4 v[220:221], off
	v_lshl_add_u64 v[220:221], v[220:221], 0, 64
	v_mfma_f32_16x16x32_bf16 v[92:95], v[174:177], v[154:157], v[92:95]
	s_mov_b32 m0, s17
	s_add_i32 s17, s17, 0x1000
	v_mfma_f32_16x16x32_bf16 v[88:91], v[174:177], v[158:161], v[88:91]
	v_mfma_f32_16x16x32_bf16 v[84:87], v[174:177], v[162:165], v[84:87]
	global_load_lds_dwordx4 v[222:223], off
	v_lshl_add_u64 v[222:223], v[222:223], 0, 64
	s_waitcnt lgkmcnt(4)
; DEVI f32x4 mfma16(bf16x8 a, bf16x8 b, f32x4 c) { return __builtin_amdgcn_mfma_f32_16x16x32_bf16(a, b, c, 0, 0, 0); }
; DEVI void gemm_core3(f32x4 (&acc)[8][4], const bf* __restrict__ A, int lda, const bf* __restrict__ Bt, int ldb, int K, char* smem) {
;     ...
;   for (int kt = 0; kt < nk; ++kt) {
;     const int k1 = min((kt + 1) * 32, klast);
;     const int sn = ((kt + 1) & 1) * STG;
;     const int so = (kt & 1) * STG;
;     bf16x8 bfr[4], af[8];
; #pragma unroll
;     for (int n = 0; n < 4; ++n) bfr[n] = *reinterpret_cast<const bf16x8*>(bbase + so + n * 16 * 64);
; #pragma unroll
;     for (int m = 0; m < 8; ++m) af[m] = *reinterpret_cast<const bf16x8*>(abase + so + m * 16 * 64);
; #pragma unroll
;     for (int i = 0; i < 4; ++i) glds16(Ap + i * sa + k1, dbase + sn + i * 4096);
; #pragma unroll
;     for (int i = 0; i < 2; ++i) glds16(Bp + i * sb + k1, dbase + sn + ASZ + i * 4096);
;     __builtin_amdgcn_s_setprio(1);
; #pragma unroll
;     for (int m = 0; m < 8; ++m)
; #pragma unroll
;       for (int n = 0; n < 4; ++n) acc[m][n] = mfma16(af[m], bfr[n], acc[m][n]);
;     __builtin_amdgcn_s_setprio(0);
;     __syncthreads();
;   }
	s_mov_b32 m0, s96
	s_add_i32 s96, s96, 0x1000
	v_mfma_f32_16x16x32_bf16 v[80:83], v[192:195], v[148:151], v[80:83]
	v_mfma_f32_16x16x32_bf16 v[76:79], v[192:195], v[154:157], v[76:79]
	global_load_lds_dwordx4 v[222:223], off
	v_lshl_add_u64 v[222:223], v[222:223], 0, 64
	v_mfma_f32_16x16x32_bf16 v[72:75], v[192:195], v[158:161], v[72:75]
	s_mov_b32 m0, s17
	s_add_i32 s17, s17, 0x1000
	v_mfma_f32_16x16x32_bf16 v[68:71], v[192:195], v[162:165], v[68:71]
	s_waitcnt lgkmcnt(3)
	v_mfma_f32_16x16x32_bf16 v[64:67], v[196:199], v[148:151], v[64:67]
	global_load_lds_dwordx4 v[224:225], off
	v_lshl_add_u64 v[224:225], v[224:225], 0, 64
	s_mov_b32 m0, s96
	s_add_i32 s96, s96, 0x1000
	v_mfma_f32_16x16x32_bf16 v[60:63], v[196:199], v[154:157], v[60:63]
	v_mfma_f32_16x16x32_bf16 v[56:59], v[196:199], v[158:161], v[56:59]
	global_load_lds_dwordx4 v[224:225], off
	v_lshl_add_u64 v[224:225], v[224:225], 0, 64
	v_mfma_f32_16x16x32_bf16 v[52:55], v[196:199], v[162:165], v[52:55]
	s_waitcnt lgkmcnt(2)
	s_mov_b32 m0, s17
	s_add_i32 s17, s17, 0x1000
	v_mfma_f32_16x16x32_bf16 v[48:51], v[204:207], v[148:151], v[48:51]
	v_mfma_f32_16x16x32_bf16 v[44:47], v[204:207], v[154:157], v[44:47]
	global_load_lds_dwordx4 v[226:227], off
	v_lshl_add_u64 v[226:227], v[226:227], 0, 64
	s_mov_b32 m0, s96
	s_add_i32 s96, s96, 0x1000
	v_mfma_f32_16x16x32_bf16 v[40:43], v[204:207], v[158:161], v[40:43]
	v_mfma_f32_16x16x32_bf16 v[36:39], v[204:207], v[162:165], v[36:39]
	global_load_lds_dwordx4 v[226:227], off
	v_lshl_add_u64 v[226:227], v[226:227], 0, 64
	s_waitcnt lgkmcnt(1)
	v_mfma_f32_16x16x32_bf16 v[32:35], v[208:211], v[148:151], v[32:35]
	s_mov_b32 m0, s17
	s_add_i32 s17, s17, 0x1000
	v_mfma_f32_16x16x32_bf16 v[28:31], v[208:211], v[154:157], v[28:31]
	v_mfma_f32_16x16x32_bf16 v[24:27], v[208:211], v[158:161], v[24:27]
	global_load_lds_dwordx4 v[228:229], off
	v_lshl_add_u64 v[228:229], v[228:229], 0, 64
	s_mov_b32 m0, s96
	s_add_i32 s96, s96, 0x1000
	v_mfma_f32_16x16x32_bf16 v[20:23], v[208:211], v[162:165], v[20:23]
	s_waitcnt lgkmcnt(0)
	v_mfma_f32_16x16x32_bf16 v[16:19], v[212:215], v[148:151], v[16:19]
	global_load_lds_dwordx4 v[228:229], off
	v_lshl_add_u64 v[228:229], v[228:229], 0, 64
	v_mfma_f32_16x16x32_bf16 v[12:15], v[212:215], v[154:157], v[12:15]
	v_mfma_f32_16x16x32_bf16 v[8:11], v[212:215], v[158:161], v[8:11]
	v_mfma_f32_16x16x32_bf16 v[4:7], v[212:215], v[162:165], v[4:7]
	s_setprio 0
	s_add_i32 s10, s10, 0x6000
	s_cmp_lg_u32 s10, 0x12000
	s_cselect_b32 s10, s10, 0
	s_sub_i32 s11, s11, 0x6000
	s_cmp_lt_i32 s11, 0
	s_cselect_b32 s11, 0xc000, s11
	s_add_i32 s3, s3, 1
	s_cmp_lt_i32 s3, 43
	s_waitcnt vmcnt(1)
	s_barrier
	s_cbranch_scc1 .Lg3_loop_926
	v_add_u32_e32 v216, s10, v146
	v_add_u32_e32 v217, s10, v2
	ds_read_b128 v[148:151], v217 offset:16384
	ds_read_b128 v[166:169], v216
	ds_read_b128 v[154:157], v217 offset:17408
	ds_read_b128 v[158:161], v217 offset:18432
	ds_read_b128 v[162:165], v217 offset:19456
	ds_read_b128 v[170:173], v216 offset:1024
	ds_read_b128 v[174:177], v216 offset:2048
	ds_read_b128 v[192:195], v216 offset:3072
	ds_read_b128 v[196:199], v216 offset:4096
	ds_read_b128 v[204:207], v216 offset:5120
	ds_read_b128 v[208:211], v216 offset:6144
	ds_read_b128 v[212:215], v216 offset:7168
	s_setprio 1
	s_waitcnt lgkmcnt(10)
	v_mfma_f32_16x16x32_bf16 v[128:131], v[166:169], v[148:151], v[128:131]
	s_waitcnt lgkmcnt(9)
	v_mfma_f32_16x16x32_bf16 v[124:127], v[166:169], v[154:157], v[124:127]
	s_waitcnt lgkmcnt(8)
	v_mfma_f32_16x16x32_bf16 v[120:123], v[166:169], v[158:161], v[120:123]
	s_waitcnt lgkmcnt(7)
	v_mfma_f32_16x16x32_bf16 v[116:119], v[166:169], v[162:165], v[116:119]
	s_waitcnt lgkmcnt(6)
	v_mfma_f32_16x16x32_bf16 v[112:115], v[170:173], v[148:151], v[112:115]
	v_mfma_f32_16x16x32_bf16 v[108:111], v[170:173], v[154:157], v[108:111]
	v_mfma_f32_16x16x32_bf16 v[104:107], v[170:173], v[158:161], v[104:107]
	v_mfma_f32_16x16x32_bf16 v[100:103], v[170:173], v[162:165], v[100:103]
	s_waitcnt lgkmcnt(5)
	v_mfma_f32_16x16x32_bf16 v[96:99], v[174:177], v[148:151], v[96:99]
	v_mfma_f32_16x16x32_bf16 v[92:95], v[174:177], v[154:157], v[92:95]
	v_mfma_f32_16x16x32_bf16 v[88:91], v[174:177], v[158:161], v[88:91]
	v_mfma_f32_16x16x32_bf16 v[84:87], v[174:177], v[162:165], v[84:87]
	s_waitcnt lgkmcnt(4)
	v_mfma_f32_16x16x32_bf16 v[80:83], v[192:195], v[148:151], v[80:83]
	v_mfma_f32_16x16x32_bf16 v[76:79], v[192:195], v[154:157], v[76:79]
	v_mfma_f32_16x16x32_bf16 v[72:75], v[192:195], v[158:161], v[72:75]
	v_mfma_f32_16x16x32_bf16 v[68:71], v[192:195], v[162:165], v[68:71]
	s_waitcnt lgkmcnt(3)
	v_mfma_f32_16x16x32_bf16 v[64:67], v[196:199], v[148:151], v[64:67]
	v_mfma_f32_16x16x32_bf16 v[60:63], v[196:199], v[154:157], v[60:63]
	v_mfma_f32_16x16x32_bf16 v[56:59], v[196:199], v[158:161], v[56:59]
	v_mfma_f32_16x16x32_bf16 v[52:55], v[196:199], v[162:165], v[52:55]
	s_waitcnt lgkmcnt(2)
	v_mfma_f32_16x16x32_bf16 v[48:51], v[204:207], v[148:151], v[48:51]
	v_mfma_f32_16x16x32_bf16 v[44:47], v[204:207], v[154:157], v[44:47]
	v_mfma_f32_16x16x32_bf16 v[40:43], v[204:207], v[158:161], v[40:43]
	v_mfma_f32_16x16x32_bf16 v[36:39], v[204:207], v[162:165], v[36:39]
	s_waitcnt lgkmcnt(1)
	v_mfma_f32_16x16x32_bf16 v[32:35], v[208:211], v[148:151], v[32:35]
	v_mfma_f32_16x16x32_bf16 v[28:31], v[208:211], v[154:157], v[28:31]
	v_mfma_f32_16x16x32_bf16 v[24:27], v[208:211], v[158:161], v[24:27]
	v_mfma_f32_16x16x32_bf16 v[20:23], v[208:211], v[162:165], v[20:23]
	s_waitcnt lgkmcnt(0)
	v_mfma_f32_16x16x32_bf16 v[16:19], v[212:215], v[148:151], v[16:19]
	v_mfma_f32_16x16x32_bf16 v[12:15], v[212:215], v[154:157], v[12:15]
	v_mfma_f32_16x16x32_bf16 v[8:11], v[212:215], v[158:161], v[8:11]
	v_mfma_f32_16x16x32_bf16 v[4:7], v[212:215], v[162:165], v[4:7]
	s_setprio 0
	s_add_i32 s10, s10, 0x6000
	s_cmp_lg_u32 s10, 0x12000
	s_cselect_b32 s10, s10, 0
	s_waitcnt vmcnt(0)
	s_barrier
; DEVI f32x4 mfma16(bf16x8 a, bf16x8 b, f32x4 c) { return __builtin_amdgcn_mfma_f32_16x16x32_bf16(a, b, c, 0, 0, 0); }
; DEVI void gemm_core3(f32x4 (&acc)[8][4], const bf* __restrict__ A, int lda, const bf* __restrict__ Bt, int ldb, int K, char* smem) {
;     ...
; #pragma unroll
;     for (int n = 0; n < 4; ++n) bfr[n] = *reinterpret_cast<const bf16x8*>(bbase + so + n * 16 * 64);
; #pragma unroll
;     for (int m = 0; m < 8; ++m) af[m] = *reinterpret_cast<const bf16x8*>(abase + so + m * 16 * 64);
; #pragma unroll
;     for (int i = 0; i < 4; ++i) glds16(Ap + i * sa + k1, dbase + sn + i * 4096);
; #pragma unroll
;     for (int i = 0; i < 2; ++i) glds16(Bp + i * sb + k1, dbase + sn + ASZ + i * 4096);
;     __builtin_amdgcn_s_setprio(1);
; #pragma unroll
;     for (int m = 0; m < 8; ++m)
; #pragma unroll
;       for (int n = 0; n < 4; ++n) acc[m][n] = mfma16(af[m], bfr[n], acc[m][n]);
;     __builtin_amdgcn_s_setprio(0);
;     __syncthreads();
;   }
; DEVI void plain_tile256(const bf* A, int lda, const bf* Wt, int K, bf* C, int ldc, long row0, int n0, char* smem) {
;     ...
;   bf* tl = reinterpret_cast<bf*>(smem);
; #pragma unroll
;   for (int m = 0; m < 8; ++m)
; #pragma unroll
;     for (int n = 0; n < 4; ++n) {
;       const int cl = wc * 64 + n * 16 + l15;
; #pragma unroll
;       for (int j = 0; j < 4; ++j) tl[(wr * 128 + m * 16 + quad * 4 + j) * 136 + cl] = f2bf(acc[m][n][j]);
;     }
;   __syncthreads();
	v_add_u32_e32 v216, s10, v146
	v_add_u32_e32 v217, s10, v2
	ds_read_b128 v[148:151], v217 offset:16384
	ds_read_b128 v[166:169], v216
	ds_read_b128 v[154:157], v217 offset:17408
	ds_read_b128 v[158:161], v217 offset:18432
	ds_read_b128 v[162:165], v217 offset:19456
	ds_read_b128 v[170:173], v216 offset:1024
	ds_read_b128 v[174:177], v216 offset:2048
	ds_read_b128 v[192:195], v216 offset:3072
	ds_read_b128 v[196:199], v216 offset:4096
	ds_read_b128 v[204:207], v216 offset:5120
	ds_read_b128 v[208:211], v216 offset:6144
	ds_read_b128 v[212:215], v216 offset:7168
	s_setprio 1
	s_waitcnt lgkmcnt(10)
	v_mfma_f32_16x16x32_bf16 v[128:131], v[166:169], v[148:151], v[128:131]
	s_waitcnt lgkmcnt(9)
	v_mfma_f32_16x16x32_bf16 v[124:127], v[166:169], v[154:157], v[124:127]
	s_waitcnt lgkmcnt(8)
	v_mfma_f32_16x16x32_bf16 v[120:123], v[166:169], v[158:161], v[120:123]
	s_waitcnt lgkmcnt(7)
	v_mfma_f32_16x16x32_bf16 v[116:119], v[166:169], v[162:165], v[116:119]
	s_waitcnt lgkmcnt(6)
	v_mfma_f32_16x16x32_bf16 v[112:115], v[170:173], v[148:151], v[112:115]
	v_mfma_f32_16x16x32_bf16 v[108:111], v[170:173], v[154:157], v[108:111]
	v_mfma_f32_16x16x32_bf16 v[104:107], v[170:173], v[158:161], v[104:107]
	v_mfma_f32_16x16x32_bf16 v[100:103], v[170:173], v[162:165], v[100:103]
	s_waitcnt lgkmcnt(5)
	v_mfma_f32_16x16x32_bf16 v[96:99], v[174:177], v[148:151], v[96:99]
	v_mfma_f32_16x16x32_bf16 v[92:95], v[174:177], v[154:157], v[92:95]
	v_mfma_f32_16x16x32_bf16 v[88:91], v[174:177], v[158:161], v[88:91]
	v_mfma_f32_16x16x32_bf16 v[84:87], v[174:177], v[162:165], v[84:87]
	s_waitcnt lgkmcnt(4)
	v_mfma_f32_16x16x32_bf16 v[80:83], v[192:195], v[148:151], v[80:83]
	v_mfma_f32_16x16x32_bf16 v[76:79], v[192:195], v[154:157], v[76:79]
	v_mfma_f32_16x16x32_bf16 v[72:75], v[192:195], v[158:161], v[72:75]
	v_mfma_f32_16x16x32_bf16 v[68:71], v[192:195], v[162:165], v[68:71]
	s_waitcnt lgkmcnt(3)
	v_mfma_f32_16x16x32_bf16 v[64:67], v[196:199], v[148:151], v[64:67]
	v_mfma_f32_16x16x32_bf16 v[60:63], v[196:199], v[154:157], v[60:63]
	v_mfma_f32_16x16x32_bf16 v[56:59], v[196:199], v[158:161], v[56:59]
	v_mfma_f32_16x16x32_bf16 v[52:55], v[196:199], v[162:165], v[52:55]
	s_waitcnt lgkmcnt(2)
	v_mfma_f32_16x16x32_bf16 v[48:51], v[204:207], v[148:151], v[48:51]
	v_mfma_f32_16x16x32_bf16 v[44:47], v[204:207], v[154:157], v[44:47]
	v_mfma_f32_16x16x32_bf16 v[40:43], v[204:207], v[158:161], v[40:43]
	v_mfma_f32_16x16x32_bf16 v[36:39], v[204:207], v[162:165], v[36:39]
	s_waitcnt lgkmcnt(1)
	v_mfma_f32_16x16x32_bf16 v[32:35], v[208:211], v[148:151], v[32:35]
	v_mfma_f32_16x16x32_bf16 v[28:31], v[208:211], v[154:157], v[28:31]
	v_mfma_f32_16x16x32_bf16 v[24:27], v[208:211], v[158:161], v[24:27]
	v_mfma_f32_16x16x32_bf16 v[20:23], v[208:211], v[162:165], v[20:23]
	s_waitcnt lgkmcnt(0)
	v_mfma_f32_16x16x32_bf16 v[16:19], v[212:215], v[148:151], v[16:19]
	v_mfma_f32_16x16x32_bf16 v[12:15], v[212:215], v[154:157], v[12:15]
	v_mfma_f32_16x16x32_bf16 v[8:11], v[212:215], v[158:161], v[8:11]
	v_mfma_f32_16x16x32_bf16 v[4:7], v[212:215], v[162:165], v[4:7]
	s_setprio 0
	s_add_i32 s10, s10, 0x6000
	s_cmp_lg_u32 s10, 0x12000
	s_cselect_b32 s10, s10, 0
	s_waitcnt vmcnt(0)
	s_barrier
	s_setprio 3
	v_and_b32_e32 v2, 0x4f, v1
	v_and_b32_e32 v132, 0xfffff80, v1
	v_lshrrev_b32_e32 v1, 2, v1
	v_and_or_b32 v1, v1, 12, v132
	v_mul_lo_u32 v1, v1, s16
	v_lshl_add_u32 v1, v2, 1, v1
	v_cvt_pk_bf16_f32 v2, v129, s0
	ds_write_b16 v1, v2 offset:272
	v_cvt_pk_bf16_f32 v2, v130, s0
	ds_write_b16 v1, v2 offset:544
	v_cvt_pk_bf16_f32 v2, v131, s0
	ds_write_b16 v1, v2 offset:816
	v_cvt_pk_bf16_f32 v2, v124, s0
	ds_write_b16 v1, v2 offset:32
	v_cvt_pk_bf16_f32 v2, v125, s0
	ds_write_b16 v1, v2 offset:304
	v_cvt_pk_bf16_f32 v2, v126, s0
	ds_write_b16 v1, v2 offset:576
	v_cvt_pk_bf16_f32 v2, v127, s0
	ds_write_b16 v1, v2 offset:848
	v_cvt_pk_bf16_f32 v2, v120, s0
	ds_write_b16 v1, v2 offset:64
	v_cvt_pk_bf16_f32 v2, v121, s0
	ds_write_b16 v1, v2 offset:336
	v_cvt_pk_bf16_f32 v2, v122, s0
	ds_write_b16 v1, v2 offset:608
	v_cvt_pk_bf16_f32 v2, v123, s0
	ds_write_b16 v1, v2 offset:880
	v_cvt_pk_bf16_f32 v2, v116, s0
	ds_write_b16 v1, v2 offset:96
	v_cvt_pk_bf16_f32 v2, v117, s0
	ds_write_b16 v1, v2 offset:368
	v_cvt_pk_bf16_f32 v2, v118, s0
	ds_write_b16 v1, v2 offset:640
	v_cvt_pk_bf16_f32 v2, v119, s0
	ds_write_b16 v1, v2 offset:912
	v_cvt_pk_bf16_f32 v2, v112, s0
	ds_write_b16 v1, v2 offset:4352
	v_cvt_pk_bf16_f32 v2, v113, s0
	ds_write_b16 v1, v2 offset:4624
	v_cvt_pk_bf16_f32 v2, v114, s0
	ds_write_b16 v1, v2 offset:4896
	v_cvt_pk_bf16_f32 v2, v115, s0
	ds_write_b16 v1, v2 offset:5168
	v_cvt_pk_bf16_f32 v2, v108, s0
	ds_write_b16 v1, v2 offset:4384
	v_cvt_pk_bf16_f32 v2, v109, s0
	ds_write_b16 v1, v2 offset:4656
	v_cvt_pk_bf16_f32 v2, v110, s0
	ds_write_b16 v1, v2 offset:4928
	v_cvt_pk_bf16_f32 v2, v111, s0
	ds_write_b16 v1, v2 offset:5200
	v_cvt_pk_bf16_f32 v2, v104, s0
	ds_write_b16 v1, v2 offset:4416
	v_cvt_pk_bf16_f32 v2, v105, s0
	ds_write_b16 v1, v2 offset:4688
	v_cvt_pk_bf16_f32 v2, v106, s0
	ds_write_b16 v1, v2 offset:4960
	v_cvt_pk_bf16_f32 v2, v107, s0
	ds_write_b16 v1, v2 offset:5232
	v_cvt_pk_bf16_f32 v2, v100, s0
	ds_write_b16 v1, v2 offset:4448
	v_cvt_pk_bf16_f32 v2, v101, s0
	ds_write_b16 v1, v2 offset:4720
	v_cvt_pk_bf16_f32 v2, v102, s0
	ds_write_b16 v1, v2 offset:4992
	v_cvt_pk_bf16_f32 v2, v103, s0
	ds_write_b16 v1, v2 offset:5264
	v_cvt_pk_bf16_f32 v2, v96, s0
	ds_write_b16 v1, v2 offset:8704
	v_cvt_pk_bf16_f32 v2, v97, s0
	ds_write_b16 v1, v2 offset:8976
	v_cvt_pk_bf16_f32 v2, v98, s0
	ds_write_b16 v1, v2 offset:9248
	v_cvt_pk_bf16_f32 v2, v99, s0
	ds_write_b16 v1, v2 offset:9520
; DEVI void plain_tile256(const bf* A, int lda, const bf* Wt, int K, bf* C, int ldc, long row0, int n0, char* smem) {
;     ...
;   bf* tl = reinterpret_cast<bf*>(smem);
; #pragma unroll
;   for (int m = 0; m < 8; ++m)
; #pragma unroll
;     for (int n = 0; n < 4; ++n) {
;       const int cl = wc * 64 + n * 16 + l15;
; #pragma unroll
;       for (int j = 0; j < 4; ++j) tl[(wr * 128 + m * 16 + quad * 4 + j) * 136 + cl] = f2bf(acc[m][n][j]);
;     }
;   __syncthreads();
	v_cvt_pk_bf16_f32 v2, v92, s0
	ds_write_b16 v1, v2 offset:8736
	v_cvt_pk_bf16_f32 v2, v93, s0
	ds_write_b16 v1, v2 offset:9008
	v_cvt_pk_bf16_f32 v2, v94, s0
	ds_write_b16 v1, v2 offset:9280
	v_cvt_pk_bf16_f32 v2, v95, s0
	ds_write_b16 v1, v2 offset:9552
	v_cvt_pk_bf16_f32 v2, v88, s0
	ds_write_b16 v1, v2 offset:8768
	v_cvt_pk_bf16_f32 v2, v89, s0
	ds_write_b16 v1, v2 offset:9040
	v_cvt_pk_bf16_f32 v2, v90, s0
	ds_write_b16 v1, v2 offset:9312
	v_cvt_pk_bf16_f32 v2, v91, s0
	ds_write_b16 v1, v2 offset:9584
	v_cvt_pk_bf16_f32 v2, v84, s0
	ds_write_b16 v1, v2 offset:8800
	v_cvt_pk_bf16_f32 v2, v85, s0
	ds_write_b16 v1, v2 offset:9072
	v_cvt_pk_bf16_f32 v2, v86, s0
	ds_write_b16 v1, v2 offset:9344
	v_cvt_pk_bf16_f32 v2, v87, s0
	ds_write_b16 v1, v2 offset:9616
	v_cvt_pk_bf16_f32 v2, v80, s0
	ds_write_b16 v1, v2 offset:13056
	v_cvt_pk_bf16_f32 v2, v81, s0
	ds_write_b16 v1, v2 offset:13328
	v_cvt_pk_bf16_f32 v2, v82, s0
	ds_write_b16 v1, v2 offset:13600
	v_cvt_pk_bf16_f32 v2, v83, s0
	ds_write_b16 v1, v2 offset:13872
	v_cvt_pk_bf16_f32 v2, v76, s0
	ds_write_b16 v1, v2 offset:13088
	v_cvt_pk_bf16_f32 v2, v77, s0
	ds_write_b16 v1, v2 offset:13360
	v_cvt_pk_bf16_f32 v2, v78, s0
	ds_write_b16 v1, v2 offset:13632
	v_cvt_pk_bf16_f32 v2, v79, s0
	ds_write_b16 v1, v2 offset:13904
	v_cvt_pk_bf16_f32 v2, v72, s0
	ds_write_b16 v1, v2 offset:13120
	v_cvt_pk_bf16_f32 v2, v73, s0
	ds_write_b16 v1, v2 offset:13392
	v_cvt_pk_bf16_f32 v2, v74, s0
	ds_write_b16 v1, v2 offset:13664
	v_cvt_pk_bf16_f32 v2, v75, s0
	ds_write_b16 v1, v2 offset:13936
	v_cvt_pk_bf16_f32 v2, v68, s0
	ds_write_b16 v1, v2 offset:13152
	v_cvt_pk_bf16_f32 v2, v69, s0
	ds_write_b16 v1, v2 offset:13424
	v_cvt_pk_bf16_f32 v2, v70, s0
	ds_write_b16 v1, v2 offset:13696
	v_cvt_pk_bf16_f32 v2, v71, s0
	ds_write_b16 v1, v2 offset:13968
	v_cvt_pk_bf16_f32 v2, v64, s0
	ds_write_b16 v1, v2 offset:17408
	v_cvt_pk_bf16_f32 v2, v65, s0
	ds_write_b16 v1, v2 offset:17680
	v_cvt_pk_bf16_f32 v2, v66, s0
	ds_write_b16 v1, v2 offset:17952
	v_cvt_pk_bf16_f32 v2, v67, s0
	ds_write_b16 v1, v2 offset:18224
	v_cvt_pk_bf16_f32 v2, v60, s0
	ds_write_b16 v1, v2 offset:17440
	v_cvt_pk_bf16_f32 v2, v61, s0
	ds_write_b16 v1, v2 offset:17712
	v_cvt_pk_bf16_f32 v2, v62, s0
	ds_write_b16 v1, v2 offset:17984
	v_cvt_pk_bf16_f32 v2, v63, s0
	ds_write_b16 v1, v2 offset:18256
	v_cvt_pk_bf16_f32 v2, v56, s0
	ds_write_b16 v1, v2 offset:17472
	v_cvt_pk_bf16_f32 v2, v57, s0
	ds_write_b16 v1, v2 offset:17744
	v_cvt_pk_bf16_f32 v2, v58, s0
	ds_write_b16 v1, v2 offset:18016
	v_cvt_pk_bf16_f32 v2, v59, s0
	ds_write_b16 v1, v2 offset:18288
	v_cvt_pk_bf16_f32 v2, v52, s0
	ds_write_b16 v1, v2 offset:17504
	v_cvt_pk_bf16_f32 v2, v53, s0
	ds_write_b16 v1, v2 offset:17776
	v_cvt_pk_bf16_f32 v2, v54, s0
	ds_write_b16 v1, v2 offset:18048
	v_cvt_pk_bf16_f32 v2, v55, s0
	ds_write_b16 v1, v2 offset:18320
	v_cvt_pk_bf16_f32 v2, v48, s0
	ds_write_b16 v1, v2 offset:21760
	v_cvt_pk_bf16_f32 v2, v49, s0
	ds_write_b16 v1, v2 offset:22032
	v_cvt_pk_bf16_f32 v2, v50, s0
	ds_write_b16 v1, v2 offset:22304
	v_cvt_pk_bf16_f32 v2, v51, s0
	ds_write_b16 v1, v2 offset:22576
	v_cvt_pk_bf16_f32 v2, v44, s0
	ds_write_b16 v1, v2 offset:21792
	v_cvt_pk_bf16_f32 v2, v45, s0
	ds_write_b16 v1, v2 offset:22064
	v_cvt_pk_bf16_f32 v2, v46, s0
	ds_write_b16 v1, v2 offset:22336
	v_cvt_pk_bf16_f32 v2, v47, s0
	ds_write_b16 v1, v2 offset:22608
	v_cvt_pk_bf16_f32 v2, v40, s0
	ds_write_b16 v1, v2 offset:21824
	v_cvt_pk_bf16_f32 v2, v41, s0
	ds_write_b16 v1, v2 offset:22096
	v_cvt_pk_bf16_f32 v2, v42, s0
	ds_write_b16 v1, v2 offset:22368
	v_cvt_pk_bf16_f32 v2, v43, s0
	ds_write_b16 v1, v2 offset:22640
	v_cvt_pk_bf16_f32 v2, v36, s0
	ds_write_b16 v1, v2 offset:21856
	v_cvt_pk_bf16_f32 v2, v37, s0
	ds_write_b16 v1, v2 offset:22128
	v_cvt_pk_bf16_f32 v2, v38, s0
	ds_write_b16 v1, v2 offset:22400
	v_cvt_pk_bf16_f32 v2, v39, s0
	ds_write_b16 v1, v2 offset:22672
	v_cvt_pk_bf16_f32 v2, v32, s0
	ds_write_b16 v1, v2 offset:26112
	v_cvt_pk_bf16_f32 v2, v33, s0
	ds_write_b16 v1, v2 offset:26384
	v_cvt_pk_bf16_f32 v2, v34, s0
	ds_write_b16 v1, v2 offset:26656
	v_cvt_pk_bf16_f32 v2, v35, s0
	ds_write_b16 v1, v2 offset:26928
	v_cvt_pk_bf16_f32 v2, v28, s0
	ds_write_b16 v1, v2 offset:26144
	v_cvt_pk_bf16_f32 v2, v29, s0
	ds_write_b16 v1, v2 offset:26416
	v_cvt_pk_bf16_f32 v2, v30, s0
	ds_write_b16 v1, v2 offset:26688
	v_cvt_pk_bf16_f32 v2, v31, s0
	ds_write_b16 v1, v2 offset:26960
	v_cvt_pk_bf16_f32 v2, v24, s0
	ds_write_b16 v1, v2 offset:26176
	v_cvt_pk_bf16_f32 v2, v25, s0
	ds_write_b16 v1, v2 offset:26448
	v_cvt_pk_bf16_f32 v2, v26, s0
	ds_write_b16 v1, v2 offset:26720
	v_cvt_pk_bf16_f32 v2, v27, s0
	ds_write_b16 v1, v2 offset:26992
	v_cvt_pk_bf16_f32 v2, v20, s0
	ds_write_b16 v1, v2 offset:26208
	v_cvt_pk_bf16_f32 v2, v21, s0
	ds_write_b16 v1, v2 offset:26480
	v_cvt_pk_bf16_f32 v2, v22, s0
	ds_write_b16 v1, v2 offset:26752
	v_cvt_pk_bf16_f32 v2, v23, s0
	ds_write_b16 v1, v2 offset:27024
	v_cvt_pk_bf16_f32 v2, v16, s0
	ds_write_b16 v1, v2 offset:30464
	v_cvt_pk_bf16_f32 v2, v17, s0
	ds_write_b16 v1, v2 offset:30736
	v_cvt_pk_bf16_f32 v2, v18, s0
	ds_write_b16 v1, v2 offset:31008
	v_cvt_pk_bf16_f32 v2, v19, s0
	ds_write_b16 v1, v2 offset:31280
	v_cvt_pk_bf16_f32 v2, v12, s0
	ds_write_b16 v1, v2 offset:30496
	v_cvt_pk_bf16_f32 v2, v13, s0
	ds_write_b16 v1, v2 offset:30768
	v_cvt_pk_bf16_f32 v2, v14, s0
	ds_write_b16 v1, v2 offset:31040
	v_cvt_pk_bf16_f32 v2, v15, s0
	ds_write_b16 v1, v2 offset:31312
	v_cvt_pk_bf16_f32 v2, v8, s0
	ds_write_b16 v1, v2 offset:30528
	v_cvt_pk_bf16_f32 v2, v9, s0
	ds_write_b16 v1, v2 offset:30800
	v_cvt_pk_bf16_f32 v2, v10, s0
	ds_write_b16 v1, v2 offset:31072
	v_cvt_pk_bf16_f32 v2, v11, s0
	ds_write_b16 v1, v2 offset:31344
	v_cvt_pk_bf16_f32 v2, v4, s0
	ds_write_b16 v1, v2 offset:30560
	v_cvt_pk_bf16_f32 v2, v5, s0
	ds_write_b16 v1, v2 offset:30832
	v_cvt_pk_bf16_f32 v2, v6, s0
	v_cvt_pk_bf16_f32 v128, v128, s0
	ds_write_b16 v1, v2 offset:31104
	v_cvt_pk_bf16_f32 v2, v7, s0
	ds_write_b16 v1, v128
	ds_write_b16 v1, v2 offset:31376
	v_mov_b32_e32 v1, v178
	s_waitcnt lgkmcnt(0)
	s_barrier
; DEVI int get_tid() { int t = threadIdx.x; asm volatile("" : "+v"(t)); return t; }
; template <int BN>
; DEVI void tile_store256(const char* smem, bf* __restrict__ C, long ldc, long row0, int col0) {
;   constexpr int LDT = BN + 8;
;   constexpr int CPR = BN / 8;
;   const int tid = get_tid();
; #pragma unroll
;   for (int i = 0; i < CPR; ++i) {
;     const int q = tid + 256 * i;
;     const int r = q / CPR, c = q - r * CPR;
;     u32x4 v = *reinterpret_cast<const u32x4*>(smem + (r * LDT + c * 8) * 2);
;     *reinterpret_cast<u32x4*>(C + (row0 + r) * ldc + col0 + c * 8) = v;
;   }
; }
	v_readlane_b32 s56, v251, 58
	v_ashrrev_i32_e32 v2, 31, v1
	v_lshrrev_b32_e32 v2, 28, v2
	v_add_u32_e32 v2, v1, v2
	v_ashrrev_i32_e32 v8, 4, v2
	s_lshl_b64 s[10:11], s[34:35], 1
	v_readlane_b32 s60, v251, 62
	v_lshlrev_b32_e32 v4, 7, v8
	v_lshlrev_b32_e32 v5, 3, v1
	v_ashrrev_i32_e32 v9, 31, v8
	v_readlane_b32 s61, v251, 63
	s_add_u32 s10, s60, s10
	v_mul_lo_u32 v2, v8, s38
	v_sub_u32_e32 v10, v5, v4
	v_lshl_add_u64 v[8:9], s[12:13], 0, v[8:9]
	s_addc_u32 s11, s61, s11
	v_add_lshl_u32 v2, v10, v2, 1
	v_lshlrev_b64 v[8:9], 11, v[8:9]
	ds_read_b128 v[4:7], v2
	v_lshl_add_u64 v[8:9], s[10:11], 0, v[8:9]
	v_ashrrev_i32_e32 v11, 31, v10
	v_add_u32_e32 v2, 0x100, v1
	v_lshl_add_u64 v[12:13], v[10:11], 1, v[8:9]
	v_ashrrev_i32_e32 v8, 31, v2
	v_lshrrev_b32_e32 v8, 28, v8
	v_add_u32_e32 v8, v2, v8
	v_ashrrev_i32_e32 v14, 4, v8
	v_lshlrev_b32_e32 v9, 7, v14
	v_lshlrev_b32_e32 v2, 3, v2
	v_mul_lo_u32 v8, v14, s38
	v_sub_u32_e32 v16, v2, v9
	v_add_lshl_u32 v2, v16, v8, 1
	ds_read_b128 v[8:11], v2
	v_ashrrev_i32_e32 v15, 31, v14
	s_waitcnt lgkmcnt(1)
	global_store_dwordx4 v[12:13], v[4:7], off
	v_ashrrev_i32_e32 v17, 31, v16
	v_add_u32_e32 v2, 0x200, v1
	v_lshl_add_u64 v[4:5], s[12:13], 0, v[14:15]
	v_lshlrev_b64 v[4:5], 11, v[4:5]
	v_lshl_add_u64 v[4:5], s[10:11], 0, v[4:5]
	v_lshl_add_u64 v[4:5], v[16:17], 1, v[4:5]
	s_waitcnt lgkmcnt(0)
	global_store_dwordx4 v[4:5], v[8:11], off
	v_ashrrev_i32_e32 v4, 31, v2
	v_lshrrev_b32_e32 v4, 28, v4
	v_add_u32_e32 v4, v2, v4
	v_ashrrev_i32_e32 v8, 4, v4
	v_lshlrev_b32_e32 v5, 7, v8
	v_lshlrev_b32_e32 v2, 3, v2
	v_ashrrev_i32_e32 v9, 31, v8
	v_mul_lo_u32 v4, v8, s38
	v_sub_u32_e32 v10, v2, v5
	v_lshl_add_u64 v[8:9], s[12:13], 0, v[8:9]
	v_add_lshl_u32 v2, v10, v4, 1
	v_lshlrev_b64 v[8:9], 11, v[8:9]
	ds_read_b128 v[4:7], v2
	v_lshl_add_u64 v[8:9], s[10:11], 0, v[8:9]
	v_ashrrev_i32_e32 v11, 31, v10
	v_add_u32_e32 v2, 0x300, v1
	v_lshl_add_u64 v[12:13], v[10:11], 1, v[8:9]
	v_ashrrev_i32_e32 v8, 31, v2
	v_lshrrev_b32_e32 v8, 28, v8
	v_add_u32_e32 v8, v2, v8
	v_ashrrev_i32_e32 v14, 4, v8
	v_lshlrev_b32_e32 v9, 7, v14
	v_lshlrev_b32_e32 v2, 3, v2
	v_mul_lo_u32 v8, v14, s38
	v_sub_u32_e32 v16, v2, v9
	v_add_lshl_u32 v2, v16, v8, 1
	ds_read_b128 v[8:11], v2
	v_ashrrev_i32_e32 v15, 31, v14
	s_waitcnt lgkmcnt(1)
	global_store_dwordx4 v[12:13], v[4:7], off
	v_ashrrev_i32_e32 v17, 31, v16
	v_add_u32_e32 v2, 0x400, v1
	v_lshl_add_u64 v[4:5], s[12:13], 0, v[14:15]
	v_lshlrev_b64 v[4:5], 11, v[4:5]
	v_lshl_add_u64 v[4:5], s[10:11], 0, v[4:5]
	v_lshl_add_u64 v[4:5], v[16:17], 1, v[4:5]
	s_waitcnt lgkmcnt(0)
	global_store_dwordx4 v[4:5], v[8:11], off
	v_ashrrev_i32_e32 v4, 31, v2
	v_lshrrev_b32_e32 v4, 28, v4
	v_add_u32_e32 v4, v2, v4
	v_ashrrev_i32_e32 v8, 4, v4
	v_lshlrev_b32_e32 v5, 7, v8
	v_lshlrev_b32_e32 v2, 3, v2
	v_ashrrev_i32_e32 v9, 31, v8
	v_mul_lo_u32 v4, v8, s38
	v_sub_u32_e32 v10, v2, v5
	v_lshl_add_u64 v[8:9], s[12:13], 0, v[8:9]
	v_add_lshl_u32 v2, v10, v4, 1
	v_lshlrev_b64 v[8:9], 11, v[8:9]
	ds_read_b128 v[4:7], v2
	v_lshl_add_u64 v[8:9], s[10:11], 0, v[8:9]
	v_ashrrev_i32_e32 v11, 31, v10
	v_add_u32_e32 v2, 0x500, v1
	v_lshl_add_u64 v[12:13], v[10:11], 1, v[8:9]
	v_ashrrev_i32_e32 v8, 31, v2
	v_lshrrev_b32_e32 v8, 28, v8
	v_add_u32_e32 v8, v2, v8
	v_ashrrev_i32_e32 v14, 4, v8
	v_lshlrev_b32_e32 v9, 7, v14
	v_lshlrev_b32_e32 v2, 3, v2
	v_mul_lo_u32 v8, v14, s38
	v_sub_u32_e32 v16, v2, v9
	v_add_lshl_u32 v2, v16, v8, 1
	ds_read_b128 v[8:11], v2
	v_ashrrev_i32_e32 v15, 31, v14
	s_waitcnt lgkmcnt(1)
	global_store_dwordx4 v[12:13], v[4:7], off
	v_ashrrev_i32_e32 v17, 31, v16
	v_add_u32_e32 v2, 0x600, v1
	v_lshl_add_u64 v[4:5], s[12:13], 0, v[14:15]
	v_lshlrev_b64 v[4:5], 11, v[4:5]
	v_lshl_add_u64 v[4:5], s[10:11], 0, v[4:5]
	v_lshl_add_u64 v[4:5], v[16:17], 1, v[4:5]
	s_waitcnt lgkmcnt(0)
	global_store_dwordx4 v[4:5], v[8:11], off
	v_ashrrev_i32_e32 v4, 31, v2
	v_lshrrev_b32_e32 v4, 28, v4
	v_add_u32_e32 v4, v2, v4
	v_ashrrev_i32_e32 v8, 4, v4
	v_lshlrev_b32_e32 v5, 7, v8
	v_lshlrev_b32_e32 v2, 3, v2
	v_ashrrev_i32_e32 v9, 31, v8
	v_mul_lo_u32 v4, v8, s38
	v_sub_u32_e32 v10, v2, v5
	v_lshl_add_u64 v[8:9], s[12:13], 0, v[8:9]
	v_add_lshl_u32 v2, v10, v4, 1
	v_lshlrev_b64 v[8:9], 11, v[8:9]
	ds_read_b128 v[4:7], v2
	v_lshl_add_u64 v[8:9], s[10:11], 0, v[8:9]
	v_ashrrev_i32_e32 v11, 31, v10
	v_add_u32_e32 v2, 0x700, v1
	v_lshl_add_u64 v[12:13], v[10:11], 1, v[8:9]
	v_ashrrev_i32_e32 v8, 31, v2
	v_lshrrev_b32_e32 v8, 28, v8
	v_add_u32_e32 v8, v2, v8
	v_ashrrev_i32_e32 v14, 4, v8
	v_lshlrev_b32_e32 v9, 7, v14
	v_lshlrev_b32_e32 v2, 3, v2
	v_mul_lo_u32 v8, v14, s38
	v_sub_u32_e32 v16, v2, v9
	v_add_lshl_u32 v2, v16, v8, 1
	ds_read_b128 v[8:11], v2
	v_ashrrev_i32_e32 v15, 31, v14
	s_waitcnt lgkmcnt(1)
	global_store_dwordx4 v[12:13], v[4:7], off
	v_ashrrev_i32_e32 v17, 31, v16
	v_add_u32_e32 v2, 0x800, v1
	v_lshl_add_u64 v[4:5], s[12:13], 0, v[14:15]
	v_lshlrev_b64 v[4:5], 11, v[4:5]
	v_lshl_add_u64 v[4:5], s[10:11], 0, v[4:5]
	v_lshl_add_u64 v[4:5], v[16:17], 1, v[4:5]
	s_waitcnt lgkmcnt(0)
; DEVI int get_tid() { int t = threadIdx.x; asm volatile("" : "+v"(t)); return t; }
; template <int BN>
; DEVI void tile_store256(const char* smem, bf* __restrict__ C, long ldc, long row0, int col0) {
;   constexpr int LDT = BN + 8;
;   constexpr int CPR = BN / 8;
;   const int tid = get_tid();
; #pragma unroll
;   for (int i = 0; i < CPR; ++i) {
;     const int q = tid + 256 * i;
;     const int r = q / CPR, c = q - r * CPR;
;     u32x4 v = *reinterpret_cast<const u32x4*>(smem + (r * LDT + c * 8) * 2);
;     *reinterpret_cast<u32x4*>(C + (row0 + r) * ldc + col0 + c * 8) = v;
;   }
; }
; DEVI void phase_gemm_plain128(const bf* A, int lda, const bf* Wt, int K, int N, bf* C, int ldc, char* smem) {
;     ...
;   for (int v = blockIdx.x; v < 128 * ntn; v += gridDim.x) {
;     int m2, nt;
;     lat_tile_map256(v, ntn, m2, nt);
;     plain_tile256(A, lda, Wt, K, C, ldc, lat_row0_256(m2), nt * 128, smem);
	global_store_dwordx4 v[4:5], v[8:11], off
	v_ashrrev_i32_e32 v4, 31, v2
	v_lshrrev_b32_e32 v4, 28, v4
	v_add_u32_e32 v4, v2, v4
	v_ashrrev_i32_e32 v8, 4, v4
	v_lshlrev_b32_e32 v5, 7, v8
	v_lshlrev_b32_e32 v2, 3, v2
	v_ashrrev_i32_e32 v9, 31, v8
	v_mul_lo_u32 v4, v8, s38
	v_sub_u32_e32 v10, v2, v5
	v_lshl_add_u64 v[8:9], s[12:13], 0, v[8:9]
	v_add_lshl_u32 v2, v10, v4, 1
	v_lshlrev_b64 v[8:9], 11, v[8:9]
	ds_read_b128 v[4:7], v2
	v_lshl_add_u64 v[8:9], s[10:11], 0, v[8:9]
	v_ashrrev_i32_e32 v11, 31, v10
	v_add_u32_e32 v2, 0x900, v1
	v_lshl_add_u64 v[12:13], v[10:11], 1, v[8:9]
	v_ashrrev_i32_e32 v8, 31, v2
	v_lshrrev_b32_e32 v8, 28, v8
	v_add_u32_e32 v8, v2, v8
	v_ashrrev_i32_e32 v14, 4, v8
	v_lshlrev_b32_e32 v9, 7, v14
	v_lshlrev_b32_e32 v2, 3, v2
	v_mul_lo_u32 v8, v14, s38
	v_sub_u32_e32 v16, v2, v9
	v_add_lshl_u32 v2, v16, v8, 1
	ds_read_b128 v[8:11], v2
	v_ashrrev_i32_e32 v15, 31, v14
	s_waitcnt lgkmcnt(1)
	global_store_dwordx4 v[12:13], v[4:7], off
	v_ashrrev_i32_e32 v17, 31, v16
	v_add_u32_e32 v2, 0xa00, v1
	v_lshl_add_u64 v[4:5], s[12:13], 0, v[14:15]
	v_lshlrev_b64 v[4:5], 11, v[4:5]
	v_lshl_add_u64 v[4:5], s[10:11], 0, v[4:5]
	v_lshl_add_u64 v[4:5], v[16:17], 1, v[4:5]
	s_waitcnt lgkmcnt(0)
	global_store_dwordx4 v[4:5], v[8:11], off
	v_ashrrev_i32_e32 v4, 31, v2
	v_lshrrev_b32_e32 v4, 28, v4
	v_add_u32_e32 v4, v2, v4
	v_ashrrev_i32_e32 v8, 4, v4
	v_lshlrev_b32_e32 v5, 7, v8
	v_lshlrev_b32_e32 v2, 3, v2
	v_ashrrev_i32_e32 v9, 31, v8
	v_mul_lo_u32 v4, v8, s38
	v_sub_u32_e32 v10, v2, v5
	v_lshl_add_u64 v[8:9], s[12:13], 0, v[8:9]
	v_add_lshl_u32 v2, v10, v4, 1
	v_lshlrev_b64 v[8:9], 11, v[8:9]
	ds_read_b128 v[4:7], v2
	v_lshl_add_u64 v[8:9], s[10:11], 0, v[8:9]
	v_ashrrev_i32_e32 v11, 31, v10
	v_add_u32_e32 v2, 0xb00, v1
	v_lshl_add_u64 v[12:13], v[10:11], 1, v[8:9]
	v_ashrrev_i32_e32 v8, 31, v2
	v_lshrrev_b32_e32 v8, 28, v8
	v_add_u32_e32 v8, v2, v8
	v_ashrrev_i32_e32 v14, 4, v8
	v_lshlrev_b32_e32 v9, 7, v14
	v_lshlrev_b32_e32 v2, 3, v2
	v_mul_lo_u32 v8, v14, s38
	v_sub_u32_e32 v16, v2, v9
	v_add_lshl_u32 v2, v16, v8, 1
	ds_read_b128 v[8:11], v2
	v_ashrrev_i32_e32 v15, 31, v14
	s_waitcnt lgkmcnt(1)
	global_store_dwordx4 v[12:13], v[4:7], off
	v_ashrrev_i32_e32 v17, 31, v16
	v_add_u32_e32 v2, 0xc00, v1
	v_lshl_add_u64 v[4:5], s[12:13], 0, v[14:15]
	v_lshlrev_b64 v[4:5], 11, v[4:5]
	v_lshl_add_u64 v[4:5], s[10:11], 0, v[4:5]
	v_lshl_add_u64 v[4:5], v[16:17], 1, v[4:5]
	s_waitcnt lgkmcnt(0)
	global_store_dwordx4 v[4:5], v[8:11], off
	v_ashrrev_i32_e32 v4, 31, v2
	v_lshrrev_b32_e32 v4, 28, v4
	v_add_u32_e32 v4, v2, v4
	v_ashrrev_i32_e32 v8, 4, v4
	v_lshlrev_b32_e32 v5, 7, v8
	v_lshlrev_b32_e32 v2, 3, v2
	v_ashrrev_i32_e32 v9, 31, v8
	v_mul_lo_u32 v4, v8, s38
	v_sub_u32_e32 v10, v2, v5
	v_lshl_add_u64 v[8:9], s[12:13], 0, v[8:9]
	v_add_lshl_u32 v2, v10, v4, 1
	v_lshlrev_b64 v[8:9], 11, v[8:9]
	ds_read_b128 v[4:7], v2
	v_lshl_add_u64 v[8:9], s[10:11], 0, v[8:9]
	v_ashrrev_i32_e32 v11, 31, v10
	v_add_u32_e32 v2, 0xd00, v1
	v_lshl_add_u64 v[12:13], v[10:11], 1, v[8:9]
	v_ashrrev_i32_e32 v8, 31, v2
	v_lshrrev_b32_e32 v8, 28, v8
	v_add_u32_e32 v8, v2, v8
	v_ashrrev_i32_e32 v14, 4, v8
	v_lshlrev_b32_e32 v9, 7, v14
	v_lshlrev_b32_e32 v2, 3, v2
	v_mul_lo_u32 v8, v14, s38
	v_sub_u32_e32 v16, v2, v9
	v_add_lshl_u32 v2, v16, v8, 1
	ds_read_b128 v[8:11], v2
	v_ashrrev_i32_e32 v15, 31, v14
	s_waitcnt lgkmcnt(1)
	global_store_dwordx4 v[12:13], v[4:7], off
	v_ashrrev_i32_e32 v17, 31, v16
	v_add_u32_e32 v2, 0xe00, v1
	v_lshl_add_u64 v[4:5], s[12:13], 0, v[14:15]
	v_lshlrev_b64 v[4:5], 11, v[4:5]
	v_lshl_add_u64 v[4:5], s[10:11], 0, v[4:5]
	v_lshl_add_u64 v[4:5], v[16:17], 1, v[4:5]
	s_waitcnt lgkmcnt(0)
	global_store_dwordx4 v[4:5], v[8:11], off
	v_ashrrev_i32_e32 v4, 31, v2
	v_lshrrev_b32_e32 v4, 28, v4
	v_add_u32_e32 v4, v2, v4
	v_ashrrev_i32_e32 v8, 4, v4
	v_lshlrev_b32_e32 v5, 7, v8
	v_lshlrev_b32_e32 v2, 3, v2
	v_mul_lo_u32 v4, v8, s38
	v_sub_u32_e32 v10, v2, v5
	v_add_lshl_u32 v2, v10, v4, 1
	v_add_u32_e32 v1, 0xf00, v1
	ds_read_b128 v[4:7], v2
	v_ashrrev_i32_e32 v9, 31, v8
	v_ashrrev_i32_e32 v2, 31, v1
	v_lshl_add_u64 v[8:9], s[12:13], 0, v[8:9]
	v_lshrrev_b32_e32 v2, 28, v2
	v_lshlrev_b64 v[8:9], 11, v[8:9]
	v_add_u32_e32 v2, v1, v2
	v_lshl_add_u64 v[8:9], s[10:11], 0, v[8:9]
	v_ashrrev_i32_e32 v11, 31, v10
	v_ashrrev_i32_e32 v14, 4, v2
	v_lshl_add_u64 v[12:13], v[10:11], 1, v[8:9]
	v_lshlrev_b32_e32 v8, 7, v14
	v_lshlrev_b32_e32 v1, 3, v1
	v_mul_lo_u32 v2, v14, s38
	v_sub_u32_e32 v16, v1, v8
	v_add_lshl_u32 v1, v16, v2, 1
	v_ashrrev_i32_e32 v15, 31, v14
	ds_read_b128 v[8:11], v1
	s_waitcnt lgkmcnt(1)
	global_store_dwordx4 v[12:13], v[4:7], off
	v_ashrrev_i32_e32 v17, 31, v16
	v_readlane_b32 s58, v251, 60
	v_lshl_add_u64 v[4:5], s[12:13], 0, v[14:15]
	v_lshlrev_b64 v[4:5], 11, v[4:5]
	v_lshl_add_u64 v[4:5], s[10:11], 0, v[4:5]
	v_readlane_b32 s10, v252, 59
	s_add_i32 s2, s2, s10
	v_readlane_b32 s59, v251, 61
	v_lshl_add_u64 v[4:5], v[16:17], 1, v[4:5]
	s_cmpk_gt_i32 s2, 0x3ff
	v_readlane_b32 s57, v251, 59
	v_readlane_b32 s62, v252, 0
	v_readlane_b32 s63, v252, 1
	v_readlane_b32 s64, v252, 2
	v_readlane_b32 s65, v252, 3
	v_readlane_b32 s66, v252, 4
	v_readlane_b32 s67, v252, 5
	v_readlane_b32 s68, v252, 6
	v_readlane_b32 s69, v252, 7
	v_readlane_b32 s70, v252, 8
	v_readlane_b32 s71, v252, 9
	s_waitcnt lgkmcnt(0)
	global_store_dwordx4 v[4:5], v[8:11], off
	s_barrier
	v_readlane_b32 s11, v252, 60
	s_cbranch_scc0 .LBB0_925

; DEVI f32x4 mfma16(bf16x8 a, bf16x8 b, f32x4 c) { return __builtin_amdgcn_mfma_f32_16x16x32_bf16(a, b, c, 0, 0, 0); }
; DEVI void gemm_core3(f32x4 (&acc)[8][4], const bf* __restrict__ A, int lda, const bf* __restrict__ Bt, int ldb, int K, char* smem) {
;     ...
;   for (int kt = 0; kt < nk; ++kt) {
;     const int k1 = min((kt + 1) * 32, klast);
;     const int sn = ((kt + 1) & 1) * STG;
;     const int so = (kt & 1) * STG;
;     bf16x8 bfr[4], af[8];
; #pragma unroll
;     for (int n = 0; n < 4; ++n) bfr[n] = *reinterpret_cast<const bf16x8*>(bbase + so + n * 16 * 64);
; #pragma unroll
;     for (int m = 0; m < 8; ++m) af[m] = *reinterpret_cast<const bf16x8*>(abase + so + m * 16 * 64);
; #pragma unroll
;     for (int i = 0; i < 4; ++i) glds16(Ap + i * sa + k1, dbase + sn + i * 4096);
; #pragma unroll
;     for (int i = 0; i < 2; ++i) glds16(Bp + i * sb + k1, dbase + sn + ASZ + i * 4096);
;     __builtin_amdgcn_s_setprio(1);
; #pragma unroll
;     for (int m = 0; m < 8; ++m)
; #pragma unroll
;       for (int n = 0; n < 4; ++n) acc[m][n] = mfma16(af[m], bfr[n], acc[m][n]);
;     __builtin_amdgcn_s_setprio(0);
;     __syncthreads();
;   }
.Lg3_loop_936:
	v_add_u32_e32 v216, s10, v146
	v_add_u32_e32 v217, s10, v2
	ds_read_b128 v[148:151], v217 offset:16384
	ds_read_b128 v[166:169], v216
	ds_read_b128 v[154:157], v217 offset:17408
	ds_read_b128 v[158:161], v217 offset:18432
	ds_read_b128 v[162:165], v217 offset:19456
	ds_read_b128 v[170:173], v216 offset:1024
	ds_read_b128 v[174:177], v216 offset:2048
	ds_read_b128 v[192:195], v216 offset:3072
	ds_read_b128 v[196:199], v216 offset:4096
	ds_read_b128 v[204:207], v216 offset:5120
	ds_read_b128 v[208:211], v216 offset:6144
	ds_read_b128 v[212:215], v216 offset:7168
	s_setprio 1
	s_waitcnt lgkmcnt(10)
	v_mfma_f32_16x16x32_bf16 v[128:131], v[166:169], v[148:151], v[128:131]
	s_waitcnt lgkmcnt(9)
	v_mfma_f32_16x16x32_bf16 v[124:127], v[166:169], v[154:157], v[124:127]
	s_waitcnt lgkmcnt(8)
	v_mfma_f32_16x16x32_bf16 v[120:123], v[166:169], v[158:161], v[120:123]
	s_waitcnt lgkmcnt(7)
	v_mfma_f32_16x16x32_bf16 v[116:119], v[166:169], v[162:165], v[116:119]
	s_waitcnt lgkmcnt(6)
	v_mfma_f32_16x16x32_bf16 v[112:115], v[170:173], v[148:151], v[112:115]
	v_mfma_f32_16x16x32_bf16 v[108:111], v[170:173], v[154:157], v[108:111]
	v_mfma_f32_16x16x32_bf16 v[104:107], v[170:173], v[158:161], v[104:107]
	v_mfma_f32_16x16x32_bf16 v[100:103], v[170:173], v[162:165], v[100:103]
	s_waitcnt lgkmcnt(5)
	v_mfma_f32_16x16x32_bf16 v[96:99], v[174:177], v[148:151], v[96:99]
	v_mfma_f32_16x16x32_bf16 v[92:95], v[174:177], v[154:157], v[92:95]
	v_mfma_f32_16x16x32_bf16 v[88:91], v[174:177], v[158:161], v[88:91]
	v_mfma_f32_16x16x32_bf16 v[84:87], v[174:177], v[162:165], v[84:87]
	s_waitcnt lgkmcnt(4)
	v_mfma_f32_16x16x32_bf16 v[80:83], v[192:195], v[148:151], v[80:83]
	v_mfma_f32_16x16x32_bf16 v[76:79], v[192:195], v[154:157], v[76:79]
	v_mfma_f32_16x16x32_bf16 v[72:75], v[192:195], v[158:161], v[72:75]
	v_mfma_f32_16x16x32_bf16 v[68:71], v[192:195], v[162:165], v[68:71]
	s_waitcnt lgkmcnt(3)
	v_mfma_f32_16x16x32_bf16 v[64:67], v[196:199], v[148:151], v[64:67]
	v_mfma_f32_16x16x32_bf16 v[60:63], v[196:199], v[154:157], v[60:63]
	v_mfma_f32_16x16x32_bf16 v[56:59], v[196:199], v[158:161], v[56:59]
	v_mfma_f32_16x16x32_bf16 v[52:55], v[196:199], v[162:165], v[52:55]
	s_waitcnt lgkmcnt(2)
	v_mfma_f32_16x16x32_bf16 v[48:51], v[204:207], v[148:151], v[48:51]
	v_mfma_f32_16x16x32_bf16 v[44:47], v[204:207], v[154:157], v[44:47]
	v_mfma_f32_16x16x32_bf16 v[40:43], v[204:207], v[158:161], v[40:43]
	v_mfma_f32_16x16x32_bf16 v[36:39], v[204:207], v[162:165], v[36:39]
	s_waitcnt lgkmcnt(1)
	v_mfma_f32_16x16x32_bf16 v[32:35], v[208:211], v[148:151], v[32:35]
	v_mfma_f32_16x16x32_bf16 v[28:31], v[208:211], v[154:157], v[28:31]
	v_mfma_f32_16x16x32_bf16 v[24:27], v[208:211], v[158:161], v[24:27]
	v_mfma_f32_16x16x32_bf16 v[20:23], v[208:211], v[162:165], v[20:23]
	s_waitcnt lgkmcnt(0)
	v_mfma_f32_16x16x32_bf16 v[16:19], v[212:215], v[148:151], v[16:19]
	v_mfma_f32_16x16x32_bf16 v[12:15], v[212:215], v[154:157], v[12:15]
	v_mfma_f32_16x16x32_bf16 v[8:11], v[212:215], v[158:161], v[8:11]
	v_mfma_f32_16x16x32_bf16 v[4:7], v[212:215], v[162:165], v[4:7]
	s_setprio 0
	s_add_i32 s10, s10, 0x6000
	s_cmp_lg_u32 s10, 0x12000
	s_cselect_b32 s10, s10, 0
	s_waitcnt vmcnt(0)
	s_barrier
	v_add_u32_e32 v216, s10, v146
	v_add_u32_e32 v217, s10, v2
	ds_read_b128 v[148:151], v217 offset:16384
	ds_read_b128 v[166:169], v216
	ds_read_b128 v[154:157], v217 offset:17408
	ds_read_b128 v[158:161], v217 offset:18432
	ds_read_b128 v[162:165], v217 offset:19456
	ds_read_b128 v[170:173], v216 offset:1024
	ds_read_b128 v[174:177], v216 offset:2048
	ds_read_b128 v[192:195], v216 offset:3072
	ds_read_b128 v[196:199], v216 offset:4096
	ds_read_b128 v[204:207], v216 offset:5120
	ds_read_b128 v[208:211], v216 offset:6144
	ds_read_b128 v[212:215], v216 offset:7168
	v_readfirstlane_b32 s17, v140
	s_add_i32 s96, s11, 0x6000
	s_cmp_lg_u32 s96, 0x12000
	s_cselect_b32 s96, s96, 0
	s_add_i32 s96, s96, s17
	s_add_i32 s17, s17, s11
	s_setprio 2
	s_waitcnt lgkmcnt(10)
	s_mov_b32 m0, s17
	s_add_i32 s17, s17, 0x1000
	v_mfma_f32_16x16x32_bf16 v[128:131], v[166:169], v[148:151], v[128:131]
	s_waitcnt lgkmcnt(9)
	v_mfma_f32_16x16x32_bf16 v[124:127], v[166:169], v[154:157], v[124:127]
	global_load_lds_dwordx4 v[218:219], off
	v_lshl_add_u64 v[218:219], v[218:219], 0, 64
	s_waitcnt lgkmcnt(8)
	s_mov_b32 m0, s96
	s_add_i32 s96, s96, 0x1000
	v_mfma_f32_16x16x32_bf16 v[120:123], v[166:169], v[158:161], v[120:123]
	s_waitcnt lgkmcnt(7)
	v_mfma_f32_16x16x32_bf16 v[116:119], v[166:169], v[162:165], v[116:119]
	global_load_lds_dwordx4 v[218:219], off
	v_lshl_add_u64 v[218:219], v[218:219], 0, 64
	s_waitcnt lgkmcnt(6)
	v_mfma_f32_16x16x32_bf16 v[112:115], v[170:173], v[148:151], v[112:115]
	s_mov_b32 m0, s17
	s_add_i32 s17, s17, 0x1000
	v_mfma_f32_16x16x32_bf16 v[108:111], v[170:173], v[154:157], v[108:111]
	v_mfma_f32_16x16x32_bf16 v[104:107], v[170:173], v[158:161], v[104:107]
	global_load_lds_dwordx4 v[220:221], off
	v_lshl_add_u64 v[220:221], v[220:221], 0, 64
	s_mov_b32 m0, s96
	s_add_i32 s96, s96, 0x1000
	v_mfma_f32_16x16x32_bf16 v[100:103], v[170:173], v[162:165], v[100:103]
	s_waitcnt lgkmcnt(5)
	v_mfma_f32_16x16x32_bf16 v[96:99], v[174:177], v[148:151], v[96:99]
	global_load_lds_dwordx4 v[220:221], off
	v_lshl_add_u64 v[220:221], v[220:221], 0, 64
	v_mfma_f32_16x16x32_bf16 v[92:95], v[174:177], v[154:157], v[92:95]
	s_mov_b32 m0, s17
	s_add_i32 s17, s17, 0x1000
	v_mfma_f32_16x16x32_bf16 v[88:91], v[174:177], v[158:161], v[88:91]
	v_mfma_f32_16x16x32_bf16 v[84:87], v[174:177], v[162:165], v[84:87]
	global_load_lds_dwordx4 v[222:223], off
	v_lshl_add_u64 v[222:223], v[222:223], 0, 64
	s_waitcnt lgkmcnt(4)
; DEVI f32x4 mfma16(bf16x8 a, bf16x8 b, f32x4 c) { return __builtin_amdgcn_mfma_f32_16x16x32_bf16(a, b, c, 0, 0, 0); }
; DEVI void gemm_core3(f32x4 (&acc)[8][4], const bf* __restrict__ A, int lda, const bf* __restrict__ Bt, int ldb, int K, char* smem) {
;     ...
;   for (int kt = 0; kt < nk; ++kt) {
;     const int k1 = min((kt + 1) * 32, klast);
;     const int sn = ((kt + 1) & 1) * STG;
;     const int so = (kt & 1) * STG;
;     bf16x8 bfr[4], af[8];
; #pragma unroll
;     for (int n = 0; n < 4; ++n) bfr[n] = *reinterpret_cast<const bf16x8*>(bbase + so + n * 16 * 64);
; #pragma unroll
;     for (int m = 0; m < 8; ++m) af[m] = *reinterpret_cast<const bf16x8*>(abase + so + m * 16 * 64);
; #pragma unroll
;     for (int i = 0; i < 4; ++i) glds16(Ap + i * sa + k1, dbase + sn + i * 4096);
; #pragma unroll
;     for (int i = 0; i < 2; ++i) glds16(Bp + i * sb + k1, dbase + sn + ASZ + i * 4096);
;     __builtin_amdgcn_s_setprio(1);
; #pragma unroll
;     for (int m = 0; m < 8; ++m)
; #pragma unroll
;       for (int n = 0; n < 4; ++n) acc[m][n] = mfma16(af[m], bfr[n], acc[m][n]);
;     __builtin_amdgcn_s_setprio(0);
;     __syncthreads();
;   }
	s_mov_b32 m0, s96
	s_add_i32 s96, s96, 0x1000
	v_mfma_f32_16x16x32_bf16 v[80:83], v[192:195], v[148:151], v[80:83]
	v_mfma_f32_16x16x32_bf16 v[76:79], v[192:195], v[154:157], v[76:79]
	global_load_lds_dwordx4 v[222:223], off
	v_lshl_add_u64 v[222:223], v[222:223], 0, 64
	v_mfma_f32_16x16x32_bf16 v[72:75], v[192:195], v[158:161], v[72:75]
	s_mov_b32 m0, s17
	s_add_i32 s17, s17, 0x1000
	v_mfma_f32_16x16x32_bf16 v[68:71], v[192:195], v[162:165], v[68:71]
	s_waitcnt lgkmcnt(3)
	v_mfma_f32_16x16x32_bf16 v[64:67], v[196:199], v[148:151], v[64:67]
	global_load_lds_dwordx4 v[224:225], off
	v_lshl_add_u64 v[224:225], v[224:225], 0, 64
	s_mov_b32 m0, s96
	s_add_i32 s96, s96, 0x1000
	v_mfma_f32_16x16x32_bf16 v[60:63], v[196:199], v[154:157], v[60:63]
	v_mfma_f32_16x16x32_bf16 v[56:59], v[196:199], v[158:161], v[56:59]
	global_load_lds_dwordx4 v[224:225], off
	v_lshl_add_u64 v[224:225], v[224:225], 0, 64
	v_mfma_f32_16x16x32_bf16 v[52:55], v[196:199], v[162:165], v[52:55]
	s_waitcnt lgkmcnt(2)
	s_mov_b32 m0, s17
	s_add_i32 s17, s17, 0x1000
	v_mfma_f32_16x16x32_bf16 v[48:51], v[204:207], v[148:151], v[48:51]
	v_mfma_f32_16x16x32_bf16 v[44:47], v[204:207], v[154:157], v[44:47]
	global_load_lds_dwordx4 v[226:227], off
	v_lshl_add_u64 v[226:227], v[226:227], 0, 64
	s_mov_b32 m0, s96
	s_add_i32 s96, s96, 0x1000
	v_mfma_f32_16x16x32_bf16 v[40:43], v[204:207], v[158:161], v[40:43]
	v_mfma_f32_16x16x32_bf16 v[36:39], v[204:207], v[162:165], v[36:39]
	global_load_lds_dwordx4 v[226:227], off
	v_lshl_add_u64 v[226:227], v[226:227], 0, 64
	s_waitcnt lgkmcnt(1)
	v_mfma_f32_16x16x32_bf16 v[32:35], v[208:211], v[148:151], v[32:35]
	s_mov_b32 m0, s17
	s_add_i32 s17, s17, 0x1000
	v_mfma_f32_16x16x32_bf16 v[28:31], v[208:211], v[154:157], v[28:31]
	v_mfma_f32_16x16x32_bf16 v[24:27], v[208:211], v[158:161], v[24:27]
	global_load_lds_dwordx4 v[228:229], off
	v_lshl_add_u64 v[228:229], v[228:229], 0, 64
	s_mov_b32 m0, s96
	s_add_i32 s96, s96, 0x1000
	v_mfma_f32_16x16x32_bf16 v[20:23], v[208:211], v[162:165], v[20:23]
	s_waitcnt lgkmcnt(0)
	v_mfma_f32_16x16x32_bf16 v[16:19], v[212:215], v[148:151], v[16:19]
	global_load_lds_dwordx4 v[228:229], off
	v_lshl_add_u64 v[228:229], v[228:229], 0, 64
	v_mfma_f32_16x16x32_bf16 v[12:15], v[212:215], v[154:157], v[12:15]
	v_mfma_f32_16x16x32_bf16 v[8:11], v[212:215], v[158:161], v[8:11]
	v_mfma_f32_16x16x32_bf16 v[4:7], v[212:215], v[162:165], v[4:7]
	s_setprio 0
	s_add_i32 s10, s10, 0x6000
	s_cmp_lg_u32 s10, 0x12000
	s_cselect_b32 s10, s10, 0
	s_sub_i32 s11, s11, 0x6000
	s_cmp_lt_i32 s11, 0
	s_cselect_b32 s11, 0xc000, s11
	s_add_i32 s3, s3, 1
	s_cmp_lt_i32 s3, 15
	s_waitcnt vmcnt(1)
	s_barrier
	s_cbranch_scc1 .Lg3_loop_936
	v_add_u32_e32 v216, s10, v146
	v_add_u32_e32 v217, s10, v2
	ds_read_b128 v[148:151], v217 offset:16384
	ds_read_b128 v[166:169], v216
	ds_read_b128 v[154:157], v217 offset:17408
	ds_read_b128 v[158:161], v217 offset:18432
	ds_read_b128 v[162:165], v217 offset:19456
	ds_read_b128 v[170:173], v216 offset:1024
	ds_read_b128 v[174:177], v216 offset:2048
	ds_read_b128 v[192:195], v216 offset:3072
	ds_read_b128 v[196:199], v216 offset:4096
	ds_read_b128 v[204:207], v216 offset:5120
	ds_read_b128 v[208:211], v216 offset:6144
	ds_read_b128 v[212:215], v216 offset:7168
	s_setprio 1
	s_waitcnt lgkmcnt(10)
	v_mfma_f32_16x16x32_bf16 v[128:131], v[166:169], v[148:151], v[128:131]
	s_waitcnt lgkmcnt(9)
	v_mfma_f32_16x16x32_bf16 v[124:127], v[166:169], v[154:157], v[124:127]
	s_waitcnt lgkmcnt(8)
	v_mfma_f32_16x16x32_bf16 v[120:123], v[166:169], v[158:161], v[120:123]
	s_waitcnt lgkmcnt(7)
	v_mfma_f32_16x16x32_bf16 v[116:119], v[166:169], v[162:165], v[116:119]
	s_waitcnt lgkmcnt(6)
	v_mfma_f32_16x16x32_bf16 v[112:115], v[170:173], v[148:151], v[112:115]
	v_mfma_f32_16x16x32_bf16 v[108:111], v[170:173], v[154:157], v[108:111]
	v_mfma_f32_16x16x32_bf16 v[104:107], v[170:173], v[158:161], v[104:107]
	v_mfma_f32_16x16x32_bf16 v[100:103], v[170:173], v[162:165], v[100:103]
	s_waitcnt lgkmcnt(5)
	v_mfma_f32_16x16x32_bf16 v[96:99], v[174:177], v[148:151], v[96:99]
	v_mfma_f32_16x16x32_bf16 v[92:95], v[174:177], v[154:157], v[92:95]
	v_mfma_f32_16x16x32_bf16 v[88:91], v[174:177], v[158:161], v[88:91]
	v_mfma_f32_16x16x32_bf16 v[84:87], v[174:177], v[162:165], v[84:87]
	s_waitcnt lgkmcnt(4)
	v_mfma_f32_16x16x32_bf16 v[80:83], v[192:195], v[148:151], v[80:83]
	v_mfma_f32_16x16x32_bf16 v[76:79], v[192:195], v[154:157], v[76:79]
	v_mfma_f32_16x16x32_bf16 v[72:75], v[192:195], v[158:161], v[72:75]
	v_mfma_f32_16x16x32_bf16 v[68:71], v[192:195], v[162:165], v[68:71]
	s_waitcnt lgkmcnt(3)
	v_mfma_f32_16x16x32_bf16 v[64:67], v[196:199], v[148:151], v[64:67]
	v_mfma_f32_16x16x32_bf16 v[60:63], v[196:199], v[154:157], v[60:63]
	v_mfma_f32_16x16x32_bf16 v[56:59], v[196:199], v[158:161], v[56:59]
	v_mfma_f32_16x16x32_bf16 v[52:55], v[196:199], v[162:165], v[52:55]
	s_waitcnt lgkmcnt(2)
	v_mfma_f32_16x16x32_bf16 v[48:51], v[204:207], v[148:151], v[48:51]
	v_mfma_f32_16x16x32_bf16 v[44:47], v[204:207], v[154:157], v[44:47]
	v_mfma_f32_16x16x32_bf16 v[40:43], v[204:207], v[158:161], v[40:43]
	v_mfma_f32_16x16x32_bf16 v[36:39], v[204:207], v[162:165], v[36:39]
	s_waitcnt lgkmcnt(1)
	v_mfma_f32_16x16x32_bf16 v[32:35], v[208:211], v[148:151], v[32:35]
	v_mfma_f32_16x16x32_bf16 v[28:31], v[208:211], v[154:157], v[28:31]
	v_mfma_f32_16x16x32_bf16 v[24:27], v[208:211], v[158:161], v[24:27]
	v_mfma_f32_16x16x32_bf16 v[20:23], v[208:211], v[162:165], v[20:23]
	s_waitcnt lgkmcnt(0)
	v_mfma_f32_16x16x32_bf16 v[16:19], v[212:215], v[148:151], v[16:19]
	v_mfma_f32_16x16x32_bf16 v[12:15], v[212:215], v[154:157], v[12:15]
	v_mfma_f32_16x16x32_bf16 v[8:11], v[212:215], v[158:161], v[8:11]
	v_mfma_f32_16x16x32_bf16 v[4:7], v[212:215], v[162:165], v[4:7]
	s_setprio 0
	s_add_i32 s10, s10, 0x6000
	s_cmp_lg_u32 s10, 0x12000
	s_cselect_b32 s10, s10, 0
	s_waitcnt vmcnt(0)
	s_barrier
; DEVI float silu_(float x) { return x / (1.f + __expf(-x)); }
; DEVI f32x4 mfma16(bf16x8 a, bf16x8 b, f32x4 c) { return __builtin_amdgcn_mfma_f32_16x16x32_bf16(a, b, c, 0, 0, 0); }
; DEVI void gemm_core3(f32x4 (&acc)[8][4], const bf* __restrict__ A, int lda, const bf* __restrict__ Bt, int ldb, int K, char* smem) {
;     ...
; #pragma unroll
;     for (int n = 0; n < 4; ++n) bfr[n] = *reinterpret_cast<const bf16x8*>(bbase + so + n * 16 * 64);
; #pragma unroll
;     for (int m = 0; m < 8; ++m) af[m] = *reinterpret_cast<const bf16x8*>(abase + so + m * 16 * 64);
; #pragma unroll
;     for (int i = 0; i < 4; ++i) glds16(Ap + i * sa + k1, dbase + sn + i * 4096);
; #pragma unroll
;     for (int i = 0; i < 2; ++i) glds16(Bp + i * sb + k1, dbase + sn + ASZ + i * 4096);
;     __builtin_amdgcn_s_setprio(1);
; #pragma unroll
;     for (int m = 0; m < 8; ++m)
; #pragma unroll
;       for (int n = 0; n < 4; ++n) acc[m][n] = mfma16(af[m], bfr[n], acc[m][n]);
;     __builtin_amdgcn_s_setprio(0);
; DEVI void ffn1_tile256(const P& p, const bf* W, long row0, int n0  , char* smem) {
;     ...
; #pragma unroll
;   for (int m = 0; m < 8; ++m)
; #pragma unroll
;     for (int pr = 0; pr < 2; ++pr) {
;       const int cl = (wc * 2 + pr) * 16 + l15;
; #pragma unroll
;       for (int j = 0; j < 4; ++j) {
;         const int rl = wr * 128 + m * 16 + quad * 4 + j;
;         float a = acc[m][2 * pr][j], b = acc[m][2 * pr + 1][j];
;         tl[rl * 72 + cl] = f2bf(silu_(a) * b);
;       }
	v_add_u32_e32 v216, s10, v146
	v_add_u32_e32 v217, s10, v2
	ds_read_b128 v[148:151], v217 offset:16384
	ds_read_b128 v[166:169], v216
	ds_read_b128 v[154:157], v217 offset:17408
	ds_read_b128 v[158:161], v217 offset:18432
	ds_read_b128 v[162:165], v217 offset:19456
	ds_read_b128 v[170:173], v216 offset:1024
	ds_read_b128 v[174:177], v216 offset:2048
	ds_read_b128 v[192:195], v216 offset:3072
	ds_read_b128 v[196:199], v216 offset:4096
	ds_read_b128 v[204:207], v216 offset:5120
	ds_read_b128 v[208:211], v216 offset:6144
	ds_read_b128 v[212:215], v216 offset:7168
	s_setprio 1
	s_waitcnt lgkmcnt(10)
	v_mfma_f32_16x16x32_bf16 v[128:131], v[166:169], v[148:151], v[128:131]
	s_waitcnt lgkmcnt(9)
	v_mfma_f32_16x16x32_bf16 v[124:127], v[166:169], v[154:157], v[124:127]
	s_waitcnt lgkmcnt(8)
	v_mfma_f32_16x16x32_bf16 v[120:123], v[166:169], v[158:161], v[120:123]
	s_waitcnt lgkmcnt(7)
	v_mfma_f32_16x16x32_bf16 v[116:119], v[166:169], v[162:165], v[116:119]
	s_waitcnt lgkmcnt(6)
	v_mfma_f32_16x16x32_bf16 v[112:115], v[170:173], v[148:151], v[112:115]
	v_mfma_f32_16x16x32_bf16 v[108:111], v[170:173], v[154:157], v[108:111]
	v_mfma_f32_16x16x32_bf16 v[104:107], v[170:173], v[158:161], v[104:107]
	v_mfma_f32_16x16x32_bf16 v[100:103], v[170:173], v[162:165], v[100:103]
	s_waitcnt lgkmcnt(5)
	v_mfma_f32_16x16x32_bf16 v[96:99], v[174:177], v[148:151], v[96:99]
	v_mfma_f32_16x16x32_bf16 v[92:95], v[174:177], v[154:157], v[92:95]
	v_mfma_f32_16x16x32_bf16 v[88:91], v[174:177], v[158:161], v[88:91]
	v_mfma_f32_16x16x32_bf16 v[84:87], v[174:177], v[162:165], v[84:87]
	s_waitcnt lgkmcnt(4)
	v_mfma_f32_16x16x32_bf16 v[80:83], v[192:195], v[148:151], v[80:83]
	v_mfma_f32_16x16x32_bf16 v[76:79], v[192:195], v[154:157], v[76:79]
	v_mfma_f32_16x16x32_bf16 v[72:75], v[192:195], v[158:161], v[72:75]
	v_mfma_f32_16x16x32_bf16 v[68:71], v[192:195], v[162:165], v[68:71]
	s_waitcnt lgkmcnt(3)
	v_mfma_f32_16x16x32_bf16 v[64:67], v[196:199], v[148:151], v[64:67]
	v_mfma_f32_16x16x32_bf16 v[60:63], v[196:199], v[154:157], v[60:63]
	v_mfma_f32_16x16x32_bf16 v[56:59], v[196:199], v[158:161], v[56:59]
	v_mfma_f32_16x16x32_bf16 v[52:55], v[196:199], v[162:165], v[52:55]
	s_waitcnt lgkmcnt(2)
	v_mfma_f32_16x16x32_bf16 v[48:51], v[204:207], v[148:151], v[48:51]
	v_mfma_f32_16x16x32_bf16 v[44:47], v[204:207], v[154:157], v[44:47]
	v_mfma_f32_16x16x32_bf16 v[40:43], v[204:207], v[158:161], v[40:43]
	v_mfma_f32_16x16x32_bf16 v[36:39], v[204:207], v[162:165], v[36:39]
	s_waitcnt lgkmcnt(1)
	v_mfma_f32_16x16x32_bf16 v[32:35], v[208:211], v[148:151], v[32:35]
	v_mfma_f32_16x16x32_bf16 v[28:31], v[208:211], v[154:157], v[28:31]
	v_mfma_f32_16x16x32_bf16 v[24:27], v[208:211], v[158:161], v[24:27]
	v_mfma_f32_16x16x32_bf16 v[20:23], v[208:211], v[162:165], v[20:23]
	s_waitcnt lgkmcnt(0)
	v_mfma_f32_16x16x32_bf16 v[16:19], v[212:215], v[148:151], v[16:19]
	v_mfma_f32_16x16x32_bf16 v[12:15], v[212:215], v[154:157], v[12:15]
	v_mfma_f32_16x16x32_bf16 v[8:11], v[212:215], v[158:161], v[8:11]
	v_mfma_f32_16x16x32_bf16 v[4:7], v[212:215], v[162:165], v[4:7]
	s_setprio 0
	s_add_i32 s10, s10, 0x6000
	s_cmp_lg_u32 s10, 0x12000
	s_cselect_b32 s10, s10, 0
	s_waitcnt vmcnt(0)
	s_barrier
	s_setprio 3
	v_mul_f32_e32 v2, 0xbfb8aa3b, v128
	v_exp_f32_e32 v2, v2
	v_and_b32_e32 v132, 15, v1
	v_and_b32_e32 v133, 0xfffff80, v1
	v_lshrrev_b32_e32 v134, 2, v1
	v_add_f32_e32 v135, 1.0, v2
	v_div_scale_f32 v136, s[10:11], v135, v135, v128
	v_rcp_f32_e32 v137, v136
	v_lshlrev_b32_e32 v2, 1, v132
	v_and_or_b32 v2, v1, 64, v2
	v_and_or_b32 v133, v134, 12, v133
	v_fma_f32 v1, -v136, v137, 1.0
	v_fmac_f32_e32 v137, v1, v137
	v_div_scale_f32 v1, vcc, v128, v135, v128
	v_mul_f32_e32 v132, v1, v137
	v_fma_f32 v134, -v136, v132, v1
	v_fmac_f32_e32 v132, v134, v137
	v_fma_f32 v1, -v136, v132, v1
	v_div_fmas_f32 v1, v1, v137, v132
	v_mul_f32_e32 v132, 0xbfb8aa3b, v129
	v_exp_f32_e32 v132, v132
	v_div_fixup_f32 v1, v1, v135, v128
	v_mul_f32_e32 v1, v124, v1
	s_movk_i32 s3, 0x90
	v_add_f32_e32 v124, 1.0, v132
	v_div_scale_f32 v128, s[10:11], v124, v124, v129
	v_rcp_f32_e32 v134, v128
	v_cvt_pk_bf16_f32 v1, v1, s0
	v_mad_u64_u32 v[132:133], s[10:11], v133, s3, v[2:3]
	ds_write_b16 v132, v1
	v_fma_f32 v1, -v128, v134, 1.0
	v_fmac_f32_e32 v134, v1, v134
	v_div_scale_f32 v1, vcc, v129, v124, v129
	v_mul_f32_e32 v2, v1, v134
	v_fma_f32 v133, -v128, v2, v1
	v_fmac_f32_e32 v2, v133, v134
	v_fma_f32 v1, -v128, v2, v1
	v_mul_f32_e32 v128, 0xbfb8aa3b, v130
	v_exp_f32_e32 v128, v128
	v_div_fmas_f32 v1, v1, v134, v2
	v_div_fixup_f32 v1, v1, v124, v129
	v_mul_f32_e32 v1, v125, v1
	v_add_f32_e32 v2, 1.0, v128
	v_div_scale_f32 v124, s[10:11], v2, v2, v130
	v_rcp_f32_e32 v128, v124
	v_cvt_pk_bf16_f32 v1, v1, s0
	ds_write_b16 v132, v1 offset:144
	v_readlane_b32 s56, v251, 58
	v_fma_f32 v1, -v124, v128, 1.0
	v_fmac_f32_e32 v128, v1, v128
	v_div_scale_f32 v1, vcc, v130, v2, v130
	v_mul_f32_e32 v125, v1, v128
	v_fma_f32 v129, -v124, v125, v1
	v_fmac_f32_e32 v125, v129, v128
	v_fma_f32 v1, -v124, v125, v1
	v_mul_f32_e32 v124, 0xbfb8aa3b, v131
	v_exp_f32_e32 v124, v124
	v_div_fmas_f32 v1, v1, v128, v125
	v_div_fixup_f32 v1, v1, v2, v130
	v_mul_f32_e32 v1, v126, v1
	v_add_f32_e32 v2, 1.0, v124
	v_div_scale_f32 v124, s[10:11], v2, v2, v131
	v_rcp_f32_e32 v125, v124
	v_cvt_pk_bf16_f32 v1, v1, s0
	ds_write_b16 v132, v1 offset:288
	v_readlane_b32 s58, v251, 60
	v_fma_f32 v1, -v124, v125, 1.0
	v_fmac_f32_e32 v125, v1, v125
	v_div_scale_f32 v1, vcc, v131, v2, v131
	v_mul_f32_e32 v126, v1, v125
	v_fma_f32 v128, -v124, v126, v1
	v_fmac_f32_e32 v126, v128, v125
	v_fma_f32 v1, -v124, v126, v1
	v_mul_f32_e32 v124, 0xbfb8aa3b, v120
	v_exp_f32_e32 v124, v124
; DEVI float silu_(float x) { return x / (1.f + __expf(-x)); }
; DEVI void ffn1_tile256(const P& p, const bf* W, long row0, int n0  , char* smem) {
;     ...
; #pragma unroll
;   for (int m = 0; m < 8; ++m)
; #pragma unroll
;     for (int pr = 0; pr < 2; ++pr) {
;       const int cl = (wc * 2 + pr) * 16 + l15;
; #pragma unroll
;       for (int j = 0; j < 4; ++j) {
;         const int rl = wr * 128 + m * 16 + quad * 4 + j;
;         float a = acc[m][2 * pr][j], b = acc[m][2 * pr + 1][j];
;         tl[rl * 72 + cl] = f2bf(silu_(a) * b);
;       }
	v_div_fmas_f32 v1, v1, v125, v126
	v_div_fixup_f32 v1, v1, v2, v131
	v_mul_f32_e32 v1, v127, v1
	v_add_f32_e32 v2, 1.0, v124
	v_div_scale_f32 v124, s[10:11], v2, v2, v120
	v_rcp_f32_e32 v125, v124
	v_cvt_pk_bf16_f32 v1, v1, s0
	ds_write_b16 v132, v1 offset:432
	v_readlane_b32 s59, v251, 61
	v_fma_f32 v1, -v124, v125, 1.0
	v_fmac_f32_e32 v125, v1, v125
	v_div_scale_f32 v1, vcc, v120, v2, v120
	v_mul_f32_e32 v126, v1, v125
	v_fma_f32 v127, -v124, v126, v1
	v_fmac_f32_e32 v126, v127, v125
	v_fma_f32 v1, -v124, v126, v1
	v_mul_f32_e32 v124, 0xbfb8aa3b, v121
	v_exp_f32_e32 v124, v124
	v_div_fmas_f32 v1, v1, v125, v126
	v_div_fixup_f32 v1, v1, v2, v120
	v_mul_f32_e32 v1, v116, v1
	v_add_f32_e32 v2, 1.0, v124
	v_div_scale_f32 v120, s[10:11], v2, v2, v121
	v_rcp_f32_e32 v124, v120
	v_cvt_pk_bf16_f32 v1, v1, s0
	ds_write_b16 v132, v1 offset:32
	v_readlane_b32 s57, v251, 59
	v_fma_f32 v1, -v120, v124, 1.0
	v_fmac_f32_e32 v124, v1, v124
	v_div_scale_f32 v1, vcc, v121, v2, v121
	v_mul_f32_e32 v116, v1, v124
	v_fma_f32 v125, -v120, v116, v1
	v_fmac_f32_e32 v116, v125, v124
	v_fma_f32 v1, -v120, v116, v1
	v_mul_f32_e32 v120, 0xbfb8aa3b, v122
	v_exp_f32_e32 v120, v120
	v_div_fmas_f32 v1, v1, v124, v116
	v_div_fixup_f32 v1, v1, v2, v121
	v_mul_f32_e32 v1, v117, v1
	v_add_f32_e32 v2, 1.0, v120
	v_div_scale_f32 v116, s[10:11], v2, v2, v122
	v_rcp_f32_e32 v120, v116
	v_cvt_pk_bf16_f32 v1, v1, s0
	ds_write_b16 v132, v1 offset:176
	v_readlane_b32 s60, v251, 62
	v_fma_f32 v1, -v116, v120, 1.0
	v_fmac_f32_e32 v120, v1, v120
	v_div_scale_f32 v1, vcc, v122, v2, v122
	v_mul_f32_e32 v117, v1, v120
	v_fma_f32 v121, -v116, v117, v1
	v_fmac_f32_e32 v117, v121, v120
	v_fma_f32 v1, -v116, v117, v1
	v_mul_f32_e32 v116, 0xbfb8aa3b, v123
	v_exp_f32_e32 v116, v116
	v_div_fmas_f32 v1, v1, v120, v117
	v_div_fixup_f32 v1, v1, v2, v122
	v_mul_f32_e32 v1, v118, v1
	v_add_f32_e32 v2, 1.0, v116
	v_div_scale_f32 v116, s[10:11], v2, v2, v123
	v_rcp_f32_e32 v117, v116
	v_cvt_pk_bf16_f32 v1, v1, s0
	ds_write_b16 v132, v1 offset:320
	v_readlane_b32 s61, v251, 63
	v_fma_f32 v1, -v116, v117, 1.0
	v_fmac_f32_e32 v117, v1, v117
	v_div_scale_f32 v1, vcc, v123, v2, v123
	v_mul_f32_e32 v118, v1, v117
	v_fma_f32 v120, -v116, v118, v1
	v_fmac_f32_e32 v118, v120, v117
	v_fma_f32 v1, -v116, v118, v1
	v_mul_f32_e32 v116, 0xbfb8aa3b, v112
	v_exp_f32_e32 v116, v116
	v_div_fmas_f32 v1, v1, v117, v118
	v_div_fixup_f32 v1, v1, v2, v123
	v_mul_f32_e32 v1, v119, v1
	v_add_f32_e32 v2, 1.0, v116
	v_div_scale_f32 v116, s[10:11], v2, v2, v112
	v_rcp_f32_e32 v117, v116
	v_cvt_pk_bf16_f32 v1, v1, s0
	ds_write_b16 v132, v1 offset:464
	v_readlane_b32 s62, v252, 0
	v_fma_f32 v1, -v116, v117, 1.0
	v_fmac_f32_e32 v117, v1, v117
	v_div_scale_f32 v1, vcc, v112, v2, v112
	v_mul_f32_e32 v118, v1, v117
	v_fma_f32 v119, -v116, v118, v1
	v_fmac_f32_e32 v118, v119, v117
	v_fma_f32 v1, -v116, v118, v1
	v_mul_f32_e32 v116, 0xbfb8aa3b, v113
	v_exp_f32_e32 v116, v116
	v_div_fmas_f32 v1, v1, v117, v118
	v_div_fixup_f32 v1, v1, v2, v112
	v_mul_f32_e32 v1, v108, v1
	v_add_f32_e32 v2, 1.0, v116
	v_div_scale_f32 v112, s[10:11], v2, v2, v113
	v_rcp_f32_e32 v116, v112
	v_cvt_pk_bf16_f32 v1, v1, s0
	ds_write_b16 v132, v1 offset:2304
	v_readlane_b32 s63, v252, 1
	v_fma_f32 v1, -v112, v116, 1.0
	v_fmac_f32_e32 v116, v1, v116
	v_div_scale_f32 v1, vcc, v113, v2, v113
	v_mul_f32_e32 v108, v1, v116
	v_fma_f32 v117, -v112, v108, v1
	v_fmac_f32_e32 v108, v117, v116
	v_fma_f32 v1, -v112, v108, v1
	v_mul_f32_e32 v112, 0xbfb8aa3b, v114
	v_exp_f32_e32 v112, v112
	v_div_fmas_f32 v1, v1, v116, v108
	v_div_fixup_f32 v1, v1, v2, v113
	v_mul_f32_e32 v1, v109, v1
	v_add_f32_e32 v2, 1.0, v112
	v_div_scale_f32 v108, s[10:11], v2, v2, v114
	v_rcp_f32_e32 v112, v108
	v_cvt_pk_bf16_f32 v1, v1, s0
	ds_write_b16 v132, v1 offset:2448
	v_readlane_b32 s64, v252, 2
	v_fma_f32 v1, -v108, v112, 1.0
	v_fmac_f32_e32 v112, v1, v112
	v_div_scale_f32 v1, vcc, v114, v2, v114
	v_mul_f32_e32 v109, v1, v112
	v_fma_f32 v113, -v108, v109, v1
	v_fmac_f32_e32 v109, v113, v112
	v_fma_f32 v1, -v108, v109, v1
	v_mul_f32_e32 v108, 0xbfb8aa3b, v115
	v_exp_f32_e32 v108, v108
	v_div_fmas_f32 v1, v1, v112, v109
	v_div_fixup_f32 v1, v1, v2, v114
	v_mul_f32_e32 v1, v110, v1
	v_add_f32_e32 v2, 1.0, v108
	v_div_scale_f32 v108, s[10:11], v2, v2, v115
	v_rcp_f32_e32 v109, v108
	v_cvt_pk_bf16_f32 v1, v1, s0
	ds_write_b16 v132, v1 offset:2592
	v_readlane_b32 s65, v252, 3
	v_fma_f32 v1, -v108, v109, 1.0
	v_fmac_f32_e32 v109, v1, v109
	v_div_scale_f32 v1, vcc, v115, v2, v115
	v_mul_f32_e32 v110, v1, v109
	v_fma_f32 v112, -v108, v110, v1
	v_fmac_f32_e32 v110, v112, v109
	v_fma_f32 v1, -v108, v110, v1
	v_mul_f32_e32 v108, 0xbfb8aa3b, v104
	v_exp_f32_e32 v108, v108
	v_div_fmas_f32 v1, v1, v109, v110
	v_div_fixup_f32 v1, v1, v2, v115
	v_mul_f32_e32 v1, v111, v1
	v_add_f32_e32 v2, 1.0, v108
	v_div_scale_f32 v108, s[10:11], v2, v2, v104
	v_rcp_f32_e32 v109, v108
	v_cvt_pk_bf16_f32 v1, v1, s0
	ds_write_b16 v132, v1 offset:2736
	v_readlane_b32 s66, v252, 4
	v_fma_f32 v1, -v108, v109, 1.0
	v_fmac_f32_e32 v109, v1, v109
	v_div_scale_f32 v1, vcc, v104, v2, v104
	v_mul_f32_e32 v110, v1, v109
	v_fma_f32 v111, -v108, v110, v1
	v_fmac_f32_e32 v110, v111, v109
	v_fma_f32 v1, -v108, v110, v1
	v_mul_f32_e32 v108, 0xbfb8aa3b, v105
	v_exp_f32_e32 v108, v108
	v_div_fmas_f32 v1, v1, v109, v110
	v_div_fixup_f32 v1, v1, v2, v104
	v_mul_f32_e32 v1, v100, v1
	v_add_f32_e32 v2, 1.0, v108
	v_div_scale_f32 v104, s[10:11], v2, v2, v105
	v_rcp_f32_e32 v108, v104
	v_cvt_pk_bf16_f32 v1, v1, s0
	ds_write_b16 v132, v1 offset:2336
	v_readlane_b32 s67, v252, 5
	v_fma_f32 v1, -v104, v108, 1.0
	v_fmac_f32_e32 v108, v1, v108
; DEVI float silu_(float x) { return x / (1.f + __expf(-x)); }
; DEVI void ffn1_tile256(const P& p, const bf* W, long row0, int n0  , char* smem) {
;     ...
; #pragma unroll
;   for (int m = 0; m < 8; ++m)
; #pragma unroll
;     for (int pr = 0; pr < 2; ++pr) {
;       const int cl = (wc * 2 + pr) * 16 + l15;
; #pragma unroll
;       for (int j = 0; j < 4; ++j) {
;         const int rl = wr * 128 + m * 16 + quad * 4 + j;
;         float a = acc[m][2 * pr][j], b = acc[m][2 * pr + 1][j];
;         tl[rl * 72 + cl] = f2bf(silu_(a) * b);
;       }
	v_div_scale_f32 v1, vcc, v105, v2, v105
	v_mul_f32_e32 v100, v1, v108
	v_fma_f32 v109, -v104, v100, v1
	v_fmac_f32_e32 v100, v109, v108
	v_fma_f32 v1, -v104, v100, v1
	v_mul_f32_e32 v104, 0xbfb8aa3b, v106
	v_exp_f32_e32 v104, v104
	v_div_fmas_f32 v1, v1, v108, v100
	v_div_fixup_f32 v1, v1, v2, v105
	v_mul_f32_e32 v1, v101, v1
	v_add_f32_e32 v2, 1.0, v104
	v_div_scale_f32 v100, s[10:11], v2, v2, v106
	v_rcp_f32_e32 v104, v100
	v_cvt_pk_bf16_f32 v1, v1, s0
	ds_write_b16 v132, v1 offset:2480
	v_readlane_b32 s68, v252, 6
	v_fma_f32 v1, -v100, v104, 1.0
	v_fmac_f32_e32 v104, v1, v104
	v_div_scale_f32 v1, vcc, v106, v2, v106
	v_mul_f32_e32 v101, v1, v104
	v_fma_f32 v105, -v100, v101, v1
	v_fmac_f32_e32 v101, v105, v104
	v_fma_f32 v1, -v100, v101, v1
	v_mul_f32_e32 v100, 0xbfb8aa3b, v107
	v_exp_f32_e32 v100, v100
	v_div_fmas_f32 v1, v1, v104, v101
	v_div_fixup_f32 v1, v1, v2, v106
	v_mul_f32_e32 v1, v102, v1
	v_add_f32_e32 v2, 1.0, v100
	v_div_scale_f32 v100, s[10:11], v2, v2, v107
	v_rcp_f32_e32 v101, v100
	v_cvt_pk_bf16_f32 v1, v1, s0
	ds_write_b16 v132, v1 offset:2624
	v_readlane_b32 s69, v252, 7
	v_fma_f32 v1, -v100, v101, 1.0
	v_fmac_f32_e32 v101, v1, v101
	v_div_scale_f32 v1, vcc, v107, v2, v107
	v_mul_f32_e32 v102, v1, v101
	v_fma_f32 v104, -v100, v102, v1
	v_fmac_f32_e32 v102, v104, v101
	v_fma_f32 v1, -v100, v102, v1
	v_mul_f32_e32 v100, 0xbfb8aa3b, v96
	v_exp_f32_e32 v100, v100
	v_div_fmas_f32 v1, v1, v101, v102
	v_div_fixup_f32 v1, v1, v2, v107
	v_mul_f32_e32 v1, v103, v1
	v_add_f32_e32 v2, 1.0, v100
	v_div_scale_f32 v100, s[10:11], v2, v2, v96
	v_rcp_f32_e32 v101, v100
	v_cvt_pk_bf16_f32 v1, v1, s0
	ds_write_b16 v132, v1 offset:2768
	v_readlane_b32 s70, v252, 8
	v_fma_f32 v1, -v100, v101, 1.0
	v_fmac_f32_e32 v101, v1, v101
	v_div_scale_f32 v1, vcc, v96, v2, v96
	v_mul_f32_e32 v102, v1, v101
	v_fma_f32 v103, -v100, v102, v1
	v_fmac_f32_e32 v102, v103, v101
	v_fma_f32 v1, -v100, v102, v1
	v_mul_f32_e32 v100, 0xbfb8aa3b, v97
	v_exp_f32_e32 v100, v100
	v_div_fmas_f32 v1, v1, v101, v102
	v_div_fixup_f32 v1, v1, v2, v96
	v_mul_f32_e32 v1, v92, v1
	v_add_f32_e32 v2, 1.0, v100
	v_div_scale_f32 v96, s[10:11], v2, v2, v97
	v_rcp_f32_e32 v100, v96
	v_cvt_pk_bf16_f32 v1, v1, s0
	ds_write_b16 v132, v1 offset:4608
	v_readlane_b32 s71, v252, 9
	v_fma_f32 v1, -v96, v100, 1.0
	v_fmac_f32_e32 v100, v1, v100
	v_div_scale_f32 v1, vcc, v97, v2, v97
	v_mul_f32_e32 v92, v1, v100
	v_fma_f32 v101, -v96, v92, v1
	v_fmac_f32_e32 v92, v101, v100
	v_fma_f32 v1, -v96, v92, v1
	v_mul_f32_e32 v96, 0xbfb8aa3b, v98
	v_exp_f32_e32 v96, v96
	v_div_fmas_f32 v1, v1, v100, v92
	v_div_fixup_f32 v1, v1, v2, v97
	v_mul_f32_e32 v1, v93, v1
	v_add_f32_e32 v2, 1.0, v96
	v_div_scale_f32 v92, s[10:11], v2, v2, v98
	v_rcp_f32_e32 v96, v92
	v_cvt_pk_bf16_f32 v1, v1, s0
	ds_write_b16 v132, v1 offset:4752
	v_fma_f32 v1, -v92, v96, 1.0
	v_fmac_f32_e32 v96, v1, v96
	v_div_scale_f32 v1, vcc, v98, v2, v98
	v_mul_f32_e32 v93, v1, v96
	v_fma_f32 v97, -v92, v93, v1
	v_fmac_f32_e32 v93, v97, v96
	v_fma_f32 v1, -v92, v93, v1
	v_mul_f32_e32 v92, 0xbfb8aa3b, v99
	v_exp_f32_e32 v92, v92
	v_div_fmas_f32 v1, v1, v96, v93
	v_div_fixup_f32 v1, v1, v2, v98
	v_mul_f32_e32 v1, v94, v1
	v_add_f32_e32 v2, 1.0, v92
	v_div_scale_f32 v92, s[10:11], v2, v2, v99
	v_rcp_f32_e32 v93, v92
	v_cvt_pk_bf16_f32 v1, v1, s0
	ds_write_b16 v132, v1 offset:4896
	v_fma_f32 v1, -v92, v93, 1.0
	v_fmac_f32_e32 v93, v1, v93
	v_div_scale_f32 v1, vcc, v99, v2, v99
	v_mul_f32_e32 v94, v1, v93
	v_fma_f32 v96, -v92, v94, v1
	v_fmac_f32_e32 v94, v96, v93
	v_fma_f32 v1, -v92, v94, v1
	v_mul_f32_e32 v92, 0xbfb8aa3b, v88
	v_exp_f32_e32 v92, v92
	v_div_fmas_f32 v1, v1, v93, v94
	v_div_fixup_f32 v1, v1, v2, v99
	v_mul_f32_e32 v1, v95, v1
	v_add_f32_e32 v2, 1.0, v92
	v_div_scale_f32 v92, s[10:11], v2, v2, v88
	v_rcp_f32_e32 v93, v92
	v_cvt_pk_bf16_f32 v1, v1, s0
	ds_write_b16 v132, v1 offset:5040
	v_fma_f32 v1, -v92, v93, 1.0
	v_fmac_f32_e32 v93, v1, v93
	v_div_scale_f32 v1, vcc, v88, v2, v88
	v_mul_f32_e32 v94, v1, v93
	v_fma_f32 v95, -v92, v94, v1
	v_fmac_f32_e32 v94, v95, v93
	v_fma_f32 v1, -v92, v94, v1
	v_mul_f32_e32 v92, 0xbfb8aa3b, v89
	v_exp_f32_e32 v92, v92
	v_div_fmas_f32 v1, v1, v93, v94
	v_div_fixup_f32 v1, v1, v2, v88
	v_mul_f32_e32 v1, v84, v1
	v_add_f32_e32 v2, 1.0, v92
	v_div_scale_f32 v88, s[10:11], v2, v2, v89
	v_rcp_f32_e32 v92, v88
	v_cvt_pk_bf16_f32 v1, v1, s0
	ds_write_b16 v132, v1 offset:4640
	v_fma_f32 v1, -v88, v92, 1.0
	v_fmac_f32_e32 v92, v1, v92
	v_div_scale_f32 v1, vcc, v89, v2, v89
	v_mul_f32_e32 v84, v1, v92
	v_fma_f32 v93, -v88, v84, v1
	v_fmac_f32_e32 v84, v93, v92
	v_fma_f32 v1, -v88, v84, v1
	v_mul_f32_e32 v88, 0xbfb8aa3b, v90
	v_exp_f32_e32 v88, v88
	v_div_fmas_f32 v1, v1, v92, v84
	v_div_fixup_f32 v1, v1, v2, v89
	v_mul_f32_e32 v1, v85, v1
	v_add_f32_e32 v2, 1.0, v88
	v_div_scale_f32 v84, s[10:11], v2, v2, v90
	v_rcp_f32_e32 v88, v84
	v_cvt_pk_bf16_f32 v1, v1, s0
	ds_write_b16 v132, v1 offset:4784
	v_fma_f32 v1, -v84, v88, 1.0
	v_fmac_f32_e32 v88, v1, v88
	v_div_scale_f32 v1, vcc, v90, v2, v90
	v_mul_f32_e32 v85, v1, v88
	v_fma_f32 v89, -v84, v85, v1
	v_fmac_f32_e32 v85, v89, v88
	v_fma_f32 v1, -v84, v85, v1
	v_mul_f32_e32 v84, 0xbfb8aa3b, v91
	v_exp_f32_e32 v84, v84
	v_div_fmas_f32 v1, v1, v88, v85
	v_div_fixup_f32 v1, v1, v2, v90
	v_mul_f32_e32 v1, v86, v1
	v_add_f32_e32 v2, 1.0, v84
	v_div_scale_f32 v84, s[10:11], v2, v2, v91
	v_rcp_f32_e32 v85, v84
	v_cvt_pk_bf16_f32 v1, v1, s0
	ds_write_b16 v132, v1 offset:4928
	v_fma_f32 v1, -v84, v85, 1.0
	v_fmac_f32_e32 v85, v1, v85
	v_div_scale_f32 v1, vcc, v91, v2, v91
	v_mul_f32_e32 v86, v1, v85
	v_fma_f32 v88, -v84, v86, v1
	v_fmac_f32_e32 v86, v88, v85
; DEVI float silu_(float x) { return x / (1.f + __expf(-x)); }
; DEVI void ffn1_tile256(const P& p, const bf* W, long row0, int n0  , char* smem) {
;     ...
; #pragma unroll
;   for (int m = 0; m < 8; ++m)
; #pragma unroll
;     for (int pr = 0; pr < 2; ++pr) {
;       const int cl = (wc * 2 + pr) * 16 + l15;
; #pragma unroll
;       for (int j = 0; j < 4; ++j) {
;         const int rl = wr * 128 + m * 16 + quad * 4 + j;
;         float a = acc[m][2 * pr][j], b = acc[m][2 * pr + 1][j];
;         tl[rl * 72 + cl] = f2bf(silu_(a) * b);
;       }
	v_fma_f32 v1, -v84, v86, v1
	v_mul_f32_e32 v84, 0xbfb8aa3b, v80
	v_exp_f32_e32 v84, v84
	v_div_fmas_f32 v1, v1, v85, v86
	v_div_fixup_f32 v1, v1, v2, v91
	v_mul_f32_e32 v1, v87, v1
	v_add_f32_e32 v2, 1.0, v84
	v_div_scale_f32 v84, s[10:11], v2, v2, v80
	v_rcp_f32_e32 v85, v84
	v_cvt_pk_bf16_f32 v1, v1, s0
	ds_write_b16 v132, v1 offset:5072
	v_fma_f32 v1, -v84, v85, 1.0
	v_fmac_f32_e32 v85, v1, v85
	v_div_scale_f32 v1, vcc, v80, v2, v80
	v_mul_f32_e32 v86, v1, v85
	v_fma_f32 v87, -v84, v86, v1
	v_fmac_f32_e32 v86, v87, v85
	v_fma_f32 v1, -v84, v86, v1
	v_mul_f32_e32 v84, 0xbfb8aa3b, v81
	v_exp_f32_e32 v84, v84
	v_div_fmas_f32 v1, v1, v85, v86
	v_div_fixup_f32 v1, v1, v2, v80
	v_mul_f32_e32 v1, v76, v1
	v_add_f32_e32 v2, 1.0, v84
	v_div_scale_f32 v80, s[10:11], v2, v2, v81
	v_rcp_f32_e32 v84, v80
	v_cvt_pk_bf16_f32 v1, v1, s0
	ds_write_b16 v132, v1 offset:6912
	v_fma_f32 v1, -v80, v84, 1.0
	v_fmac_f32_e32 v84, v1, v84
	v_div_scale_f32 v1, vcc, v81, v2, v81
	v_mul_f32_e32 v76, v1, v84
	v_fma_f32 v85, -v80, v76, v1
	v_fmac_f32_e32 v76, v85, v84
	v_fma_f32 v1, -v80, v76, v1
	v_mul_f32_e32 v80, 0xbfb8aa3b, v82
	v_exp_f32_e32 v80, v80
	v_div_fmas_f32 v1, v1, v84, v76
	v_div_fixup_f32 v1, v1, v2, v81
	v_mul_f32_e32 v1, v77, v1
	v_add_f32_e32 v2, 1.0, v80
	v_div_scale_f32 v76, s[10:11], v2, v2, v82
	v_rcp_f32_e32 v80, v76
	v_cvt_pk_bf16_f32 v1, v1, s0
	ds_write_b16 v132, v1 offset:7056
	v_fma_f32 v1, -v76, v80, 1.0
	v_fmac_f32_e32 v80, v1, v80
	v_div_scale_f32 v1, vcc, v82, v2, v82
	v_mul_f32_e32 v77, v1, v80
	v_fma_f32 v81, -v76, v77, v1
	v_fmac_f32_e32 v77, v81, v80
	v_fma_f32 v1, -v76, v77, v1
	v_mul_f32_e32 v76, 0xbfb8aa3b, v83
	v_exp_f32_e32 v76, v76
	v_div_fmas_f32 v1, v1, v80, v77
	v_div_fixup_f32 v1, v1, v2, v82
	v_mul_f32_e32 v1, v78, v1
	v_add_f32_e32 v2, 1.0, v76
	v_div_scale_f32 v76, s[10:11], v2, v2, v83
	v_rcp_f32_e32 v77, v76
	v_cvt_pk_bf16_f32 v1, v1, s0
	ds_write_b16 v132, v1 offset:7200
	v_fma_f32 v1, -v76, v77, 1.0
	v_fmac_f32_e32 v77, v1, v77
	v_div_scale_f32 v1, vcc, v83, v2, v83
	v_mul_f32_e32 v78, v1, v77
	v_fma_f32 v80, -v76, v78, v1
	v_fmac_f32_e32 v78, v80, v77
	v_fma_f32 v1, -v76, v78, v1
	v_mul_f32_e32 v76, 0xbfb8aa3b, v72
	v_exp_f32_e32 v76, v76
	v_div_fmas_f32 v1, v1, v77, v78
	v_div_fixup_f32 v1, v1, v2, v83
	v_mul_f32_e32 v1, v79, v1
	v_add_f32_e32 v2, 1.0, v76
	v_div_scale_f32 v76, s[10:11], v2, v2, v72
	v_rcp_f32_e32 v77, v76
	v_cvt_pk_bf16_f32 v1, v1, s0
	ds_write_b16 v132, v1 offset:7344
	v_fma_f32 v1, -v76, v77, 1.0
	v_fmac_f32_e32 v77, v1, v77
	v_div_scale_f32 v1, vcc, v72, v2, v72
	v_mul_f32_e32 v78, v1, v77
	v_fma_f32 v79, -v76, v78, v1
	v_fmac_f32_e32 v78, v79, v77
	v_fma_f32 v1, -v76, v78, v1
	v_mul_f32_e32 v76, 0xbfb8aa3b, v73
	v_exp_f32_e32 v76, v76
	v_div_fmas_f32 v1, v1, v77, v78
	v_div_fixup_f32 v1, v1, v2, v72
	v_mul_f32_e32 v1, v68, v1
	v_add_f32_e32 v2, 1.0, v76
	v_div_scale_f32 v72, s[10:11], v2, v2, v73
	v_rcp_f32_e32 v76, v72
	v_cvt_pk_bf16_f32 v1, v1, s0
	ds_write_b16 v132, v1 offset:6944
	v_fma_f32 v1, -v72, v76, 1.0
	v_fmac_f32_e32 v76, v1, v76
	v_div_scale_f32 v1, vcc, v73, v2, v73
	v_mul_f32_e32 v68, v1, v76
	v_fma_f32 v77, -v72, v68, v1
	v_fmac_f32_e32 v68, v77, v76
	v_fma_f32 v1, -v72, v68, v1
	v_mul_f32_e32 v72, 0xbfb8aa3b, v74
	v_exp_f32_e32 v72, v72
	v_div_fmas_f32 v1, v1, v76, v68
	v_div_fixup_f32 v1, v1, v2, v73
	v_mul_f32_e32 v1, v69, v1
	v_add_f32_e32 v2, 1.0, v72
	v_div_scale_f32 v68, s[10:11], v2, v2, v74
	v_rcp_f32_e32 v72, v68
	v_cvt_pk_bf16_f32 v1, v1, s0
	ds_write_b16 v132, v1 offset:7088
	v_fma_f32 v1, -v68, v72, 1.0
	v_fmac_f32_e32 v72, v1, v72
	v_div_scale_f32 v1, vcc, v74, v2, v74
	v_mul_f32_e32 v69, v1, v72
	v_fma_f32 v73, -v68, v69, v1
	v_fmac_f32_e32 v69, v73, v72
	v_fma_f32 v1, -v68, v69, v1
	v_mul_f32_e32 v68, 0xbfb8aa3b, v75
	v_exp_f32_e32 v68, v68
	v_div_fmas_f32 v1, v1, v72, v69
	v_div_fixup_f32 v1, v1, v2, v74
	v_mul_f32_e32 v1, v70, v1
	v_add_f32_e32 v2, 1.0, v68
	v_div_scale_f32 v68, s[10:11], v2, v2, v75
	v_rcp_f32_e32 v69, v68
	v_cvt_pk_bf16_f32 v1, v1, s0
	ds_write_b16 v132, v1 offset:7232
	v_fma_f32 v1, -v68, v69, 1.0
	v_fmac_f32_e32 v69, v1, v69
	v_div_scale_f32 v1, vcc, v75, v2, v75
	v_mul_f32_e32 v70, v1, v69
	v_fma_f32 v72, -v68, v70, v1
	v_fmac_f32_e32 v70, v72, v69
	v_fma_f32 v1, -v68, v70, v1
	v_mul_f32_e32 v68, 0xbfb8aa3b, v64
	v_exp_f32_e32 v68, v68
	v_div_fmas_f32 v1, v1, v69, v70
	v_div_fixup_f32 v1, v1, v2, v75
	v_mul_f32_e32 v1, v71, v1
	v_add_f32_e32 v2, 1.0, v68
	v_div_scale_f32 v68, s[10:11], v2, v2, v64
	v_rcp_f32_e32 v69, v68
	v_cvt_pk_bf16_f32 v1, v1, s0
	ds_write_b16 v132, v1 offset:7376
	v_fma_f32 v1, -v68, v69, 1.0
	v_fmac_f32_e32 v69, v1, v69
	v_div_scale_f32 v1, vcc, v64, v2, v64
	v_mul_f32_e32 v70, v1, v69
	v_fma_f32 v71, -v68, v70, v1
	v_fmac_f32_e32 v70, v71, v69
	v_fma_f32 v1, -v68, v70, v1
	v_mul_f32_e32 v68, 0xbfb8aa3b, v65
	v_exp_f32_e32 v68, v68
	v_div_fmas_f32 v1, v1, v69, v70
	v_div_fixup_f32 v1, v1, v2, v64
	v_mul_f32_e32 v1, v60, v1
	v_add_f32_e32 v2, 1.0, v68
	v_div_scale_f32 v64, s[10:11], v2, v2, v65
	v_rcp_f32_e32 v68, v64
	v_cvt_pk_bf16_f32 v1, v1, s0
	ds_write_b16 v132, v1 offset:9216
	v_fma_f32 v1, -v64, v68, 1.0
	v_fmac_f32_e32 v68, v1, v68
	v_div_scale_f32 v1, vcc, v65, v2, v65
	v_mul_f32_e32 v60, v1, v68
	v_fma_f32 v69, -v64, v60, v1
	v_fmac_f32_e32 v60, v69, v68
	v_fma_f32 v1, -v64, v60, v1
	v_mul_f32_e32 v64, 0xbfb8aa3b, v66
	v_exp_f32_e32 v64, v64
	v_div_fmas_f32 v1, v1, v68, v60
	v_div_fixup_f32 v1, v1, v2, v65
	v_mul_f32_e32 v1, v61, v1
	v_add_f32_e32 v2, 1.0, v64
	v_div_scale_f32 v60, s[10:11], v2, v2, v66
	v_rcp_f32_e32 v64, v60
	v_cvt_pk_bf16_f32 v1, v1, s0
	ds_write_b16 v132, v1 offset:9360
; DEVI float silu_(float x) { return x / (1.f + __expf(-x)); }
; DEVI void ffn1_tile256(const P& p, const bf* W, long row0, int n0  , char* smem) {
;     ...
; #pragma unroll
;   for (int m = 0; m < 8; ++m)
; #pragma unroll
;     for (int pr = 0; pr < 2; ++pr) {
;       const int cl = (wc * 2 + pr) * 16 + l15;
; #pragma unroll
;       for (int j = 0; j < 4; ++j) {
;         const int rl = wr * 128 + m * 16 + quad * 4 + j;
;         float a = acc[m][2 * pr][j], b = acc[m][2 * pr + 1][j];
;         tl[rl * 72 + cl] = f2bf(silu_(a) * b);
;       }
	v_fma_f32 v1, -v60, v64, 1.0
	v_fmac_f32_e32 v64, v1, v64
	v_div_scale_f32 v1, vcc, v66, v2, v66
	v_mul_f32_e32 v61, v1, v64
	v_fma_f32 v65, -v60, v61, v1
	v_fmac_f32_e32 v61, v65, v64
	v_fma_f32 v1, -v60, v61, v1
	v_mul_f32_e32 v60, 0xbfb8aa3b, v67
	v_exp_f32_e32 v60, v60
	v_div_fmas_f32 v1, v1, v64, v61
	v_div_fixup_f32 v1, v1, v2, v66
	v_mul_f32_e32 v1, v62, v1
	v_add_f32_e32 v2, 1.0, v60
	v_div_scale_f32 v60, s[10:11], v2, v2, v67
	v_rcp_f32_e32 v61, v60
	v_cvt_pk_bf16_f32 v1, v1, s0
	ds_write_b16 v132, v1 offset:9504
	v_fma_f32 v1, -v60, v61, 1.0
	v_fmac_f32_e32 v61, v1, v61
	v_div_scale_f32 v1, vcc, v67, v2, v67
	v_mul_f32_e32 v62, v1, v61
	v_fma_f32 v64, -v60, v62, v1
	v_fmac_f32_e32 v62, v64, v61
	v_fma_f32 v1, -v60, v62, v1
	v_mul_f32_e32 v60, 0xbfb8aa3b, v56
	v_exp_f32_e32 v60, v60
	v_div_fmas_f32 v1, v1, v61, v62
	v_div_fixup_f32 v1, v1, v2, v67
	v_mul_f32_e32 v1, v63, v1
	v_add_f32_e32 v2, 1.0, v60
	v_div_scale_f32 v60, s[10:11], v2, v2, v56
	v_rcp_f32_e32 v61, v60
	v_cvt_pk_bf16_f32 v1, v1, s0
	ds_write_b16 v132, v1 offset:9648
	v_fma_f32 v1, -v60, v61, 1.0
	v_fmac_f32_e32 v61, v1, v61
	v_div_scale_f32 v1, vcc, v56, v2, v56
	v_mul_f32_e32 v62, v1, v61
	v_fma_f32 v63, -v60, v62, v1
	v_fmac_f32_e32 v62, v63, v61
	v_fma_f32 v1, -v60, v62, v1
	v_mul_f32_e32 v60, 0xbfb8aa3b, v57
	v_exp_f32_e32 v60, v60
	v_div_fmas_f32 v1, v1, v61, v62
	v_div_fixup_f32 v1, v1, v2, v56
	v_mul_f32_e32 v1, v52, v1
	v_add_f32_e32 v2, 1.0, v60
	v_div_scale_f32 v56, s[10:11], v2, v2, v57
	v_rcp_f32_e32 v60, v56
	v_cvt_pk_bf16_f32 v1, v1, s0
	ds_write_b16 v132, v1 offset:9248
	v_fma_f32 v1, -v56, v60, 1.0
	v_fmac_f32_e32 v60, v1, v60
	v_div_scale_f32 v1, vcc, v57, v2, v57
	v_mul_f32_e32 v52, v1, v60
	v_fma_f32 v61, -v56, v52, v1
	v_fmac_f32_e32 v52, v61, v60
	v_fma_f32 v1, -v56, v52, v1
	v_mul_f32_e32 v56, 0xbfb8aa3b, v58
	v_exp_f32_e32 v56, v56
	v_div_fmas_f32 v1, v1, v60, v52
	v_div_fixup_f32 v1, v1, v2, v57
	v_mul_f32_e32 v1, v53, v1
	v_add_f32_e32 v2, 1.0, v56
	v_div_scale_f32 v52, s[10:11], v2, v2, v58
	v_rcp_f32_e32 v56, v52
	v_cvt_pk_bf16_f32 v1, v1, s0
	ds_write_b16 v132, v1 offset:9392
	v_fma_f32 v1, -v52, v56, 1.0
	v_fmac_f32_e32 v56, v1, v56
	v_div_scale_f32 v1, vcc, v58, v2, v58
	v_mul_f32_e32 v53, v1, v56
	v_fma_f32 v57, -v52, v53, v1
	v_fmac_f32_e32 v53, v57, v56
	v_fma_f32 v1, -v52, v53, v1
	v_mul_f32_e32 v52, 0xbfb8aa3b, v59
	v_exp_f32_e32 v52, v52
	v_div_fmas_f32 v1, v1, v56, v53
	v_div_fixup_f32 v1, v1, v2, v58
	v_mul_f32_e32 v1, v54, v1
	v_add_f32_e32 v2, 1.0, v52
	v_div_scale_f32 v52, s[10:11], v2, v2, v59
	v_rcp_f32_e32 v53, v52
	v_cvt_pk_bf16_f32 v1, v1, s0
	ds_write_b16 v132, v1 offset:9536
	v_fma_f32 v1, -v52, v53, 1.0
	v_fmac_f32_e32 v53, v1, v53
	v_div_scale_f32 v1, vcc, v59, v2, v59
	v_mul_f32_e32 v54, v1, v53
	v_fma_f32 v56, -v52, v54, v1
	v_fmac_f32_e32 v54, v56, v53
	v_fma_f32 v1, -v52, v54, v1
	v_mul_f32_e32 v52, 0xbfb8aa3b, v48
	v_exp_f32_e32 v52, v52
	v_div_fmas_f32 v1, v1, v53, v54
	v_div_fixup_f32 v1, v1, v2, v59
	v_mul_f32_e32 v1, v55, v1
	v_add_f32_e32 v2, 1.0, v52
	v_div_scale_f32 v52, s[10:11], v2, v2, v48
	v_rcp_f32_e32 v53, v52
	v_cvt_pk_bf16_f32 v1, v1, s0
	ds_write_b16 v132, v1 offset:9680
	v_fma_f32 v1, -v52, v53, 1.0
	v_fmac_f32_e32 v53, v1, v53
	v_div_scale_f32 v1, vcc, v48, v2, v48
	v_mul_f32_e32 v54, v1, v53
	v_fma_f32 v55, -v52, v54, v1
	v_fmac_f32_e32 v54, v55, v53
	v_fma_f32 v1, -v52, v54, v1
	v_mul_f32_e32 v52, 0xbfb8aa3b, v49
	v_exp_f32_e32 v52, v52
	v_div_fmas_f32 v1, v1, v53, v54
	v_div_fixup_f32 v1, v1, v2, v48
	v_mul_f32_e32 v1, v44, v1
	v_add_f32_e32 v2, 1.0, v52
	v_div_scale_f32 v48, s[10:11], v2, v2, v49
	v_rcp_f32_e32 v52, v48
	v_cvt_pk_bf16_f32 v1, v1, s0
	ds_write_b16 v132, v1 offset:11520
	v_fma_f32 v1, -v48, v52, 1.0
	v_fmac_f32_e32 v52, v1, v52
	v_div_scale_f32 v1, vcc, v49, v2, v49
	v_mul_f32_e32 v44, v1, v52
	v_fma_f32 v53, -v48, v44, v1
	v_fmac_f32_e32 v44, v53, v52
	v_fma_f32 v1, -v48, v44, v1
	v_mul_f32_e32 v48, 0xbfb8aa3b, v50
	v_exp_f32_e32 v48, v48
	v_div_fmas_f32 v1, v1, v52, v44
	v_div_fixup_f32 v1, v1, v2, v49
	v_mul_f32_e32 v1, v45, v1
	v_add_f32_e32 v2, 1.0, v48
	v_div_scale_f32 v44, s[10:11], v2, v2, v50
	v_rcp_f32_e32 v48, v44
	v_cvt_pk_bf16_f32 v1, v1, s0
	ds_write_b16 v132, v1 offset:11664
	v_fma_f32 v1, -v44, v48, 1.0
	v_fmac_f32_e32 v48, v1, v48
	v_div_scale_f32 v1, vcc, v50, v2, v50
	v_mul_f32_e32 v45, v1, v48
	v_fma_f32 v49, -v44, v45, v1
	v_fmac_f32_e32 v45, v49, v48
	v_fma_f32 v1, -v44, v45, v1
	v_mul_f32_e32 v44, 0xbfb8aa3b, v51
	v_exp_f32_e32 v44, v44
	v_div_fmas_f32 v1, v1, v48, v45
	v_div_fixup_f32 v1, v1, v2, v50
	v_mul_f32_e32 v1, v46, v1
	v_add_f32_e32 v2, 1.0, v44
	v_div_scale_f32 v44, s[10:11], v2, v2, v51
	v_rcp_f32_e32 v45, v44
	v_cvt_pk_bf16_f32 v1, v1, s0
	ds_write_b16 v132, v1 offset:11808
	v_fma_f32 v1, -v44, v45, 1.0
	v_fmac_f32_e32 v45, v1, v45
	v_div_scale_f32 v1, vcc, v51, v2, v51
	v_mul_f32_e32 v46, v1, v45
	v_fma_f32 v48, -v44, v46, v1
	v_fmac_f32_e32 v46, v48, v45
	v_fma_f32 v1, -v44, v46, v1
	v_mul_f32_e32 v44, 0xbfb8aa3b, v40
	v_exp_f32_e32 v44, v44
	v_div_fmas_f32 v1, v1, v45, v46
	v_div_fixup_f32 v1, v1, v2, v51
	v_mul_f32_e32 v1, v47, v1
	v_add_f32_e32 v2, 1.0, v44
	v_div_scale_f32 v44, s[10:11], v2, v2, v40
	v_rcp_f32_e32 v45, v44
	v_cvt_pk_bf16_f32 v1, v1, s0
	ds_write_b16 v132, v1 offset:11952
	v_fma_f32 v1, -v44, v45, 1.0
	v_fmac_f32_e32 v45, v1, v45
	v_div_scale_f32 v1, vcc, v40, v2, v40
	v_mul_f32_e32 v46, v1, v45
	v_fma_f32 v47, -v44, v46, v1
	v_fmac_f32_e32 v46, v47, v45
	v_fma_f32 v1, -v44, v46, v1
	v_mul_f32_e32 v44, 0xbfb8aa3b, v41
	v_exp_f32_e32 v44, v44
	v_div_fmas_f32 v1, v1, v45, v46
	v_div_fixup_f32 v1, v1, v2, v40
; DEVI float silu_(float x) { return x / (1.f + __expf(-x)); }
; DEVI void ffn1_tile256(const P& p, const bf* W, long row0, int n0  , char* smem) {
;     ...
; #pragma unroll
;   for (int m = 0; m < 8; ++m)
; #pragma unroll
;     for (int pr = 0; pr < 2; ++pr) {
;       const int cl = (wc * 2 + pr) * 16 + l15;
; #pragma unroll
;       for (int j = 0; j < 4; ++j) {
;         const int rl = wr * 128 + m * 16 + quad * 4 + j;
;         float a = acc[m][2 * pr][j], b = acc[m][2 * pr + 1][j];
;         tl[rl * 72 + cl] = f2bf(silu_(a) * b);
;       }
	v_mul_f32_e32 v1, v36, v1
	v_add_f32_e32 v2, 1.0, v44
	v_div_scale_f32 v40, s[10:11], v2, v2, v41
	v_rcp_f32_e32 v44, v40
	v_cvt_pk_bf16_f32 v1, v1, s0
	ds_write_b16 v132, v1 offset:11552
	v_fma_f32 v1, -v40, v44, 1.0
	v_fmac_f32_e32 v44, v1, v44
	v_div_scale_f32 v1, vcc, v41, v2, v41
	v_mul_f32_e32 v36, v1, v44
	v_fma_f32 v45, -v40, v36, v1
	v_fmac_f32_e32 v36, v45, v44
	v_fma_f32 v1, -v40, v36, v1
	v_mul_f32_e32 v40, 0xbfb8aa3b, v42
	v_exp_f32_e32 v40, v40
	v_div_fmas_f32 v1, v1, v44, v36
	v_div_fixup_f32 v1, v1, v2, v41
	v_mul_f32_e32 v1, v37, v1
	v_add_f32_e32 v2, 1.0, v40
	v_div_scale_f32 v36, s[10:11], v2, v2, v42
	v_rcp_f32_e32 v40, v36
	v_cvt_pk_bf16_f32 v1, v1, s0
	ds_write_b16 v132, v1 offset:11696
	v_fma_f32 v1, -v36, v40, 1.0
	v_fmac_f32_e32 v40, v1, v40
	v_div_scale_f32 v1, vcc, v42, v2, v42
	v_mul_f32_e32 v37, v1, v40
	v_fma_f32 v41, -v36, v37, v1
	v_fmac_f32_e32 v37, v41, v40
	v_fma_f32 v1, -v36, v37, v1
	v_mul_f32_e32 v36, 0xbfb8aa3b, v43
	v_exp_f32_e32 v36, v36
	v_div_fmas_f32 v1, v1, v40, v37
	v_div_fixup_f32 v1, v1, v2, v42
	v_mul_f32_e32 v1, v38, v1
	v_add_f32_e32 v2, 1.0, v36
	v_div_scale_f32 v36, s[10:11], v2, v2, v43
	v_rcp_f32_e32 v37, v36
	v_cvt_pk_bf16_f32 v1, v1, s0
	ds_write_b16 v132, v1 offset:11840
	v_fma_f32 v1, -v36, v37, 1.0
	v_fmac_f32_e32 v37, v1, v37
	v_div_scale_f32 v1, vcc, v43, v2, v43
	v_mul_f32_e32 v38, v1, v37
	v_fma_f32 v40, -v36, v38, v1
	v_fmac_f32_e32 v38, v40, v37
	v_fma_f32 v1, -v36, v38, v1
	v_mul_f32_e32 v36, 0xbfb8aa3b, v32
	v_exp_f32_e32 v36, v36
	v_div_fmas_f32 v1, v1, v37, v38
	v_div_fixup_f32 v1, v1, v2, v43
	v_mul_f32_e32 v1, v39, v1
	v_add_f32_e32 v2, 1.0, v36
	v_div_scale_f32 v36, s[10:11], v2, v2, v32
	v_rcp_f32_e32 v37, v36
	v_cvt_pk_bf16_f32 v1, v1, s0
	ds_write_b16 v132, v1 offset:11984
	v_fma_f32 v1, -v36, v37, 1.0
	v_fmac_f32_e32 v37, v1, v37
	v_div_scale_f32 v1, vcc, v32, v2, v32
	v_mul_f32_e32 v38, v1, v37
	v_fma_f32 v39, -v36, v38, v1
	v_fmac_f32_e32 v38, v39, v37
	v_fma_f32 v1, -v36, v38, v1
	v_mul_f32_e32 v36, 0xbfb8aa3b, v33
	v_exp_f32_e32 v36, v36
	v_div_fmas_f32 v1, v1, v37, v38
	v_div_fixup_f32 v1, v1, v2, v32
	v_mul_f32_e32 v1, v28, v1
	v_add_f32_e32 v2, 1.0, v36
	v_div_scale_f32 v32, s[10:11], v2, v2, v33
	v_rcp_f32_e32 v36, v32
	v_cvt_pk_bf16_f32 v1, v1, s0
	ds_write_b16 v132, v1 offset:13824
	v_fma_f32 v1, -v32, v36, 1.0
	v_fmac_f32_e32 v36, v1, v36
	v_div_scale_f32 v1, vcc, v33, v2, v33
	v_mul_f32_e32 v28, v1, v36
	v_fma_f32 v37, -v32, v28, v1
	v_fmac_f32_e32 v28, v37, v36
	v_fma_f32 v1, -v32, v28, v1
	v_mul_f32_e32 v32, 0xbfb8aa3b, v34
	v_exp_f32_e32 v32, v32
	v_div_fmas_f32 v1, v1, v36, v28
	v_div_fixup_f32 v1, v1, v2, v33
	v_mul_f32_e32 v1, v29, v1
	v_add_f32_e32 v2, 1.0, v32
	v_div_scale_f32 v28, s[10:11], v2, v2, v34
	v_rcp_f32_e32 v32, v28
	v_cvt_pk_bf16_f32 v1, v1, s0
	ds_write_b16 v132, v1 offset:13968
	v_fma_f32 v1, -v28, v32, 1.0
	v_fmac_f32_e32 v32, v1, v32
	v_div_scale_f32 v1, vcc, v34, v2, v34
	v_mul_f32_e32 v29, v1, v32
	v_fma_f32 v33, -v28, v29, v1
	v_fmac_f32_e32 v29, v33, v32
	v_fma_f32 v1, -v28, v29, v1
	v_mul_f32_e32 v28, 0xbfb8aa3b, v35
	v_exp_f32_e32 v28, v28
	v_div_fmas_f32 v1, v1, v32, v29
	v_div_fixup_f32 v1, v1, v2, v34
	v_mul_f32_e32 v1, v30, v1
	v_add_f32_e32 v2, 1.0, v28
	v_div_scale_f32 v28, s[10:11], v2, v2, v35
	v_rcp_f32_e32 v29, v28
	v_cvt_pk_bf16_f32 v1, v1, s0
	ds_write_b16 v132, v1 offset:14112
	v_fma_f32 v1, -v28, v29, 1.0
	v_fmac_f32_e32 v29, v1, v29
	v_div_scale_f32 v1, vcc, v35, v2, v35
	v_mul_f32_e32 v30, v1, v29
	v_fma_f32 v32, -v28, v30, v1
	v_fmac_f32_e32 v30, v32, v29
	v_fma_f32 v1, -v28, v30, v1
	v_mul_f32_e32 v28, 0xbfb8aa3b, v24
	v_exp_f32_e32 v28, v28
	v_div_fmas_f32 v1, v1, v29, v30
	v_div_fixup_f32 v1, v1, v2, v35
	v_mul_f32_e32 v1, v31, v1
	v_add_f32_e32 v2, 1.0, v28
	v_div_scale_f32 v28, s[10:11], v2, v2, v24
	v_rcp_f32_e32 v29, v28
	v_cvt_pk_bf16_f32 v1, v1, s0
	ds_write_b16 v132, v1 offset:14256
	v_fma_f32 v1, -v28, v29, 1.0
	v_fmac_f32_e32 v29, v1, v29
	v_div_scale_f32 v1, vcc, v24, v2, v24
	v_mul_f32_e32 v30, v1, v29
	v_fma_f32 v31, -v28, v30, v1
	v_fmac_f32_e32 v30, v31, v29
	v_fma_f32 v1, -v28, v30, v1
	v_mul_f32_e32 v28, 0xbfb8aa3b, v25
	v_exp_f32_e32 v28, v28
	v_div_fmas_f32 v1, v1, v29, v30
	v_div_fixup_f32 v1, v1, v2, v24
	v_mul_f32_e32 v1, v20, v1
	v_add_f32_e32 v2, 1.0, v28
	v_div_scale_f32 v24, s[10:11], v2, v2, v25
	v_rcp_f32_e32 v28, v24
	v_cvt_pk_bf16_f32 v1, v1, s0
	ds_write_b16 v132, v1 offset:13856
	v_fma_f32 v1, -v24, v28, 1.0
	v_fmac_f32_e32 v28, v1, v28
	v_div_scale_f32 v1, vcc, v25, v2, v25
	v_mul_f32_e32 v20, v1, v28
	v_fma_f32 v29, -v24, v20, v1
	v_fmac_f32_e32 v20, v29, v28
	v_fma_f32 v1, -v24, v20, v1
	v_mul_f32_e32 v24, 0xbfb8aa3b, v26
	v_exp_f32_e32 v24, v24
	v_div_fmas_f32 v1, v1, v28, v20
	v_div_fixup_f32 v1, v1, v2, v25
	v_mul_f32_e32 v1, v21, v1
	v_add_f32_e32 v2, 1.0, v24
	v_div_scale_f32 v20, s[10:11], v2, v2, v26
	v_rcp_f32_e32 v24, v20
	v_cvt_pk_bf16_f32 v1, v1, s0
	ds_write_b16 v132, v1 offset:14000
	v_fma_f32 v1, -v20, v24, 1.0
	v_fmac_f32_e32 v24, v1, v24
	v_div_scale_f32 v1, vcc, v26, v2, v26
	v_mul_f32_e32 v21, v1, v24
	v_fma_f32 v25, -v20, v21, v1
	v_fmac_f32_e32 v21, v25, v24
	v_fma_f32 v1, -v20, v21, v1
	v_mul_f32_e32 v20, 0xbfb8aa3b, v27
	v_exp_f32_e32 v20, v20
	v_div_fmas_f32 v1, v1, v24, v21
	v_div_fixup_f32 v1, v1, v2, v26
	v_mul_f32_e32 v1, v22, v1
	v_add_f32_e32 v2, 1.0, v20
	v_div_scale_f32 v20, s[10:11], v2, v2, v27
	v_rcp_f32_e32 v21, v20
	v_cvt_pk_bf16_f32 v1, v1, s0
	ds_write_b16 v132, v1 offset:14144
	v_fma_f32 v1, -v20, v21, 1.0
	v_fmac_f32_e32 v21, v1, v21
	v_div_scale_f32 v1, vcc, v27, v2, v27
	v_mul_f32_e32 v22, v1, v21
	v_fma_f32 v24, -v20, v22, v1
; DEVI float silu_(float x) { return x / (1.f + __expf(-x)); }
; DEVI void ffn1_tile256(const P& p, const bf* W, long row0, int n0  , char* smem) {
;     ...
; #pragma unroll
;   for (int m = 0; m < 8; ++m)
; #pragma unroll
;     for (int pr = 0; pr < 2; ++pr) {
;       const int cl = (wc * 2 + pr) * 16 + l15;
; #pragma unroll
;       for (int j = 0; j < 4; ++j) {
;         const int rl = wr * 128 + m * 16 + quad * 4 + j;
;         float a = acc[m][2 * pr][j], b = acc[m][2 * pr + 1][j];
;         tl[rl * 72 + cl] = f2bf(silu_(a) * b);
;       }
;     }
;   __syncthreads();
	v_fmac_f32_e32 v22, v24, v21
	v_fma_f32 v1, -v20, v22, v1
	v_mul_f32_e32 v20, 0xbfb8aa3b, v16
	v_exp_f32_e32 v20, v20
	v_div_fmas_f32 v1, v1, v21, v22
	v_div_fixup_f32 v1, v1, v2, v27
	v_mul_f32_e32 v1, v23, v1
	v_add_f32_e32 v2, 1.0, v20
	v_div_scale_f32 v20, s[10:11], v2, v2, v16
	v_rcp_f32_e32 v21, v20
	v_cvt_pk_bf16_f32 v1, v1, s0
	ds_write_b16 v132, v1 offset:14288
	v_fma_f32 v1, -v20, v21, 1.0
	v_fmac_f32_e32 v21, v1, v21
	v_div_scale_f32 v1, vcc, v16, v2, v16
	v_mul_f32_e32 v22, v1, v21
	v_fma_f32 v23, -v20, v22, v1
	v_fmac_f32_e32 v22, v23, v21
	v_fma_f32 v1, -v20, v22, v1
	v_mul_f32_e32 v20, 0xbfb8aa3b, v17
	v_exp_f32_e32 v20, v20
	v_div_fmas_f32 v1, v1, v21, v22
	v_div_fixup_f32 v1, v1, v2, v16
	v_mul_f32_e32 v1, v12, v1
	v_add_f32_e32 v2, 1.0, v20
	v_div_scale_f32 v16, s[10:11], v2, v2, v17
	v_rcp_f32_e32 v20, v16
	v_cvt_pk_bf16_f32 v1, v1, s0
	ds_write_b16 v132, v1 offset:16128
	v_fma_f32 v1, -v16, v20, 1.0
	v_fmac_f32_e32 v20, v1, v20
	v_div_scale_f32 v1, vcc, v17, v2, v17
	v_mul_f32_e32 v12, v1, v20
	v_fma_f32 v21, -v16, v12, v1
	v_fmac_f32_e32 v12, v21, v20
	v_fma_f32 v1, -v16, v12, v1
	v_mul_f32_e32 v16, 0xbfb8aa3b, v18
	v_exp_f32_e32 v16, v16
	v_div_fmas_f32 v1, v1, v20, v12
	v_div_fixup_f32 v1, v1, v2, v17
	v_mul_f32_e32 v1, v13, v1
	v_add_f32_e32 v2, 1.0, v16
	v_div_scale_f32 v12, s[10:11], v2, v2, v18
	v_rcp_f32_e32 v16, v12
	v_cvt_pk_bf16_f32 v1, v1, s0
	ds_write_b16 v132, v1 offset:16272
	v_fma_f32 v1, -v12, v16, 1.0
	v_fmac_f32_e32 v16, v1, v16
	v_div_scale_f32 v1, vcc, v18, v2, v18
	v_mul_f32_e32 v13, v1, v16
	v_fma_f32 v17, -v12, v13, v1
	v_fmac_f32_e32 v13, v17, v16
	v_fma_f32 v1, -v12, v13, v1
	v_mul_f32_e32 v12, 0xbfb8aa3b, v19
	v_exp_f32_e32 v12, v12
	v_div_fmas_f32 v1, v1, v16, v13
	v_div_fixup_f32 v1, v1, v2, v18
	v_mul_f32_e32 v1, v14, v1
	v_add_f32_e32 v2, 1.0, v12
	v_div_scale_f32 v12, s[10:11], v2, v2, v19
	v_rcp_f32_e32 v13, v12
	v_cvt_pk_bf16_f32 v1, v1, s0
	ds_write_b16 v132, v1 offset:16416
	v_fma_f32 v1, -v12, v13, 1.0
	v_fmac_f32_e32 v13, v1, v13
	v_div_scale_f32 v1, vcc, v19, v2, v19
	v_mul_f32_e32 v14, v1, v13
	v_fma_f32 v16, -v12, v14, v1
	v_fmac_f32_e32 v14, v16, v13
	v_fma_f32 v1, -v12, v14, v1
	v_mul_f32_e32 v12, 0xbfb8aa3b, v8
	v_exp_f32_e32 v12, v12
	v_div_fmas_f32 v1, v1, v13, v14
	v_div_fixup_f32 v1, v1, v2, v19
	v_mul_f32_e32 v1, v15, v1
	v_add_f32_e32 v2, 1.0, v12
	v_div_scale_f32 v12, s[10:11], v2, v2, v8
	v_rcp_f32_e32 v13, v12
	v_cvt_pk_bf16_f32 v1, v1, s0
	ds_write_b16 v132, v1 offset:16560
	v_fma_f32 v1, -v12, v13, 1.0
	v_fmac_f32_e32 v13, v1, v13
	v_div_scale_f32 v1, vcc, v8, v2, v8
	v_mul_f32_e32 v14, v1, v13
	v_fma_f32 v15, -v12, v14, v1
	v_fmac_f32_e32 v14, v15, v13
	v_fma_f32 v1, -v12, v14, v1
	v_mul_f32_e32 v12, 0xbfb8aa3b, v9
	v_exp_f32_e32 v12, v12
	v_div_fmas_f32 v1, v1, v13, v14
	v_div_fixup_f32 v1, v1, v2, v8
	v_mul_f32_e32 v1, v4, v1
	v_add_f32_e32 v2, 1.0, v12
	v_div_scale_f32 v8, s[10:11], v2, v2, v9
	v_rcp_f32_e32 v12, v8
	v_cvt_pk_bf16_f32 v1, v1, s0
	ds_write_b16 v132, v1 offset:16160
	v_fma_f32 v1, -v8, v12, 1.0
	v_fmac_f32_e32 v12, v1, v12
	v_div_scale_f32 v1, vcc, v9, v2, v9
	v_mul_f32_e32 v4, v1, v12
	v_fma_f32 v13, -v8, v4, v1
	v_fmac_f32_e32 v4, v13, v12
	v_fma_f32 v1, -v8, v4, v1
	v_mul_f32_e32 v8, 0xbfb8aa3b, v10
	v_exp_f32_e32 v8, v8
	v_div_fmas_f32 v1, v1, v12, v4
	v_div_fixup_f32 v1, v1, v2, v9
	v_mul_f32_e32 v1, v5, v1
	v_add_f32_e32 v2, 1.0, v8
	v_div_scale_f32 v4, s[10:11], v2, v2, v10
	v_rcp_f32_e32 v8, v4
	v_cvt_pk_bf16_f32 v1, v1, s0
	ds_write_b16 v132, v1 offset:16304
	v_fma_f32 v1, -v4, v8, 1.0
	v_fmac_f32_e32 v8, v1, v8
	v_div_scale_f32 v1, vcc, v10, v2, v10
	v_mul_f32_e32 v5, v1, v8
	v_fma_f32 v9, -v4, v5, v1
	v_fmac_f32_e32 v5, v9, v8
	v_fma_f32 v1, -v4, v5, v1
	v_mul_f32_e32 v4, 0xbfb8aa3b, v11
	v_exp_f32_e32 v4, v4
	v_div_fmas_f32 v1, v1, v8, v5
	v_div_fixup_f32 v1, v1, v2, v10
	v_mul_f32_e32 v1, v6, v1
	v_add_f32_e32 v2, 1.0, v4
	v_div_scale_f32 v4, s[10:11], v2, v2, v11
	v_rcp_f32_e32 v5, v4
	v_cvt_pk_bf16_f32 v1, v1, s0
	ds_write_b16 v132, v1 offset:16448
	s_ashr_i32 s10, s38, 1
	v_fma_f32 v1, -v4, v5, 1.0
	v_fmac_f32_e32 v5, v1, v5
	v_div_scale_f32 v1, vcc, v11, v2, v11
	v_mul_f32_e32 v6, v1, v5
	v_fma_f32 v8, -v4, v6, v1
	v_fmac_f32_e32 v6, v8, v5
	v_fma_f32 v1, -v4, v6, v1
	v_div_fmas_f32 v1, v1, v5, v6
	v_div_fixup_f32 v1, v1, v2, v11
	v_mul_f32_e32 v1, v7, v1
	v_cvt_pk_bf16_f32 v1, v1, s0
	ds_write_b16 v132, v1 offset:16592
	v_mov_b32_e32 v1, v178
	s_waitcnt lgkmcnt(0)
	s_barrier
; DEVI int get_tid() { int t = threadIdx.x; asm volatile("" : "+v"(t)); return t; }
; template <int BN>
; DEVI void tile_store256(const char* smem, bf* __restrict__ C, long ldc, long row0, int col0) {
;   constexpr int LDT = BN + 8;
;   constexpr int CPR = BN / 8;
;   const int tid = get_tid();
; #pragma unroll
;   for (int i = 0; i < CPR; ++i) {
;     const int q = tid + 256 * i;
;     const int r = q / CPR, c = q - r * CPR;
;     u32x4 v = *reinterpret_cast<const u32x4*>(smem + (r * LDT + c * 8) * 2);
;     *reinterpret_cast<u32x4*>(C + (row0 + r) * ldc + col0 + c * 8) = v;
;   }
; }
; DEVI void phase_ffn1(const P& p, int f, char* smem) {
;     ...
;   for (int v = blockIdx.x; v < 128 * 44; v += gridDim.x) {
;     int m2, nt;
;     lat_tile_map256(v, 44, m2, nt);
;     ffn1_tile256(p, W, lat_row0_256(m2), nt * 128, smem);
	s_ashr_i32 s11, s10, 31
	v_ashrrev_i32_e32 v2, 31, v1
	v_lshrrev_b32_e32 v2, 29, v2
	s_lshl_b64 s[10:11], s[10:11], 1
	v_add_u32_e32 v2, v1, v2
	s_add_u32 s10, s58, s10
	v_ashrrev_i32_e32 v8, 3, v2
	s_addc_u32 s11, s59, s11
	v_lshlrev_b32_e32 v4, 6, v8
	v_lshlrev_b32_e32 v5, 3, v1
	v_ashrrev_i32_e32 v9, 31, v8
	v_mul_lo_u32 v2, v8, s80
	v_sub_u32_e32 v10, v5, v4
	v_lshl_add_u64 v[8:9], s[34:35], 0, v[8:9]
	v_mov_b64_e32 v[12:13], s[10:11]
	v_add_lshl_u32 v2, v10, v2, 1
	v_mad_u64_u32 v[14:15], s[10:11], v8, s31, v[12:13]
	ds_read_b128 v[4:7], v2
	v_mov_b32_e32 v2, v15
	v_mad_u64_u32 v[8:9], s[10:11], v9, s31, v[2:3]
	v_add_u32_e32 v2, 0x100, v1
	v_mov_b32_e32 v15, v8
	v_ashrrev_i32_e32 v8, 31, v2
	v_lshrrev_b32_e32 v8, 29, v8
	v_add_u32_e32 v8, v2, v8
	v_ashrrev_i32_e32 v16, 3, v8
	v_ashrrev_i32_e32 v11, 31, v10
	v_lshlrev_b32_e32 v9, 6, v16
	v_lshlrev_b32_e32 v2, 3, v2
	v_lshl_add_u64 v[14:15], v[10:11], 1, v[14:15]
	v_mul_lo_u32 v8, v16, s80
	v_sub_u32_e32 v18, v2, v9
	v_ashrrev_i32_e32 v17, 31, v16
	v_add_lshl_u32 v2, v18, v8, 1
	s_waitcnt lgkmcnt(0)
	global_store_dwordx4 v[14:15], v[4:7], off
	ds_read_b128 v[8:11], v2
	v_ashrrev_i32_e32 v19, 31, v18
	v_lshl_add_u64 v[4:5], s[34:35], 0, v[16:17]
	v_mad_u64_u32 v[6:7], s[10:11], v4, s31, v[12:13]
	v_mov_b32_e32 v2, v7
	v_mad_u64_u32 v[4:5], s[10:11], v5, s31, v[2:3]
	v_mov_b32_e32 v7, v4
	v_lshl_add_u64 v[4:5], v[18:19], 1, v[6:7]
	v_add_u32_e32 v2, 0x200, v1
	s_waitcnt lgkmcnt(0)
	global_store_dwordx4 v[4:5], v[8:11], off
	v_ashrrev_i32_e32 v4, 31, v2
	v_lshrrev_b32_e32 v4, 29, v4
	v_add_u32_e32 v4, v2, v4
	v_ashrrev_i32_e32 v8, 3, v4
	v_lshlrev_b32_e32 v5, 6, v8
	v_lshlrev_b32_e32 v2, 3, v2
	v_ashrrev_i32_e32 v9, 31, v8
	v_mul_lo_u32 v4, v8, s80
	v_sub_u32_e32 v10, v2, v5
	v_lshl_add_u64 v[8:9], s[34:35], 0, v[8:9]
	v_add_lshl_u32 v2, v10, v4, 1
	v_mad_u64_u32 v[14:15], s[10:11], v8, s31, v[12:13]
	ds_read_b128 v[4:7], v2
	v_mov_b32_e32 v2, v15
	v_mad_u64_u32 v[8:9], s[10:11], v9, s31, v[2:3]
	v_add_u32_e32 v2, 0x300, v1
	v_mov_b32_e32 v15, v8
	v_ashrrev_i32_e32 v8, 31, v2
	v_lshrrev_b32_e32 v8, 29, v8
	v_add_u32_e32 v8, v2, v8
	v_ashrrev_i32_e32 v16, 3, v8
	v_ashrrev_i32_e32 v11, 31, v10
	v_lshlrev_b32_e32 v9, 6, v16
	v_lshlrev_b32_e32 v2, 3, v2
	v_lshl_add_u64 v[14:15], v[10:11], 1, v[14:15]
	v_mul_lo_u32 v8, v16, s80
	v_sub_u32_e32 v18, v2, v9
	v_ashrrev_i32_e32 v17, 31, v16
	v_add_lshl_u32 v2, v18, v8, 1
	s_waitcnt lgkmcnt(0)
	global_store_dwordx4 v[14:15], v[4:7], off
	ds_read_b128 v[8:11], v2
	v_ashrrev_i32_e32 v19, 31, v18
	v_lshl_add_u64 v[4:5], s[34:35], 0, v[16:17]
	v_mad_u64_u32 v[6:7], s[10:11], v4, s31, v[12:13]
	v_mov_b32_e32 v2, v7
	v_mad_u64_u32 v[4:5], s[10:11], v5, s31, v[2:3]
	v_mov_b32_e32 v7, v4
	v_lshl_add_u64 v[4:5], v[18:19], 1, v[6:7]
	v_add_u32_e32 v2, 0x400, v1
	s_waitcnt lgkmcnt(0)
	global_store_dwordx4 v[4:5], v[8:11], off
	v_ashrrev_i32_e32 v4, 31, v2
	v_lshrrev_b32_e32 v4, 29, v4
	v_add_u32_e32 v4, v2, v4
	v_ashrrev_i32_e32 v8, 3, v4
	v_lshlrev_b32_e32 v5, 6, v8
	v_lshlrev_b32_e32 v2, 3, v2
	v_ashrrev_i32_e32 v9, 31, v8
	v_mul_lo_u32 v4, v8, s80
	v_sub_u32_e32 v10, v2, v5
	v_lshl_add_u64 v[8:9], s[34:35], 0, v[8:9]
	v_add_lshl_u32 v2, v10, v4, 1
	v_mad_u64_u32 v[14:15], s[10:11], v8, s31, v[12:13]
	ds_read_b128 v[4:7], v2
	v_mov_b32_e32 v2, v15
	v_mad_u64_u32 v[8:9], s[10:11], v9, s31, v[2:3]
	v_add_u32_e32 v2, 0x500, v1
	v_mov_b32_e32 v15, v8
	v_ashrrev_i32_e32 v8, 31, v2
	v_lshrrev_b32_e32 v8, 29, v8
	v_add_u32_e32 v8, v2, v8
	v_ashrrev_i32_e32 v16, 3, v8
	v_ashrrev_i32_e32 v11, 31, v10
	v_lshlrev_b32_e32 v9, 6, v16
	v_lshlrev_b32_e32 v2, 3, v2
	v_lshl_add_u64 v[14:15], v[10:11], 1, v[14:15]
	v_mul_lo_u32 v8, v16, s80
	v_sub_u32_e32 v18, v2, v9
	v_ashrrev_i32_e32 v17, 31, v16
	v_add_lshl_u32 v2, v18, v8, 1
	s_waitcnt lgkmcnt(0)
	global_store_dwordx4 v[14:15], v[4:7], off
	ds_read_b128 v[8:11], v2
	v_ashrrev_i32_e32 v19, 31, v18
	v_lshl_add_u64 v[4:5], s[34:35], 0, v[16:17]
	v_mad_u64_u32 v[6:7], s[10:11], v4, s31, v[12:13]
	v_mov_b32_e32 v2, v7
	v_mad_u64_u32 v[4:5], s[10:11], v5, s31, v[2:3]
	v_mov_b32_e32 v7, v4
	v_lshl_add_u64 v[4:5], v[18:19], 1, v[6:7]
	v_add_u32_e32 v2, 0x600, v1
	s_waitcnt lgkmcnt(0)
	global_store_dwordx4 v[4:5], v[8:11], off
	v_ashrrev_i32_e32 v4, 31, v2
	v_lshrrev_b32_e32 v4, 29, v4
	v_add_u32_e32 v4, v2, v4
	v_ashrrev_i32_e32 v8, 3, v4
	v_lshlrev_b32_e32 v5, 6, v8
	v_lshlrev_b32_e32 v2, 3, v2
	v_ashrrev_i32_e32 v9, 31, v8
	v_mul_lo_u32 v4, v8, s80
	v_sub_u32_e32 v10, v2, v5
	v_lshl_add_u64 v[8:9], s[34:35], 0, v[8:9]
	v_add_lshl_u32 v2, v10, v4, 1
	v_mad_u64_u32 v[14:15], s[10:11], v8, s31, v[12:13]
	ds_read_b128 v[4:7], v2
	v_mov_b32_e32 v2, v15
	v_add_u32_e32 v1, 0x700, v1
	v_mad_u64_u32 v[8:9], s[10:11], v9, s31, v[2:3]
	v_ashrrev_i32_e32 v2, 31, v1
	v_lshrrev_b32_e32 v2, 29, v2
	v_add_u32_e32 v2, v1, v2
	v_mov_b32_e32 v15, v8
	v_ashrrev_i32_e32 v11, 31, v10
	v_ashrrev_i32_e32 v16, 3, v2
	v_lshl_add_u64 v[14:15], v[10:11], 1, v[14:15]
	v_lshlrev_b32_e32 v8, 6, v16
	v_lshlrev_b32_e32 v1, 3, v1
	v_ashrrev_i32_e32 v17, 31, v16
	v_mul_lo_u32 v2, v16, s80
	v_sub_u32_e32 v18, v1, v8
	s_waitcnt lgkmcnt(0)
	global_store_dwordx4 v[14:15], v[4:7], off
	v_add_lshl_u32 v1, v18, v2, 1
	ds_read_b128 v[8:11], v1
	v_lshl_add_u64 v[4:5], s[34:35], 0, v[16:17]
	v_mad_u64_u32 v[6:7], s[10:11], v4, s31, v[12:13]
	v_mov_b32_e32 v2, v7
	v_mad_u64_u32 v[4:5], s[10:11], v5, s31, v[2:3]
	v_readlane_b32 s10, v252, 59
	v_mov_b32_e32 v7, v4
	v_ashrrev_i32_e32 v19, 31, v18
	s_add_i32 s2, s2, s10
	v_lshl_add_u64 v[4:5], v[18:19], 1, v[6:7]
	s_cmpk_gt_i32 s2, 0x15ff
	s_waitcnt lgkmcnt(0)
	global_store_dwordx4 v[4:5], v[8:11], off
	s_barrier
	v_readlane_b32 s11, v252, 60
	s_cbranch_scc0 .LBB0_935

; __global__ void __launch_bounds__(256, 2) fwd_kernel(P p, int ph_begin, int ph_end) {
;     ...
;   for (int ph = ph_begin; ph < ph_end; ++ph) {
;     if (ph == 2) continue;
;     run_phase(p, ph, smem);
;     if (ph + 1 < ph_end) {
;       if (ph_end < 0) grid.sync();
;       xcd_barrier(xb);
;     }
.LBB0_946:
	s_setprio 0
	v_readlane_b32 s2, v254, 63
	s_add_i32 s20, s2, 1
	v_readlane_b32 s2, v251, 48
	v_readlane_b32 s3, v251, 49
	s_cmp_ge_i32 s20, s3
	s_cbranch_scc0 .LBB0_947
	s_getpc_b64 s[98:99]
